# baseline (speedup 1.0000x reference)
; #define PG8_STAGE(bufoff, gbase, voff) do { _Pragma("unroll") for (int _i = 0; _i < 2; ++_i) \
;         __builtin_amdgcn_global_load_lds((const unsigned*)((const char*)(gbase) + (voff)[_i]), (LAS unsigned*)(lds + (bufoff) + ldsw + _i * 8192), 16, 0, 0); } while (0)
; #define PG8_LDA(dst, b, h) do { _Pragma("unroll") for (int m = 0; m < 4; ++m) _Pragma("unroll") for (int k = 0; k < 2; ++k) dst[m][k] = *(const LAS bf16x8*)(lds + PG8_SA(b, h) + aoff + m * 2048 + k * 1024); } while (0)
; #define PG8_LDB(dst, b, h) do { _Pragma("unroll") for (int n = 0; n < 2; ++n) _Pragma("unroll") for (int k = 0; k < 2; ++k) dst[n][k] = *(const LAS bf16x8*)(lds + PG8_SB(b, h) + boff + n * 2048 + k * 1024); } while (0)
; #define PG8_MMA(ai, bj, At, Bt) do { __builtin_amdgcn_s_setprio(1); _Pragma("unroll") for (int m = 0; m < 4; ++m) _Pragma("unroll") for (int n = 0; n < 2; ++n) _Pragma("unroll") for (int k = 0; k < 2; ++k) \
;         acc[ai][bj][m][n] = __builtin_amdgcn_mfma_f32_16x16x32_bf16(Bt[n][k], At[m][k], acc[ai][bj][m][n], 0, 0, 0); __builtin_amdgcn_s_setprio(0); } while (0)
; #define PG8_WAIT_L(n) asm volatile("s_waitcnt lgkmcnt(" #n ")" ::: "memory")
; #define PG8_BAR __builtin_amdgcn_s_barrier()
; #define PG8_SCHED __builtin_amdgcn_sched_barrier(0)
; template <class Epi>
; DEV void gemm_phase(LAS unsigned char* lds, const Gemm g, const StaticOrder& S, const Epi& E) {
;     ...
;             PG8_LDB(B0, 0, 0); PG8_SCHED; PG8_LDA(At, 0, 0); PG8_STAGE(PG8_SA(1, 1), a1 + hstep, voffA);
;             PG8_WAIT_L(8); PG8_BAR; PG8_WAIT_L(0); PG8_MMA(0, 0, At, B0); PG8_BAR; PG8_SCHED;
;             PG8_LDB(B1, 0, 1); PG8_STAGE(PG8_SB(0, 0), b2, voffB);
;             PG8_BAR; PG8_WAIT_L(0); PG8_MMA(0, 1, At, B1); PG8_BAR;
;             PG8_LDA(At, 0, 1); PG8_STAGE(PG8_SA(0, 0), a2, voffA);
;             PG8_BAR; PG8_WAIT_L(0); PG8_MMA(1, 0, At, B0); PG8_BAR; PG8_SCHED;
.LBB0_61:
	s_add_u32 s28, s26, 0xfff80080
	s_addc_u32 s29, s27, -1
	s_add_i32 s49, 0, 0x10000
	v_add_u32_e32 v140, s49, v178
	ds_read_b128 v[128:131], v140
	ds_read_b128 v[132:135], v140 offset:1024
	ds_read_b128 v[136:139], v140 offset:2048
	ds_read_b128 v[140:143], v140 offset:3072
	s_cmp_eq_u32 s48, 28
	s_cselect_b32 s31, s15, s29
	s_cselect_b32 s30, s19, s28
	s_cselect_b32 s29, s17, s47
	s_cselect_b32 s28, s25, s46
	s_add_i32 m0, s37, 0xc000
	ds_read_b128 v[154:157], v181
	ds_read_b128 v[174:177], v181 offset:1024
	ds_read_b128 v[182:185], v181 offset:2048
	ds_read_b128 v[186:189], v181 offset:3072
	ds_read_b128 v[190:193], v181 offset:4096
	ds_read_b128 v[194:197], v181 offset:5120
	ds_read_b128 v[214:217], v181 offset:6144
	ds_read_b128 v[218:221], v181 offset:7168
	global_load_lds_dwordx4 v150, s[26:27]
	s_add_i32 m0, s37, 0xe000
	s_nop 0
	global_load_lds_dwordx4 v152, s[26:27]
	s_waitcnt lgkmcnt(8)
	s_barrier
	s_waitcnt lgkmcnt(7)
	v_mfma_f32_16x16x32_bf16 v[124:127], v[128:131], v[154:157], v[124:127]
	v_mfma_f32_16x16x32_bf16 v[120:123], v[136:139], v[154:157], v[120:123]
	s_waitcnt lgkmcnt(5)
	v_mfma_f32_16x16x32_bf16 v[108:111], v[128:131], v[182:185], v[108:111]
	v_mfma_f32_16x16x32_bf16 v[104:107], v[136:139], v[182:185], v[104:107]
	s_waitcnt lgkmcnt(3)
	v_mfma_f32_16x16x32_bf16 v[92:95], v[128:131], v[190:193], v[92:95]
	v_mfma_f32_16x16x32_bf16 v[88:91], v[136:139], v[190:193], v[88:91]
	s_waitcnt lgkmcnt(1)
	v_mfma_f32_16x16x32_bf16 v[76:79], v[128:131], v[214:217], v[76:79]
	v_mfma_f32_16x16x32_bf16 v[72:75], v[136:139], v[214:217], v[72:75]
	v_mfma_f32_16x16x32_bf16 v[124:127], v[132:135], v[174:177], v[124:127]
	v_mfma_f32_16x16x32_bf16 v[120:123], v[140:143], v[174:177], v[120:123]
	v_mfma_f32_16x16x32_bf16 v[108:111], v[132:135], v[186:189], v[108:111]
	v_mfma_f32_16x16x32_bf16 v[104:107], v[140:143], v[186:189], v[104:107]
	v_mfma_f32_16x16x32_bf16 v[92:95], v[132:135], v[194:197], v[92:95]
	v_mfma_f32_16x16x32_bf16 v[88:91], v[140:143], v[194:197], v[88:91]
	s_waitcnt lgkmcnt(0)
	v_mfma_f32_16x16x32_bf16 v[76:79], v[132:135], v[218:221], v[76:79]
	v_mfma_f32_16x16x32_bf16 v[72:75], v[140:143], v[218:221], v[72:75]
	s_barrier
	s_add_i32 s52, 0, 0x14000
	v_add_u32_e32 v158, s52, v178
	s_add_i32 s49, s49, s36
	ds_read_b128 v[222:225], v158
	ds_read_b128 v[226:229], v158 offset:1024
	ds_read_b128 v[230:233], v158 offset:2048
	ds_read_b128 v[234:237], v158 offset:3072
	v_lshl_add_u64 v[158:159], s[28:29], 0, v[160:161]
	s_mov_b32 m0, s49
	v_lshl_add_u64 v[238:239], s[28:29], 0, v[148:149]
	global_load_lds_dwordx4 v160, s[28:29]
	s_add_i32 m0, s49, 0x2000
	s_nop 0
	global_load_lds_dwordx4 v148, s[28:29]
	s_barrier
	s_waitcnt lgkmcnt(3)
	v_mfma_f32_16x16x32_bf16 v[116:119], v[222:225], v[154:157], v[116:119]
	s_waitcnt lgkmcnt(1)
	v_mfma_f32_16x16x32_bf16 v[112:115], v[230:233], v[154:157], v[112:115]
	v_mfma_f32_16x16x32_bf16 v[100:103], v[222:225], v[182:185], v[100:103]
	v_mfma_f32_16x16x32_bf16 v[96:99], v[230:233], v[182:185], v[96:99]
	v_mfma_f32_16x16x32_bf16 v[84:87], v[222:225], v[190:193], v[84:87]
	v_mfma_f32_16x16x32_bf16 v[80:83], v[230:233], v[190:193], v[80:83]
	v_mfma_f32_16x16x32_bf16 v[68:71], v[222:225], v[214:217], v[68:71]
	v_mfma_f32_16x16x32_bf16 v[64:67], v[230:233], v[214:217], v[64:67]
	v_mfma_f32_16x16x32_bf16 v[116:119], v[226:229], v[174:177], v[116:119]
	s_waitcnt lgkmcnt(0)
	v_mfma_f32_16x16x32_bf16 v[112:115], v[234:237], v[174:177], v[112:115]
	v_mfma_f32_16x16x32_bf16 v[100:103], v[226:229], v[186:189], v[100:103]
	v_mfma_f32_16x16x32_bf16 v[96:99], v[234:237], v[186:189], v[96:99]
	v_mfma_f32_16x16x32_bf16 v[84:87], v[226:229], v[194:197], v[84:87]
	v_mfma_f32_16x16x32_bf16 v[80:83], v[234:237], v[194:197], v[80:83]
	v_mfma_f32_16x16x32_bf16 v[68:71], v[226:229], v[218:221], v[68:71]
	v_mfma_f32_16x16x32_bf16 v[64:67], v[234:237], v[218:221], v[64:67]
	s_mov_b32 m0, s37
	v_lshl_add_u64 v[240:241], s[30:31], 0, v[144:145]
	s_barrier
	ds_read_b128 v[154:157], v181 offset:16384
	ds_read_b128 v[174:177], v181 offset:17408
	ds_read_b128 v[182:185], v181 offset:18432
	ds_read_b128 v[186:189], v181 offset:19456
	ds_read_b128 v[190:193], v181 offset:20480
	ds_read_b128 v[194:197], v181 offset:21504
	ds_read_b128 v[214:217], v181 offset:22528
	ds_read_b128 v[218:221], v181 offset:23552
	global_load_lds_dwordx4 v144, s[30:31]
	v_lshl_add_u64 v[242:243], s[30:31], 0, v[146:147]
	s_mov_b32 m0, s38
	s_nop 0
	global_load_lds_dwordx4 v146, s[30:31]
	s_barrier
	s_waitcnt lgkmcnt(7)
	v_mfma_f32_16x16x32_bf16 v[60:63], v[128:131], v[154:157], v[60:63]
	v_mfma_f32_16x16x32_bf16 v[56:59], v[136:139], v[154:157], v[56:59]
	s_waitcnt lgkmcnt(5)
	v_mfma_f32_16x16x32_bf16 v[44:47], v[128:131], v[182:185], v[44:47]
	v_mfma_f32_16x16x32_bf16 v[40:43], v[136:139], v[182:185], v[40:43]
	s_waitcnt lgkmcnt(3)
	v_mfma_f32_16x16x32_bf16 v[28:31], v[128:131], v[190:193], v[28:31]
	v_mfma_f32_16x16x32_bf16 v[24:27], v[136:139], v[190:193], v[24:27]
	s_waitcnt lgkmcnt(1)
	v_mfma_f32_16x16x32_bf16 v[12:15], v[128:131], v[214:217], v[12:15]
	v_mfma_f32_16x16x32_bf16 v[8:11], v[136:139], v[214:217], v[8:11]
	v_mfma_f32_16x16x32_bf16 v[60:63], v[132:135], v[174:177], v[60:63]
	v_mfma_f32_16x16x32_bf16 v[56:59], v[140:143], v[174:177], v[56:59]
	v_mfma_f32_16x16x32_bf16 v[44:47], v[132:135], v[186:189], v[44:47]
	v_mfma_f32_16x16x32_bf16 v[40:43], v[140:143], v[186:189], v[40:43]
	v_mfma_f32_16x16x32_bf16 v[28:31], v[132:135], v[194:197], v[28:31]
	v_mfma_f32_16x16x32_bf16 v[24:27], v[140:143], v[194:197], v[24:27]
	s_waitcnt lgkmcnt(0)
	v_mfma_f32_16x16x32_bf16 v[12:15], v[132:135], v[218:221], v[12:15]
	v_mfma_f32_16x16x32_bf16 v[8:11], v[140:143], v[218:221], v[8:11]
	s_barrier
; #define PG8_STAGE(bufoff, gbase, voff) do { _Pragma("unroll") for (int _i = 0; _i < 2; ++_i) \
;         __builtin_amdgcn_global_load_lds((const unsigned*)((const char*)(gbase) + (voff)[_i]), (LAS unsigned*)(lds + (bufoff) + ldsw + _i * 8192), 16, 0, 0); } while (0)
; #define PG8_LDA(dst, b, h) do { _Pragma("unroll") for (int m = 0; m < 4; ++m) _Pragma("unroll") for (int k = 0; k < 2; ++k) dst[m][k] = *(const LAS bf16x8*)(lds + PG8_SA(b, h) + aoff + m * 2048 + k * 1024); } while (0)
; #define PG8_LDB(dst, b, h) do { _Pragma("unroll") for (int n = 0; n < 2; ++n) _Pragma("unroll") for (int k = 0; k < 2; ++k) dst[n][k] = *(const LAS bf16x8*)(lds + PG8_SB(b, h) + boff + n * 2048 + k * 1024); } while (0)
; #define PG8_MMA(ai, bj, At, Bt) do { __builtin_amdgcn_s_setprio(1); _Pragma("unroll") for (int m = 0; m < 4; ++m) _Pragma("unroll") for (int n = 0; n < 2; ++n) _Pragma("unroll") for (int k = 0; k < 2; ++k) \
;         acc[ai][bj][m][n] = __builtin_amdgcn_mfma_f32_16x16x32_bf16(Bt[n][k], At[m][k], acc[ai][bj][m][n], 0, 0, 0); __builtin_amdgcn_s_setprio(0); } while (0)
; #define PG8_WAIT_V(n) asm volatile("s_waitcnt vmcnt(" #n ")" ::: "memory")
; #define PG8_WAIT_L(n) asm volatile("s_waitcnt lgkmcnt(" #n ")" ::: "memory")
; #define PG8_BAR __builtin_amdgcn_s_barrier()
; #define PG8_SCHED __builtin_amdgcn_sched_barrier(0)
; template <class Epi>
; DEV void gemm_phase(LAS unsigned char* lds, const Gemm g, const StaticOrder& S, const Epi& E) {
;     ...
;             PG8_STAGE(PG8_SB(0, 1), b2 + hstep, voffB);
;             PG8_WAIT_V(6); PG8_BAR; PG8_MMA(1, 1, At, B1); PG8_BAR;
;             PG8_LDB(B0, 1, 0); PG8_SCHED; PG8_LDA(At, 1, 0); PG8_STAGE(PG8_SA(0, 1), a2 + hstep, voffA);
;             PG8_WAIT_L(8); PG8_BAR; PG8_WAIT_L(0); PG8_MMA(0, 0, At, B0); PG8_BAR; PG8_SCHED;
;             PG8_LDB(B1, 1, 1); PG8_STAGE(PG8_SB(1, 0), b3, voffB);
;             PG8_BAR; PG8_WAIT_L(0); PG8_MMA(0, 1, At, B1); PG8_BAR;
;             PG8_LDA(At, 1, 1); PG8_STAGE(PG8_SA(1, 0), a3, voffA);
	s_add_u32 s50, s28, 0x80000
	s_addc_u32 s51, s29, 0
	s_add_i32 s49, s52, s36
	s_mov_b32 m0, s49
	s_nop 0
	global_load_lds_dwordx4 v160, s[50:51]
	s_add_i32 m0, s49, 0x2000
	s_nop 0
	global_load_lds_dwordx4 v148, s[50:51]
	s_waitcnt vmcnt(6)
	s_barrier
	v_mfma_f32_16x16x32_bf16 v[52:55], v[222:225], v[154:157], v[52:55]
	v_mfma_f32_16x16x32_bf16 v[48:51], v[230:233], v[154:157], v[48:51]
	v_mfma_f32_16x16x32_bf16 v[36:39], v[222:225], v[182:185], v[36:39]
	v_mfma_f32_16x16x32_bf16 v[32:35], v[230:233], v[182:185], v[32:35]
	v_mfma_f32_16x16x32_bf16 v[20:23], v[222:225], v[190:193], v[20:23]
	v_mfma_f32_16x16x32_bf16 v[16:19], v[230:233], v[190:193], v[16:19]
	v_mfma_f32_16x16x32_bf16 v[4:7], v[222:225], v[214:217], v[4:7]
	v_mfma_f32_16x16x32_bf16 v[0:3], v[230:233], v[214:217], v[0:3]
	v_mfma_f32_16x16x32_bf16 v[52:55], v[226:229], v[174:177], v[52:55]
	v_mfma_f32_16x16x32_bf16 v[48:51], v[234:237], v[174:177], v[48:51]
	v_mfma_f32_16x16x32_bf16 v[36:39], v[226:229], v[186:189], v[36:39]
	v_mfma_f32_16x16x32_bf16 v[32:35], v[234:237], v[186:189], v[32:35]
	v_mfma_f32_16x16x32_bf16 v[20:23], v[226:229], v[194:197], v[20:23]
	v_mfma_f32_16x16x32_bf16 v[16:19], v[234:237], v[194:197], v[16:19]
	v_mfma_f32_16x16x32_bf16 v[4:7], v[226:229], v[218:221], v[4:7]
	v_mfma_f32_16x16x32_bf16 v[0:3], v[234:237], v[218:221], v[0:3]
	s_add_i32 s49, 0, 0x18000
	v_add_u32_e32 v140, s49, v178
	s_barrier
	ds_read_b128 v[128:131], v140
	ds_read_b128 v[132:135], v140 offset:1024
	ds_read_b128 v[136:139], v140 offset:2048
	ds_read_b128 v[140:143], v140 offset:3072
	s_add_u32 s30, s30, 0x80000
	s_addc_u32 s31, s31, 0
	s_mov_b32 m0, s39
	ds_read_b128 v[154:157], v181 offset:32768
	ds_read_b128 v[174:177], v181 offset:33792
	ds_read_b128 v[182:185], v181 offset:34816
	ds_read_b128 v[186:189], v181 offset:35840
	ds_read_b128 v[190:193], v181 offset:36864
	ds_read_b128 v[194:197], v181 offset:37888
	ds_read_b128 v[214:217], v181 offset:38912
	ds_read_b128 v[218:221], v181 offset:39936
	global_load_lds_dwordx4 v144, s[30:31]
	s_mov_b32 m0, s40
	s_nop 0
	global_load_lds_dwordx4 v146, s[30:31]
	s_waitcnt lgkmcnt(8)
	s_barrier
	s_waitcnt lgkmcnt(7)
	v_mfma_f32_16x16x32_bf16 v[124:127], v[128:131], v[154:157], v[124:127]
	v_mfma_f32_16x16x32_bf16 v[120:123], v[136:139], v[154:157], v[120:123]
	s_waitcnt lgkmcnt(5)
	v_mfma_f32_16x16x32_bf16 v[108:111], v[128:131], v[182:185], v[108:111]
	v_mfma_f32_16x16x32_bf16 v[104:107], v[136:139], v[182:185], v[104:107]
	s_waitcnt lgkmcnt(3)
	v_mfma_f32_16x16x32_bf16 v[92:95], v[128:131], v[190:193], v[92:95]
	v_mfma_f32_16x16x32_bf16 v[88:91], v[136:139], v[190:193], v[88:91]
	s_waitcnt lgkmcnt(1)
	v_mfma_f32_16x16x32_bf16 v[76:79], v[128:131], v[214:217], v[76:79]
	v_mfma_f32_16x16x32_bf16 v[72:75], v[136:139], v[214:217], v[72:75]
	v_mfma_f32_16x16x32_bf16 v[124:127], v[132:135], v[174:177], v[124:127]
	v_mfma_f32_16x16x32_bf16 v[120:123], v[140:143], v[174:177], v[120:123]
	v_mfma_f32_16x16x32_bf16 v[108:111], v[132:135], v[186:189], v[108:111]
	v_mfma_f32_16x16x32_bf16 v[104:107], v[140:143], v[186:189], v[104:107]
	v_mfma_f32_16x16x32_bf16 v[92:95], v[132:135], v[194:197], v[92:95]
	v_mfma_f32_16x16x32_bf16 v[88:91], v[140:143], v[194:197], v[88:91]
	s_waitcnt lgkmcnt(0)
	v_mfma_f32_16x16x32_bf16 v[76:79], v[132:135], v[218:221], v[76:79]
	v_mfma_f32_16x16x32_bf16 v[72:75], v[140:143], v[218:221], v[72:75]
	s_barrier
	s_add_i32 s30, 0, 0x1c000
	s_add_i32 s31, s49, s36
	v_add_u32_e32 v234, s30, v178
	v_lshl_add_u64 v[158:159], v[158:159], 0, s[2:3]
	s_mov_b32 m0, s31
	ds_read_b128 v[222:225], v234
	ds_read_b128 v[226:229], v234 offset:1024
	ds_read_b128 v[230:233], v234 offset:2048
	ds_read_b128 v[234:237], v234 offset:3072
	global_load_lds_dwordx4 v[158:159], off
	v_lshl_add_u64 v[158:159], v[238:239], 0, s[2:3]
	s_add_i32 m0, s31, 0x2000
	s_nop 0
	global_load_lds_dwordx4 v[158:159], off
	s_barrier
	s_waitcnt lgkmcnt(3)
	v_mfma_f32_16x16x32_bf16 v[116:119], v[222:225], v[154:157], v[116:119]
	s_waitcnt lgkmcnt(1)
	v_mfma_f32_16x16x32_bf16 v[112:115], v[230:233], v[154:157], v[112:115]
	v_mfma_f32_16x16x32_bf16 v[100:103], v[222:225], v[182:185], v[100:103]
	v_mfma_f32_16x16x32_bf16 v[96:99], v[230:233], v[182:185], v[96:99]
	v_mfma_f32_16x16x32_bf16 v[84:87], v[222:225], v[190:193], v[84:87]
	v_mfma_f32_16x16x32_bf16 v[80:83], v[230:233], v[190:193], v[80:83]
	v_mfma_f32_16x16x32_bf16 v[68:71], v[222:225], v[214:217], v[68:71]
	v_mfma_f32_16x16x32_bf16 v[64:67], v[230:233], v[214:217], v[64:67]
	v_mfma_f32_16x16x32_bf16 v[116:119], v[226:229], v[174:177], v[116:119]
	s_waitcnt lgkmcnt(0)
	v_mfma_f32_16x16x32_bf16 v[112:115], v[234:237], v[174:177], v[112:115]
	v_mfma_f32_16x16x32_bf16 v[100:103], v[226:229], v[186:189], v[100:103]
	v_mfma_f32_16x16x32_bf16 v[96:99], v[234:237], v[186:189], v[96:99]
	v_mfma_f32_16x16x32_bf16 v[84:87], v[226:229], v[194:197], v[84:87]
	v_mfma_f32_16x16x32_bf16 v[80:83], v[234:237], v[194:197], v[80:83]
	v_mfma_f32_16x16x32_bf16 v[68:71], v[226:229], v[218:221], v[68:71]
	v_mfma_f32_16x16x32_bf16 v[64:67], v[234:237], v[218:221], v[64:67]
	s_mov_b32 m0, s41
	v_lshl_add_u64 v[158:159], v[240:241], 0, s[2:3]
	s_barrier
	ds_read_b128 v[154:157], v181 offset:49152
	ds_read_b128 v[174:177], v181 offset:50176
	ds_read_b128 v[182:185], v181 offset:51200
	ds_read_b128 v[186:189], v181 offset:52224
	ds_read_b128 v[190:193], v181 offset:53248
	ds_read_b128 v[194:197], v181 offset:54272
	ds_read_b128 v[214:217], v181 offset:55296
	ds_read_b128 v[218:221], v181 offset:56320
	global_load_lds_dwordx4 v[158:159], off
	v_lshl_add_u64 v[158:159], v[242:243], 0, s[2:3]
	s_mov_b32 m0, s42
	s_nop 0
	global_load_lds_dwordx4 v[158:159], off
	s_barrier
; DEV bf16x8 pack8(f32x4 a, f32x4 b) { u32x4 w; w.x = cvt_pk_bf16(a[0], a[1]); w.y = cvt_pk_bf16(a[2], a[3]); w.z = cvt_pk_bf16(b[0], b[1]); w.w = cvt_pk_bf16(b[2], b[3]); return __builtin_bit_cast(bf16x8, w); }
; #define PG8_STAGE(bufoff, gbase, voff) do { _Pragma("unroll") for (int _i = 0; _i < 2; ++_i) \
;         __builtin_amdgcn_global_load_lds((const unsigned*)((const char*)(gbase) + (voff)[_i]), (LAS unsigned*)(lds + (bufoff) + ldsw + _i * 8192), 16, 0, 0); } while (0)
; #define PG8_LDA(dst, b, h) do { _Pragma("unroll") for (int m = 0; m < 4; ++m) _Pragma("unroll") for (int k = 0; k < 2; ++k) dst[m][k] = *(const LAS bf16x8*)(lds + PG8_SA(b, h) + aoff + m * 2048 + k * 1024); } while (0)
; #define PG8_BAR __builtin_amdgcn_s_barrier()
; template <class Epi>
; DEV void gemm_phase(LAS unsigned char* lds, const Gemm g, const StaticOrder& S, const Epi& E) {
;     ...
;             PG8_LDA(At, 1, 1); PG8_STAGE(PG8_SA(1, 0), a3, voffA);
;             PG8_BAR; PG8_WAIT_L(0); PG8_MMA(1, 0, At, B0); PG8_BAR; PG8_SCHED;
;             PG8_STAGE(PG8_SB(1, 1), b3 + hstep, voffB);
;             PG8_WAIT_V(6); PG8_BAR; PG8_MMA(1, 1, At, B1); PG8_BAR;
;         }
;     DEV void operator()(AccRef acc, const pg8::Unit& u, int wr, int wc, int fr, int fq) const {
;     ...
;                     for (int n = 0; n < 2; ++n) bv[m][bj][n] = *(const f32x4*)(base + (size_t)(row0 + ai * 128 + m * 16) * 2048 + col0 + bj * 128 + n * 4);
; #pragma unroll
;             for (int m = m0; m < m0 + 2; ++m) { const size_t off = (size_t)(row0 + ai * 128 + m * 16) * 2048 + col0; float sq = 0.f;
; #pragma unroll
;                 for (int bj = 0; bj < 2; ++bj) { const f32x4 o0 = bv[m][bj][0] + scale * acc[ai][bj][m][0], o1 = bv[m][bj][1] + scale * acc[ai][bj][m][1];
;                     *(f32x4*)(out + off + bj * 128) = o0; *(f32x4*)(out + off + bj * 128 + 4) = o1;
;                     if (xb) { *(u32x4*)(xb + off + bj * 128) = __builtin_bit_cast(u32x4, pack8(o0, o1));
;                         sq += (o0[0] * o0[0] + o0[1] * o0[1] + o0[2] * o0[2] + o0[3] * o0[3]) + (o1[0] * o1[0] + o1[1] * o1[1] + o1[2] * o1[2] + o1[3] * o1[3]); } }
;                 if (ssout) { sq += __shfl_xor(sq, 16); sq += __shfl_xor(sq, 32);
;                     if (fq == 0) { if (red) red[(ai * 128 + wr * 64 + m * 16 + fr) * 4 + wc] = sq; else atomicAdd(ssout + (size_t)(row0 + ai * 128 + m * 16) * 8 + u.pn, sq); } } }
	s_waitcnt lgkmcnt(7)
	v_mfma_f32_16x16x32_bf16 v[60:63], v[128:131], v[154:157], v[60:63]
	v_mfma_f32_16x16x32_bf16 v[56:59], v[136:139], v[154:157], v[56:59]
	s_waitcnt lgkmcnt(5)
	v_mfma_f32_16x16x32_bf16 v[44:47], v[128:131], v[182:185], v[44:47]
	v_mfma_f32_16x16x32_bf16 v[40:43], v[136:139], v[182:185], v[40:43]
	s_waitcnt lgkmcnt(3)
	v_mfma_f32_16x16x32_bf16 v[28:31], v[128:131], v[190:193], v[28:31]
	v_mfma_f32_16x16x32_bf16 v[24:27], v[136:139], v[190:193], v[24:27]
	s_waitcnt lgkmcnt(1)
	v_mfma_f32_16x16x32_bf16 v[12:15], v[128:131], v[214:217], v[12:15]
	v_mfma_f32_16x16x32_bf16 v[8:11], v[136:139], v[214:217], v[8:11]
	v_mfma_f32_16x16x32_bf16 v[60:63], v[132:135], v[174:177], v[60:63]
	v_mfma_f32_16x16x32_bf16 v[56:59], v[140:143], v[174:177], v[56:59]
	v_mfma_f32_16x16x32_bf16 v[44:47], v[132:135], v[186:189], v[44:47]
	v_mfma_f32_16x16x32_bf16 v[40:43], v[140:143], v[186:189], v[40:43]
	v_mfma_f32_16x16x32_bf16 v[28:31], v[132:135], v[194:197], v[28:31]
	v_mfma_f32_16x16x32_bf16 v[24:27], v[140:143], v[194:197], v[24:27]
	s_waitcnt lgkmcnt(0)
	v_mfma_f32_16x16x32_bf16 v[12:15], v[132:135], v[218:221], v[12:15]
	v_mfma_f32_16x16x32_bf16 v[8:11], v[140:143], v[218:221], v[8:11]
	s_barrier
	s_add_u32 s28, s28, 0x80080
	s_addc_u32 s29, s29, 0
	s_add_i32 s30, s30, s36
	s_mov_b32 m0, s30
	s_nop 0
	global_load_lds_dwordx4 v160, s[28:29]
	s_add_i32 m0, s30, 0x2000
	s_nop 0
	global_load_lds_dwordx4 v148, s[28:29]
	s_waitcnt vmcnt(6)
	s_barrier
	v_mfma_f32_16x16x32_bf16 v[52:55], v[222:225], v[154:157], v[52:55]
	v_mfma_f32_16x16x32_bf16 v[48:51], v[230:233], v[154:157], v[48:51]
	v_mfma_f32_16x16x32_bf16 v[36:39], v[222:225], v[182:185], v[36:39]
	v_mfma_f32_16x16x32_bf16 v[32:35], v[230:233], v[182:185], v[32:35]
	v_mfma_f32_16x16x32_bf16 v[20:23], v[222:225], v[190:193], v[20:23]
	v_mfma_f32_16x16x32_bf16 v[16:19], v[230:233], v[190:193], v[16:19]
	v_mfma_f32_16x16x32_bf16 v[4:7], v[222:225], v[214:217], v[4:7]
	v_mfma_f32_16x16x32_bf16 v[0:3], v[230:233], v[214:217], v[0:3]
	v_mfma_f32_16x16x32_bf16 v[52:55], v[226:229], v[174:177], v[52:55]
	v_mfma_f32_16x16x32_bf16 v[48:51], v[234:237], v[174:177], v[48:51]
	v_mfma_f32_16x16x32_bf16 v[36:39], v[226:229], v[186:189], v[36:39]
	v_mfma_f32_16x16x32_bf16 v[32:35], v[234:237], v[186:189], v[32:35]
	v_mfma_f32_16x16x32_bf16 v[20:23], v[226:229], v[194:197], v[20:23]
	v_mfma_f32_16x16x32_bf16 v[16:19], v[234:237], v[194:197], v[16:19]
	v_mfma_f32_16x16x32_bf16 v[4:7], v[226:229], v[218:221], v[4:7]
	v_mfma_f32_16x16x32_bf16 v[0:3], v[234:237], v[218:221], v[0:3]
	s_add_i32 s48, s48, 2
	s_add_u32 s26, s26, 0x100
	s_addc_u32 s27, s27, 0
	s_add_u32 s46, s46, 0x100
	s_addc_u32 s47, s47, 0
	s_cmp_gt_u32 s48, 29
	s_barrier
	s_cbranch_scc0 .LBB0_61
	v_lshl_add_u32 v156, s24, 8, v167
	v_lshl_or_b32 v154, s14, 8, v179
	v_readlane_b32 s24, v254, 16
	v_ashrrev_i32_e32 v155, 31, v154
	v_readlane_b32 s25, v254, 17
	v_ashrrev_i32_e32 v157, 31, v156
	v_lshlrev_b64 v[128:129], 13, v[156:157]
	v_lshl_add_u64 v[158:159], v[154:155], 2, s[24:25]
	v_lshl_add_u64 v[214:215], v[158:159], 0, v[128:129]
	global_load_dwordx4 v[182:185], v[214:215], off offset:16
	global_load_dwordx4 v[186:189], v[214:215], off
	global_load_dwordx4 v[190:193], v[214:215], off offset:528
	global_load_dwordx4 v[194:197], v[214:215], off offset:512
	v_or_b32_e32 v174, 16, v156
	v_ashrrev_i32_e32 v175, 31, v174
	v_lshlrev_b64 v[128:129], 13, v[174:175]
	v_lshl_add_u64 v[176:177], v[158:159], 0, v[128:129]
	global_load_dwordx4 v[136:139], v[176:177], off offset:16
	global_load_dwordx4 v[140:143], v[176:177], off
	global_load_dwordx4 v[128:131], v[176:177], off offset:528
	global_load_dwordx4 v[132:135], v[176:177], off offset:512
	v_lshlrev_b64 v[216:217], 11, v[156:157]
	v_readlane_b32 s24, v250, 9
	v_lshl_add_u64 v[216:217], v[216:217], 0, v[154:155]
	v_readlane_b32 s25, v250, 10
	v_cmp_lt_i32_e32 vcc, v208, v206
	s_ashr_i32 s15, s14, 31
	s_waitcnt vmcnt(0)
	v_pk_add_f32 v[120:121], v[120:121], v[182:183]
	v_pk_add_f32 v[126:127], v[126:127], v[188:189]
	v_pk_add_f32 v[124:125], v[124:125], v[186:187]
	v_pk_add_f32 v[122:123], v[122:123], v[184:185]
	global_store_dwordx4 v[214:215], v[124:127], off
	global_store_dwordx4 v[214:215], v[120:123], off offset:16
	v_cvt_pk_bf16_f32 v184, v120, v121
	v_cvt_pk_bf16_f32 v182, v124, v125
	v_mul_f32_e32 v121, v121, v121
	v_cvt_pk_bf16_f32 v183, v126, v127
	v_cvt_pk_bf16_f32 v185, v122, v123
	v_lshl_add_u64 v[186:187], v[216:217], 1, s[24:25]
	v_fmac_f32_e32 v121, v120, v120
	v_pk_add_f32 v[118:119], v[118:119], v[196:197]
	v_pk_add_f32 v[116:117], v[116:117], v[194:195]
	v_pk_add_f32 v[112:113], v[112:113], v[190:191]
	global_store_dwordx4 v[186:187], v[182:185], off
	v_mul_f32_e32 v125, v125, v125
	v_fmac_f32_e32 v121, v122, v122
	v_pk_add_f32 v[114:115], v[114:115], v[192:193]
	global_store_dwordx4 v[214:215], v[116:119], off offset:512
	global_store_dwordx4 v[214:215], v[112:115], off offset:528
	v_cvt_pk_bf16_f32 v120, v116, v117
	v_cvt_pk_bf16_f32 v122, v112, v113
	v_mul_f32_e32 v117, v117, v117
	v_mul_f32_e32 v113, v113, v113
	v_fmac_f32_e32 v125, v124, v124
	v_fmac_f32_e32 v117, v116, v116
	v_fmac_f32_e32 v113, v112, v112
	v_fmac_f32_e32 v125, v126, v126
	v_fmac_f32_e32 v117, v118, v118
	v_fmac_f32_e32 v113, v114, v114
	v_fmac_f32_e32 v125, v127, v127
	v_fmac_f32_e32 v121, v123, v123
	v_fmac_f32_e32 v117, v119, v119
	v_fmac_f32_e32 v113, v115, v115
	v_add_f32_e32 v124, v125, v121
	v_add_f32_e32 v112, v117, v113
	v_cndmask_b32_e32 v113, v204, v208, vcc
	v_cvt_pk_bf16_f32 v121, v118, v119
	v_add_f32_e32 v112, v124, v112
	v_lshlrev_b32_e32 v118, 2, v113
	ds_bpermute_b32 v113, v118, v112
	v_cmp_lt_i32_e32 vcc, v207, v206
	v_cvt_pk_bf16_f32 v123, v114, v115
	global_store_dwordx4 v[186:187], v[120:123], off offset:256
	s_waitcnt lgkmcnt(0)
	v_add_f32_e32 v112, v112, v113
	v_cndmask_b32_e32 v113, v204, v207, vcc
	v_lshlrev_b32_e32 v119, 2, v113
	ds_bpermute_b32 v113, v119, v112
	s_and_saveexec_b64 s[24:25], s[6:7]
	s_cbranch_execz .LBB0_67
	s_waitcnt lgkmcnt(0)
	v_add_f32_e32 v112, v112, v113
	s_mov_b64 s[26:27], -1
	s_and_b64 vcc, exec, s[12:13]
	s_cbranch_vccz .LBB0_65
	v_readlane_b32 s26, v250, 37
	v_lshlrev_b64 v[114:115], 5, v[156:157]
	v_readlane_b32 s27, v250, 38
	s_nop 1
	v_lshl_add_u64 v[114:115], s[26:27], 0, v[114:115]
	v_lshl_add_u64 v[114:115], s[14:15], 2, v[114:115]
	global_atomic_add_f32 v[114:115], v112, off
	s_mov_b64 s[26:27], 0

; #define PG8_STAGE(bufoff, gbase, voff) do { _Pragma("unroll") for (int _i = 0; _i < 2; ++_i) \
;         __builtin_amdgcn_global_load_lds((const unsigned*)((const char*)(gbase) + (voff)[_i]), (LAS unsigned*)(lds + (bufoff) + ldsw + _i * 8192), 16, 0, 0); } while (0)
; #define PG8_LDA(dst, b, h) do { _Pragma("unroll") for (int m = 0; m < 4; ++m) _Pragma("unroll") for (int k = 0; k < 2; ++k) dst[m][k] = *(const LAS bf16x8*)(lds + PG8_SA(b, h) + aoff + m * 2048 + k * 1024); } while (0)
; #define PG8_LDB(dst, b, h) do { _Pragma("unroll") for (int n = 0; n < 2; ++n) _Pragma("unroll") for (int k = 0; k < 2; ++k) dst[n][k] = *(const LAS bf16x8*)(lds + PG8_SB(b, h) + boff + n * 2048 + k * 1024); } while (0)
; #define PG8_MMA(ai, bj, At, Bt) do { __builtin_amdgcn_s_setprio(1); _Pragma("unroll") for (int m = 0; m < 4; ++m) _Pragma("unroll") for (int n = 0; n < 2; ++n) _Pragma("unroll") for (int k = 0; k < 2; ++k) \
;         acc[ai][bj][m][n] = __builtin_amdgcn_mfma_f32_16x16x32_bf16(Bt[n][k], At[m][k], acc[ai][bj][m][n], 0, 0, 0); __builtin_amdgcn_s_setprio(0); } while (0)
; #define PG8_WAIT_L(n) asm volatile("s_waitcnt lgkmcnt(" #n ")" ::: "memory")
; #define PG8_BAR __builtin_amdgcn_s_barrier()
; #define PG8_SCHED __builtin_amdgcn_sched_barrier(0)
; template <class Epi>
; DEV void gemm_phase(LAS unsigned char* lds, const Gemm g, const StaticOrder& S, const Epi& E) {
;     ...
;             PG8_LDB(B0, 0, 0); PG8_SCHED; PG8_LDA(At, 0, 0); PG8_STAGE(PG8_SA(1, 1), a1 + hstep, voffA);
;             PG8_WAIT_L(8); PG8_BAR; PG8_WAIT_L(0); PG8_MMA(0, 0, At, B0); PG8_BAR; PG8_SCHED;
;             PG8_LDB(B1, 0, 1); PG8_STAGE(PG8_SB(0, 0), b2, voffB);
;             PG8_BAR; PG8_WAIT_L(0); PG8_MMA(0, 1, At, B1); PG8_BAR;
;             PG8_LDA(At, 0, 1); PG8_STAGE(PG8_SA(0, 0), a2, voffA);
;             PG8_BAR; PG8_WAIT_L(0); PG8_MMA(1, 0, At, B0); PG8_BAR; PG8_SCHED;
.LBB0_152:
	s_add_u32 s20, s18, 0xfff80080
	s_addc_u32 s21, s19, -1
	s_add_i32 s41, 0, 0x10000
	v_add_u32_e32 v140, s41, v176
	ds_read_b128 v[128:131], v140
	ds_read_b128 v[132:135], v140 offset:1024
	ds_read_b128 v[136:139], v140 offset:2048
	ds_read_b128 v[140:143], v140 offset:3072
	s_cmp_eq_u32 s40, 28
	s_cselect_b32 s23, s5, s21
	s_cselect_b32 s22, s11, s20
	s_cselect_b32 s21, s9, s39
	s_cselect_b32 s20, s37, s38
	s_add_i32 m0, s17, 0xc000
	ds_read_b128 v[180:183], v178
	ds_read_b128 v[184:187], v178 offset:1024
	ds_read_b128 v[188:191], v178 offset:2048
	ds_read_b128 v[192:195], v178 offset:3072
	ds_read_b128 v[214:217], v178 offset:4096
	ds_read_b128 v[218:221], v178 offset:5120
	ds_read_b128 v[222:225], v178 offset:6144
	ds_read_b128 v[226:229], v178 offset:7168
	global_load_lds_dwordx4 v154, s[18:19]
	s_add_i32 m0, s17, 0xe000
	s_nop 0
	global_load_lds_dwordx4 v156, s[18:19]
	s_waitcnt lgkmcnt(8)
	s_barrier
	s_waitcnt lgkmcnt(7)
	v_mfma_f32_16x16x32_bf16 v[124:127], v[128:131], v[180:183], v[124:127]
	v_mfma_f32_16x16x32_bf16 v[120:123], v[136:139], v[180:183], v[120:123]
	s_waitcnt lgkmcnt(5)
	v_mfma_f32_16x16x32_bf16 v[108:111], v[128:131], v[188:191], v[108:111]
	v_mfma_f32_16x16x32_bf16 v[104:107], v[136:139], v[188:191], v[104:107]
	s_waitcnt lgkmcnt(3)
	v_mfma_f32_16x16x32_bf16 v[92:95], v[128:131], v[214:217], v[92:95]
	v_mfma_f32_16x16x32_bf16 v[88:91], v[136:139], v[214:217], v[88:91]
	s_waitcnt lgkmcnt(1)
	v_mfma_f32_16x16x32_bf16 v[76:79], v[128:131], v[222:225], v[76:79]
	v_mfma_f32_16x16x32_bf16 v[72:75], v[136:139], v[222:225], v[72:75]
	v_mfma_f32_16x16x32_bf16 v[124:127], v[132:135], v[184:187], v[124:127]
	v_mfma_f32_16x16x32_bf16 v[120:123], v[140:143], v[184:187], v[120:123]
	v_mfma_f32_16x16x32_bf16 v[108:111], v[132:135], v[192:195], v[108:111]
	v_mfma_f32_16x16x32_bf16 v[104:107], v[140:143], v[192:195], v[104:107]
	v_mfma_f32_16x16x32_bf16 v[92:95], v[132:135], v[218:221], v[92:95]
	v_mfma_f32_16x16x32_bf16 v[88:91], v[140:143], v[218:221], v[88:91]
	s_waitcnt lgkmcnt(0)
	v_mfma_f32_16x16x32_bf16 v[76:79], v[132:135], v[226:229], v[76:79]
	v_mfma_f32_16x16x32_bf16 v[72:75], v[140:143], v[226:229], v[72:75]
	s_barrier
	s_add_i32 s44, 0, 0x14000
	v_add_u32_e32 v158, s44, v176
	s_add_i32 s41, s41, s26
	ds_read_b128 v[230:233], v158
	ds_read_b128 v[234:237], v158 offset:1024
	ds_read_b128 v[238:241], v158 offset:2048
	ds_read_b128 v[242:245], v158 offset:3072
	v_lshl_add_u64 v[158:159], s[20:21], 0, v[160:161]
	s_mov_b32 m0, s41
	v_lshl_add_u64 v[174:175], s[20:21], 0, v[144:145]
	global_load_lds_dwordx4 v160, s[20:21]
	s_add_i32 m0, s41, 0x2000
	s_nop 0
	global_load_lds_dwordx4 v144, s[20:21]
	s_barrier
	s_waitcnt lgkmcnt(3)
	v_mfma_f32_16x16x32_bf16 v[116:119], v[230:233], v[180:183], v[116:119]
	s_waitcnt lgkmcnt(1)
	v_mfma_f32_16x16x32_bf16 v[112:115], v[238:241], v[180:183], v[112:115]
	v_mfma_f32_16x16x32_bf16 v[100:103], v[230:233], v[188:191], v[100:103]
	v_mfma_f32_16x16x32_bf16 v[96:99], v[238:241], v[188:191], v[96:99]
	v_mfma_f32_16x16x32_bf16 v[84:87], v[230:233], v[214:217], v[84:87]
	v_mfma_f32_16x16x32_bf16 v[80:83], v[238:241], v[214:217], v[80:83]
	v_mfma_f32_16x16x32_bf16 v[68:71], v[230:233], v[222:225], v[68:71]
	v_mfma_f32_16x16x32_bf16 v[64:67], v[238:241], v[222:225], v[64:67]
	v_mfma_f32_16x16x32_bf16 v[116:119], v[234:237], v[184:187], v[116:119]
	s_waitcnt lgkmcnt(0)
	v_mfma_f32_16x16x32_bf16 v[112:115], v[242:245], v[184:187], v[112:115]
	v_mfma_f32_16x16x32_bf16 v[100:103], v[234:237], v[192:195], v[100:103]
	v_mfma_f32_16x16x32_bf16 v[96:99], v[242:245], v[192:195], v[96:99]
	v_mfma_f32_16x16x32_bf16 v[84:87], v[234:237], v[218:221], v[84:87]
	v_mfma_f32_16x16x32_bf16 v[80:83], v[242:245], v[218:221], v[80:83]
	v_mfma_f32_16x16x32_bf16 v[68:71], v[234:237], v[226:229], v[68:71]
	v_mfma_f32_16x16x32_bf16 v[64:67], v[242:245], v[226:229], v[64:67]
	s_mov_b32 m0, s17
	v_lshl_add_u64 v[196:197], s[22:23], 0, v[160:161]
	s_barrier
	ds_read_b128 v[180:183], v178 offset:16384
	ds_read_b128 v[184:187], v178 offset:17408
	ds_read_b128 v[188:191], v178 offset:18432
	ds_read_b128 v[192:195], v178 offset:19456
	ds_read_b128 v[214:217], v178 offset:20480
	ds_read_b128 v[218:221], v178 offset:21504
	ds_read_b128 v[222:225], v178 offset:22528
	ds_read_b128 v[226:229], v178 offset:23552
	global_load_lds_dwordx4 v160, s[22:23]
	v_lshl_add_u64 v[246:247], s[22:23], 0, v[144:145]
	s_mov_b32 m0, s27
	s_nop 0
	global_load_lds_dwordx4 v144, s[22:23]
	s_barrier
	s_waitcnt lgkmcnt(7)
	v_mfma_f32_16x16x32_bf16 v[60:63], v[128:131], v[180:183], v[60:63]
	v_mfma_f32_16x16x32_bf16 v[56:59], v[136:139], v[180:183], v[56:59]
	s_waitcnt lgkmcnt(5)
	v_mfma_f32_16x16x32_bf16 v[44:47], v[128:131], v[188:191], v[44:47]
	v_mfma_f32_16x16x32_bf16 v[40:43], v[136:139], v[188:191], v[40:43]
	s_waitcnt lgkmcnt(3)
	v_mfma_f32_16x16x32_bf16 v[28:31], v[128:131], v[214:217], v[28:31]
	v_mfma_f32_16x16x32_bf16 v[24:27], v[136:139], v[214:217], v[24:27]
	s_waitcnt lgkmcnt(1)
	v_mfma_f32_16x16x32_bf16 v[12:15], v[128:131], v[222:225], v[12:15]
	v_mfma_f32_16x16x32_bf16 v[8:11], v[136:139], v[222:225], v[8:11]
	v_mfma_f32_16x16x32_bf16 v[60:63], v[132:135], v[184:187], v[60:63]
	v_mfma_f32_16x16x32_bf16 v[56:59], v[140:143], v[184:187], v[56:59]
	v_mfma_f32_16x16x32_bf16 v[44:47], v[132:135], v[192:195], v[44:47]
	v_mfma_f32_16x16x32_bf16 v[40:43], v[140:143], v[192:195], v[40:43]
	v_mfma_f32_16x16x32_bf16 v[28:31], v[132:135], v[218:221], v[28:31]
	v_mfma_f32_16x16x32_bf16 v[24:27], v[140:143], v[218:221], v[24:27]
	s_waitcnt lgkmcnt(0)
	v_mfma_f32_16x16x32_bf16 v[12:15], v[132:135], v[226:229], v[12:15]
	v_mfma_f32_16x16x32_bf16 v[8:11], v[140:143], v[226:229], v[8:11]
	s_barrier
; #define PG8_STAGE(bufoff, gbase, voff) do { _Pragma("unroll") for (int _i = 0; _i < 2; ++_i) \
;         __builtin_amdgcn_global_load_lds((const unsigned*)((const char*)(gbase) + (voff)[_i]), (LAS unsigned*)(lds + (bufoff) + ldsw + _i * 8192), 16, 0, 0); } while (0)
; #define PG8_LDA(dst, b, h) do { _Pragma("unroll") for (int m = 0; m < 4; ++m) _Pragma("unroll") for (int k = 0; k < 2; ++k) dst[m][k] = *(const LAS bf16x8*)(lds + PG8_SA(b, h) + aoff + m * 2048 + k * 1024); } while (0)
; #define PG8_LDB(dst, b, h) do { _Pragma("unroll") for (int n = 0; n < 2; ++n) _Pragma("unroll") for (int k = 0; k < 2; ++k) dst[n][k] = *(const LAS bf16x8*)(lds + PG8_SB(b, h) + boff + n * 2048 + k * 1024); } while (0)
; #define PG8_MMA(ai, bj, At, Bt) do { __builtin_amdgcn_s_setprio(1); _Pragma("unroll") for (int m = 0; m < 4; ++m) _Pragma("unroll") for (int n = 0; n < 2; ++n) _Pragma("unroll") for (int k = 0; k < 2; ++k) \
;         acc[ai][bj][m][n] = __builtin_amdgcn_mfma_f32_16x16x32_bf16(Bt[n][k], At[m][k], acc[ai][bj][m][n], 0, 0, 0); __builtin_amdgcn_s_setprio(0); } while (0)
; #define PG8_WAIT_V(n) asm volatile("s_waitcnt vmcnt(" #n ")" ::: "memory")
; #define PG8_WAIT_L(n) asm volatile("s_waitcnt lgkmcnt(" #n ")" ::: "memory")
; #define PG8_BAR __builtin_amdgcn_s_barrier()
; #define PG8_SCHED __builtin_amdgcn_sched_barrier(0)
; template <class Epi>
; DEV void gemm_phase(LAS unsigned char* lds, const Gemm g, const StaticOrder& S, const Epi& E) {
;     ...
;             PG8_STAGE(PG8_SB(0, 1), b2 + hstep, voffB);
;             PG8_WAIT_V(6); PG8_BAR; PG8_MMA(1, 1, At, B1); PG8_BAR;
;             PG8_LDB(B0, 1, 0); PG8_SCHED; PG8_LDA(At, 1, 0); PG8_STAGE(PG8_SA(0, 1), a2 + hstep, voffA);
;             PG8_WAIT_L(8); PG8_BAR; PG8_WAIT_L(0); PG8_MMA(0, 0, At, B0); PG8_BAR; PG8_SCHED;
;             PG8_LDB(B1, 1, 1); PG8_STAGE(PG8_SB(1, 0), b3, voffB);
;             PG8_BAR; PG8_WAIT_L(0); PG8_MMA(0, 1, At, B1); PG8_BAR;
;             PG8_LDA(At, 1, 1); PG8_STAGE(PG8_SA(1, 0), a3, voffA);
	s_add_u32 s42, s20, 0x80000
	s_addc_u32 s43, s21, 0
	s_add_i32 s41, s44, s26
	s_mov_b32 m0, s41
	s_nop 0
	global_load_lds_dwordx4 v160, s[42:43]
	s_add_i32 m0, s41, 0x2000
	s_nop 0
	global_load_lds_dwordx4 v144, s[42:43]
	s_waitcnt vmcnt(6)
	s_barrier
	v_mfma_f32_16x16x32_bf16 v[52:55], v[230:233], v[180:183], v[52:55]
	v_mfma_f32_16x16x32_bf16 v[48:51], v[238:241], v[180:183], v[48:51]
	v_mfma_f32_16x16x32_bf16 v[36:39], v[230:233], v[188:191], v[36:39]
	v_mfma_f32_16x16x32_bf16 v[32:35], v[238:241], v[188:191], v[32:35]
	v_mfma_f32_16x16x32_bf16 v[20:23], v[230:233], v[214:217], v[20:23]
	v_mfma_f32_16x16x32_bf16 v[16:19], v[238:241], v[214:217], v[16:19]
	v_mfma_f32_16x16x32_bf16 v[4:7], v[230:233], v[222:225], v[4:7]
	v_mfma_f32_16x16x32_bf16 v[0:3], v[238:241], v[222:225], v[0:3]
	v_mfma_f32_16x16x32_bf16 v[52:55], v[234:237], v[184:187], v[52:55]
	v_mfma_f32_16x16x32_bf16 v[48:51], v[242:245], v[184:187], v[48:51]
	v_mfma_f32_16x16x32_bf16 v[36:39], v[234:237], v[192:195], v[36:39]
	v_mfma_f32_16x16x32_bf16 v[32:35], v[242:245], v[192:195], v[32:35]
	v_mfma_f32_16x16x32_bf16 v[20:23], v[234:237], v[218:221], v[20:23]
	v_mfma_f32_16x16x32_bf16 v[16:19], v[242:245], v[218:221], v[16:19]
	v_mfma_f32_16x16x32_bf16 v[4:7], v[234:237], v[226:229], v[4:7]
	v_mfma_f32_16x16x32_bf16 v[0:3], v[242:245], v[226:229], v[0:3]
	s_add_i32 s41, 0, 0x18000
	v_add_u32_e32 v140, s41, v176
	s_barrier
	ds_read_b128 v[128:131], v140
	ds_read_b128 v[132:135], v140 offset:1024
	ds_read_b128 v[136:139], v140 offset:2048
	ds_read_b128 v[140:143], v140 offset:3072
	s_add_u32 s22, s22, 0x80000
	s_addc_u32 s23, s23, 0
	s_mov_b32 m0, s28
	ds_read_b128 v[180:183], v178 offset:32768
	ds_read_b128 v[184:187], v178 offset:33792
	ds_read_b128 v[188:191], v178 offset:34816
	ds_read_b128 v[192:195], v178 offset:35840
	ds_read_b128 v[214:217], v178 offset:36864
	ds_read_b128 v[218:221], v178 offset:37888
	ds_read_b128 v[222:225], v178 offset:38912
	ds_read_b128 v[226:229], v178 offset:39936
	global_load_lds_dwordx4 v160, s[22:23]
	s_mov_b32 m0, s29
	s_nop 0
	global_load_lds_dwordx4 v144, s[22:23]
	s_waitcnt lgkmcnt(8)
	s_barrier
	s_waitcnt lgkmcnt(7)
	v_mfma_f32_16x16x32_bf16 v[124:127], v[128:131], v[180:183], v[124:127]
	v_mfma_f32_16x16x32_bf16 v[120:123], v[136:139], v[180:183], v[120:123]
	s_waitcnt lgkmcnt(5)
	v_mfma_f32_16x16x32_bf16 v[108:111], v[128:131], v[188:191], v[108:111]
	v_mfma_f32_16x16x32_bf16 v[104:107], v[136:139], v[188:191], v[104:107]
	s_waitcnt lgkmcnt(3)
	v_mfma_f32_16x16x32_bf16 v[92:95], v[128:131], v[214:217], v[92:95]
	v_mfma_f32_16x16x32_bf16 v[88:91], v[136:139], v[214:217], v[88:91]
	s_waitcnt lgkmcnt(1)
	v_mfma_f32_16x16x32_bf16 v[76:79], v[128:131], v[222:225], v[76:79]
	v_mfma_f32_16x16x32_bf16 v[72:75], v[136:139], v[222:225], v[72:75]
	v_mfma_f32_16x16x32_bf16 v[124:127], v[132:135], v[184:187], v[124:127]
	v_mfma_f32_16x16x32_bf16 v[120:123], v[140:143], v[184:187], v[120:123]
	v_mfma_f32_16x16x32_bf16 v[108:111], v[132:135], v[192:195], v[108:111]
	v_mfma_f32_16x16x32_bf16 v[104:107], v[140:143], v[192:195], v[104:107]
	v_mfma_f32_16x16x32_bf16 v[92:95], v[132:135], v[218:221], v[92:95]
	v_mfma_f32_16x16x32_bf16 v[88:91], v[140:143], v[218:221], v[88:91]
	s_waitcnt lgkmcnt(0)
	v_mfma_f32_16x16x32_bf16 v[76:79], v[132:135], v[226:229], v[76:79]
	v_mfma_f32_16x16x32_bf16 v[72:75], v[140:143], v[226:229], v[72:75]
	s_barrier
	s_add_i32 s22, 0, 0x1c000
	s_add_i32 s23, s41, s26
	v_add_u32_e32 v179, s22, v176
	v_lshl_add_u64 v[158:159], v[158:159], 0, s[2:3]
	s_mov_b32 m0, s23
	ds_read_b128 v[230:233], v179
	ds_read_b128 v[234:237], v179 offset:1024
	ds_read_b128 v[238:241], v179 offset:2048
	ds_read_b128 v[242:245], v179 offset:3072
	global_load_lds_dwordx4 v[158:159], off
	v_lshl_add_u64 v[158:159], v[174:175], 0, s[2:3]
	s_add_i32 m0, s23, 0x2000
	s_nop 0
	global_load_lds_dwordx4 v[158:159], off
	s_barrier
	s_waitcnt lgkmcnt(3)
	v_mfma_f32_16x16x32_bf16 v[116:119], v[230:233], v[180:183], v[116:119]
	s_waitcnt lgkmcnt(1)
	v_mfma_f32_16x16x32_bf16 v[112:115], v[238:241], v[180:183], v[112:115]
	v_mfma_f32_16x16x32_bf16 v[100:103], v[230:233], v[188:191], v[100:103]
	v_mfma_f32_16x16x32_bf16 v[96:99], v[238:241], v[188:191], v[96:99]
	v_mfma_f32_16x16x32_bf16 v[84:87], v[230:233], v[214:217], v[84:87]
	v_mfma_f32_16x16x32_bf16 v[80:83], v[238:241], v[214:217], v[80:83]
	v_mfma_f32_16x16x32_bf16 v[68:71], v[230:233], v[222:225], v[68:71]
	v_mfma_f32_16x16x32_bf16 v[64:67], v[238:241], v[222:225], v[64:67]
	v_mfma_f32_16x16x32_bf16 v[116:119], v[234:237], v[184:187], v[116:119]
	s_waitcnt lgkmcnt(0)
	v_mfma_f32_16x16x32_bf16 v[112:115], v[242:245], v[184:187], v[112:115]
	v_mfma_f32_16x16x32_bf16 v[100:103], v[234:237], v[192:195], v[100:103]
	v_mfma_f32_16x16x32_bf16 v[96:99], v[242:245], v[192:195], v[96:99]
	v_mfma_f32_16x16x32_bf16 v[84:87], v[234:237], v[218:221], v[84:87]
	v_mfma_f32_16x16x32_bf16 v[80:83], v[242:245], v[218:221], v[80:83]
	v_mfma_f32_16x16x32_bf16 v[68:71], v[234:237], v[226:229], v[68:71]
	v_mfma_f32_16x16x32_bf16 v[64:67], v[242:245], v[226:229], v[64:67]
	s_mov_b32 m0, s30
	v_lshl_add_u64 v[158:159], v[196:197], 0, s[2:3]
	s_barrier
; #define PG8_STAGE(bufoff, gbase, voff) do { _Pragma("unroll") for (int _i = 0; _i < 2; ++_i) \
;         __builtin_amdgcn_global_load_lds((const unsigned*)((const char*)(gbase) + (voff)[_i]), (LAS unsigned*)(lds + (bufoff) + ldsw + _i * 8192), 16, 0, 0); } while (0)
; #define PG8_LDA(dst, b, h) do { _Pragma("unroll") for (int m = 0; m < 4; ++m) _Pragma("unroll") for (int k = 0; k < 2; ++k) dst[m][k] = *(const LAS bf16x8*)(lds + PG8_SA(b, h) + aoff + m * 2048 + k * 1024); } while (0)
; #define PG8_MMA(ai, bj, At, Bt) do { __builtin_amdgcn_s_setprio(1); _Pragma("unroll") for (int m = 0; m < 4; ++m) _Pragma("unroll") for (int n = 0; n < 2; ++n) _Pragma("unroll") for (int k = 0; k < 2; ++k) \
;         acc[ai][bj][m][n] = __builtin_amdgcn_mfma_f32_16x16x32_bf16(Bt[n][k], At[m][k], acc[ai][bj][m][n], 0, 0, 0); __builtin_amdgcn_s_setprio(0); } while (0)
; #define PG8_WAIT_V(n) asm volatile("s_waitcnt vmcnt(" #n ")" ::: "memory")
; #define PG8_WAIT_L(n) asm volatile("s_waitcnt lgkmcnt(" #n ")" ::: "memory")
; #define PG8_BAR __builtin_amdgcn_s_barrier()
; #define PG8_SCHED __builtin_amdgcn_sched_barrier(0)
; template <class Epi>
; DEV void gemm_phase(LAS unsigned char* lds, const Gemm g, const StaticOrder& S, const Epi& E) {
;     ...
;             PG8_LDA(At, 1, 1); PG8_STAGE(PG8_SA(1, 0), a3, voffA);
;             PG8_BAR; PG8_WAIT_L(0); PG8_MMA(1, 0, At, B0); PG8_BAR; PG8_SCHED;
;             PG8_STAGE(PG8_SB(1, 1), b3 + hstep, voffB);
;             PG8_WAIT_V(6); PG8_BAR; PG8_MMA(1, 1, At, B1); PG8_BAR;
;         }
;     DEV void operator()(AccRef acc, const pg8::Unit& u, int wr, int wc, int fr, int fq) const {
;         const int row0 = u.pm * 256 + wr * 64 + fr, col0 = u.pn * 256 + wc * 32 + 4 * fq;
;         const bool rope = (u.pn < 9) && ((wc & 1) == 0);
; #pragma unroll
;         for (int ai = 0; ai < 2; ++ai)
; #pragma unroll
;             for (int m = 0; m < 4; ++m) { const int row = row0 + ai * 128 + m * 16; u16* rowp = O + (size_t)row * 2560 + col0; const float rs = rowscale(ss, row);
;                 f32x4 cs = (f32x4){1.f, 1.f, 1.f, 1.f}, sn = (f32x4){0.f, 0.f, 0.f, 0.f};
;                 if (rope) { cs = *(const f32x4*)(cosT + row * 8 + 4 * (fq & 1)); sn = *(const f32x4*)(sinT + row * 8 + 4 * (fq & 1)); }
	ds_read_b128 v[180:183], v178 offset:49152
	ds_read_b128 v[184:187], v178 offset:50176
	ds_read_b128 v[188:191], v178 offset:51200
	ds_read_b128 v[192:195], v178 offset:52224
	ds_read_b128 v[214:217], v178 offset:53248
	ds_read_b128 v[218:221], v178 offset:54272
	ds_read_b128 v[222:225], v178 offset:55296
	ds_read_b128 v[226:229], v178 offset:56320
	global_load_lds_dwordx4 v[158:159], off
	v_lshl_add_u64 v[158:159], v[246:247], 0, s[2:3]
	s_mov_b32 m0, s31
	s_nop 0
	global_load_lds_dwordx4 v[158:159], off
	s_barrier
	s_waitcnt lgkmcnt(7)
	v_mfma_f32_16x16x32_bf16 v[60:63], v[128:131], v[180:183], v[60:63]
	v_mfma_f32_16x16x32_bf16 v[56:59], v[136:139], v[180:183], v[56:59]
	s_waitcnt lgkmcnt(5)
	v_mfma_f32_16x16x32_bf16 v[44:47], v[128:131], v[188:191], v[44:47]
	v_mfma_f32_16x16x32_bf16 v[40:43], v[136:139], v[188:191], v[40:43]
	s_waitcnt lgkmcnt(3)
	v_mfma_f32_16x16x32_bf16 v[28:31], v[128:131], v[214:217], v[28:31]
	v_mfma_f32_16x16x32_bf16 v[24:27], v[136:139], v[214:217], v[24:27]
	s_waitcnt lgkmcnt(1)
	v_mfma_f32_16x16x32_bf16 v[12:15], v[128:131], v[222:225], v[12:15]
	v_mfma_f32_16x16x32_bf16 v[8:11], v[136:139], v[222:225], v[8:11]
	v_mfma_f32_16x16x32_bf16 v[60:63], v[132:135], v[184:187], v[60:63]
	v_mfma_f32_16x16x32_bf16 v[56:59], v[140:143], v[184:187], v[56:59]
	v_mfma_f32_16x16x32_bf16 v[44:47], v[132:135], v[192:195], v[44:47]
	v_mfma_f32_16x16x32_bf16 v[40:43], v[140:143], v[192:195], v[40:43]
	v_mfma_f32_16x16x32_bf16 v[28:31], v[132:135], v[218:221], v[28:31]
	v_mfma_f32_16x16x32_bf16 v[24:27], v[140:143], v[218:221], v[24:27]
	s_waitcnt lgkmcnt(0)
	v_mfma_f32_16x16x32_bf16 v[12:15], v[132:135], v[226:229], v[12:15]
	v_mfma_f32_16x16x32_bf16 v[8:11], v[140:143], v[226:229], v[8:11]
	s_barrier
	s_add_u32 s20, s20, 0x80080
	s_addc_u32 s21, s21, 0
	s_add_i32 s22, s22, s26
	s_mov_b32 m0, s22
	s_nop 0
	global_load_lds_dwordx4 v160, s[20:21]
	s_add_i32 m0, s22, 0x2000
	s_nop 0
	global_load_lds_dwordx4 v144, s[20:21]
	s_waitcnt vmcnt(6)
	s_barrier
	v_mfma_f32_16x16x32_bf16 v[52:55], v[230:233], v[180:183], v[52:55]
	v_mfma_f32_16x16x32_bf16 v[48:51], v[238:241], v[180:183], v[48:51]
	v_mfma_f32_16x16x32_bf16 v[36:39], v[230:233], v[188:191], v[36:39]
	v_mfma_f32_16x16x32_bf16 v[32:35], v[238:241], v[188:191], v[32:35]
	v_mfma_f32_16x16x32_bf16 v[20:23], v[230:233], v[214:217], v[20:23]
	v_mfma_f32_16x16x32_bf16 v[16:19], v[238:241], v[214:217], v[16:19]
	v_mfma_f32_16x16x32_bf16 v[4:7], v[230:233], v[222:225], v[4:7]
	v_mfma_f32_16x16x32_bf16 v[0:3], v[238:241], v[222:225], v[0:3]
	v_mfma_f32_16x16x32_bf16 v[52:55], v[234:237], v[184:187], v[52:55]
	v_mfma_f32_16x16x32_bf16 v[48:51], v[242:245], v[184:187], v[48:51]
	v_mfma_f32_16x16x32_bf16 v[36:39], v[234:237], v[192:195], v[36:39]
	v_mfma_f32_16x16x32_bf16 v[32:35], v[242:245], v[192:195], v[32:35]
	v_mfma_f32_16x16x32_bf16 v[20:23], v[234:237], v[218:221], v[20:23]
	v_mfma_f32_16x16x32_bf16 v[16:19], v[242:245], v[218:221], v[16:19]
	v_mfma_f32_16x16x32_bf16 v[4:7], v[234:237], v[226:229], v[4:7]
	v_mfma_f32_16x16x32_bf16 v[0:3], v[242:245], v[226:229], v[0:3]
	s_add_i32 s40, s40, 2
	s_add_u32 s18, s18, 0x100
	s_addc_u32 s19, s19, 0
	s_add_u32 s38, s38, 0x100
	s_addc_u32 s39, s39, 0
	s_cmp_gt_u32 s40, 29
	s_barrier
	s_cbranch_scc0 .LBB0_152
	v_lshl_add_u32 v174, s4, 8, v167
	v_ashrrev_i32_e32 v175, 31, v174
	v_readlane_b32 s20, v250, 47
	v_lshlrev_b64 v[128:129], 5, v[174:175]
	v_readlane_b32 s21, v250, 48
	s_cmp_lt_i32 s16, 9
	s_cselect_b64 s[4:5], -1, 0
	v_lshl_add_u64 v[128:129], s[20:21], 0, v[128:129]
	global_load_dwordx4 v[136:139], v[128:129], off offset:16
	global_load_dwordx4 v[140:143], v[128:129], off
	s_and_b64 s[18:19], s[6:7], s[4:5]
	v_cndmask_b32_e64 v128, 0, 1, s[18:19]
	v_cmp_ne_u32_e64 s[4:5], 1, v128
	s_andn2_b64 vcc, exec, s[18:19]
	s_cbranch_vccnz .LBB0_155
	v_lshlrev_b32_e32 v128, 3, v174
	v_ashrrev_i32_e32 v129, 31, v128
	v_lshlrev_b64 v[128:129], 2, v[128:129]
	v_lshl_add_u64 v[130:131], v[152:153], 0, v[128:129]
	v_lshl_add_u64 v[132:133], v[150:151], 0, v[128:129]
	global_load_dwordx4 v[128:131], v[130:131], off
	s_nop 0
	global_load_dwordx4 v[132:135], v[132:133], off
	s_branch .LBB0_156

; #define PG8_STAGE(bufoff, gbase, voff) do { _Pragma("unroll") for (int _i = 0; _i < 2; ++_i) \
;         __builtin_amdgcn_global_load_lds((const unsigned*)((const char*)(gbase) + (voff)[_i]), (LAS unsigned*)(lds + (bufoff) + ldsw + _i * 8192), 16, 0, 0); } while (0)
; #define PG8_LDA(dst, b, h) do { _Pragma("unroll") for (int m = 0; m < 4; ++m) _Pragma("unroll") for (int k = 0; k < 2; ++k) dst[m][k] = *(const LAS bf16x8*)(lds + PG8_SA(b, h) + aoff + m * 2048 + k * 1024); } while (0)
; #define PG8_LDB(dst, b, h) do { _Pragma("unroll") for (int n = 0; n < 2; ++n) _Pragma("unroll") for (int k = 0; k < 2; ++k) dst[n][k] = *(const LAS bf16x8*)(lds + PG8_SB(b, h) + boff + n * 2048 + k * 1024); } while (0)
; #define PG8_MMA(ai, bj, At, Bt) do { __builtin_amdgcn_s_setprio(1); _Pragma("unroll") for (int m = 0; m < 4; ++m) _Pragma("unroll") for (int n = 0; n < 2; ++n) _Pragma("unroll") for (int k = 0; k < 2; ++k) \
;         acc[ai][bj][m][n] = __builtin_amdgcn_mfma_f32_16x16x32_bf16(Bt[n][k], At[m][k], acc[ai][bj][m][n], 0, 0, 0); __builtin_amdgcn_s_setprio(0); } while (0)
; #define PG8_WAIT_L(n) asm volatile("s_waitcnt lgkmcnt(" #n ")" ::: "memory")
; #define PG8_BAR __builtin_amdgcn_s_barrier()
; #define PG8_SCHED __builtin_amdgcn_sched_barrier(0)
; template <class Epi>
; DEV void gemm_phase(LAS unsigned char* lds, const Gemm g, const StaticOrder& S, const Epi& E) {
;     ...
;             PG8_LDB(B0, 0, 0); PG8_SCHED; PG8_LDA(At, 0, 0); PG8_STAGE(PG8_SA(1, 1), a1 + hstep, voffA);
;             PG8_WAIT_L(8); PG8_BAR; PG8_WAIT_L(0); PG8_MMA(0, 0, At, B0); PG8_BAR; PG8_SCHED;
;             PG8_LDB(B1, 0, 1); PG8_STAGE(PG8_SB(0, 0), b2, voffB);
;             PG8_BAR; PG8_WAIT_L(0); PG8_MMA(0, 1, At, B1); PG8_BAR;
;             PG8_LDA(At, 0, 1); PG8_STAGE(PG8_SA(0, 0), a2, voffA);
;             PG8_BAR; PG8_WAIT_L(0); PG8_MMA(1, 0, At, B0); PG8_BAR; PG8_SCHED;
.LBB0_260:
	s_add_u32 s34, s30, 0xfffe0080
	s_addc_u32 s35, s31, -1
	s_add_i32 s55, 0, 0x10000
	v_add_u32_e32 v140, s55, v178
	ds_read_b128 v[128:131], v140
	ds_read_b128 v[132:135], v140 offset:1024
	ds_read_b128 v[136:139], v140 offset:2048
	ds_read_b128 v[140:143], v140 offset:3072
	s_cmp_eq_u32 s54, 4
	s_cselect_b32 s37, s19, s35
	s_cselect_b32 s36, s23, s34
	s_cselect_b32 s35, s21, s53
	s_cselect_b32 s34, s29, s52
	s_add_i32 m0, s43, 0xc000
	ds_read_b128 v[154:157], v181
	ds_read_b128 v[174:177], v181 offset:1024
	ds_read_b128 v[182:185], v181 offset:2048
	ds_read_b128 v[186:189], v181 offset:3072
	ds_read_b128 v[190:193], v181 offset:4096
	ds_read_b128 v[194:197], v181 offset:5120
	ds_read_b128 v[214:217], v181 offset:6144
	ds_read_b128 v[218:221], v181 offset:7168
	global_load_lds_dwordx4 v150, s[30:31]
	s_add_i32 m0, s43, 0xe000
	s_nop 0
	global_load_lds_dwordx4 v152, s[30:31]
	s_waitcnt lgkmcnt(8)
	s_barrier
	s_waitcnt lgkmcnt(7)
	v_mfma_f32_16x16x32_bf16 v[124:127], v[128:131], v[154:157], v[124:127]
	v_mfma_f32_16x16x32_bf16 v[120:123], v[136:139], v[154:157], v[120:123]
	s_waitcnt lgkmcnt(5)
	v_mfma_f32_16x16x32_bf16 v[108:111], v[128:131], v[182:185], v[108:111]
	v_mfma_f32_16x16x32_bf16 v[104:107], v[136:139], v[182:185], v[104:107]
	s_waitcnt lgkmcnt(3)
	v_mfma_f32_16x16x32_bf16 v[92:95], v[128:131], v[190:193], v[92:95]
	v_mfma_f32_16x16x32_bf16 v[88:91], v[136:139], v[190:193], v[88:91]
	s_waitcnt lgkmcnt(1)
	v_mfma_f32_16x16x32_bf16 v[76:79], v[128:131], v[214:217], v[76:79]
	v_mfma_f32_16x16x32_bf16 v[72:75], v[136:139], v[214:217], v[72:75]
	v_mfma_f32_16x16x32_bf16 v[124:127], v[132:135], v[174:177], v[124:127]
	v_mfma_f32_16x16x32_bf16 v[120:123], v[140:143], v[174:177], v[120:123]
	v_mfma_f32_16x16x32_bf16 v[108:111], v[132:135], v[186:189], v[108:111]
	v_mfma_f32_16x16x32_bf16 v[104:107], v[140:143], v[186:189], v[104:107]
	v_mfma_f32_16x16x32_bf16 v[92:95], v[132:135], v[194:197], v[92:95]
	v_mfma_f32_16x16x32_bf16 v[88:91], v[140:143], v[194:197], v[88:91]
	s_waitcnt lgkmcnt(0)
	v_mfma_f32_16x16x32_bf16 v[76:79], v[132:135], v[218:221], v[76:79]
	v_mfma_f32_16x16x32_bf16 v[72:75], v[140:143], v[218:221], v[72:75]
	s_barrier
	s_add_i32 s58, 0, 0x14000
	v_add_u32_e32 v158, s58, v178
	s_add_i32 s55, s55, s42
	ds_read_b128 v[222:225], v158
	ds_read_b128 v[226:229], v158 offset:1024
	ds_read_b128 v[230:233], v158 offset:2048
	ds_read_b128 v[234:237], v158 offset:3072
	v_lshl_add_u64 v[158:159], s[34:35], 0, v[160:161]
	s_mov_b32 m0, s55
	v_lshl_add_u64 v[238:239], s[34:35], 0, v[148:149]
	global_load_lds_dwordx4 v160, s[34:35]
	s_add_i32 m0, s55, 0x2000
	s_nop 0
	global_load_lds_dwordx4 v148, s[34:35]
	s_barrier
	s_waitcnt lgkmcnt(3)
	v_mfma_f32_16x16x32_bf16 v[116:119], v[222:225], v[154:157], v[116:119]
	s_waitcnt lgkmcnt(1)
	v_mfma_f32_16x16x32_bf16 v[112:115], v[230:233], v[154:157], v[112:115]
	v_mfma_f32_16x16x32_bf16 v[100:103], v[222:225], v[182:185], v[100:103]
	v_mfma_f32_16x16x32_bf16 v[96:99], v[230:233], v[182:185], v[96:99]
	v_mfma_f32_16x16x32_bf16 v[84:87], v[222:225], v[190:193], v[84:87]
	v_mfma_f32_16x16x32_bf16 v[80:83], v[230:233], v[190:193], v[80:83]
	v_mfma_f32_16x16x32_bf16 v[68:71], v[222:225], v[214:217], v[68:71]
	v_mfma_f32_16x16x32_bf16 v[64:67], v[230:233], v[214:217], v[64:67]
	v_mfma_f32_16x16x32_bf16 v[116:119], v[226:229], v[174:177], v[116:119]
	s_waitcnt lgkmcnt(0)
	v_mfma_f32_16x16x32_bf16 v[112:115], v[234:237], v[174:177], v[112:115]
	v_mfma_f32_16x16x32_bf16 v[100:103], v[226:229], v[186:189], v[100:103]
	v_mfma_f32_16x16x32_bf16 v[96:99], v[234:237], v[186:189], v[96:99]
	v_mfma_f32_16x16x32_bf16 v[84:87], v[226:229], v[194:197], v[84:87]
	v_mfma_f32_16x16x32_bf16 v[80:83], v[234:237], v[194:197], v[80:83]
	v_mfma_f32_16x16x32_bf16 v[68:71], v[226:229], v[218:221], v[68:71]
	v_mfma_f32_16x16x32_bf16 v[64:67], v[234:237], v[218:221], v[64:67]
	s_mov_b32 m0, s43
	v_lshl_add_u64 v[240:241], s[36:37], 0, v[144:145]
	s_barrier
	ds_read_b128 v[154:157], v181 offset:16384
	ds_read_b128 v[174:177], v181 offset:17408
	ds_read_b128 v[182:185], v181 offset:18432
	ds_read_b128 v[186:189], v181 offset:19456
	ds_read_b128 v[190:193], v181 offset:20480
	ds_read_b128 v[194:197], v181 offset:21504
	ds_read_b128 v[214:217], v181 offset:22528
	ds_read_b128 v[218:221], v181 offset:23552
	global_load_lds_dwordx4 v144, s[36:37]
	v_lshl_add_u64 v[242:243], s[36:37], 0, v[146:147]
	s_mov_b32 m0, s44
	s_nop 0
	global_load_lds_dwordx4 v146, s[36:37]
	s_barrier
	s_waitcnt lgkmcnt(7)
	v_mfma_f32_16x16x32_bf16 v[60:63], v[128:131], v[154:157], v[60:63]
	v_mfma_f32_16x16x32_bf16 v[56:59], v[136:139], v[154:157], v[56:59]
	s_waitcnt lgkmcnt(5)
	v_mfma_f32_16x16x32_bf16 v[44:47], v[128:131], v[182:185], v[44:47]
	v_mfma_f32_16x16x32_bf16 v[40:43], v[136:139], v[182:185], v[40:43]
	s_waitcnt lgkmcnt(3)
	v_mfma_f32_16x16x32_bf16 v[28:31], v[128:131], v[190:193], v[28:31]
	v_mfma_f32_16x16x32_bf16 v[24:27], v[136:139], v[190:193], v[24:27]
	s_waitcnt lgkmcnt(1)
	v_mfma_f32_16x16x32_bf16 v[12:15], v[128:131], v[214:217], v[12:15]
	v_mfma_f32_16x16x32_bf16 v[8:11], v[136:139], v[214:217], v[8:11]
	v_mfma_f32_16x16x32_bf16 v[60:63], v[132:135], v[174:177], v[60:63]
	v_mfma_f32_16x16x32_bf16 v[56:59], v[140:143], v[174:177], v[56:59]
	v_mfma_f32_16x16x32_bf16 v[44:47], v[132:135], v[186:189], v[44:47]
	v_mfma_f32_16x16x32_bf16 v[40:43], v[140:143], v[186:189], v[40:43]
	v_mfma_f32_16x16x32_bf16 v[28:31], v[132:135], v[194:197], v[28:31]
	v_mfma_f32_16x16x32_bf16 v[24:27], v[140:143], v[194:197], v[24:27]
	s_waitcnt lgkmcnt(0)
	v_mfma_f32_16x16x32_bf16 v[12:15], v[132:135], v[218:221], v[12:15]
	v_mfma_f32_16x16x32_bf16 v[8:11], v[140:143], v[218:221], v[8:11]
	s_barrier
; #define PG8_STAGE(bufoff, gbase, voff) do { _Pragma("unroll") for (int _i = 0; _i < 2; ++_i) \
;         __builtin_amdgcn_global_load_lds((const unsigned*)((const char*)(gbase) + (voff)[_i]), (LAS unsigned*)(lds + (bufoff) + ldsw + _i * 8192), 16, 0, 0); } while (0)
; #define PG8_LDA(dst, b, h) do { _Pragma("unroll") for (int m = 0; m < 4; ++m) _Pragma("unroll") for (int k = 0; k < 2; ++k) dst[m][k] = *(const LAS bf16x8*)(lds + PG8_SA(b, h) + aoff + m * 2048 + k * 1024); } while (0)
; #define PG8_LDB(dst, b, h) do { _Pragma("unroll") for (int n = 0; n < 2; ++n) _Pragma("unroll") for (int k = 0; k < 2; ++k) dst[n][k] = *(const LAS bf16x8*)(lds + PG8_SB(b, h) + boff + n * 2048 + k * 1024); } while (0)
; #define PG8_MMA(ai, bj, At, Bt) do { __builtin_amdgcn_s_setprio(1); _Pragma("unroll") for (int m = 0; m < 4; ++m) _Pragma("unroll") for (int n = 0; n < 2; ++n) _Pragma("unroll") for (int k = 0; k < 2; ++k) \
;         acc[ai][bj][m][n] = __builtin_amdgcn_mfma_f32_16x16x32_bf16(Bt[n][k], At[m][k], acc[ai][bj][m][n], 0, 0, 0); __builtin_amdgcn_s_setprio(0); } while (0)
; #define PG8_WAIT_V(n) asm volatile("s_waitcnt vmcnt(" #n ")" ::: "memory")
; #define PG8_WAIT_L(n) asm volatile("s_waitcnt lgkmcnt(" #n ")" ::: "memory")
; #define PG8_BAR __builtin_amdgcn_s_barrier()
; #define PG8_SCHED __builtin_amdgcn_sched_barrier(0)
; template <class Epi>
; DEV void gemm_phase(LAS unsigned char* lds, const Gemm g, const StaticOrder& S, const Epi& E) {
;     ...
;             PG8_STAGE(PG8_SB(0, 1), b2 + hstep, voffB);
;             PG8_WAIT_V(6); PG8_BAR; PG8_MMA(1, 1, At, B1); PG8_BAR;
;             PG8_LDB(B0, 1, 0); PG8_SCHED; PG8_LDA(At, 1, 0); PG8_STAGE(PG8_SA(0, 1), a2 + hstep, voffA);
;             PG8_WAIT_L(8); PG8_BAR; PG8_WAIT_L(0); PG8_MMA(0, 0, At, B0); PG8_BAR; PG8_SCHED;
;             PG8_LDB(B1, 1, 1); PG8_STAGE(PG8_SB(1, 0), b3, voffB);
;             PG8_BAR; PG8_WAIT_L(0); PG8_MMA(0, 1, At, B1); PG8_BAR;
;             PG8_LDA(At, 1, 1); PG8_STAGE(PG8_SA(1, 0), a3, voffA);
	s_add_u32 s56, s34, 0x20000
	s_addc_u32 s57, s35, 0
	s_add_i32 s55, s58, s42
	s_mov_b32 m0, s55
	s_nop 0
	global_load_lds_dwordx4 v160, s[56:57]
	s_add_i32 m0, s55, 0x2000
	s_nop 0
	global_load_lds_dwordx4 v148, s[56:57]
	s_waitcnt vmcnt(6)
	s_barrier
	v_mfma_f32_16x16x32_bf16 v[52:55], v[222:225], v[154:157], v[52:55]
	v_mfma_f32_16x16x32_bf16 v[48:51], v[230:233], v[154:157], v[48:51]
	v_mfma_f32_16x16x32_bf16 v[36:39], v[222:225], v[182:185], v[36:39]
	v_mfma_f32_16x16x32_bf16 v[32:35], v[230:233], v[182:185], v[32:35]
	v_mfma_f32_16x16x32_bf16 v[20:23], v[222:225], v[190:193], v[20:23]
	v_mfma_f32_16x16x32_bf16 v[16:19], v[230:233], v[190:193], v[16:19]
	v_mfma_f32_16x16x32_bf16 v[4:7], v[222:225], v[214:217], v[4:7]
	v_mfma_f32_16x16x32_bf16 v[0:3], v[230:233], v[214:217], v[0:3]
	v_mfma_f32_16x16x32_bf16 v[52:55], v[226:229], v[174:177], v[52:55]
	v_mfma_f32_16x16x32_bf16 v[48:51], v[234:237], v[174:177], v[48:51]
	v_mfma_f32_16x16x32_bf16 v[36:39], v[226:229], v[186:189], v[36:39]
	v_mfma_f32_16x16x32_bf16 v[32:35], v[234:237], v[186:189], v[32:35]
	v_mfma_f32_16x16x32_bf16 v[20:23], v[226:229], v[194:197], v[20:23]
	v_mfma_f32_16x16x32_bf16 v[16:19], v[234:237], v[194:197], v[16:19]
	v_mfma_f32_16x16x32_bf16 v[4:7], v[226:229], v[218:221], v[4:7]
	v_mfma_f32_16x16x32_bf16 v[0:3], v[234:237], v[218:221], v[0:3]
	s_add_i32 s55, 0, 0x18000
	v_add_u32_e32 v140, s55, v178
	s_barrier
	ds_read_b128 v[128:131], v140
	ds_read_b128 v[132:135], v140 offset:1024
	ds_read_b128 v[136:139], v140 offset:2048
	ds_read_b128 v[140:143], v140 offset:3072
	s_add_u32 s36, s36, 0x20000
	s_addc_u32 s37, s37, 0
	s_mov_b32 m0, s45
	ds_read_b128 v[154:157], v181 offset:32768
	ds_read_b128 v[174:177], v181 offset:33792
	ds_read_b128 v[182:185], v181 offset:34816
	ds_read_b128 v[186:189], v181 offset:35840
	ds_read_b128 v[190:193], v181 offset:36864
	ds_read_b128 v[194:197], v181 offset:37888
	ds_read_b128 v[214:217], v181 offset:38912
	ds_read_b128 v[218:221], v181 offset:39936
	global_load_lds_dwordx4 v144, s[36:37]
	s_mov_b32 m0, s46
	s_nop 0
	global_load_lds_dwordx4 v146, s[36:37]
	s_waitcnt lgkmcnt(8)
	s_barrier
	s_waitcnt lgkmcnt(7)
	v_mfma_f32_16x16x32_bf16 v[124:127], v[128:131], v[154:157], v[124:127]
	v_mfma_f32_16x16x32_bf16 v[120:123], v[136:139], v[154:157], v[120:123]
	s_waitcnt lgkmcnt(5)
	v_mfma_f32_16x16x32_bf16 v[108:111], v[128:131], v[182:185], v[108:111]
	v_mfma_f32_16x16x32_bf16 v[104:107], v[136:139], v[182:185], v[104:107]
	s_waitcnt lgkmcnt(3)
	v_mfma_f32_16x16x32_bf16 v[92:95], v[128:131], v[190:193], v[92:95]
	v_mfma_f32_16x16x32_bf16 v[88:91], v[136:139], v[190:193], v[88:91]
	s_waitcnt lgkmcnt(1)
	v_mfma_f32_16x16x32_bf16 v[76:79], v[128:131], v[214:217], v[76:79]
	v_mfma_f32_16x16x32_bf16 v[72:75], v[136:139], v[214:217], v[72:75]
	v_mfma_f32_16x16x32_bf16 v[124:127], v[132:135], v[174:177], v[124:127]
	v_mfma_f32_16x16x32_bf16 v[120:123], v[140:143], v[174:177], v[120:123]
	v_mfma_f32_16x16x32_bf16 v[108:111], v[132:135], v[186:189], v[108:111]
	v_mfma_f32_16x16x32_bf16 v[104:107], v[140:143], v[186:189], v[104:107]
	v_mfma_f32_16x16x32_bf16 v[92:95], v[132:135], v[194:197], v[92:95]
	v_mfma_f32_16x16x32_bf16 v[88:91], v[140:143], v[194:197], v[88:91]
	s_waitcnt lgkmcnt(0)
	v_mfma_f32_16x16x32_bf16 v[76:79], v[132:135], v[218:221], v[76:79]
	v_mfma_f32_16x16x32_bf16 v[72:75], v[140:143], v[218:221], v[72:75]
	s_barrier
	s_add_i32 s36, 0, 0x1c000
	s_add_i32 s37, s55, s42
	v_add_u32_e32 v234, s36, v178
	v_lshl_add_u64 v[158:159], v[158:159], 0, s[2:3]
	s_mov_b32 m0, s37
	ds_read_b128 v[222:225], v234
	ds_read_b128 v[226:229], v234 offset:1024
	ds_read_b128 v[230:233], v234 offset:2048
	ds_read_b128 v[234:237], v234 offset:3072
	global_load_lds_dwordx4 v[158:159], off
	v_lshl_add_u64 v[158:159], v[238:239], 0, s[2:3]
	s_add_i32 m0, s37, 0x2000
	s_nop 0
	global_load_lds_dwordx4 v[158:159], off
	s_barrier
	s_waitcnt lgkmcnt(3)
	v_mfma_f32_16x16x32_bf16 v[116:119], v[222:225], v[154:157], v[116:119]
	s_waitcnt lgkmcnt(1)
	v_mfma_f32_16x16x32_bf16 v[112:115], v[230:233], v[154:157], v[112:115]
	v_mfma_f32_16x16x32_bf16 v[100:103], v[222:225], v[182:185], v[100:103]
	v_mfma_f32_16x16x32_bf16 v[96:99], v[230:233], v[182:185], v[96:99]
	v_mfma_f32_16x16x32_bf16 v[84:87], v[222:225], v[190:193], v[84:87]
	v_mfma_f32_16x16x32_bf16 v[80:83], v[230:233], v[190:193], v[80:83]
	v_mfma_f32_16x16x32_bf16 v[68:71], v[222:225], v[214:217], v[68:71]
	v_mfma_f32_16x16x32_bf16 v[64:67], v[230:233], v[214:217], v[64:67]
	v_mfma_f32_16x16x32_bf16 v[116:119], v[226:229], v[174:177], v[116:119]
	s_waitcnt lgkmcnt(0)
	v_mfma_f32_16x16x32_bf16 v[112:115], v[234:237], v[174:177], v[112:115]
	v_mfma_f32_16x16x32_bf16 v[100:103], v[226:229], v[186:189], v[100:103]
	v_mfma_f32_16x16x32_bf16 v[96:99], v[234:237], v[186:189], v[96:99]
	v_mfma_f32_16x16x32_bf16 v[84:87], v[226:229], v[194:197], v[84:87]
	v_mfma_f32_16x16x32_bf16 v[80:83], v[234:237], v[194:197], v[80:83]
	v_mfma_f32_16x16x32_bf16 v[68:71], v[226:229], v[218:221], v[68:71]
	v_mfma_f32_16x16x32_bf16 v[64:67], v[234:237], v[218:221], v[64:67]
	s_mov_b32 m0, s47
	v_lshl_add_u64 v[158:159], v[240:241], 0, s[2:3]
	s_barrier
	ds_read_b128 v[154:157], v181 offset:49152
	ds_read_b128 v[174:177], v181 offset:50176
	ds_read_b128 v[182:185], v181 offset:51200
	ds_read_b128 v[186:189], v181 offset:52224
	ds_read_b128 v[190:193], v181 offset:53248
	ds_read_b128 v[194:197], v181 offset:54272
	ds_read_b128 v[214:217], v181 offset:55296
	ds_read_b128 v[218:221], v181 offset:56320
	global_load_lds_dwordx4 v[158:159], off
	v_lshl_add_u64 v[158:159], v[242:243], 0, s[2:3]
	s_mov_b32 m0, s48
	s_nop 0
	global_load_lds_dwordx4 v[158:159], off
	s_barrier
; DEV bf16x8 pack8(f32x4 a, f32x4 b) { u32x4 w; w.x = cvt_pk_bf16(a[0], a[1]); w.y = cvt_pk_bf16(a[2], a[3]); w.z = cvt_pk_bf16(b[0], b[1]); w.w = cvt_pk_bf16(b[2], b[3]); return __builtin_bit_cast(bf16x8, w); }
; #define PG8_STAGE(bufoff, gbase, voff) do { _Pragma("unroll") for (int _i = 0; _i < 2; ++_i) \
;         __builtin_amdgcn_global_load_lds((const unsigned*)((const char*)(gbase) + (voff)[_i]), (LAS unsigned*)(lds + (bufoff) + ldsw + _i * 8192), 16, 0, 0); } while (0)
; #define PG8_LDA(dst, b, h) do { _Pragma("unroll") for (int m = 0; m < 4; ++m) _Pragma("unroll") for (int k = 0; k < 2; ++k) dst[m][k] = *(const LAS bf16x8*)(lds + PG8_SA(b, h) + aoff + m * 2048 + k * 1024); } while (0)
; #define PG8_BAR __builtin_amdgcn_s_barrier()
; template <class Epi>
; DEV void gemm_phase(LAS unsigned char* lds, const Gemm g, const StaticOrder& S, const Epi& E) {
;     ...
;             PG8_LDA(At, 1, 1); PG8_STAGE(PG8_SA(1, 0), a3, voffA);
;             PG8_BAR; PG8_WAIT_L(0); PG8_MMA(1, 0, At, B0); PG8_BAR; PG8_SCHED;
;             PG8_STAGE(PG8_SB(1, 1), b3 + hstep, voffB);
;             PG8_WAIT_V(6); PG8_BAR; PG8_MMA(1, 1, At, B1); PG8_BAR;
;         }
;     DEV void operator()(AccRef acc, const pg8::Unit& u, int wr, int wc, int fr, int fq) const {
;     ...
;                     for (int n = 0; n < 2; ++n) bv[m][bj][n] = *(const f32x4*)(base + (size_t)(row0 + ai * 128 + m * 16) * 2048 + col0 + bj * 128 + n * 4);
; #pragma unroll
;             for (int m = m0; m < m0 + 2; ++m) { const size_t off = (size_t)(row0 + ai * 128 + m * 16) * 2048 + col0; float sq = 0.f;
; #pragma unroll
;                 for (int bj = 0; bj < 2; ++bj) { const f32x4 o0 = bv[m][bj][0] + scale * acc[ai][bj][m][0], o1 = bv[m][bj][1] + scale * acc[ai][bj][m][1];
;                     *(f32x4*)(out + off + bj * 128) = o0; *(f32x4*)(out + off + bj * 128 + 4) = o1;
;                     if (xb) { *(u32x4*)(xb + off + bj * 128) = __builtin_bit_cast(u32x4, pack8(o0, o1));
;                         sq += (o0[0] * o0[0] + o0[1] * o0[1] + o0[2] * o0[2] + o0[3] * o0[3]) + (o1[0] * o1[0] + o1[1] * o1[1] + o1[2] * o1[2] + o1[3] * o1[3]); } }
;                 if (ssout) { sq += __shfl_xor(sq, 16); sq += __shfl_xor(sq, 32);
;                     if (fq == 0) { if (red) red[(ai * 128 + wr * 64 + m * 16 + fr) * 4 + wc] = sq; else atomicAdd(ssout + (size_t)(row0 + ai * 128 + m * 16) * 8 + u.pn, sq); } } }
	s_waitcnt lgkmcnt(7)
	v_mfma_f32_16x16x32_bf16 v[60:63], v[128:131], v[154:157], v[60:63]
	v_mfma_f32_16x16x32_bf16 v[56:59], v[136:139], v[154:157], v[56:59]
	s_waitcnt lgkmcnt(5)
	v_mfma_f32_16x16x32_bf16 v[44:47], v[128:131], v[182:185], v[44:47]
	v_mfma_f32_16x16x32_bf16 v[40:43], v[136:139], v[182:185], v[40:43]
	s_waitcnt lgkmcnt(3)
	v_mfma_f32_16x16x32_bf16 v[28:31], v[128:131], v[190:193], v[28:31]
	v_mfma_f32_16x16x32_bf16 v[24:27], v[136:139], v[190:193], v[24:27]
	s_waitcnt lgkmcnt(1)
	v_mfma_f32_16x16x32_bf16 v[12:15], v[128:131], v[214:217], v[12:15]
	v_mfma_f32_16x16x32_bf16 v[8:11], v[136:139], v[214:217], v[8:11]
	v_mfma_f32_16x16x32_bf16 v[60:63], v[132:135], v[174:177], v[60:63]
	v_mfma_f32_16x16x32_bf16 v[56:59], v[140:143], v[174:177], v[56:59]
	v_mfma_f32_16x16x32_bf16 v[44:47], v[132:135], v[186:189], v[44:47]
	v_mfma_f32_16x16x32_bf16 v[40:43], v[140:143], v[186:189], v[40:43]
	v_mfma_f32_16x16x32_bf16 v[28:31], v[132:135], v[194:197], v[28:31]
	v_mfma_f32_16x16x32_bf16 v[24:27], v[140:143], v[194:197], v[24:27]
	s_waitcnt lgkmcnt(0)
	v_mfma_f32_16x16x32_bf16 v[12:15], v[132:135], v[218:221], v[12:15]
	v_mfma_f32_16x16x32_bf16 v[8:11], v[140:143], v[218:221], v[8:11]
	s_barrier
	s_add_u32 s34, s34, 0x20080
	s_addc_u32 s35, s35, 0
	s_add_i32 s36, s36, s42
	s_mov_b32 m0, s36
	s_nop 0
	global_load_lds_dwordx4 v160, s[34:35]
	s_add_i32 m0, s36, 0x2000
	s_nop 0
	global_load_lds_dwordx4 v148, s[34:35]
	s_waitcnt vmcnt(6)
	s_barrier
	v_mfma_f32_16x16x32_bf16 v[52:55], v[222:225], v[154:157], v[52:55]
	v_mfma_f32_16x16x32_bf16 v[48:51], v[230:233], v[154:157], v[48:51]
	v_mfma_f32_16x16x32_bf16 v[36:39], v[222:225], v[182:185], v[36:39]
	v_mfma_f32_16x16x32_bf16 v[32:35], v[230:233], v[182:185], v[32:35]
	v_mfma_f32_16x16x32_bf16 v[20:23], v[222:225], v[190:193], v[20:23]
	v_mfma_f32_16x16x32_bf16 v[16:19], v[230:233], v[190:193], v[16:19]
	v_mfma_f32_16x16x32_bf16 v[4:7], v[222:225], v[214:217], v[4:7]
	v_mfma_f32_16x16x32_bf16 v[0:3], v[230:233], v[214:217], v[0:3]
	v_mfma_f32_16x16x32_bf16 v[52:55], v[226:229], v[174:177], v[52:55]
	v_mfma_f32_16x16x32_bf16 v[48:51], v[234:237], v[174:177], v[48:51]
	v_mfma_f32_16x16x32_bf16 v[36:39], v[226:229], v[186:189], v[36:39]
	v_mfma_f32_16x16x32_bf16 v[32:35], v[234:237], v[186:189], v[32:35]
	v_mfma_f32_16x16x32_bf16 v[20:23], v[226:229], v[194:197], v[20:23]
	v_mfma_f32_16x16x32_bf16 v[16:19], v[234:237], v[194:197], v[16:19]
	v_mfma_f32_16x16x32_bf16 v[4:7], v[226:229], v[218:221], v[4:7]
	v_mfma_f32_16x16x32_bf16 v[0:3], v[234:237], v[218:221], v[0:3]
	s_add_i32 s54, s54, 2
	s_add_u32 s30, s30, 0x100
	s_addc_u32 s31, s31, 0
	s_add_u32 s52, s52, 0x100
	s_addc_u32 s53, s53, 0
	s_cmp_gt_u32 s54, 5
	s_barrier
	s_cbranch_scc0 .LBB0_260
	v_lshl_add_u32 v156, s28, 8, v167
	v_lshl_or_b32 v154, s18, 8, v179
	v_readlane_b32 s28, v254, 16
	v_ashrrev_i32_e32 v155, 31, v154
	v_readlane_b32 s29, v254, 17
	v_ashrrev_i32_e32 v157, 31, v156
	v_lshlrev_b64 v[128:129], 13, v[156:157]
	v_lshl_add_u64 v[158:159], v[154:155], 2, s[28:29]
	v_lshl_add_u64 v[214:215], v[158:159], 0, v[128:129]
	global_load_dwordx4 v[182:185], v[214:215], off offset:16
	global_load_dwordx4 v[186:189], v[214:215], off
	global_load_dwordx4 v[190:193], v[214:215], off offset:528
	global_load_dwordx4 v[194:197], v[214:215], off offset:512
	v_or_b32_e32 v174, 16, v156
	v_ashrrev_i32_e32 v175, 31, v174
	v_lshlrev_b64 v[128:129], 13, v[174:175]
	v_lshl_add_u64 v[176:177], v[158:159], 0, v[128:129]
	global_load_dwordx4 v[136:139], v[176:177], off offset:16
	global_load_dwordx4 v[140:143], v[176:177], off
	global_load_dwordx4 v[128:131], v[176:177], off offset:528
	global_load_dwordx4 v[132:135], v[176:177], off offset:512
	v_lshlrev_b64 v[216:217], 11, v[156:157]
	v_readlane_b32 s28, v250, 9
	v_lshl_add_u64 v[216:217], v[216:217], 0, v[154:155]
	v_readlane_b32 s29, v250, 10
	v_cmp_lt_i32_e32 vcc, v208, v206
	s_ashr_i32 s19, s18, 31
	s_waitcnt vmcnt(0)
	v_pk_add_f32 v[120:121], v[120:121], v[182:183]
	v_pk_add_f32 v[126:127], v[126:127], v[188:189]
	v_pk_add_f32 v[124:125], v[124:125], v[186:187]
	v_pk_add_f32 v[122:123], v[122:123], v[184:185]
	global_store_dwordx4 v[214:215], v[124:127], off
	global_store_dwordx4 v[214:215], v[120:123], off offset:16
	v_cvt_pk_bf16_f32 v184, v120, v121
	v_cvt_pk_bf16_f32 v182, v124, v125
	v_mul_f32_e32 v121, v121, v121
	v_cvt_pk_bf16_f32 v183, v126, v127
	v_cvt_pk_bf16_f32 v185, v122, v123
	v_lshl_add_u64 v[186:187], v[216:217], 1, s[28:29]
	v_fmac_f32_e32 v121, v120, v120
	v_pk_add_f32 v[118:119], v[118:119], v[196:197]
	v_pk_add_f32 v[116:117], v[116:117], v[194:195]
	v_pk_add_f32 v[112:113], v[112:113], v[190:191]
	global_store_dwordx4 v[186:187], v[182:185], off
	v_mul_f32_e32 v125, v125, v125
	v_fmac_f32_e32 v121, v122, v122
	v_pk_add_f32 v[114:115], v[114:115], v[192:193]
	global_store_dwordx4 v[214:215], v[116:119], off offset:512
	global_store_dwordx4 v[214:215], v[112:115], off offset:528
	v_cvt_pk_bf16_f32 v120, v116, v117
	v_cvt_pk_bf16_f32 v122, v112, v113
	v_mul_f32_e32 v117, v117, v117
	v_mul_f32_e32 v113, v113, v113
	v_fmac_f32_e32 v125, v124, v124
	v_fmac_f32_e32 v117, v116, v116
	v_fmac_f32_e32 v113, v112, v112
	v_fmac_f32_e32 v125, v126, v126
	v_fmac_f32_e32 v117, v118, v118
	v_fmac_f32_e32 v113, v114, v114
	v_fmac_f32_e32 v125, v127, v127
	v_fmac_f32_e32 v121, v123, v123
	v_fmac_f32_e32 v117, v119, v119
	v_fmac_f32_e32 v113, v115, v115
	v_add_f32_e32 v124, v125, v121
	v_add_f32_e32 v112, v117, v113
	v_cndmask_b32_e32 v113, v204, v208, vcc
	v_cvt_pk_bf16_f32 v121, v118, v119
	v_add_f32_e32 v112, v124, v112
	v_lshlrev_b32_e32 v118, 2, v113
	ds_bpermute_b32 v113, v118, v112
	v_cmp_lt_i32_e32 vcc, v207, v206
	v_cvt_pk_bf16_f32 v123, v114, v115
	global_store_dwordx4 v[186:187], v[120:123], off offset:256
	s_waitcnt lgkmcnt(0)
	v_add_f32_e32 v112, v112, v113
	v_cndmask_b32_e32 v113, v204, v207, vcc
	v_lshlrev_b32_e32 v119, 2, v113
	ds_bpermute_b32 v113, v119, v112
	s_and_saveexec_b64 s[28:29], s[6:7]
	s_cbranch_execz .LBB0_266
	s_waitcnt lgkmcnt(0)
	v_add_f32_e32 v112, v112, v113
	s_mov_b64 s[30:31], -1
	s_and_b64 vcc, exec, s[16:17]
	s_cbranch_vccz .LBB0_264
	v_lshlrev_b64 v[114:115], 5, v[156:157]
	v_lshl_add_u64 v[114:115], s[12:13], 0, v[114:115]
	v_lshl_add_u64 v[114:115], s[18:19], 2, v[114:115]
	global_atomic_add_f32 v[114:115], v112, off
	s_mov_b64 s[30:31], 0

; #define PG8_STAGE(bufoff, gbase, voff) do { _Pragma("unroll") for (int _i = 0; _i < 2; ++_i) \
;         __builtin_amdgcn_global_load_lds((const unsigned*)((const char*)(gbase) + (voff)[_i]), (LAS unsigned*)(lds + (bufoff) + ldsw + _i * 8192), 16, 0, 0); } while (0)
; #define PG8_LDA(dst, b, h) do { _Pragma("unroll") for (int m = 0; m < 4; ++m) _Pragma("unroll") for (int k = 0; k < 2; ++k) dst[m][k] = *(const LAS bf16x8*)(lds + PG8_SA(b, h) + aoff + m * 2048 + k * 1024); } while (0)
; #define PG8_LDB(dst, b, h) do { _Pragma("unroll") for (int n = 0; n < 2; ++n) _Pragma("unroll") for (int k = 0; k < 2; ++k) dst[n][k] = *(const LAS bf16x8*)(lds + PG8_SB(b, h) + boff + n * 2048 + k * 1024); } while (0)
; #define PG8_MMA(ai, bj, At, Bt) do { __builtin_amdgcn_s_setprio(1); _Pragma("unroll") for (int m = 0; m < 4; ++m) _Pragma("unroll") for (int n = 0; n < 2; ++n) _Pragma("unroll") for (int k = 0; k < 2; ++k) \
;         acc[ai][bj][m][n] = __builtin_amdgcn_mfma_f32_16x16x32_bf16(Bt[n][k], At[m][k], acc[ai][bj][m][n], 0, 0, 0); __builtin_amdgcn_s_setprio(0); } while (0)
; #define PG8_WAIT_L(n) asm volatile("s_waitcnt lgkmcnt(" #n ")" ::: "memory")
; #define PG8_BAR __builtin_amdgcn_s_barrier()
; #define PG8_SCHED __builtin_amdgcn_sched_barrier(0)
; template <class Epi>
; DEV void gemm_phase(LAS unsigned char* lds, const Gemm g, const StaticOrder& S, const Epi& E) {
;     ...
;             PG8_LDB(B0, 0, 0); PG8_SCHED; PG8_LDA(At, 0, 0); PG8_STAGE(PG8_SA(1, 1), a1 + hstep, voffA);
;             PG8_WAIT_L(8); PG8_BAR; PG8_WAIT_L(0); PG8_MMA(0, 0, At, B0); PG8_BAR; PG8_SCHED;
;             PG8_LDB(B1, 0, 1); PG8_STAGE(PG8_SB(0, 0), b2, voffB);
;             PG8_BAR; PG8_WAIT_L(0); PG8_MMA(0, 1, At, B1); PG8_BAR;
;             PG8_LDA(At, 0, 1); PG8_STAGE(PG8_SA(0, 0), a2, voffA);
;             PG8_BAR; PG8_WAIT_L(0); PG8_MMA(1, 0, At, B0); PG8_BAR; PG8_SCHED;
.LBB0_344:
	s_add_u32 s20, s18, 0xfff80080
	s_addc_u32 s21, s19, -1
	s_add_i32 s45, 0, 0x10000
	v_add_u32_e32 v146, s45, v149
	ds_read_b128 v[128:131], v146
	ds_read_b128 v[132:135], v146 offset:1024
	ds_read_b128 v[142:145], v146 offset:2048
	ds_read_b128 v[150:153], v146 offset:3072
	s_cmp_eq_u32 s44, 28
	s_cselect_b32 s23, s1, s21
	s_cselect_b32 s22, s13, s20
	s_cselect_b32 s21, s11, s43
	s_cselect_b32 s20, s41, s42
	s_add_i32 m0, s30, 0xc000
	ds_read_b128 v[174:177], v159
	ds_read_b128 v[178:181], v159 offset:1024
	ds_read_b128 v[182:185], v159 offset:2048
	ds_read_b128 v[186:189], v159 offset:3072
	ds_read_b128 v[190:193], v159 offset:4096
	ds_read_b128 v[194:197], v159 offset:5120
	ds_read_b128 v[214:217], v159 offset:6144
	ds_read_b128 v[218:221], v159 offset:7168
	global_load_lds_dwordx4 v138, s[18:19]
	s_add_i32 m0, s30, 0xe000
	s_nop 0
	global_load_lds_dwordx4 v140, s[18:19]
	s_waitcnt lgkmcnt(8)
	s_barrier
	s_waitcnt lgkmcnt(7)
	v_mfma_f32_16x16x32_bf16 v[124:127], v[128:131], v[174:177], v[124:127]
	v_mfma_f32_16x16x32_bf16 v[120:123], v[142:145], v[174:177], v[120:123]
	s_waitcnt lgkmcnt(5)
	v_mfma_f32_16x16x32_bf16 v[116:119], v[128:131], v[182:185], v[116:119]
	v_mfma_f32_16x16x32_bf16 v[108:111], v[142:145], v[182:185], v[108:111]
	s_waitcnt lgkmcnt(3)
	v_mfma_f32_16x16x32_bf16 v[100:103], v[128:131], v[190:193], v[100:103]
	v_mfma_f32_16x16x32_bf16 v[92:95], v[142:145], v[190:193], v[92:95]
	s_waitcnt lgkmcnt(1)
	v_mfma_f32_16x16x32_bf16 v[84:87], v[128:131], v[214:217], v[84:87]
	v_mfma_f32_16x16x32_bf16 v[76:79], v[142:145], v[214:217], v[76:79]
	v_mfma_f32_16x16x32_bf16 v[124:127], v[132:135], v[178:181], v[124:127]
	v_mfma_f32_16x16x32_bf16 v[120:123], v[150:153], v[178:181], v[120:123]
	v_mfma_f32_16x16x32_bf16 v[116:119], v[132:135], v[186:189], v[116:119]
	v_mfma_f32_16x16x32_bf16 v[108:111], v[150:153], v[186:189], v[108:111]
	v_mfma_f32_16x16x32_bf16 v[100:103], v[132:135], v[194:197], v[100:103]
	v_mfma_f32_16x16x32_bf16 v[92:95], v[150:153], v[194:197], v[92:95]
	s_waitcnt lgkmcnt(0)
	v_mfma_f32_16x16x32_bf16 v[84:87], v[132:135], v[218:221], v[84:87]
	v_mfma_f32_16x16x32_bf16 v[76:79], v[150:153], v[218:221], v[76:79]
	s_barrier
	s_add_i32 s48, 0, 0x14000
	s_add_i32 s45, s45, s29
	v_add_u32_e32 v146, s48, v149
	v_lshl_add_u64 v[154:155], s[20:21], 0, v[160:161]
	s_mov_b32 m0, s45
	ds_read_b128 v[222:225], v146
	ds_read_b128 v[226:229], v146 offset:1024
	ds_read_b128 v[230:233], v146 offset:2048
	ds_read_b128 v[234:237], v146 offset:3072
	global_load_lds_dwordx4 v160, s[20:21]
	v_lshl_add_u64 v[238:239], s[20:21], 0, v[136:137]
	s_add_i32 m0, s45, 0x2000
	s_nop 0
	global_load_lds_dwordx4 v136, s[20:21]
	s_barrier
	s_waitcnt lgkmcnt(3)
	v_mfma_f32_16x16x32_bf16 v[112:115], v[222:225], v[174:177], v[112:115]
	s_waitcnt lgkmcnt(1)
	v_mfma_f32_16x16x32_bf16 v[104:107], v[230:233], v[174:177], v[104:107]
	v_mfma_f32_16x16x32_bf16 v[96:99], v[222:225], v[182:185], v[96:99]
	v_mfma_f32_16x16x32_bf16 v[88:91], v[230:233], v[182:185], v[88:91]
	v_mfma_f32_16x16x32_bf16 v[80:83], v[222:225], v[190:193], v[80:83]
	v_mfma_f32_16x16x32_bf16 v[72:75], v[230:233], v[190:193], v[72:75]
	v_mfma_f32_16x16x32_bf16 v[68:71], v[222:225], v[214:217], v[68:71]
	v_mfma_f32_16x16x32_bf16 v[64:67], v[230:233], v[214:217], v[64:67]
	v_mfma_f32_16x16x32_bf16 v[112:115], v[226:229], v[178:181], v[112:115]
	s_waitcnt lgkmcnt(0)
	v_mfma_f32_16x16x32_bf16 v[104:107], v[234:237], v[178:181], v[104:107]
	v_mfma_f32_16x16x32_bf16 v[96:99], v[226:229], v[186:189], v[96:99]
	v_mfma_f32_16x16x32_bf16 v[88:91], v[234:237], v[186:189], v[88:91]
	v_mfma_f32_16x16x32_bf16 v[80:83], v[226:229], v[194:197], v[80:83]
	v_mfma_f32_16x16x32_bf16 v[72:75], v[234:237], v[194:197], v[72:75]
	v_mfma_f32_16x16x32_bf16 v[68:71], v[226:229], v[218:221], v[68:71]
	v_mfma_f32_16x16x32_bf16 v[64:67], v[234:237], v[218:221], v[64:67]
	s_mov_b32 m0, s30
	v_lshl_add_u64 v[240:241], s[22:23], 0, v[160:161]
	s_barrier
	ds_read_b128 v[174:177], v159 offset:16384
	ds_read_b128 v[178:181], v159 offset:17408
	ds_read_b128 v[182:185], v159 offset:18432
	ds_read_b128 v[186:189], v159 offset:19456
	ds_read_b128 v[190:193], v159 offset:20480
	ds_read_b128 v[194:197], v159 offset:21504
	ds_read_b128 v[214:217], v159 offset:22528
	ds_read_b128 v[218:221], v159 offset:23552
	global_load_lds_dwordx4 v160, s[22:23]
	v_lshl_add_u64 v[242:243], s[22:23], 0, v[136:137]
	s_mov_b32 m0, s31
	s_nop 0
	global_load_lds_dwordx4 v136, s[22:23]
	s_barrier
	s_waitcnt lgkmcnt(7)
	v_mfma_f32_16x16x32_bf16 v[60:63], v[128:131], v[174:177], v[60:63]
	v_mfma_f32_16x16x32_bf16 v[56:59], v[142:145], v[174:177], v[56:59]
	s_waitcnt lgkmcnt(5)
	v_mfma_f32_16x16x32_bf16 v[52:55], v[128:131], v[182:185], v[52:55]
	v_mfma_f32_16x16x32_bf16 v[44:47], v[142:145], v[182:185], v[44:47]
	s_waitcnt lgkmcnt(3)
	v_mfma_f32_16x16x32_bf16 v[36:39], v[128:131], v[190:193], v[36:39]
	v_mfma_f32_16x16x32_bf16 v[28:31], v[142:145], v[190:193], v[28:31]
	s_waitcnt lgkmcnt(1)
	v_mfma_f32_16x16x32_bf16 v[20:23], v[128:131], v[214:217], v[20:23]
	v_mfma_f32_16x16x32_bf16 v[12:15], v[142:145], v[214:217], v[12:15]
	v_mfma_f32_16x16x32_bf16 v[60:63], v[132:135], v[178:181], v[60:63]
	v_mfma_f32_16x16x32_bf16 v[56:59], v[150:153], v[178:181], v[56:59]
	v_mfma_f32_16x16x32_bf16 v[52:55], v[132:135], v[186:189], v[52:55]
	v_mfma_f32_16x16x32_bf16 v[44:47], v[150:153], v[186:189], v[44:47]
	v_mfma_f32_16x16x32_bf16 v[36:39], v[132:135], v[194:197], v[36:39]
	v_mfma_f32_16x16x32_bf16 v[28:31], v[150:153], v[194:197], v[28:31]
	s_waitcnt lgkmcnt(0)
	v_mfma_f32_16x16x32_bf16 v[20:23], v[132:135], v[218:221], v[20:23]
	v_mfma_f32_16x16x32_bf16 v[12:15], v[150:153], v[218:221], v[12:15]
	s_barrier
; #define PG8_STAGE(bufoff, gbase, voff) do { _Pragma("unroll") for (int _i = 0; _i < 2; ++_i) \
;         __builtin_amdgcn_global_load_lds((const unsigned*)((const char*)(gbase) + (voff)[_i]), (LAS unsigned*)(lds + (bufoff) + ldsw + _i * 8192), 16, 0, 0); } while (0)
; #define PG8_LDA(dst, b, h) do { _Pragma("unroll") for (int m = 0; m < 4; ++m) _Pragma("unroll") for (int k = 0; k < 2; ++k) dst[m][k] = *(const LAS bf16x8*)(lds + PG8_SA(b, h) + aoff + m * 2048 + k * 1024); } while (0)
; #define PG8_LDB(dst, b, h) do { _Pragma("unroll") for (int n = 0; n < 2; ++n) _Pragma("unroll") for (int k = 0; k < 2; ++k) dst[n][k] = *(const LAS bf16x8*)(lds + PG8_SB(b, h) + boff + n * 2048 + k * 1024); } while (0)
; #define PG8_MMA(ai, bj, At, Bt) do { __builtin_amdgcn_s_setprio(1); _Pragma("unroll") for (int m = 0; m < 4; ++m) _Pragma("unroll") for (int n = 0; n < 2; ++n) _Pragma("unroll") for (int k = 0; k < 2; ++k) \
;         acc[ai][bj][m][n] = __builtin_amdgcn_mfma_f32_16x16x32_bf16(Bt[n][k], At[m][k], acc[ai][bj][m][n], 0, 0, 0); __builtin_amdgcn_s_setprio(0); } while (0)
; #define PG8_WAIT_V(n) asm volatile("s_waitcnt vmcnt(" #n ")" ::: "memory")
; #define PG8_WAIT_L(n) asm volatile("s_waitcnt lgkmcnt(" #n ")" ::: "memory")
; #define PG8_BAR __builtin_amdgcn_s_barrier()
; #define PG8_SCHED __builtin_amdgcn_sched_barrier(0)
; template <class Epi>
; DEV void gemm_phase(LAS unsigned char* lds, const Gemm g, const StaticOrder& S, const Epi& E) {
;     ...
;             PG8_STAGE(PG8_SB(0, 1), b2 + hstep, voffB);
;             PG8_WAIT_V(6); PG8_BAR; PG8_MMA(1, 1, At, B1); PG8_BAR;
;             PG8_LDB(B0, 1, 0); PG8_SCHED; PG8_LDA(At, 1, 0); PG8_STAGE(PG8_SA(0, 1), a2 + hstep, voffA);
;             PG8_WAIT_L(8); PG8_BAR; PG8_WAIT_L(0); PG8_MMA(0, 0, At, B0); PG8_BAR; PG8_SCHED;
;             PG8_LDB(B1, 1, 1); PG8_STAGE(PG8_SB(1, 0), b3, voffB);
;             PG8_BAR; PG8_WAIT_L(0); PG8_MMA(0, 1, At, B1); PG8_BAR;
;             PG8_LDA(At, 1, 1); PG8_STAGE(PG8_SA(1, 0), a3, voffA);
	s_add_u32 s46, s20, 0x80000
	s_addc_u32 s47, s21, 0
	s_add_i32 s45, s48, s29
	s_mov_b32 m0, s45
	s_nop 0
	global_load_lds_dwordx4 v160, s[46:47]
	s_add_i32 m0, s45, 0x2000
	s_nop 0
	global_load_lds_dwordx4 v136, s[46:47]
	s_waitcnt vmcnt(6)
	s_barrier
	v_mfma_f32_16x16x32_bf16 v[48:51], v[222:225], v[174:177], v[48:51]
	v_mfma_f32_16x16x32_bf16 v[40:43], v[230:233], v[174:177], v[40:43]
	v_mfma_f32_16x16x32_bf16 v[32:35], v[222:225], v[182:185], v[32:35]
	v_mfma_f32_16x16x32_bf16 v[24:27], v[230:233], v[182:185], v[24:27]
	v_mfma_f32_16x16x32_bf16 v[16:19], v[222:225], v[190:193], v[16:19]
	v_mfma_f32_16x16x32_bf16 v[8:11], v[230:233], v[190:193], v[8:11]
	v_mfma_f32_16x16x32_bf16 v[4:7], v[222:225], v[214:217], v[4:7]
	v_mfma_f32_16x16x32_bf16 v[0:3], v[230:233], v[214:217], v[0:3]
	v_mfma_f32_16x16x32_bf16 v[48:51], v[226:229], v[178:181], v[48:51]
	v_mfma_f32_16x16x32_bf16 v[40:43], v[234:237], v[178:181], v[40:43]
	v_mfma_f32_16x16x32_bf16 v[32:35], v[226:229], v[186:189], v[32:35]
	v_mfma_f32_16x16x32_bf16 v[24:27], v[234:237], v[186:189], v[24:27]
	v_mfma_f32_16x16x32_bf16 v[16:19], v[226:229], v[194:197], v[16:19]
	v_mfma_f32_16x16x32_bf16 v[8:11], v[234:237], v[194:197], v[8:11]
	v_mfma_f32_16x16x32_bf16 v[4:7], v[226:229], v[218:221], v[4:7]
	v_mfma_f32_16x16x32_bf16 v[0:3], v[234:237], v[218:221], v[0:3]
	s_add_i32 s45, 0, 0x18000
	v_add_u32_e32 v146, s45, v149
	s_barrier
	ds_read_b128 v[128:131], v146
	ds_read_b128 v[132:135], v146 offset:1024
	ds_read_b128 v[142:145], v146 offset:2048
	ds_read_b128 v[150:153], v146 offset:3072
	s_add_u32 s22, s22, 0x80000
	s_addc_u32 s23, s23, 0
	s_mov_b32 m0, s34
	ds_read_b128 v[174:177], v159 offset:32768
	ds_read_b128 v[178:181], v159 offset:33792
	ds_read_b128 v[182:185], v159 offset:34816
	ds_read_b128 v[186:189], v159 offset:35840
	ds_read_b128 v[190:193], v159 offset:36864
	ds_read_b128 v[194:197], v159 offset:37888
	ds_read_b128 v[214:217], v159 offset:38912
	ds_read_b128 v[218:221], v159 offset:39936
	global_load_lds_dwordx4 v160, s[22:23]
	s_mov_b32 m0, s35
	s_nop 0
	global_load_lds_dwordx4 v136, s[22:23]
	s_waitcnt lgkmcnt(8)
	s_barrier
	s_waitcnt lgkmcnt(7)
	v_mfma_f32_16x16x32_bf16 v[124:127], v[128:131], v[174:177], v[124:127]
	v_mfma_f32_16x16x32_bf16 v[120:123], v[142:145], v[174:177], v[120:123]
	s_waitcnt lgkmcnt(5)
	v_mfma_f32_16x16x32_bf16 v[116:119], v[128:131], v[182:185], v[116:119]
	v_mfma_f32_16x16x32_bf16 v[108:111], v[142:145], v[182:185], v[108:111]
	s_waitcnt lgkmcnt(3)
	v_mfma_f32_16x16x32_bf16 v[100:103], v[128:131], v[190:193], v[100:103]
	v_mfma_f32_16x16x32_bf16 v[92:95], v[142:145], v[190:193], v[92:95]
	s_waitcnt lgkmcnt(1)
	v_mfma_f32_16x16x32_bf16 v[84:87], v[128:131], v[214:217], v[84:87]
	v_mfma_f32_16x16x32_bf16 v[76:79], v[142:145], v[214:217], v[76:79]
	v_mfma_f32_16x16x32_bf16 v[124:127], v[132:135], v[178:181], v[124:127]
	v_mfma_f32_16x16x32_bf16 v[120:123], v[150:153], v[178:181], v[120:123]
	v_mfma_f32_16x16x32_bf16 v[116:119], v[132:135], v[186:189], v[116:119]
	v_mfma_f32_16x16x32_bf16 v[108:111], v[150:153], v[186:189], v[108:111]
	v_mfma_f32_16x16x32_bf16 v[100:103], v[132:135], v[194:197], v[100:103]
	v_mfma_f32_16x16x32_bf16 v[92:95], v[150:153], v[194:197], v[92:95]
	s_waitcnt lgkmcnt(0)
	v_mfma_f32_16x16x32_bf16 v[84:87], v[132:135], v[218:221], v[84:87]
	v_mfma_f32_16x16x32_bf16 v[76:79], v[150:153], v[218:221], v[76:79]
	s_barrier
	s_add_i32 s22, 0, 0x1c000
	s_add_i32 s23, s45, s29
	v_add_u32_e32 v146, s22, v149
	v_lshl_add_u64 v[154:155], v[154:155], 0, s[2:3]
	s_mov_b32 m0, s23
	ds_read_b128 v[222:225], v146
	ds_read_b128 v[226:229], v146 offset:1024
	ds_read_b128 v[230:233], v146 offset:2048
	ds_read_b128 v[234:237], v146 offset:3072
	global_load_lds_dwordx4 v[154:155], off
	v_lshl_add_u64 v[154:155], v[238:239], 0, s[2:3]
	s_add_i32 m0, s23, 0x2000
	s_nop 0
	global_load_lds_dwordx4 v[154:155], off
	s_barrier
	s_waitcnt lgkmcnt(3)
	v_mfma_f32_16x16x32_bf16 v[112:115], v[222:225], v[174:177], v[112:115]
	s_waitcnt lgkmcnt(1)
	v_mfma_f32_16x16x32_bf16 v[104:107], v[230:233], v[174:177], v[104:107]
	v_mfma_f32_16x16x32_bf16 v[96:99], v[222:225], v[182:185], v[96:99]
	v_mfma_f32_16x16x32_bf16 v[88:91], v[230:233], v[182:185], v[88:91]
	v_mfma_f32_16x16x32_bf16 v[80:83], v[222:225], v[190:193], v[80:83]
	v_mfma_f32_16x16x32_bf16 v[72:75], v[230:233], v[190:193], v[72:75]
	v_mfma_f32_16x16x32_bf16 v[68:71], v[222:225], v[214:217], v[68:71]
	v_mfma_f32_16x16x32_bf16 v[64:67], v[230:233], v[214:217], v[64:67]
	v_mfma_f32_16x16x32_bf16 v[112:115], v[226:229], v[178:181], v[112:115]
	s_waitcnt lgkmcnt(0)
	v_mfma_f32_16x16x32_bf16 v[104:107], v[234:237], v[178:181], v[104:107]
	v_mfma_f32_16x16x32_bf16 v[96:99], v[226:229], v[186:189], v[96:99]
	v_mfma_f32_16x16x32_bf16 v[88:91], v[234:237], v[186:189], v[88:91]
	v_mfma_f32_16x16x32_bf16 v[80:83], v[226:229], v[194:197], v[80:83]
	v_mfma_f32_16x16x32_bf16 v[72:75], v[234:237], v[194:197], v[72:75]
	v_mfma_f32_16x16x32_bf16 v[68:71], v[226:229], v[218:221], v[68:71]
	v_mfma_f32_16x16x32_bf16 v[64:67], v[234:237], v[218:221], v[64:67]
	s_mov_b32 m0, s37
	v_lshl_add_u64 v[154:155], v[240:241], 0, s[2:3]
	s_barrier
	ds_read_b128 v[174:177], v159 offset:49152
	ds_read_b128 v[178:181], v159 offset:50176
	ds_read_b128 v[182:185], v159 offset:51200
	ds_read_b128 v[186:189], v159 offset:52224
	ds_read_b128 v[190:193], v159 offset:53248
	ds_read_b128 v[194:197], v159 offset:54272
	ds_read_b128 v[214:217], v159 offset:55296
	ds_read_b128 v[218:221], v159 offset:56320
	global_load_lds_dwordx4 v[154:155], off
	v_lshl_add_u64 v[154:155], v[242:243], 0, s[2:3]
	s_mov_b32 m0, s38
	s_nop 0
	global_load_lds_dwordx4 v[154:155], off
	s_barrier
; #define PG8_STAGE(bufoff, gbase, voff) do { _Pragma("unroll") for (int _i = 0; _i < 2; ++_i) \
;         __builtin_amdgcn_global_load_lds((const unsigned*)((const char*)(gbase) + (voff)[_i]), (LAS unsigned*)(lds + (bufoff) + ldsw + _i * 8192), 16, 0, 0); } while (0)
; #define PG8_LDA(dst, b, h) do { _Pragma("unroll") for (int m = 0; m < 4; ++m) _Pragma("unroll") for (int k = 0; k < 2; ++k) dst[m][k] = *(const LAS bf16x8*)(lds + PG8_SA(b, h) + aoff + m * 2048 + k * 1024); } while (0)
; #define PG8_MMA(ai, bj, At, Bt) do { __builtin_amdgcn_s_setprio(1); _Pragma("unroll") for (int m = 0; m < 4; ++m) _Pragma("unroll") for (int n = 0; n < 2; ++n) _Pragma("unroll") for (int k = 0; k < 2; ++k) \
;         acc[ai][bj][m][n] = __builtin_amdgcn_mfma_f32_16x16x32_bf16(Bt[n][k], At[m][k], acc[ai][bj][m][n], 0, 0, 0); __builtin_amdgcn_s_setprio(0); } while (0)
; #define PG8_WAIT_V(n) asm volatile("s_waitcnt vmcnt(" #n ")" ::: "memory")
; #define PG8_WAIT_L(n) asm volatile("s_waitcnt lgkmcnt(" #n ")" ::: "memory")
; #define PG8_BAR __builtin_amdgcn_s_barrier()
; #define PG8_SCHED __builtin_amdgcn_sched_barrier(0)
; template <class Epi>
; DEV void gemm_phase(LAS unsigned char* lds, const Gemm g, const StaticOrder& S, const Epi& E) {
;     ...
;             PG8_LDA(At, 1, 1); PG8_STAGE(PG8_SA(1, 0), a3, voffA);
;             PG8_BAR; PG8_WAIT_L(0); PG8_MMA(1, 0, At, B0); PG8_BAR; PG8_SCHED;
;             PG8_STAGE(PG8_SB(1, 1), b3 + hstep, voffB);
;             PG8_WAIT_V(6); PG8_BAR; PG8_MMA(1, 1, At, B1); PG8_BAR;
;         }
; template <int ACT, bool PERM>
; DEV void store_bf16_tile(AccRef acc, u16* O, int ld, int row0, int col0, const float* ss) {
;     float rsv[2][4];
; #pragma unroll
;     for (int ai = 0; ai < 2; ++ai)
; #pragma unroll
;         for (int m = 0; m < 4; ++m) rsv[ai][m] = ss ? rowscale(ss, row0 + ai * 128 + m * 16) : 1.0f;
; #pragma unroll
;     for (int ai = 0; ai < 2; ++ai)
; #pragma unroll
;         for (int m = 0; m < 4; ++m) { u16* rowp = O + (size_t)(row0 + ai * 128 + m * 16) * ld + col0; const float rs = rsv[ai][m];
	s_waitcnt lgkmcnt(7)
	v_mfma_f32_16x16x32_bf16 v[60:63], v[128:131], v[174:177], v[60:63]
	v_mfma_f32_16x16x32_bf16 v[56:59], v[142:145], v[174:177], v[56:59]
	s_waitcnt lgkmcnt(5)
	v_mfma_f32_16x16x32_bf16 v[52:55], v[128:131], v[182:185], v[52:55]
	v_mfma_f32_16x16x32_bf16 v[44:47], v[142:145], v[182:185], v[44:47]
	s_waitcnt lgkmcnt(3)
	v_mfma_f32_16x16x32_bf16 v[36:39], v[128:131], v[190:193], v[36:39]
	v_mfma_f32_16x16x32_bf16 v[28:31], v[142:145], v[190:193], v[28:31]
	s_waitcnt lgkmcnt(1)
	v_mfma_f32_16x16x32_bf16 v[20:23], v[128:131], v[214:217], v[20:23]
	v_mfma_f32_16x16x32_bf16 v[12:15], v[142:145], v[214:217], v[12:15]
	v_mfma_f32_16x16x32_bf16 v[60:63], v[132:135], v[178:181], v[60:63]
	v_mfma_f32_16x16x32_bf16 v[56:59], v[150:153], v[178:181], v[56:59]
	v_mfma_f32_16x16x32_bf16 v[52:55], v[132:135], v[186:189], v[52:55]
	v_mfma_f32_16x16x32_bf16 v[44:47], v[150:153], v[186:189], v[44:47]
	v_mfma_f32_16x16x32_bf16 v[36:39], v[132:135], v[194:197], v[36:39]
	v_mfma_f32_16x16x32_bf16 v[28:31], v[150:153], v[194:197], v[28:31]
	s_waitcnt lgkmcnt(0)
	v_mfma_f32_16x16x32_bf16 v[20:23], v[132:135], v[218:221], v[20:23]
	v_mfma_f32_16x16x32_bf16 v[12:15], v[150:153], v[218:221], v[12:15]
	s_barrier
	s_add_u32 s20, s20, 0x80080
	s_addc_u32 s21, s21, 0
	s_add_i32 s22, s22, s29
	s_mov_b32 m0, s22
	s_nop 0
	global_load_lds_dwordx4 v160, s[20:21]
	s_add_i32 m0, s22, 0x2000
	s_nop 0
	global_load_lds_dwordx4 v136, s[20:21]
	s_waitcnt vmcnt(6)
	s_barrier
	v_mfma_f32_16x16x32_bf16 v[48:51], v[222:225], v[174:177], v[48:51]
	v_mfma_f32_16x16x32_bf16 v[40:43], v[230:233], v[174:177], v[40:43]
	v_mfma_f32_16x16x32_bf16 v[32:35], v[222:225], v[182:185], v[32:35]
	v_mfma_f32_16x16x32_bf16 v[24:27], v[230:233], v[182:185], v[24:27]
	v_mfma_f32_16x16x32_bf16 v[16:19], v[222:225], v[190:193], v[16:19]
	v_mfma_f32_16x16x32_bf16 v[8:11], v[230:233], v[190:193], v[8:11]
	v_mfma_f32_16x16x32_bf16 v[4:7], v[222:225], v[214:217], v[4:7]
	v_mfma_f32_16x16x32_bf16 v[0:3], v[230:233], v[214:217], v[0:3]
	v_mfma_f32_16x16x32_bf16 v[48:51], v[226:229], v[178:181], v[48:51]
	v_mfma_f32_16x16x32_bf16 v[40:43], v[234:237], v[178:181], v[40:43]
	v_mfma_f32_16x16x32_bf16 v[32:35], v[226:229], v[186:189], v[32:35]
	v_mfma_f32_16x16x32_bf16 v[24:27], v[234:237], v[186:189], v[24:27]
	v_mfma_f32_16x16x32_bf16 v[16:19], v[226:229], v[194:197], v[16:19]
	v_mfma_f32_16x16x32_bf16 v[8:11], v[234:237], v[194:197], v[8:11]
	v_mfma_f32_16x16x32_bf16 v[4:7], v[226:229], v[218:221], v[4:7]
	v_mfma_f32_16x16x32_bf16 v[0:3], v[234:237], v[218:221], v[0:3]
	s_add_i32 s44, s44, 2
	s_add_u32 s18, s18, 0x100
	s_addc_u32 s19, s19, 0
	s_add_u32 s42, s42, 0x100
	s_addc_u32 s43, s43, 0
	s_cmp_gt_u32 s44, 29
	s_barrier
	s_cbranch_scc0 .LBB0_344
	v_lshl_add_u32 v142, s0, 8, v147
	v_ashrrev_i32_e32 v143, 31, v142
	v_lshlrev_b64 v[128:129], 5, v[142:143]
	v_lshl_add_u64 v[132:133], s[4:5], 0, v[128:129]
	global_load_dwordx4 v[128:131], v[132:133], off offset:16
	s_nop 0
	global_load_dwordx4 v[132:135], v[132:133], off
	s_mov_b32 s0, 0x3727c5ac
	s_mov_b32 s18, 0x3a000000
	s_mov_b32 s11, 0x800000
	s_mov_b64 s[20:21], s[16:17]
	s_waitcnt vmcnt(0)
	v_mov_b32_e32 v144, v133
	v_mov_b32_e32 v145, v134
	v_mov_b32_e32 v133, v135
	v_pk_add_f32 v[150:151], v[144:145], v[132:133]
	v_or_b32_e32 v144, 16, v142
	v_mov_b32_e32 v132, v130
	v_mov_b32_e32 v133, v128
	v_mov_b32_e32 v128, v131
	v_ashrrev_i32_e32 v145, 31, v144
	v_pk_add_f32 v[152:153], v[132:133], v[128:129]
	v_lshlrev_b64 v[128:129], 5, v[144:145]
	v_lshl_add_u64 v[132:133], s[4:5], 0, v[128:129]
	global_load_dwordx4 v[128:131], v[132:133], off offset:16
	s_nop 0
	global_load_dwordx4 v[132:135], v[132:133], off
	s_waitcnt vmcnt(0)
	v_mov_b32_e32 v154, v133
	v_mov_b32_e32 v155, v134
	v_mov_b32_e32 v133, v135
	v_pk_add_f32 v[132:133], v[154:155], v[132:133]
	v_mov_b32_e32 v134, v130
	v_mov_b32_e32 v135, v128
	v_mov_b32_e32 v128, v131
	v_pk_add_f32 v[128:129], v[134:135], v[128:129]
	v_mov_b32_e32 v130, v132
	v_mov_b32_e32 v131, v150
	v_mov_b32_e32 v150, v133
	v_pk_add_f32 v[130:131], v[130:131], v[150:151]
	v_mov_b32_e32 v132, v129
	v_mov_b32_e32 v133, v153
	v_pk_add_f32 v[130:131], v[130:131], v[132:133]
	v_mov_b32_e32 v129, v152
	v_pk_add_f32 v[128:129], v[128:129], v[130:131]
	v_mov_b64_e32 v[150:151], s[0:1]
	v_pk_fma_f32 v[128:129], v[128:129], s[18:19], v[150:151] op_sel_hi:[1,0,0]
	v_or_b32_e32 v152, 32, v142
	v_mul_f32_e32 v130, 0x4b800000, v129
	v_cmp_gt_f32_e64 s[0:1], s11, v129
	v_cmp_gt_f32_e32 vcc, s11, v128
	v_ashrrev_i32_e32 v153, 31, v152
	v_cndmask_b32_e64 v129, v129, v130, s[0:1]
	v_rsq_f32_e32 v129, v129
	s_nop 0
	v_mul_f32_e32 v130, 0x45800000, v129
	v_cndmask_b32_e64 v148, v129, v130, s[0:1]
	v_mul_f32_e32 v129, 0x4b800000, v128
	v_cndmask_b32_e32 v128, v128, v129, vcc
	v_rsq_f32_e32 v128, v128
	v_pk_mul_f32 v[106:107], v[106:107], v[148:149] op_sel_hi:[1,0]
	v_pk_mul_f32 v[104:105], v[104:105], v[148:149] op_sel_hi:[1,0]
	v_pk_mul_f32 v[114:115], v[114:115], v[148:149] op_sel_hi:[1,0]
	v_mul_f32_e32 v129, 0x45800000, v128
	v_cndmask_b32_e32 v146, v128, v129, vcc
	v_lshlrev_b64 v[128:129], 5, v[152:153]
	v_lshl_add_u64 v[132:133], s[4:5], 0, v[128:129]
	global_load_dwordx4 v[128:131], v[132:133], off offset:16
	s_nop 0
	global_load_dwordx4 v[132:135], v[132:133], off
	v_cvt_pk_bf16_f32 v104, v104, v105
	v_cvt_pk_bf16_f32 v105, v106, v107
	v_pk_mul_f32 v[90:91], v[90:91], v[146:147] op_sel_hi:[1,0]
	v_pk_mul_f32 v[88:89], v[88:89], v[146:147] op_sel_hi:[1,0]
	v_pk_mul_f32 v[112:113], v[112:113], v[148:149] op_sel_hi:[1,0]
	v_cvt_pk_bf16_f32 v88, v88, v89
	v_cvt_pk_bf16_f32 v89, v90, v91
	v_pk_mul_f32 v[98:99], v[98:99], v[146:147] op_sel_hi:[1,0]
	v_pk_mul_f32 v[96:97], v[96:97], v[146:147] op_sel_hi:[1,0]
	v_cvt_pk_bf16_f32 v112, v112, v113
	v_cvt_pk_bf16_f32 v113, v114, v115
	v_cvt_pk_bf16_f32 v96, v96, v97
	v_cvt_pk_bf16_f32 v97, v98, v99
	v_pk_mul_f32 v[126:127], v[126:127], v[148:149] op_sel_hi:[1,0]
	v_pk_mul_f32 v[124:125], v[124:125], v[148:149] op_sel_hi:[1,0]
	v_pk_mul_f32 v[122:123], v[122:123], v[148:149] op_sel_hi:[1,0]
	v_pk_mul_f32 v[120:121], v[120:121], v[148:149] op_sel_hi:[1,0]
	v_pk_mul_f32 v[106:107], v[118:119], v[146:147] op_sel_hi:[1,0]
	v_pk_mul_f32 v[110:111], v[110:111], v[146:147] op_sel_hi:[1,0]
	v_pk_mul_f32 v[108:109], v[108:109], v[146:147] op_sel_hi:[1,0]
	v_cvt_pk_bf16_f32 v124, v124, v125
	v_cvt_pk_bf16_f32 v125, v126, v127
	v_cvt_pk_bf16_f32 v120, v120, v121
	v_cvt_pk_bf16_f32 v121, v122, v123
	s_waitcnt vmcnt(0)
; DEV bf16x8 pack8(f32x4 a, f32x4 b) { u32x4 w; w.x = cvt_pk_bf16(a[0], a[1]); w.y = cvt_pk_bf16(a[2], a[3]); w.z = cvt_pk_bf16(b[0], b[1]); w.w = cvt_pk_bf16(b[2], b[3]); return __builtin_bit_cast(bf16x8, w); }
; DEV u32x2 pack4(f32x4 a) { u32x2 w; w.x = cvt_pk_bf16(a[0], a[1]); w.y = cvt_pk_bf16(a[2], a[3]); return w; }
; DEV f32x4 gelu4(f32x4 v) { f32x2 a = gelu_pk((f32x2){v[0], v[1]}), b = gelu_pk((f32x2){v[2], v[3]}); return (f32x4){a.x, a.y, b.x, b.y}; }
; DEV float rowscale(const float* ss, int row) { const f32x4 a = *(const f32x4*)(ss + (size_t)row * 8), b = *(const f32x4*)(ss + (size_t)row * 8 + 4);
;     return rsqrtf(((a[0] + a[1]) + (a[2] + a[3]) + (b[0] + b[1]) + (b[2] + b[3])) * (1.0f / 2048.0f) + EPS); }
; template <int ACT, bool PERM>
; DEV void store_bf16_tile(AccRef acc, u16* O, int ld, int row0, int col0, const float* ss) {
;     float rsv[2][4];
; #pragma unroll
;     for (int ai = 0; ai < 2; ++ai)
; #pragma unroll
;         for (int m = 0; m < 4; ++m) rsv[ai][m] = ss ? rowscale(ss, row0 + ai * 128 + m * 16) : 1.0f;
; #pragma unroll
;     for (int ai = 0; ai < 2; ++ai)
; #pragma unroll
;         for (int m = 0; m < 4; ++m) { u16* rowp = O + (size_t)(row0 + ai * 128 + m * 16) * ld + col0; const float rs = rsv[ai][m];
; #pragma unroll
;             for (int bj = 0; bj < 2; ++bj) { f32x4 v0 = acc[ai][bj][m][0] * rs, v1 = acc[ai][bj][m][1] * rs; if (ACT == 1) { v0 = gelu4(v0); v1 = gelu4(v1); }
;                 if (PERM) *(u32x4*)(rowp + bj * 128) = __builtin_bit_cast(u32x4, pack8(v0, v1));
;                 else { *(u32x2*)(rowp + bj * 128) = pack4(v0); *(u32x2*)(rowp + bj * 128 + 16) = pack4(v1); } } }
	v_mov_b32_e32 v154, v133
	v_mov_b32_e32 v155, v134
	v_mov_b32_e32 v133, v135
	v_pk_add_f32 v[174:175], v[154:155], v[132:133]
	v_or_b32_e32 v154, 48, v142
	v_mov_b32_e32 v132, v130
	v_mov_b32_e32 v133, v128
	v_mov_b32_e32 v128, v131
	v_ashrrev_i32_e32 v155, 31, v154
	v_pk_add_f32 v[176:177], v[132:133], v[128:129]
	v_lshlrev_b64 v[128:129], 5, v[154:155]
	v_lshl_add_u64 v[132:133], s[4:5], 0, v[128:129]
	global_load_dwordx4 v[128:131], v[132:133], off offset:16
	s_nop 0
	global_load_dwordx4 v[132:135], v[132:133], off
	s_waitcnt vmcnt(0)
	v_mov_b32_e32 v178, v133
	v_mov_b32_e32 v179, v134
	v_mov_b32_e32 v133, v135
	v_pk_add_f32 v[132:133], v[178:179], v[132:133]
	v_mov_b32_e32 v134, v130
	v_mov_b32_e32 v135, v128
	v_mov_b32_e32 v128, v131
	v_pk_add_f32 v[128:129], v[134:135], v[128:129]
	v_mov_b32_e32 v130, v132
	v_mov_b32_e32 v131, v174
	v_mov_b32_e32 v174, v133
	v_pk_add_f32 v[130:131], v[130:131], v[174:175]
	v_mov_b32_e32 v132, v129
	v_mov_b32_e32 v133, v177
	v_pk_add_f32 v[130:131], v[130:131], v[132:133]
	v_mov_b32_e32 v129, v176
	v_pk_add_f32 v[128:129], v[128:129], v[130:131]
	v_add_u32_e32 v174, 0x80, v142
	v_pk_fma_f32 v[128:129], v[128:129], s[18:19], v[150:151] op_sel_hi:[1,0,0]
	v_ashrrev_i32_e32 v175, 31, v174
	v_mul_f32_e32 v130, 0x4b800000, v129
	v_cmp_gt_f32_e64 s[0:1], s11, v129
	v_cmp_gt_f32_e32 vcc, s11, v128
	s_nop 0
	v_cndmask_b32_e64 v129, v129, v130, s[0:1]
	v_rsq_f32_e32 v129, v129
	s_nop 0
	v_mul_f32_e32 v130, 0x45800000, v129
	v_cndmask_b32_e64 v158, v129, v130, s[0:1]
	v_mul_f32_e32 v129, 0x4b800000, v128
	v_cndmask_b32_e32 v128, v128, v129, vcc
	v_rsq_f32_e32 v128, v128
	v_pk_mul_f32 v[74:75], v[74:75], v[158:159] op_sel_hi:[1,0]
	v_pk_mul_f32 v[72:73], v[72:73], v[158:159] op_sel_hi:[1,0]
	v_pk_mul_f32 v[82:83], v[82:83], v[158:159] op_sel_hi:[1,0]
	v_mul_f32_e32 v129, 0x45800000, v128
	v_cndmask_b32_e32 v156, v128, v129, vcc
	v_lshlrev_b64 v[128:129], 5, v[174:175]
	v_lshl_add_u64 v[132:133], s[4:5], 0, v[128:129]
	global_load_dwordx4 v[128:131], v[132:133], off offset:16
	s_nop 0
	global_load_dwordx4 v[132:135], v[132:133], off
	v_cvt_pk_bf16_f32 v72, v72, v73
	v_cvt_pk_bf16_f32 v73, v74, v75
	v_pk_mul_f32 v[66:67], v[66:67], v[156:157] op_sel_hi:[1,0]
	v_pk_mul_f32 v[64:65], v[64:65], v[156:157] op_sel_hi:[1,0]
	v_pk_mul_f32 v[80:81], v[80:81], v[158:159] op_sel_hi:[1,0]
	v_cvt_pk_bf16_f32 v64, v64, v65
	v_cvt_pk_bf16_f32 v65, v66, v67
	v_cvt_pk_bf16_f32 v80, v80, v81
	v_cvt_pk_bf16_f32 v81, v82, v83
	v_pk_mul_f32 v[90:91], v[102:103], v[158:159] op_sel_hi:[1,0]
	v_pk_mul_f32 v[94:95], v[94:95], v[158:159] op_sel_hi:[1,0]
	v_pk_mul_f32 v[92:93], v[92:93], v[158:159] op_sel_hi:[1,0]
	v_pk_mul_f32 v[74:75], v[86:87], v[156:157] op_sel_hi:[1,0]
	v_pk_mul_f32 v[78:79], v[78:79], v[156:157] op_sel_hi:[1,0]
	v_pk_mul_f32 v[76:77], v[76:77], v[156:157] op_sel_hi:[1,0]
	v_pk_mul_f32 v[70:71], v[70:71], v[156:157] op_sel_hi:[1,0]
	v_pk_mul_f32 v[68:69], v[68:69], v[156:157] op_sel_hi:[1,0]
	s_waitcnt vmcnt(0)
	v_mov_b32_e32 v176, v133
	v_mov_b32_e32 v177, v134
	v_mov_b32_e32 v133, v135
	v_pk_add_f32 v[178:179], v[176:177], v[132:133]
	v_add_u32_e32 v176, 0x90, v142
	v_mov_b32_e32 v132, v130
	v_mov_b32_e32 v133, v128
	v_mov_b32_e32 v128, v131
	v_ashrrev_i32_e32 v177, 31, v176
	v_pk_add_f32 v[180:181], v[132:133], v[128:129]
	v_lshlrev_b64 v[128:129], 5, v[176:177]
	v_lshl_add_u64 v[132:133], s[4:5], 0, v[128:129]
	global_load_dwordx4 v[128:131], v[132:133], off offset:16
	s_nop 0
	global_load_dwordx4 v[132:135], v[132:133], off
	v_cvt_pk_bf16_f32 v68, v68, v69
	v_cvt_pk_bf16_f32 v69, v70, v71
	s_waitcnt vmcnt(0)
	v_mov_b32_e32 v182, v133
	v_mov_b32_e32 v183, v134
	v_mov_b32_e32 v133, v135
	v_pk_add_f32 v[132:133], v[182:183], v[132:133]
	v_mov_b32_e32 v134, v130
	v_mov_b32_e32 v135, v128
	v_mov_b32_e32 v128, v131
	v_pk_add_f32 v[128:129], v[134:135], v[128:129]
	v_mov_b32_e32 v130, v132
	v_mov_b32_e32 v131, v178
	v_mov_b32_e32 v178, v133
	v_pk_add_f32 v[130:131], v[130:131], v[178:179]
	v_mov_b32_e32 v132, v129
	v_mov_b32_e32 v133, v181
	v_pk_add_f32 v[130:131], v[130:131], v[132:133]
	v_mov_b32_e32 v129, v180
	v_pk_add_f32 v[128:129], v[128:129], v[130:131]
	v_add_u32_e32 v182, 0xa0, v142
	v_pk_fma_f32 v[128:129], v[128:129], s[18:19], v[150:151] op_sel_hi:[1,0,0]
	v_ashrrev_i32_e32 v183, 31, v182
	v_mul_f32_e32 v130, 0x4b800000, v129
	v_cmp_gt_f32_e64 s[0:1], s11, v129
	v_cmp_gt_f32_e32 vcc, s11, v128
	s_nop 0
	v_cndmask_b32_e64 v129, v129, v130, s[0:1]
	v_rsq_f32_e32 v129, v129
	s_nop 0
	v_mul_f32_e32 v130, 0x45800000, v129
	v_cndmask_b32_e64 v180, v129, v130, s[0:1]
	v_mul_f32_e32 v129, 0x4b800000, v128
	v_cndmask_b32_e32 v128, v128, v129, vcc
	v_rsq_f32_e32 v128, v128
	v_pk_mul_f32 v[42:43], v[42:43], v[180:181] op_sel_hi:[1,0]
	v_pk_mul_f32 v[40:41], v[40:41], v[180:181] op_sel_hi:[1,0]
	v_pk_mul_f32 v[50:51], v[50:51], v[180:181] op_sel_hi:[1,0]
	v_mul_f32_e32 v129, 0x45800000, v128
	v_cndmask_b32_e32 v178, v128, v129, vcc
	v_lshlrev_b64 v[128:129], 5, v[182:183]
	v_lshl_add_u64 v[132:133], s[4:5], 0, v[128:129]
	global_load_dwordx4 v[128:131], v[132:133], off offset:16
	s_nop 0
	global_load_dwordx4 v[132:135], v[132:133], off
	v_cvt_pk_bf16_f32 v40, v40, v41
	v_cvt_pk_bf16_f32 v41, v42, v43
	v_pk_mul_f32 v[26:27], v[26:27], v[178:179] op_sel_hi:[1,0]
	v_pk_mul_f32 v[24:25], v[24:25], v[178:179] op_sel_hi:[1,0]
	v_pk_mul_f32 v[48:49], v[48:49], v[180:181] op_sel_hi:[1,0]
	v_cvt_pk_bf16_f32 v24, v24, v25
	v_cvt_pk_bf16_f32 v25, v26, v27
	v_pk_mul_f32 v[34:35], v[34:35], v[178:179] op_sel_hi:[1,0]
	v_pk_mul_f32 v[32:33], v[32:33], v[178:179] op_sel_hi:[1,0]
	v_cvt_pk_bf16_f32 v48, v48, v49
	v_cvt_pk_bf16_f32 v49, v50, v51
	v_cvt_pk_bf16_f32 v32, v32, v33
	v_cvt_pk_bf16_f32 v33, v34, v35
	v_pk_mul_f32 v[62:63], v[62:63], v[180:181] op_sel_hi:[1,0]
	v_pk_mul_f32 v[60:61], v[60:61], v[180:181] op_sel_hi:[1,0]
	v_pk_mul_f32 v[58:59], v[58:59], v[180:181] op_sel_hi:[1,0]
	v_pk_mul_f32 v[56:57], v[56:57], v[180:181] op_sel_hi:[1,0]
	v_pk_mul_f32 v[42:43], v[54:55], v[178:179] op_sel_hi:[1,0]
	v_pk_mul_f32 v[46:47], v[46:47], v[178:179] op_sel_hi:[1,0]
	v_pk_mul_f32 v[44:45], v[44:45], v[178:179] op_sel_hi:[1,0]
	v_cvt_pk_bf16_f32 v60, v60, v61
	v_cvt_pk_bf16_f32 v61, v62, v63
	v_cvt_pk_bf16_f32 v56, v56, v57
	v_cvt_pk_bf16_f32 v57, v58, v59
	s_waitcnt vmcnt(0)
; DEV bf16x8 pack8(f32x4 a, f32x4 b) { u32x4 w; w.x = cvt_pk_bf16(a[0], a[1]); w.y = cvt_pk_bf16(a[2], a[3]); w.z = cvt_pk_bf16(b[0], b[1]); w.w = cvt_pk_bf16(b[2], b[3]); return __builtin_bit_cast(bf16x8, w); }
; DEV u32x2 pack4(f32x4 a) { u32x2 w; w.x = cvt_pk_bf16(a[0], a[1]); w.y = cvt_pk_bf16(a[2], a[3]); return w; }
; DEV f32x4 gelu4(f32x4 v) { f32x2 a = gelu_pk((f32x2){v[0], v[1]}), b = gelu_pk((f32x2){v[2], v[3]}); return (f32x4){a.x, a.y, b.x, b.y}; }
; #define PG8_WAIT_V(n) asm volatile("s_waitcnt vmcnt(" #n ")" ::: "memory")
; #define PG8_BAR __builtin_amdgcn_s_barrier()
; template <class Epi>
; DEV void gemm_phase(LAS unsigned char* lds, const Gemm g, const StaticOrder& S, const Epi& E) {
;     ...
;     PG8_WAIT_V(0);
;     if (wr == 0) PG8_BAR;
;     PG8_BAR;
; template <int ACT, bool PERM>
; DEV void store_bf16_tile(AccRef acc, u16* O, int ld, int row0, int col0, const float* ss) {
;     float rsv[2][4];
; #pragma unroll
;     for (int ai = 0; ai < 2; ++ai)
; #pragma unroll
;         for (int m = 0; m < 4; ++m) rsv[ai][m] = ss ? rowscale(ss, row0 + ai * 128 + m * 16) : 1.0f;
; #pragma unroll
;     for (int ai = 0; ai < 2; ++ai)
; #pragma unroll
;         for (int m = 0; m < 4; ++m) { u16* rowp = O + (size_t)(row0 + ai * 128 + m * 16) * ld + col0; const float rs = rsv[ai][m];
; #pragma unroll
;             for (int bj = 0; bj < 2; ++bj) { f32x4 v0 = acc[ai][bj][m][0] * rs, v1 = acc[ai][bj][m][1] * rs; if (ACT == 1) { v0 = gelu4(v0); v1 = gelu4(v1); }
;                 if (PERM) *(u32x4*)(rowp + bj * 128) = __builtin_bit_cast(u32x4, pack8(v0, v1));
;                 else { *(u32x2*)(rowp + bj * 128) = pack4(v0); *(u32x2*)(rowp + bj * 128 + 16) = pack4(v1); } } }
	v_mov_b32_e32 v184, v133
	v_mov_b32_e32 v185, v134
	v_mov_b32_e32 v133, v135
	v_pk_add_f32 v[188:189], v[184:185], v[132:133]
	v_add_u32_e32 v184, 0xb0, v142
	v_mov_b32_e32 v132, v130
	v_mov_b32_e32 v133, v128
	v_mov_b32_e32 v128, v131
	v_ashrrev_i32_e32 v185, 31, v184
	v_pk_add_f32 v[186:187], v[132:133], v[128:129]
	v_lshlrev_b64 v[128:129], 5, v[184:185]
	v_lshl_add_u64 v[132:133], s[4:5], 0, v[128:129]
	global_load_dwordx4 v[128:131], v[132:133], off offset:16
	s_nop 0
	global_load_dwordx4 v[132:135], v[132:133], off
	s_waitcnt vmcnt(0)
	v_mov_b32_e32 v190, v133
	v_mov_b32_e32 v191, v134
	v_mov_b32_e32 v133, v135
	v_pk_add_f32 v[132:133], v[190:191], v[132:133]
	v_mov_b32_e32 v134, v130
	v_mov_b32_e32 v135, v128
	v_mov_b32_e32 v128, v131
	v_pk_add_f32 v[128:129], v[134:135], v[128:129]
	v_mov_b32_e32 v130, v132
	v_mov_b32_e32 v131, v188
	v_mov_b32_e32 v188, v133
	v_pk_add_f32 v[130:131], v[130:131], v[188:189]
	v_mov_b32_e32 v132, v129
	v_mov_b32_e32 v133, v187
	v_pk_add_f32 v[130:131], v[130:131], v[132:133]
	v_mov_b32_e32 v129, v186
	v_pk_add_f32 v[128:129], v[128:129], v[130:131]
	v_lshl_or_b32 v132, s40, 8, v157
	v_pk_fma_f32 v[128:129], v[128:129], s[18:19], v[150:151] op_sel_hi:[1,0,0]
	v_ashrrev_i32_e32 v133, 31, v132
	v_mul_f32_e32 v130, 0x4b800000, v129
	v_cmp_gt_f32_e64 s[0:1], s11, v129
	v_lshlrev_b64 v[134:135], 10, v[142:143]
	v_cmp_gt_f32_e32 vcc, s11, v128
	v_cndmask_b32_e64 v129, v129, v130, s[0:1]
	v_rsq_f32_e32 v129, v129
	s_mov_b32 s40, s10
	s_mov_b64 s[18:19], s[14:15]
	v_mul_f32_e32 v130, 0x45800000, v129
	v_cndmask_b32_e64 v130, v129, v130, s[0:1]
	v_readlane_b32 s0, v250, 11
	v_readlane_b32 s1, v250, 12
	v_mul_f32_e32 v129, 0x4b800000, v128
	v_cndmask_b32_e32 v128, v128, v129, vcc
	v_lshl_add_u64 v[132:133], v[132:133], 1, s[0:1]
	v_lshl_add_u64 v[134:135], v[132:133], 0, v[134:135]
	global_store_dwordx2 v[134:135], v[104:105], off offset:288
	v_lshlrev_b64 v[104:105], 10, v[144:145]
	v_lshl_add_u64 v[104:105], v[132:133], 0, v[104:105]
	global_store_dwordx2 v[104:105], v[88:89], off offset:288
	v_lshlrev_b64 v[88:89], 10, v[152:153]
	v_lshl_add_u64 v[88:89], v[132:133], 0, v[88:89]
	global_store_dwordx2 v[88:89], v[72:73], off offset:288
	v_lshlrev_b64 v[72:73], 10, v[154:155]
	v_lshl_add_u64 v[72:73], v[132:133], 0, v[72:73]
	v_rsq_f32_e32 v128, v128
	global_store_dwordx2 v[72:73], v[64:65], off offset:288
	v_lshlrev_b64 v[64:65], 10, v[174:175]
	v_lshl_add_u64 v[64:65], v[132:133], 0, v[64:65]
	global_store_dwordx2 v[64:65], v[40:41], off offset:288
	v_lshlrev_b64 v[40:41], 10, v[176:177]
	v_lshl_add_u64 v[40:41], v[132:133], 0, v[40:41]
	v_mul_f32_e32 v129, 0x45800000, v128
	global_store_dwordx2 v[40:41], v[24:25], off offset:288
	v_lshlrev_b64 v[24:25], 10, v[182:183]
	v_pk_mul_f32 v[18:19], v[18:19], v[130:131] op_sel_hi:[1,0]
	v_pk_mul_f32 v[16:17], v[16:17], v[130:131] op_sel_hi:[1,0]
	v_pk_mul_f32 v[10:11], v[10:11], v[130:131] op_sel_hi:[1,0]
	v_pk_mul_f32 v[8:9], v[8:9], v[130:131] op_sel_hi:[1,0]
	v_cndmask_b32_e32 v128, v128, v129, vcc
	v_lshl_add_u64 v[24:25], v[132:133], 0, v[24:25]
	v_cvt_pk_bf16_f32 v16, v16, v17
	v_cvt_pk_bf16_f32 v17, v18, v19
	v_cvt_pk_bf16_f32 v8, v8, v9
	v_cvt_pk_bf16_f32 v9, v10, v11
	global_store_dwordx2 v[134:135], v[112:113], off offset:256
	v_pk_mul_f32 v[112:113], v[116:117], v[146:147] op_sel_hi:[1,0]
	global_store_dwordx2 v[104:105], v[96:97], off offset:256
	v_pk_mul_f32 v[96:97], v[100:101], v[158:159] op_sel_hi:[1,0]
	global_store_dwordx2 v[88:89], v[80:81], off offset:256
	v_pk_mul_f32 v[80:81], v[84:85], v[156:157] op_sel_hi:[1,0]
	global_store_dwordx2 v[64:65], v[48:49], off offset:256
	v_pk_mul_f32 v[48:49], v[52:53], v[178:179] op_sel_hi:[1,0]
	global_store_dwordx2 v[40:41], v[32:33], off offset:256
	v_pk_mul_f32 v[26:27], v[38:39], v[130:131] op_sel_hi:[1,0]
	v_pk_mul_f32 v[32:33], v[36:37], v[130:131] op_sel_hi:[1,0]
	v_pk_mul_f32 v[30:31], v[30:31], v[130:131] op_sel_hi:[1,0]
	v_pk_mul_f32 v[28:29], v[28:29], v[130:131] op_sel_hi:[1,0]
	global_store_dwordx2 v[24:25], v[16:17], off offset:256
	global_store_dwordx2 v[24:25], v[8:9], off offset:288
	v_lshlrev_b64 v[8:9], 10, v[184:185]
	v_pk_mul_f32 v[10:11], v[22:23], v[128:129] op_sel_hi:[1,0]
	v_pk_mul_f32 v[16:17], v[20:21], v[128:129] op_sel_hi:[1,0]
	v_pk_mul_f32 v[14:15], v[14:15], v[128:129] op_sel_hi:[1,0]
	v_pk_mul_f32 v[12:13], v[12:13], v[128:129] op_sel_hi:[1,0]
	v_pk_mul_f32 v[6:7], v[6:7], v[128:129] op_sel_hi:[1,0]
	v_pk_mul_f32 v[4:5], v[4:5], v[128:129] op_sel_hi:[1,0]
	v_pk_mul_f32 v[2:3], v[2:3], v[128:129] op_sel_hi:[1,0]
	v_pk_mul_f32 v[0:1], v[0:1], v[128:129] op_sel_hi:[1,0]
	v_cvt_pk_bf16_f32 v112, v112, v113
	v_cvt_pk_bf16_f32 v113, v106, v107
	v_cvt_pk_bf16_f32 v106, v108, v109
	v_cvt_pk_bf16_f32 v107, v110, v111
	v_cvt_pk_bf16_f32 v96, v96, v97
	v_cvt_pk_bf16_f32 v97, v90, v91
	v_cvt_pk_bf16_f32 v90, v92, v93
	v_cvt_pk_bf16_f32 v91, v94, v95
	v_cvt_pk_bf16_f32 v80, v80, v81
	v_cvt_pk_bf16_f32 v81, v74, v75
	v_cvt_pk_bf16_f32 v74, v76, v77
	v_cvt_pk_bf16_f32 v75, v78, v79
	v_cvt_pk_bf16_f32 v48, v48, v49
	v_cvt_pk_bf16_f32 v49, v42, v43
	v_cvt_pk_bf16_f32 v42, v44, v45
	v_cvt_pk_bf16_f32 v43, v46, v47
	v_cvt_pk_bf16_f32 v32, v32, v33
	v_cvt_pk_bf16_f32 v33, v26, v27
	v_cvt_pk_bf16_f32 v26, v28, v29
	v_cvt_pk_bf16_f32 v27, v30, v31
	v_lshl_add_u64 v[8:9], v[132:133], 0, v[8:9]
	v_cvt_pk_bf16_f32 v16, v16, v17
	v_cvt_pk_bf16_f32 v17, v10, v11
	v_cvt_pk_bf16_f32 v10, v12, v13
	v_cvt_pk_bf16_f32 v11, v14, v15
	v_cvt_pk_bf16_f32 v4, v4, v5
	v_cvt_pk_bf16_f32 v5, v6, v7
	v_cvt_pk_bf16_f32 v0, v0, v1
	v_cvt_pk_bf16_f32 v1, v2, v3
	s_and_b64 vcc, exec, s[6:7]
	s_mov_b32 s0, s12
	global_store_dwordx2 v[134:135], v[124:125], off
	global_store_dwordx2 v[134:135], v[120:121], off offset:32
	global_store_dwordx2 v[104:105], v[112:113], off
	global_store_dwordx2 v[104:105], v[106:107], off offset:32
	global_store_dwordx2 v[88:89], v[96:97], off
	global_store_dwordx2 v[88:89], v[90:91], off offset:32
	global_store_dwordx2 v[72:73], v[80:81], off
	global_store_dwordx2 v[72:73], v[74:75], off offset:32
	global_store_dwordx2 v[72:73], v[68:69], off offset:256
	global_store_dwordx2 v[64:65], v[60:61], off
	global_store_dwordx2 v[64:65], v[56:57], off offset:32
	global_store_dwordx2 v[40:41], v[48:49], off
	global_store_dwordx2 v[40:41], v[42:43], off offset:32
	global_store_dwordx2 v[24:25], v[32:33], off
	global_store_dwordx2 v[24:25], v[26:27], off offset:32
	global_store_dwordx2 v[8:9], v[16:17], off
	global_store_dwordx2 v[8:9], v[10:11], off offset:32
	global_store_dwordx2 v[8:9], v[4:5], off offset:256
	global_store_dwordx2 v[8:9], v[0:1], off offset:288
	s_cbranch_vccz .LBB0_337
	s_waitcnt vmcnt(0)
	s_cmpk_gt_u32 s25, 0xff
	s_cbranch_scc1 .LBB0_348
	s_barrier

; #define PG8_STAGE(bufoff, gbase, voff) do { _Pragma("unroll") for (int _i = 0; _i < 2; ++_i) \
;         __builtin_amdgcn_global_load_lds((const unsigned*)((const char*)(gbase) + (voff)[_i]), (LAS unsigned*)(lds + (bufoff) + ldsw + _i * 8192), 16, 0, 0); } while (0)
; #define PG8_LDA(dst, b, h) do { _Pragma("unroll") for (int m = 0; m < 4; ++m) _Pragma("unroll") for (int k = 0; k < 2; ++k) dst[m][k] = *(const LAS bf16x8*)(lds + PG8_SA(b, h) + aoff + m * 2048 + k * 1024); } while (0)
; #define PG8_LDB(dst, b, h) do { _Pragma("unroll") for (int n = 0; n < 2; ++n) _Pragma("unroll") for (int k = 0; k < 2; ++k) dst[n][k] = *(const LAS bf16x8*)(lds + PG8_SB(b, h) + boff + n * 2048 + k * 1024); } while (0)
; #define PG8_MMA(ai, bj, At, Bt) do { __builtin_amdgcn_s_setprio(1); _Pragma("unroll") for (int m = 0; m < 4; ++m) _Pragma("unroll") for (int n = 0; n < 2; ++n) _Pragma("unroll") for (int k = 0; k < 2; ++k) \
;         acc[ai][bj][m][n] = __builtin_amdgcn_mfma_f32_16x16x32_bf16(Bt[n][k], At[m][k], acc[ai][bj][m][n], 0, 0, 0); __builtin_amdgcn_s_setprio(0); } while (0)
; #define PG8_WAIT_L(n) asm volatile("s_waitcnt lgkmcnt(" #n ")" ::: "memory")
; #define PG8_BAR __builtin_amdgcn_s_barrier()
; #define PG8_SCHED __builtin_amdgcn_sched_barrier(0)
; template <class Epi>
; DEV void gemm_phase(LAS unsigned char* lds, const Gemm g, const StaticOrder& S, const Epi& E) {
;     ...
;             PG8_LDB(B0, 0, 0); PG8_SCHED; PG8_LDA(At, 0, 0); PG8_STAGE(PG8_SA(1, 1), a1 + hstep, voffA);
;             PG8_WAIT_L(8); PG8_BAR; PG8_WAIT_L(0); PG8_MMA(0, 0, At, B0); PG8_BAR; PG8_SCHED;
;             PG8_LDB(B1, 0, 1); PG8_STAGE(PG8_SB(0, 0), b2, voffB);
;             PG8_BAR; PG8_WAIT_L(0); PG8_MMA(0, 1, At, B1); PG8_BAR;
;             PG8_LDA(At, 0, 1); PG8_STAGE(PG8_SA(0, 0), a2, voffA);
;             PG8_BAR; PG8_WAIT_L(0); PG8_MMA(1, 0, At, B0); PG8_BAR; PG8_SCHED;
.LBB0_362:
	s_add_u32 s26, s24, 0xfff80080
	s_addc_u32 s27, s25, -1
	s_add_i32 s56, 0, 0x10000
	v_add_u32_e32 v150, s56, v135
	ds_read_b128 v[138:141], v150
	ds_read_b128 v[142:145], v150 offset:1024
	ds_read_b128 v[146:149], v150 offset:2048
	ds_read_b128 v[150:153], v150 offset:3072
	s_cmp_eq_u32 s55, 28
	s_cselect_b32 s29, s19, s27
	s_cselect_b32 s28, s51, s26
	s_cselect_b32 s27, s17, s54
	s_cselect_b32 s26, s52, s53
	s_add_i32 m0, s13, 0xc000
	ds_read_b128 v[154:157], v137
	ds_read_b128 v[174:177], v137 offset:1024
	ds_read_b128 v[178:181], v137 offset:2048
	ds_read_b128 v[182:185], v137 offset:3072
	ds_read_b128 v[186:189], v137 offset:4096
	ds_read_b128 v[190:193], v137 offset:5120
	ds_read_b128 v[194:197], v137 offset:6144
	ds_read_b128 v[214:217], v137 offset:7168
	global_load_lds_dwordx4 v130, s[24:25]
	s_add_i32 m0, s13, 0xe000
	s_nop 0
	global_load_lds_dwordx4 v132, s[24:25]
	s_waitcnt lgkmcnt(8)
	s_barrier
	s_waitcnt lgkmcnt(7)
	v_mfma_f32_16x16x32_bf16 v[124:127], v[138:141], v[154:157], v[124:127]
	v_mfma_f32_16x16x32_bf16 v[120:123], v[146:149], v[154:157], v[120:123]
	s_waitcnt lgkmcnt(5)
	v_mfma_f32_16x16x32_bf16 v[116:119], v[138:141], v[178:181], v[116:119]
	v_mfma_f32_16x16x32_bf16 v[108:111], v[146:149], v[178:181], v[108:111]
	s_waitcnt lgkmcnt(3)
	v_mfma_f32_16x16x32_bf16 v[100:103], v[138:141], v[186:189], v[100:103]
	v_mfma_f32_16x16x32_bf16 v[92:95], v[146:149], v[186:189], v[92:95]
	s_waitcnt lgkmcnt(1)
	v_mfma_f32_16x16x32_bf16 v[84:87], v[138:141], v[194:197], v[84:87]
	v_mfma_f32_16x16x32_bf16 v[76:79], v[146:149], v[194:197], v[76:79]
	v_mfma_f32_16x16x32_bf16 v[124:127], v[142:145], v[174:177], v[124:127]
	v_mfma_f32_16x16x32_bf16 v[120:123], v[150:153], v[174:177], v[120:123]
	v_mfma_f32_16x16x32_bf16 v[116:119], v[142:145], v[182:185], v[116:119]
	v_mfma_f32_16x16x32_bf16 v[108:111], v[150:153], v[182:185], v[108:111]
	v_mfma_f32_16x16x32_bf16 v[100:103], v[142:145], v[190:193], v[100:103]
	v_mfma_f32_16x16x32_bf16 v[92:95], v[150:153], v[190:193], v[92:95]
	s_waitcnt lgkmcnt(0)
	v_mfma_f32_16x16x32_bf16 v[84:87], v[142:145], v[214:217], v[84:87]
	v_mfma_f32_16x16x32_bf16 v[76:79], v[150:153], v[214:217], v[76:79]
	s_barrier
	s_add_i32 s58, 0, 0x14000
	v_add_u32_e32 v158, s58, v135
	s_add_i32 s56, s56, s41
	ds_read_b128 v[218:221], v158
	ds_read_b128 v[222:225], v158 offset:1024
	ds_read_b128 v[226:229], v158 offset:2048
	ds_read_b128 v[230:233], v158 offset:3072
	v_lshl_add_u64 v[158:159], s[26:27], 0, v[160:161]
	s_mov_b32 m0, s56
	v_lshl_add_u64 v[234:235], s[26:27], 0, v[128:129]
	global_load_lds_dwordx4 v160, s[26:27]
	s_add_i32 m0, s56, 0x2000
	s_nop 0
	global_load_lds_dwordx4 v128, s[26:27]
	s_barrier
	s_waitcnt lgkmcnt(3)
	v_mfma_f32_16x16x32_bf16 v[112:115], v[218:221], v[154:157], v[112:115]
	s_waitcnt lgkmcnt(1)
	v_mfma_f32_16x16x32_bf16 v[104:107], v[226:229], v[154:157], v[104:107]
	v_mfma_f32_16x16x32_bf16 v[96:99], v[218:221], v[178:181], v[96:99]
	v_mfma_f32_16x16x32_bf16 v[88:91], v[226:229], v[178:181], v[88:91]
	v_mfma_f32_16x16x32_bf16 v[80:83], v[218:221], v[186:189], v[80:83]
	v_mfma_f32_16x16x32_bf16 v[72:75], v[226:229], v[186:189], v[72:75]
	v_mfma_f32_16x16x32_bf16 v[68:71], v[218:221], v[194:197], v[68:71]
	v_mfma_f32_16x16x32_bf16 v[64:67], v[226:229], v[194:197], v[64:67]
	v_mfma_f32_16x16x32_bf16 v[112:115], v[222:225], v[174:177], v[112:115]
	s_waitcnt lgkmcnt(0)
	v_mfma_f32_16x16x32_bf16 v[104:107], v[230:233], v[174:177], v[104:107]
	v_mfma_f32_16x16x32_bf16 v[96:99], v[222:225], v[182:185], v[96:99]
	v_mfma_f32_16x16x32_bf16 v[88:91], v[230:233], v[182:185], v[88:91]
	v_mfma_f32_16x16x32_bf16 v[80:83], v[222:225], v[190:193], v[80:83]
	v_mfma_f32_16x16x32_bf16 v[72:75], v[230:233], v[190:193], v[72:75]
	v_mfma_f32_16x16x32_bf16 v[68:71], v[222:225], v[214:217], v[68:71]
	v_mfma_f32_16x16x32_bf16 v[64:67], v[230:233], v[214:217], v[64:67]
	s_mov_b32 m0, s13
	v_lshl_add_u64 v[236:237], s[28:29], 0, v[160:161]
	s_barrier
	ds_read_b128 v[154:157], v137 offset:16384
	ds_read_b128 v[174:177], v137 offset:17408
	ds_read_b128 v[178:181], v137 offset:18432
	ds_read_b128 v[182:185], v137 offset:19456
	ds_read_b128 v[186:189], v137 offset:20480
	ds_read_b128 v[190:193], v137 offset:21504
	ds_read_b128 v[194:197], v137 offset:22528
	ds_read_b128 v[214:217], v137 offset:23552
	global_load_lds_dwordx4 v160, s[28:29]
	v_lshl_add_u64 v[238:239], s[28:29], 0, v[128:129]
	s_mov_b32 m0, s43
	s_nop 0
	global_load_lds_dwordx4 v128, s[28:29]
	s_barrier
	s_waitcnt lgkmcnt(7)
	v_mfma_f32_16x16x32_bf16 v[60:63], v[138:141], v[154:157], v[60:63]
	v_mfma_f32_16x16x32_bf16 v[56:59], v[146:149], v[154:157], v[56:59]
	s_waitcnt lgkmcnt(5)
	v_mfma_f32_16x16x32_bf16 v[52:55], v[138:141], v[178:181], v[52:55]
	v_mfma_f32_16x16x32_bf16 v[44:47], v[146:149], v[178:181], v[44:47]
	s_waitcnt lgkmcnt(3)
	v_mfma_f32_16x16x32_bf16 v[36:39], v[138:141], v[186:189], v[36:39]
	v_mfma_f32_16x16x32_bf16 v[28:31], v[146:149], v[186:189], v[28:31]
	s_waitcnt lgkmcnt(1)
	v_mfma_f32_16x16x32_bf16 v[20:23], v[138:141], v[194:197], v[20:23]
	v_mfma_f32_16x16x32_bf16 v[12:15], v[146:149], v[194:197], v[12:15]
	v_mfma_f32_16x16x32_bf16 v[60:63], v[142:145], v[174:177], v[60:63]
	v_mfma_f32_16x16x32_bf16 v[56:59], v[150:153], v[174:177], v[56:59]
	v_mfma_f32_16x16x32_bf16 v[52:55], v[142:145], v[182:185], v[52:55]
	v_mfma_f32_16x16x32_bf16 v[44:47], v[150:153], v[182:185], v[44:47]
	v_mfma_f32_16x16x32_bf16 v[36:39], v[142:145], v[190:193], v[36:39]
	v_mfma_f32_16x16x32_bf16 v[28:31], v[150:153], v[190:193], v[28:31]
	s_waitcnt lgkmcnt(0)
	v_mfma_f32_16x16x32_bf16 v[20:23], v[142:145], v[214:217], v[20:23]
	v_mfma_f32_16x16x32_bf16 v[12:15], v[150:153], v[214:217], v[12:15]
	s_barrier
; #define PG8_STAGE(bufoff, gbase, voff) do { _Pragma("unroll") for (int _i = 0; _i < 2; ++_i) \
;         __builtin_amdgcn_global_load_lds((const unsigned*)((const char*)(gbase) + (voff)[_i]), (LAS unsigned*)(lds + (bufoff) + ldsw + _i * 8192), 16, 0, 0); } while (0)
; #define PG8_LDA(dst, b, h) do { _Pragma("unroll") for (int m = 0; m < 4; ++m) _Pragma("unroll") for (int k = 0; k < 2; ++k) dst[m][k] = *(const LAS bf16x8*)(lds + PG8_SA(b, h) + aoff + m * 2048 + k * 1024); } while (0)
; #define PG8_LDB(dst, b, h) do { _Pragma("unroll") for (int n = 0; n < 2; ++n) _Pragma("unroll") for (int k = 0; k < 2; ++k) dst[n][k] = *(const LAS bf16x8*)(lds + PG8_SB(b, h) + boff + n * 2048 + k * 1024); } while (0)
; #define PG8_MMA(ai, bj, At, Bt) do { __builtin_amdgcn_s_setprio(1); _Pragma("unroll") for (int m = 0; m < 4; ++m) _Pragma("unroll") for (int n = 0; n < 2; ++n) _Pragma("unroll") for (int k = 0; k < 2; ++k) \
;         acc[ai][bj][m][n] = __builtin_amdgcn_mfma_f32_16x16x32_bf16(Bt[n][k], At[m][k], acc[ai][bj][m][n], 0, 0, 0); __builtin_amdgcn_s_setprio(0); } while (0)
; #define PG8_WAIT_V(n) asm volatile("s_waitcnt vmcnt(" #n ")" ::: "memory")
; #define PG8_WAIT_L(n) asm volatile("s_waitcnt lgkmcnt(" #n ")" ::: "memory")
; #define PG8_BAR __builtin_amdgcn_s_barrier()
; #define PG8_SCHED __builtin_amdgcn_sched_barrier(0)
; template <class Epi>
; DEV void gemm_phase(LAS unsigned char* lds, const Gemm g, const StaticOrder& S, const Epi& E) {
;     ...
;             PG8_STAGE(PG8_SB(0, 1), b2 + hstep, voffB);
;             PG8_WAIT_V(6); PG8_BAR; PG8_MMA(1, 1, At, B1); PG8_BAR;
;             PG8_LDB(B0, 1, 0); PG8_SCHED; PG8_LDA(At, 1, 0); PG8_STAGE(PG8_SA(0, 1), a2 + hstep, voffA);
;             PG8_WAIT_L(8); PG8_BAR; PG8_WAIT_L(0); PG8_MMA(0, 0, At, B0); PG8_BAR; PG8_SCHED;
;             PG8_LDB(B1, 1, 1); PG8_STAGE(PG8_SB(1, 0), b3, voffB);
;             PG8_BAR; PG8_WAIT_L(0); PG8_MMA(0, 1, At, B1); PG8_BAR;
;             PG8_LDA(At, 1, 1); PG8_STAGE(PG8_SA(1, 0), a3, voffA);
	s_add_u32 s56, s26, 0x80000
	s_addc_u32 s57, s27, 0
	s_add_i32 s58, s58, s41
	s_mov_b32 m0, s58
	s_nop 0
	global_load_lds_dwordx4 v160, s[56:57]
	s_add_i32 m0, s58, 0x2000
	s_nop 0
	global_load_lds_dwordx4 v128, s[56:57]
	s_waitcnt vmcnt(6)
	s_barrier
	v_mfma_f32_16x16x32_bf16 v[48:51], v[218:221], v[154:157], v[48:51]
	v_mfma_f32_16x16x32_bf16 v[40:43], v[226:229], v[154:157], v[40:43]
	v_mfma_f32_16x16x32_bf16 v[32:35], v[218:221], v[178:181], v[32:35]
	v_mfma_f32_16x16x32_bf16 v[24:27], v[226:229], v[178:181], v[24:27]
	v_mfma_f32_16x16x32_bf16 v[16:19], v[218:221], v[186:189], v[16:19]
	v_mfma_f32_16x16x32_bf16 v[8:11], v[226:229], v[186:189], v[8:11]
	v_mfma_f32_16x16x32_bf16 v[4:7], v[218:221], v[194:197], v[4:7]
	v_mfma_f32_16x16x32_bf16 v[0:3], v[226:229], v[194:197], v[0:3]
	v_mfma_f32_16x16x32_bf16 v[48:51], v[222:225], v[174:177], v[48:51]
	v_mfma_f32_16x16x32_bf16 v[40:43], v[230:233], v[174:177], v[40:43]
	v_mfma_f32_16x16x32_bf16 v[32:35], v[222:225], v[182:185], v[32:35]
	v_mfma_f32_16x16x32_bf16 v[24:27], v[230:233], v[182:185], v[24:27]
	v_mfma_f32_16x16x32_bf16 v[16:19], v[222:225], v[190:193], v[16:19]
	v_mfma_f32_16x16x32_bf16 v[8:11], v[230:233], v[190:193], v[8:11]
	v_mfma_f32_16x16x32_bf16 v[4:7], v[222:225], v[214:217], v[4:7]
	v_mfma_f32_16x16x32_bf16 v[0:3], v[230:233], v[214:217], v[0:3]
	s_add_i32 s56, 0, 0x18000
	v_add_u32_e32 v150, s56, v135
	s_barrier
	ds_read_b128 v[138:141], v150
	ds_read_b128 v[142:145], v150 offset:1024
	ds_read_b128 v[146:149], v150 offset:2048
	ds_read_b128 v[150:153], v150 offset:3072
	s_add_u32 s28, s28, 0x80000
	s_addc_u32 s29, s29, 0
	s_mov_b32 m0, s44
	ds_read_b128 v[154:157], v137 offset:32768
	ds_read_b128 v[174:177], v137 offset:33792
	ds_read_b128 v[178:181], v137 offset:34816
	ds_read_b128 v[182:185], v137 offset:35840
	ds_read_b128 v[186:189], v137 offset:36864
	ds_read_b128 v[190:193], v137 offset:37888
	ds_read_b128 v[194:197], v137 offset:38912
	ds_read_b128 v[214:217], v137 offset:39936
	global_load_lds_dwordx4 v160, s[28:29]
	s_mov_b32 m0, s45
	s_nop 0
	global_load_lds_dwordx4 v128, s[28:29]
	s_waitcnt lgkmcnt(8)
	s_barrier
	s_waitcnt lgkmcnt(7)
	v_mfma_f32_16x16x32_bf16 v[124:127], v[138:141], v[154:157], v[124:127]
	v_mfma_f32_16x16x32_bf16 v[120:123], v[146:149], v[154:157], v[120:123]
	s_waitcnt lgkmcnt(5)
	v_mfma_f32_16x16x32_bf16 v[116:119], v[138:141], v[178:181], v[116:119]
	v_mfma_f32_16x16x32_bf16 v[108:111], v[146:149], v[178:181], v[108:111]
	s_waitcnt lgkmcnt(3)
	v_mfma_f32_16x16x32_bf16 v[100:103], v[138:141], v[186:189], v[100:103]
	v_mfma_f32_16x16x32_bf16 v[92:95], v[146:149], v[186:189], v[92:95]
	s_waitcnt lgkmcnt(1)
	v_mfma_f32_16x16x32_bf16 v[84:87], v[138:141], v[194:197], v[84:87]
	v_mfma_f32_16x16x32_bf16 v[76:79], v[146:149], v[194:197], v[76:79]
	v_mfma_f32_16x16x32_bf16 v[124:127], v[142:145], v[174:177], v[124:127]
	v_mfma_f32_16x16x32_bf16 v[120:123], v[150:153], v[174:177], v[120:123]
	v_mfma_f32_16x16x32_bf16 v[116:119], v[142:145], v[182:185], v[116:119]
	v_mfma_f32_16x16x32_bf16 v[108:111], v[150:153], v[182:185], v[108:111]
	v_mfma_f32_16x16x32_bf16 v[100:103], v[142:145], v[190:193], v[100:103]
	v_mfma_f32_16x16x32_bf16 v[92:95], v[150:153], v[190:193], v[92:95]
	s_waitcnt lgkmcnt(0)
	v_mfma_f32_16x16x32_bf16 v[84:87], v[142:145], v[214:217], v[84:87]
	v_mfma_f32_16x16x32_bf16 v[76:79], v[150:153], v[214:217], v[76:79]
	s_barrier
	s_add_i32 s28, 0, 0x1c000
	s_add_i32 s29, s56, s41
	v_add_u32_e32 v167, s28, v135
	v_lshl_add_u64 v[158:159], v[158:159], 0, s[2:3]
	s_mov_b32 m0, s29
	ds_read_b128 v[218:221], v167
	ds_read_b128 v[222:225], v167 offset:1024
	ds_read_b128 v[226:229], v167 offset:2048
	ds_read_b128 v[230:233], v167 offset:3072
	global_load_lds_dwordx4 v[158:159], off
	v_lshl_add_u64 v[158:159], v[234:235], 0, s[2:3]
	s_add_i32 m0, s29, 0x2000
	s_nop 0
	global_load_lds_dwordx4 v[158:159], off
	s_barrier
	s_waitcnt lgkmcnt(3)
	v_mfma_f32_16x16x32_bf16 v[112:115], v[218:221], v[154:157], v[112:115]
	s_waitcnt lgkmcnt(1)
	v_mfma_f32_16x16x32_bf16 v[104:107], v[226:229], v[154:157], v[104:107]
	v_mfma_f32_16x16x32_bf16 v[96:99], v[218:221], v[178:181], v[96:99]
	v_mfma_f32_16x16x32_bf16 v[88:91], v[226:229], v[178:181], v[88:91]
	v_mfma_f32_16x16x32_bf16 v[80:83], v[218:221], v[186:189], v[80:83]
	v_mfma_f32_16x16x32_bf16 v[72:75], v[226:229], v[186:189], v[72:75]
	v_mfma_f32_16x16x32_bf16 v[68:71], v[218:221], v[194:197], v[68:71]
	v_mfma_f32_16x16x32_bf16 v[64:67], v[226:229], v[194:197], v[64:67]
	v_mfma_f32_16x16x32_bf16 v[112:115], v[222:225], v[174:177], v[112:115]
	s_waitcnt lgkmcnt(0)
	v_mfma_f32_16x16x32_bf16 v[104:107], v[230:233], v[174:177], v[104:107]
	v_mfma_f32_16x16x32_bf16 v[96:99], v[222:225], v[182:185], v[96:99]
	v_mfma_f32_16x16x32_bf16 v[88:91], v[230:233], v[182:185], v[88:91]
	v_mfma_f32_16x16x32_bf16 v[80:83], v[222:225], v[190:193], v[80:83]
	v_mfma_f32_16x16x32_bf16 v[72:75], v[230:233], v[190:193], v[72:75]
	v_mfma_f32_16x16x32_bf16 v[68:71], v[222:225], v[214:217], v[68:71]
	v_mfma_f32_16x16x32_bf16 v[64:67], v[230:233], v[214:217], v[64:67]
	s_mov_b32 m0, s46
	v_lshl_add_u64 v[158:159], v[236:237], 0, s[2:3]
	s_barrier
	ds_read_b128 v[154:157], v137 offset:49152
	ds_read_b128 v[174:177], v137 offset:50176
	ds_read_b128 v[178:181], v137 offset:51200
	ds_read_b128 v[182:185], v137 offset:52224
	ds_read_b128 v[186:189], v137 offset:53248
	ds_read_b128 v[190:193], v137 offset:54272
	ds_read_b128 v[194:197], v137 offset:55296
	ds_read_b128 v[214:217], v137 offset:56320
	global_load_lds_dwordx4 v[158:159], off
	v_lshl_add_u64 v[158:159], v[238:239], 0, s[2:3]
	s_mov_b32 m0, s47
	s_nop 0
	global_load_lds_dwordx4 v[158:159], off
	s_barrier
; #define PG8_STAGE(bufoff, gbase, voff) do { _Pragma("unroll") for (int _i = 0; _i < 2; ++_i) \
;         __builtin_amdgcn_global_load_lds((const unsigned*)((const char*)(gbase) + (voff)[_i]), (LAS unsigned*)(lds + (bufoff) + ldsw + _i * 8192), 16, 0, 0); } while (0)
; #define PG8_LDA(dst, b, h) do { _Pragma("unroll") for (int m = 0; m < 4; ++m) _Pragma("unroll") for (int k = 0; k < 2; ++k) dst[m][k] = *(const LAS bf16x8*)(lds + PG8_SA(b, h) + aoff + m * 2048 + k * 1024); } while (0)
; #define PG8_MMA(ai, bj, At, Bt) do { __builtin_amdgcn_s_setprio(1); _Pragma("unroll") for (int m = 0; m < 4; ++m) _Pragma("unroll") for (int n = 0; n < 2; ++n) _Pragma("unroll") for (int k = 0; k < 2; ++k) \
;         acc[ai][bj][m][n] = __builtin_amdgcn_mfma_f32_16x16x32_bf16(Bt[n][k], At[m][k], acc[ai][bj][m][n], 0, 0, 0); __builtin_amdgcn_s_setprio(0); } while (0)
; #define PG8_WAIT_V(n) asm volatile("s_waitcnt vmcnt(" #n ")" ::: "memory")
; #define PG8_WAIT_L(n) asm volatile("s_waitcnt lgkmcnt(" #n ")" ::: "memory")
; #define PG8_BAR __builtin_amdgcn_s_barrier()
; #define PG8_SCHED __builtin_amdgcn_sched_barrier(0)
; template <class Epi>
; DEV void gemm_phase(LAS unsigned char* lds, const Gemm g, const StaticOrder& S, const Epi& E) {
;     ...
;             PG8_LDA(At, 1, 1); PG8_STAGE(PG8_SA(1, 0), a3, voffA);
;             PG8_BAR; PG8_WAIT_L(0); PG8_MMA(1, 0, At, B0); PG8_BAR; PG8_SCHED;
;             PG8_STAGE(PG8_SB(1, 1), b3 + hstep, voffB);
;             PG8_WAIT_V(6); PG8_BAR; PG8_MMA(1, 1, At, B1); PG8_BAR;
;         }
	s_waitcnt lgkmcnt(7)
	v_mfma_f32_16x16x32_bf16 v[60:63], v[138:141], v[154:157], v[60:63]
	v_mfma_f32_16x16x32_bf16 v[56:59], v[146:149], v[154:157], v[56:59]
	s_waitcnt lgkmcnt(5)
	v_mfma_f32_16x16x32_bf16 v[52:55], v[138:141], v[178:181], v[52:55]
	v_mfma_f32_16x16x32_bf16 v[44:47], v[146:149], v[178:181], v[44:47]
	s_waitcnt lgkmcnt(3)
	v_mfma_f32_16x16x32_bf16 v[36:39], v[138:141], v[186:189], v[36:39]
	v_mfma_f32_16x16x32_bf16 v[28:31], v[146:149], v[186:189], v[28:31]
	s_waitcnt lgkmcnt(1)
	v_mfma_f32_16x16x32_bf16 v[20:23], v[138:141], v[194:197], v[20:23]
	v_mfma_f32_16x16x32_bf16 v[12:15], v[146:149], v[194:197], v[12:15]
	v_mfma_f32_16x16x32_bf16 v[60:63], v[142:145], v[174:177], v[60:63]
	v_mfma_f32_16x16x32_bf16 v[56:59], v[150:153], v[174:177], v[56:59]
	v_mfma_f32_16x16x32_bf16 v[52:55], v[142:145], v[182:185], v[52:55]
	v_mfma_f32_16x16x32_bf16 v[44:47], v[150:153], v[182:185], v[44:47]
	v_mfma_f32_16x16x32_bf16 v[36:39], v[142:145], v[190:193], v[36:39]
	v_mfma_f32_16x16x32_bf16 v[28:31], v[150:153], v[190:193], v[28:31]
	s_waitcnt lgkmcnt(0)
	v_mfma_f32_16x16x32_bf16 v[20:23], v[142:145], v[214:217], v[20:23]
	v_mfma_f32_16x16x32_bf16 v[12:15], v[150:153], v[214:217], v[12:15]
	s_barrier
	s_add_u32 s26, s26, 0x80080
	s_addc_u32 s27, s27, 0
	s_add_i32 s28, s28, s41
	s_mov_b32 m0, s28
	s_nop 0
	global_load_lds_dwordx4 v160, s[26:27]
	s_add_i32 m0, s28, 0x2000
	s_nop 0
	global_load_lds_dwordx4 v128, s[26:27]
	s_waitcnt vmcnt(6)
	s_barrier
	v_mfma_f32_16x16x32_bf16 v[48:51], v[218:221], v[154:157], v[48:51]
	v_mfma_f32_16x16x32_bf16 v[40:43], v[226:229], v[154:157], v[40:43]
	v_mfma_f32_16x16x32_bf16 v[32:35], v[218:221], v[178:181], v[32:35]
	v_mfma_f32_16x16x32_bf16 v[24:27], v[226:229], v[178:181], v[24:27]
	v_mfma_f32_16x16x32_bf16 v[16:19], v[218:221], v[186:189], v[16:19]
	v_mfma_f32_16x16x32_bf16 v[8:11], v[226:229], v[186:189], v[8:11]
	v_mfma_f32_16x16x32_bf16 v[4:7], v[218:221], v[194:197], v[4:7]
	v_mfma_f32_16x16x32_bf16 v[0:3], v[226:229], v[194:197], v[0:3]
	v_mfma_f32_16x16x32_bf16 v[48:51], v[222:225], v[174:177], v[48:51]
	v_mfma_f32_16x16x32_bf16 v[40:43], v[230:233], v[174:177], v[40:43]
	v_mfma_f32_16x16x32_bf16 v[32:35], v[222:225], v[182:185], v[32:35]
	v_mfma_f32_16x16x32_bf16 v[24:27], v[230:233], v[182:185], v[24:27]
	v_mfma_f32_16x16x32_bf16 v[16:19], v[222:225], v[190:193], v[16:19]
	v_mfma_f32_16x16x32_bf16 v[8:11], v[230:233], v[190:193], v[8:11]
	v_mfma_f32_16x16x32_bf16 v[4:7], v[222:225], v[214:217], v[4:7]
	v_mfma_f32_16x16x32_bf16 v[0:3], v[230:233], v[214:217], v[0:3]
	s_add_i32 s55, s55, 2
	s_add_u32 s24, s24, 0x100
	s_addc_u32 s25, s25, 0
	s_add_u32 s53, s53, 0x100
	s_addc_u32 s54, s54, 0
	s_cmp_gt_u32 s55, 29
	s_barrier
	s_cbranch_scc0 .LBB0_362
; DEV bf16x8 pack8(f32x4 a, f32x4 b) { u32x4 w; w.x = cvt_pk_bf16(a[0], a[1]); w.y = cvt_pk_bf16(a[2], a[3]); w.z = cvt_pk_bf16(b[0], b[1]); w.w = cvt_pk_bf16(b[2], b[3]); return __builtin_bit_cast(bf16x8, w); }
; DEV u32x2 pack4(f32x4 a) { u32x2 w; w.x = cvt_pk_bf16(a[0], a[1]); w.y = cvt_pk_bf16(a[2], a[3]); return w; }
; DEV f32x4 gelu4(f32x4 v) { f32x2 a = gelu_pk((f32x2){v[0], v[1]}), b = gelu_pk((f32x2){v[2], v[3]}); return (f32x4){a.x, a.y, b.x, b.y}; }
; template <int ACT, bool PERM>
; DEV void store_bf16_tile(AccRef acc, u16* O, int ld, int row0, int col0, const float* ss) {
;     ...
;     for (int ai = 0; ai < 2; ++ai)
; #pragma unroll
;         for (int m = 0; m < 4; ++m) { u16* rowp = O + (size_t)(row0 + ai * 128 + m * 16) * ld + col0; const float rs = rsv[ai][m];
; #pragma unroll
;             for (int bj = 0; bj < 2; ++bj) { f32x4 v0 = acc[ai][bj][m][0] * rs, v1 = acc[ai][bj][m][1] * rs; if (ACT == 1) { v0 = gelu4(v0); v1 = gelu4(v1); }
;                 if (PERM) *(u32x4*)(rowp + bj * 128) = __builtin_bit_cast(u32x4, pack8(v0, v1));
;                 else { *(u32x2*)(rowp + bj * 128) = pack4(v0); *(u32x2*)(rowp + bj * 128 + 16) = pack4(v1); } } }
; DEV void run_phase(const P& p, int ph, LAS unsigned char* lds) {
;     ...
;             for (int l = 0; l < 2; ++l) { EpiBf16 E{(u16*)(ws + O_KVX) + (size_t)l * 256 * 1024, 1024, nullptr};
;                 const int first = (64 + 4 * l) % G;
;                 run_gemm(lds, (const u16*)(ws + O_MEMN) + (size_t)l * 256 * 2048, (const u16*)(ws + O_WXKV) + (size_t)l * 1024 * 2048, 256, 1024, 2048, E, (bx + G - first) % G); }
	v_lshl_add_u32 v138, s12, 8, v134
	v_lshl_or_b32 v140, s50, 8, v136
	v_ashrrev_i32_e32 v141, 31, v140
	v_ashrrev_i32_e32 v139, 31, v138
	v_lshl_add_u64 v[140:141], v[140:141], 1, s[10:11]
	v_lshlrev_b64 v[142:143], 11, v[138:139]
	v_lshl_add_u64 v[142:143], v[140:141], 0, v[142:143]
	v_cvt_pk_bf16_f32 v104, v104, v105
	v_cvt_pk_bf16_f32 v105, v106, v107
	global_store_dwordx2 v[142:143], v[104:105], off offset:288
	v_or_b32_e32 v104, 16, v138
	v_ashrrev_i32_e32 v105, 31, v104
	v_lshlrev_b64 v[104:105], 11, v[104:105]
	v_lshl_add_u64 v[104:105], v[140:141], 0, v[104:105]
	v_cvt_pk_bf16_f32 v88, v88, v89
	v_cvt_pk_bf16_f32 v89, v90, v91
	global_store_dwordx2 v[104:105], v[88:89], off offset:288
	v_or_b32_e32 v88, 32, v138
	v_ashrrev_i32_e32 v89, 31, v88
	v_lshlrev_b64 v[88:89], 11, v[88:89]
	v_lshl_add_u64 v[88:89], v[140:141], 0, v[88:89]
	v_cvt_pk_bf16_f32 v72, v72, v73
	v_cvt_pk_bf16_f32 v73, v74, v75
	global_store_dwordx2 v[88:89], v[72:73], off offset:288
	v_or_b32_e32 v72, 48, v138
	v_ashrrev_i32_e32 v73, 31, v72
	v_lshlrev_b64 v[72:73], 11, v[72:73]
	s_mov_b32 s12, 0x40000
	v_lshl_add_u64 v[72:73], v[140:141], 0, v[72:73]
	v_cvt_pk_bf16_f32 v64, v64, v65
	v_cvt_pk_bf16_f32 v65, v66, v67
	s_mov_b64 s[24:25], 0x40000
	v_cvt_pk_bf16_f32 v60, v60, v61
	v_cvt_pk_bf16_f32 v61, v62, v63
	v_add_co_u32_e32 v62, vcc, s12, v142
	global_store_dwordx2 v[72:73], v[64:65], off offset:288
	v_lshl_add_u64 v[64:65], v[142:143], 0, s[24:25]
	v_addc_co_u32_e32 v63, vcc, 0, v143, vcc
	v_cvt_pk_bf16_f32 v48, v48, v49
	v_cvt_pk_bf16_f32 v49, v50, v51
	s_mov_b32 s12, 0x48000
	global_store_dwordx2 v[64:65], v[48:49], off offset:256
	v_cvt_pk_bf16_f32 v40, v40, v41
	v_cvt_pk_bf16_f32 v41, v42, v43
	s_mov_b64 s[24:25], 0x48000
	v_add_co_u32_e32 v48, vcc, s12, v142
	global_store_dwordx2 v[64:65], v[40:41], off offset:288
	v_lshl_add_u64 v[40:41], v[142:143], 0, s[24:25]
	v_addc_co_u32_e32 v49, vcc, 0, v143, vcc
	v_cvt_pk_bf16_f32 v32, v32, v33
	v_cvt_pk_bf16_f32 v33, v34, v35
	s_mov_b32 s12, 0x50000
	global_store_dwordx2 v[40:41], v[32:33], off offset:256
	v_cvt_pk_bf16_f32 v24, v24, v25
	v_cvt_pk_bf16_f32 v25, v26, v27
	s_mov_b64 s[24:25], 0x50000
	v_add_co_u32_e32 v32, vcc, s12, v142
	global_store_dwordx2 v[40:41], v[24:25], off offset:288
	v_lshl_add_u64 v[24:25], v[142:143], 0, s[24:25]
	v_addc_co_u32_e32 v33, vcc, 0, v143, vcc
	v_cvt_pk_bf16_f32 v16, v16, v17
	v_cvt_pk_bf16_f32 v17, v18, v19
	global_store_dwordx2 v[24:25], v[16:17], off offset:256
	v_add_co_u32_e32 v16, vcc, s59, v142
	v_cvt_pk_bf16_f32 v106, v116, v117
	v_cvt_pk_bf16_f32 v107, v118, v119
	v_cvt_pk_bf16_f32 v90, v100, v101
	v_cvt_pk_bf16_f32 v91, v102, v103
	v_cvt_pk_bf16_f32 v74, v84, v85
	v_cvt_pk_bf16_f32 v75, v86, v87
	v_cvt_pk_bf16_f32 v42, v52, v53
	v_cvt_pk_bf16_f32 v43, v54, v55
	v_cvt_pk_bf16_f32 v26, v36, v37
	v_cvt_pk_bf16_f32 v27, v38, v39
	v_cvt_pk_bf16_f32 v8, v8, v9
	v_cvt_pk_bf16_f32 v9, v10, v11
	s_mov_b64 s[24:25], 0x58000
	v_cvt_pk_bf16_f32 v10, v20, v21
	v_cvt_pk_bf16_f32 v11, v22, v23
	v_addc_co_u32_e32 v17, vcc, 0, v143, vcc
	v_cvt_pk_bf16_f32 v124, v124, v125
	v_cvt_pk_bf16_f32 v125, v126, v127
	v_cvt_pk_bf16_f32 v120, v120, v121
	v_cvt_pk_bf16_f32 v121, v122, v123
	v_cvt_pk_bf16_f32 v112, v112, v113
	v_cvt_pk_bf16_f32 v113, v114, v115
	global_store_dwordx2 v[104:105], v[106:107], off
	v_cvt_pk_bf16_f32 v106, v108, v109
	v_cvt_pk_bf16_f32 v107, v110, v111
	v_cvt_pk_bf16_f32 v96, v96, v97
	v_cvt_pk_bf16_f32 v97, v98, v99
	global_store_dwordx2 v[88:89], v[90:91], off
	v_cvt_pk_bf16_f32 v90, v92, v93
	v_cvt_pk_bf16_f32 v91, v94, v95
	v_cvt_pk_bf16_f32 v80, v80, v81
	v_cvt_pk_bf16_f32 v81, v82, v83
	global_store_dwordx2 v[72:73], v[74:75], off
	v_cvt_pk_bf16_f32 v74, v76, v77
	v_cvt_pk_bf16_f32 v75, v78, v79
	v_cvt_pk_bf16_f32 v68, v68, v69
	v_cvt_pk_bf16_f32 v69, v70, v71
	v_cvt_pk_bf16_f32 v56, v56, v57
	v_cvt_pk_bf16_f32 v57, v58, v59
	global_store_dwordx2 v[48:49], v[42:43], off
	v_cvt_pk_bf16_f32 v42, v44, v45
	v_cvt_pk_bf16_f32 v43, v46, v47
	global_store_dwordx2 v[32:33], v[26:27], off
	v_cvt_pk_bf16_f32 v26, v28, v29
	v_cvt_pk_bf16_f32 v27, v30, v31
	global_store_dwordx2 v[24:25], v[8:9], off offset:288
	v_lshl_add_u64 v[8:9], v[142:143], 0, s[24:25]
	global_store_dwordx2 v[16:17], v[10:11], off
	v_cvt_pk_bf16_f32 v10, v12, v13
	v_cvt_pk_bf16_f32 v11, v14, v15
	v_cvt_pk_bf16_f32 v4, v4, v5
	v_cvt_pk_bf16_f32 v5, v6, v7
	v_cvt_pk_bf16_f32 v0, v0, v1
	v_cvt_pk_bf16_f32 v1, v2, v3
	s_and_b64 vcc, exec, s[14:15]
	s_mov_b32 s50, s16
	s_mov_b32 s12, s18
	s_mov_b64 s[26:27], s[22:23]
	s_mov_b64 s[24:25], s[20:21]
	global_store_dwordx2 v[142:143], v[124:125], off
	global_store_dwordx2 v[142:143], v[120:121], off offset:32
	global_store_dwordx2 v[142:143], v[112:113], off offset:256
	global_store_dwordx2 v[104:105], v[106:107], off offset:32
	global_store_dwordx2 v[104:105], v[96:97], off offset:256
	global_store_dwordx2 v[88:89], v[90:91], off offset:32
	global_store_dwordx2 v[88:89], v[80:81], off offset:256
	global_store_dwordx2 v[72:73], v[74:75], off offset:32
	global_store_dwordx2 v[72:73], v[68:69], off offset:256
	global_store_dwordx2 v[62:63], v[60:61], off
	global_store_dwordx2 v[64:65], v[56:57], off offset:32
	global_store_dwordx2 v[40:41], v[42:43], off offset:32
	global_store_dwordx2 v[24:25], v[26:27], off offset:32
	global_store_dwordx2 v[8:9], v[10:11], off offset:32
	global_store_dwordx2 v[8:9], v[4:5], off offset:256
	global_store_dwordx2 v[8:9], v[0:1], off offset:288
	s_cbranch_vccz .LBB0_359
	s_waitcnt vmcnt(0)
	s_cmpk_gt_u32 s36, 0xff
	s_cbranch_scc1 .LBB0_353
	s_barrier
	s_branch .LBB0_353

; #define PG8_STAGE(bufoff, gbase, voff) do { _Pragma("unroll") for (int _i = 0; _i < 2; ++_i) \
;         __builtin_amdgcn_global_load_lds((const unsigned*)((const char*)(gbase) + (voff)[_i]), (LAS unsigned*)(lds + (bufoff) + ldsw + _i * 8192), 16, 0, 0); } while (0)
; #define PG8_LDA(dst, b, h) do { _Pragma("unroll") for (int m = 0; m < 4; ++m) _Pragma("unroll") for (int k = 0; k < 2; ++k) dst[m][k] = *(const LAS bf16x8*)(lds + PG8_SA(b, h) + aoff + m * 2048 + k * 1024); } while (0)
; #define PG8_LDB(dst, b, h) do { _Pragma("unroll") for (int n = 0; n < 2; ++n) _Pragma("unroll") for (int k = 0; k < 2; ++k) dst[n][k] = *(const LAS bf16x8*)(lds + PG8_SB(b, h) + boff + n * 2048 + k * 1024); } while (0)
; #define PG8_MMA(ai, bj, At, Bt) do { __builtin_amdgcn_s_setprio(1); _Pragma("unroll") for (int m = 0; m < 4; ++m) _Pragma("unroll") for (int n = 0; n < 2; ++n) _Pragma("unroll") for (int k = 0; k < 2; ++k) \
;         acc[ai][bj][m][n] = __builtin_amdgcn_mfma_f32_16x16x32_bf16(Bt[n][k], At[m][k], acc[ai][bj][m][n], 0, 0, 0); __builtin_amdgcn_s_setprio(0); } while (0)
; #define PG8_WAIT_L(n) asm volatile("s_waitcnt lgkmcnt(" #n ")" ::: "memory")
; #define PG8_BAR __builtin_amdgcn_s_barrier()
; #define PG8_SCHED __builtin_amdgcn_sched_barrier(0)
; template <class Epi>
; DEV void gemm_phase(LAS unsigned char* lds, const Gemm g, const StaticOrder& S, const Epi& E) {
;     ...
;             PG8_LDB(B0, 0, 0); PG8_SCHED; PG8_LDA(At, 0, 0); PG8_STAGE(PG8_SA(1, 1), a1 + hstep, voffA);
;             PG8_WAIT_L(8); PG8_BAR; PG8_WAIT_L(0); PG8_MMA(0, 0, At, B0); PG8_BAR; PG8_SCHED;
;             PG8_LDB(B1, 0, 1); PG8_STAGE(PG8_SB(0, 0), b2, voffB);
;             PG8_BAR; PG8_WAIT_L(0); PG8_MMA(0, 1, At, B1); PG8_BAR;
;             PG8_LDA(At, 0, 1); PG8_STAGE(PG8_SA(0, 0), a2, voffA);
;             PG8_BAR; PG8_WAIT_L(0); PG8_MMA(1, 0, At, B0); PG8_BAR; PG8_SCHED;
.LBB0_404:
	s_add_u32 s28, s26, 0xfff00080
	s_addc_u32 s29, s27, -1
	s_add_i32 s49, 0, 0x10000
	v_add_u32_e32 v140, s49, v178
	ds_read_b128 v[128:131], v140
	ds_read_b128 v[132:135], v140 offset:1024
	ds_read_b128 v[136:139], v140 offset:2048
	ds_read_b128 v[140:143], v140 offset:3072
	s_cmp_eq_u32 s48, 60
	s_cselect_b32 s31, s15, s29
	s_cselect_b32 s30, s19, s28
	s_cselect_b32 s29, s17, s47
	s_cselect_b32 s28, s25, s46
	s_add_i32 m0, s37, 0xc000
	ds_read_b128 v[154:157], v181
	ds_read_b128 v[174:177], v181 offset:1024
	ds_read_b128 v[182:185], v181 offset:2048
	ds_read_b128 v[186:189], v181 offset:3072
	ds_read_b128 v[190:193], v181 offset:4096
	ds_read_b128 v[194:197], v181 offset:5120
	ds_read_b128 v[214:217], v181 offset:6144
	ds_read_b128 v[218:221], v181 offset:7168
	global_load_lds_dwordx4 v150, s[26:27]
	s_add_i32 m0, s37, 0xe000
	s_nop 0
	global_load_lds_dwordx4 v152, s[26:27]
	s_waitcnt lgkmcnt(8)
	s_barrier
	s_waitcnt lgkmcnt(7)
	v_mfma_f32_16x16x32_bf16 v[124:127], v[128:131], v[154:157], v[124:127]
	v_mfma_f32_16x16x32_bf16 v[120:123], v[136:139], v[154:157], v[120:123]
	s_waitcnt lgkmcnt(5)
	v_mfma_f32_16x16x32_bf16 v[108:111], v[128:131], v[182:185], v[108:111]
	v_mfma_f32_16x16x32_bf16 v[104:107], v[136:139], v[182:185], v[104:107]
	s_waitcnt lgkmcnt(3)
	v_mfma_f32_16x16x32_bf16 v[92:95], v[128:131], v[190:193], v[92:95]
	v_mfma_f32_16x16x32_bf16 v[88:91], v[136:139], v[190:193], v[88:91]
	s_waitcnt lgkmcnt(1)
	v_mfma_f32_16x16x32_bf16 v[76:79], v[128:131], v[214:217], v[76:79]
	v_mfma_f32_16x16x32_bf16 v[72:75], v[136:139], v[214:217], v[72:75]
	v_mfma_f32_16x16x32_bf16 v[124:127], v[132:135], v[174:177], v[124:127]
	v_mfma_f32_16x16x32_bf16 v[120:123], v[140:143], v[174:177], v[120:123]
	v_mfma_f32_16x16x32_bf16 v[108:111], v[132:135], v[186:189], v[108:111]
	v_mfma_f32_16x16x32_bf16 v[104:107], v[140:143], v[186:189], v[104:107]
	v_mfma_f32_16x16x32_bf16 v[92:95], v[132:135], v[194:197], v[92:95]
	v_mfma_f32_16x16x32_bf16 v[88:91], v[140:143], v[194:197], v[88:91]
	s_waitcnt lgkmcnt(0)
	v_mfma_f32_16x16x32_bf16 v[76:79], v[132:135], v[218:221], v[76:79]
	v_mfma_f32_16x16x32_bf16 v[72:75], v[140:143], v[218:221], v[72:75]
	s_barrier
	s_add_i32 s52, 0, 0x14000
	v_add_u32_e32 v158, s52, v178
	s_add_i32 s49, s49, s36
	ds_read_b128 v[222:225], v158
	ds_read_b128 v[226:229], v158 offset:1024
	ds_read_b128 v[230:233], v158 offset:2048
	ds_read_b128 v[234:237], v158 offset:3072
	v_lshl_add_u64 v[158:159], s[28:29], 0, v[160:161]
	s_mov_b32 m0, s49
	v_lshl_add_u64 v[238:239], s[28:29], 0, v[148:149]
	global_load_lds_dwordx4 v160, s[28:29]
	s_add_i32 m0, s49, 0x2000
	s_nop 0
	global_load_lds_dwordx4 v148, s[28:29]
	s_barrier
	s_waitcnt lgkmcnt(3)
	v_mfma_f32_16x16x32_bf16 v[116:119], v[222:225], v[154:157], v[116:119]
	s_waitcnt lgkmcnt(1)
	v_mfma_f32_16x16x32_bf16 v[112:115], v[230:233], v[154:157], v[112:115]
	v_mfma_f32_16x16x32_bf16 v[100:103], v[222:225], v[182:185], v[100:103]
	v_mfma_f32_16x16x32_bf16 v[96:99], v[230:233], v[182:185], v[96:99]
	v_mfma_f32_16x16x32_bf16 v[84:87], v[222:225], v[190:193], v[84:87]
	v_mfma_f32_16x16x32_bf16 v[80:83], v[230:233], v[190:193], v[80:83]
	v_mfma_f32_16x16x32_bf16 v[68:71], v[222:225], v[214:217], v[68:71]
	v_mfma_f32_16x16x32_bf16 v[64:67], v[230:233], v[214:217], v[64:67]
	v_mfma_f32_16x16x32_bf16 v[116:119], v[226:229], v[174:177], v[116:119]
	s_waitcnt lgkmcnt(0)
	v_mfma_f32_16x16x32_bf16 v[112:115], v[234:237], v[174:177], v[112:115]
	v_mfma_f32_16x16x32_bf16 v[100:103], v[226:229], v[186:189], v[100:103]
	v_mfma_f32_16x16x32_bf16 v[96:99], v[234:237], v[186:189], v[96:99]
	v_mfma_f32_16x16x32_bf16 v[84:87], v[226:229], v[194:197], v[84:87]
	v_mfma_f32_16x16x32_bf16 v[80:83], v[234:237], v[194:197], v[80:83]
	v_mfma_f32_16x16x32_bf16 v[68:71], v[226:229], v[218:221], v[68:71]
	v_mfma_f32_16x16x32_bf16 v[64:67], v[234:237], v[218:221], v[64:67]
	s_mov_b32 m0, s37
	v_lshl_add_u64 v[240:241], s[30:31], 0, v[144:145]
	s_barrier
	ds_read_b128 v[154:157], v181 offset:16384
	ds_read_b128 v[174:177], v181 offset:17408
	ds_read_b128 v[182:185], v181 offset:18432
	ds_read_b128 v[186:189], v181 offset:19456
	ds_read_b128 v[190:193], v181 offset:20480
	ds_read_b128 v[194:197], v181 offset:21504
	ds_read_b128 v[214:217], v181 offset:22528
	ds_read_b128 v[218:221], v181 offset:23552
	global_load_lds_dwordx4 v144, s[30:31]
	v_lshl_add_u64 v[242:243], s[30:31], 0, v[146:147]
	s_mov_b32 m0, s38
	s_nop 0
	global_load_lds_dwordx4 v146, s[30:31]
	s_barrier
	s_waitcnt lgkmcnt(7)
	v_mfma_f32_16x16x32_bf16 v[60:63], v[128:131], v[154:157], v[60:63]
	v_mfma_f32_16x16x32_bf16 v[56:59], v[136:139], v[154:157], v[56:59]
	s_waitcnt lgkmcnt(5)
	v_mfma_f32_16x16x32_bf16 v[44:47], v[128:131], v[182:185], v[44:47]
	v_mfma_f32_16x16x32_bf16 v[40:43], v[136:139], v[182:185], v[40:43]
	s_waitcnt lgkmcnt(3)
	v_mfma_f32_16x16x32_bf16 v[28:31], v[128:131], v[190:193], v[28:31]
	v_mfma_f32_16x16x32_bf16 v[24:27], v[136:139], v[190:193], v[24:27]
	s_waitcnt lgkmcnt(1)
	v_mfma_f32_16x16x32_bf16 v[12:15], v[128:131], v[214:217], v[12:15]
	v_mfma_f32_16x16x32_bf16 v[8:11], v[136:139], v[214:217], v[8:11]
	v_mfma_f32_16x16x32_bf16 v[60:63], v[132:135], v[174:177], v[60:63]
	v_mfma_f32_16x16x32_bf16 v[56:59], v[140:143], v[174:177], v[56:59]
	v_mfma_f32_16x16x32_bf16 v[44:47], v[132:135], v[186:189], v[44:47]
	v_mfma_f32_16x16x32_bf16 v[40:43], v[140:143], v[186:189], v[40:43]
	v_mfma_f32_16x16x32_bf16 v[28:31], v[132:135], v[194:197], v[28:31]
	v_mfma_f32_16x16x32_bf16 v[24:27], v[140:143], v[194:197], v[24:27]
	s_waitcnt lgkmcnt(0)
	v_mfma_f32_16x16x32_bf16 v[12:15], v[132:135], v[218:221], v[12:15]
	v_mfma_f32_16x16x32_bf16 v[8:11], v[140:143], v[218:221], v[8:11]
	s_barrier
; #define PG8_STAGE(bufoff, gbase, voff) do { _Pragma("unroll") for (int _i = 0; _i < 2; ++_i) \
;         __builtin_amdgcn_global_load_lds((const unsigned*)((const char*)(gbase) + (voff)[_i]), (LAS unsigned*)(lds + (bufoff) + ldsw + _i * 8192), 16, 0, 0); } while (0)
; #define PG8_LDA(dst, b, h) do { _Pragma("unroll") for (int m = 0; m < 4; ++m) _Pragma("unroll") for (int k = 0; k < 2; ++k) dst[m][k] = *(const LAS bf16x8*)(lds + PG8_SA(b, h) + aoff + m * 2048 + k * 1024); } while (0)
; #define PG8_LDB(dst, b, h) do { _Pragma("unroll") for (int n = 0; n < 2; ++n) _Pragma("unroll") for (int k = 0; k < 2; ++k) dst[n][k] = *(const LAS bf16x8*)(lds + PG8_SB(b, h) + boff + n * 2048 + k * 1024); } while (0)
; #define PG8_MMA(ai, bj, At, Bt) do { __builtin_amdgcn_s_setprio(1); _Pragma("unroll") for (int m = 0; m < 4; ++m) _Pragma("unroll") for (int n = 0; n < 2; ++n) _Pragma("unroll") for (int k = 0; k < 2; ++k) \
;         acc[ai][bj][m][n] = __builtin_amdgcn_mfma_f32_16x16x32_bf16(Bt[n][k], At[m][k], acc[ai][bj][m][n], 0, 0, 0); __builtin_amdgcn_s_setprio(0); } while (0)
; #define PG8_WAIT_V(n) asm volatile("s_waitcnt vmcnt(" #n ")" ::: "memory")
; #define PG8_WAIT_L(n) asm volatile("s_waitcnt lgkmcnt(" #n ")" ::: "memory")
; #define PG8_BAR __builtin_amdgcn_s_barrier()
; #define PG8_SCHED __builtin_amdgcn_sched_barrier(0)
; template <class Epi>
; DEV void gemm_phase(LAS unsigned char* lds, const Gemm g, const StaticOrder& S, const Epi& E) {
;     ...
;             PG8_STAGE(PG8_SB(0, 1), b2 + hstep, voffB);
;             PG8_WAIT_V(6); PG8_BAR; PG8_MMA(1, 1, At, B1); PG8_BAR;
;             PG8_LDB(B0, 1, 0); PG8_SCHED; PG8_LDA(At, 1, 0); PG8_STAGE(PG8_SA(0, 1), a2 + hstep, voffA);
;             PG8_WAIT_L(8); PG8_BAR; PG8_WAIT_L(0); PG8_MMA(0, 0, At, B0); PG8_BAR; PG8_SCHED;
;             PG8_LDB(B1, 1, 1); PG8_STAGE(PG8_SB(1, 0), b3, voffB);
;             PG8_BAR; PG8_WAIT_L(0); PG8_MMA(0, 1, At, B1); PG8_BAR;
;             PG8_LDA(At, 1, 1); PG8_STAGE(PG8_SA(1, 0), a3, voffA);
	s_add_u32 s50, s28, 0x100000
	s_addc_u32 s51, s29, 0
	s_add_i32 s49, s52, s36
	s_mov_b32 m0, s49
	s_nop 0
	global_load_lds_dwordx4 v160, s[50:51]
	s_add_i32 m0, s49, 0x2000
	s_nop 0
	global_load_lds_dwordx4 v148, s[50:51]
	s_waitcnt vmcnt(6)
	s_barrier
	v_mfma_f32_16x16x32_bf16 v[52:55], v[222:225], v[154:157], v[52:55]
	v_mfma_f32_16x16x32_bf16 v[48:51], v[230:233], v[154:157], v[48:51]
	v_mfma_f32_16x16x32_bf16 v[36:39], v[222:225], v[182:185], v[36:39]
	v_mfma_f32_16x16x32_bf16 v[32:35], v[230:233], v[182:185], v[32:35]
	v_mfma_f32_16x16x32_bf16 v[20:23], v[222:225], v[190:193], v[20:23]
	v_mfma_f32_16x16x32_bf16 v[16:19], v[230:233], v[190:193], v[16:19]
	v_mfma_f32_16x16x32_bf16 v[4:7], v[222:225], v[214:217], v[4:7]
	v_mfma_f32_16x16x32_bf16 v[0:3], v[230:233], v[214:217], v[0:3]
	v_mfma_f32_16x16x32_bf16 v[52:55], v[226:229], v[174:177], v[52:55]
	v_mfma_f32_16x16x32_bf16 v[48:51], v[234:237], v[174:177], v[48:51]
	v_mfma_f32_16x16x32_bf16 v[36:39], v[226:229], v[186:189], v[36:39]
	v_mfma_f32_16x16x32_bf16 v[32:35], v[234:237], v[186:189], v[32:35]
	v_mfma_f32_16x16x32_bf16 v[20:23], v[226:229], v[194:197], v[20:23]
	v_mfma_f32_16x16x32_bf16 v[16:19], v[234:237], v[194:197], v[16:19]
	v_mfma_f32_16x16x32_bf16 v[4:7], v[226:229], v[218:221], v[4:7]
	v_mfma_f32_16x16x32_bf16 v[0:3], v[234:237], v[218:221], v[0:3]
	s_add_i32 s49, 0, 0x18000
	v_add_u32_e32 v140, s49, v178
	s_barrier
	ds_read_b128 v[128:131], v140
	ds_read_b128 v[132:135], v140 offset:1024
	ds_read_b128 v[136:139], v140 offset:2048
	ds_read_b128 v[140:143], v140 offset:3072
	s_add_u32 s30, s30, 0x100000
	s_addc_u32 s31, s31, 0
	s_mov_b32 m0, s39
	ds_read_b128 v[154:157], v181 offset:32768
	ds_read_b128 v[174:177], v181 offset:33792
	ds_read_b128 v[182:185], v181 offset:34816
	ds_read_b128 v[186:189], v181 offset:35840
	ds_read_b128 v[190:193], v181 offset:36864
	ds_read_b128 v[194:197], v181 offset:37888
	ds_read_b128 v[214:217], v181 offset:38912
	ds_read_b128 v[218:221], v181 offset:39936
	global_load_lds_dwordx4 v144, s[30:31]
	s_mov_b32 m0, s40
	s_nop 0
	global_load_lds_dwordx4 v146, s[30:31]
	s_waitcnt lgkmcnt(8)
	s_barrier
	s_waitcnt lgkmcnt(7)
	v_mfma_f32_16x16x32_bf16 v[124:127], v[128:131], v[154:157], v[124:127]
	v_mfma_f32_16x16x32_bf16 v[120:123], v[136:139], v[154:157], v[120:123]
	s_waitcnt lgkmcnt(5)
	v_mfma_f32_16x16x32_bf16 v[108:111], v[128:131], v[182:185], v[108:111]
	v_mfma_f32_16x16x32_bf16 v[104:107], v[136:139], v[182:185], v[104:107]
	s_waitcnt lgkmcnt(3)
	v_mfma_f32_16x16x32_bf16 v[92:95], v[128:131], v[190:193], v[92:95]
	v_mfma_f32_16x16x32_bf16 v[88:91], v[136:139], v[190:193], v[88:91]
	s_waitcnt lgkmcnt(1)
	v_mfma_f32_16x16x32_bf16 v[76:79], v[128:131], v[214:217], v[76:79]
	v_mfma_f32_16x16x32_bf16 v[72:75], v[136:139], v[214:217], v[72:75]
	v_mfma_f32_16x16x32_bf16 v[124:127], v[132:135], v[174:177], v[124:127]
	v_mfma_f32_16x16x32_bf16 v[120:123], v[140:143], v[174:177], v[120:123]
	v_mfma_f32_16x16x32_bf16 v[108:111], v[132:135], v[186:189], v[108:111]
	v_mfma_f32_16x16x32_bf16 v[104:107], v[140:143], v[186:189], v[104:107]
	v_mfma_f32_16x16x32_bf16 v[92:95], v[132:135], v[194:197], v[92:95]
	v_mfma_f32_16x16x32_bf16 v[88:91], v[140:143], v[194:197], v[88:91]
	s_waitcnt lgkmcnt(0)
	v_mfma_f32_16x16x32_bf16 v[76:79], v[132:135], v[218:221], v[76:79]
	v_mfma_f32_16x16x32_bf16 v[72:75], v[140:143], v[218:221], v[72:75]
	s_barrier
	s_add_i32 s30, 0, 0x1c000
	s_add_i32 s31, s49, s36
	v_add_u32_e32 v234, s30, v178
	v_lshl_add_u64 v[158:159], v[158:159], 0, s[2:3]
	s_mov_b32 m0, s31
	ds_read_b128 v[222:225], v234
	ds_read_b128 v[226:229], v234 offset:1024
	ds_read_b128 v[230:233], v234 offset:2048
	ds_read_b128 v[234:237], v234 offset:3072
	global_load_lds_dwordx4 v[158:159], off
	v_lshl_add_u64 v[158:159], v[238:239], 0, s[2:3]
	s_add_i32 m0, s31, 0x2000
	s_nop 0
	global_load_lds_dwordx4 v[158:159], off
	s_barrier
	s_waitcnt lgkmcnt(3)
	v_mfma_f32_16x16x32_bf16 v[116:119], v[222:225], v[154:157], v[116:119]
	s_waitcnt lgkmcnt(1)
	v_mfma_f32_16x16x32_bf16 v[112:115], v[230:233], v[154:157], v[112:115]
	v_mfma_f32_16x16x32_bf16 v[100:103], v[222:225], v[182:185], v[100:103]
	v_mfma_f32_16x16x32_bf16 v[96:99], v[230:233], v[182:185], v[96:99]
	v_mfma_f32_16x16x32_bf16 v[84:87], v[222:225], v[190:193], v[84:87]
	v_mfma_f32_16x16x32_bf16 v[80:83], v[230:233], v[190:193], v[80:83]
	v_mfma_f32_16x16x32_bf16 v[68:71], v[222:225], v[214:217], v[68:71]
	v_mfma_f32_16x16x32_bf16 v[64:67], v[230:233], v[214:217], v[64:67]
	v_mfma_f32_16x16x32_bf16 v[116:119], v[226:229], v[174:177], v[116:119]
	s_waitcnt lgkmcnt(0)
	v_mfma_f32_16x16x32_bf16 v[112:115], v[234:237], v[174:177], v[112:115]
	v_mfma_f32_16x16x32_bf16 v[100:103], v[226:229], v[186:189], v[100:103]
	v_mfma_f32_16x16x32_bf16 v[96:99], v[234:237], v[186:189], v[96:99]
	v_mfma_f32_16x16x32_bf16 v[84:87], v[226:229], v[194:197], v[84:87]
	v_mfma_f32_16x16x32_bf16 v[80:83], v[234:237], v[194:197], v[80:83]
	v_mfma_f32_16x16x32_bf16 v[68:71], v[226:229], v[218:221], v[68:71]
	v_mfma_f32_16x16x32_bf16 v[64:67], v[234:237], v[218:221], v[64:67]
	s_mov_b32 m0, s41
	v_lshl_add_u64 v[158:159], v[240:241], 0, s[2:3]
	s_barrier
	ds_read_b128 v[154:157], v181 offset:49152
	ds_read_b128 v[174:177], v181 offset:50176
	ds_read_b128 v[182:185], v181 offset:51200
	ds_read_b128 v[186:189], v181 offset:52224
	ds_read_b128 v[190:193], v181 offset:53248
	ds_read_b128 v[194:197], v181 offset:54272
	ds_read_b128 v[214:217], v181 offset:55296
	ds_read_b128 v[218:221], v181 offset:56320
	global_load_lds_dwordx4 v[158:159], off
	v_lshl_add_u64 v[158:159], v[242:243], 0, s[2:3]
	s_mov_b32 m0, s42
	s_nop 0
	global_load_lds_dwordx4 v[158:159], off
	s_barrier
; DEV bf16x8 pack8(f32x4 a, f32x4 b) { u32x4 w; w.x = cvt_pk_bf16(a[0], a[1]); w.y = cvt_pk_bf16(a[2], a[3]); w.z = cvt_pk_bf16(b[0], b[1]); w.w = cvt_pk_bf16(b[2], b[3]); return __builtin_bit_cast(bf16x8, w); }
; #define PG8_WAIT_V(n) asm volatile("s_waitcnt vmcnt(" #n ")" ::: "memory")
; template <class Epi>
; DEV void gemm_phase(LAS unsigned char* lds, const Gemm g, const StaticOrder& S, const Epi& E) {
;     ...
;             PG8_BAR; PG8_WAIT_L(0); PG8_MMA(0, 1, At, B1); PG8_BAR;
;             PG8_LDA(At, 1, 1); PG8_STAGE(PG8_SA(1, 0), a3, voffA);
;             PG8_BAR; PG8_WAIT_L(0); PG8_MMA(1, 0, At, B0); PG8_BAR; PG8_SCHED;
;             PG8_STAGE(PG8_SB(1, 1), b3 + hstep, voffB);
;             PG8_WAIT_V(6); PG8_BAR; PG8_MMA(1, 1, At, B1); PG8_BAR;
;     DEV void operator()(AccRef acc, const pg8::Unit& u, int wr, int wc, int fr, int fq) const {
;         const int row0 = u.pm * 256 + wr * 64 + fr, col0 = u.pn * 256 + wc * 32 + 8 * fq;
; #pragma unroll
;         for (int am = 0; am < 4; ++am) { const int ai = am >> 1, m0 = (am & 1) * 2;
;             f32x4 bv[4][2][2];
; #pragma unroll
;             for (int m = m0; m < m0 + 2; ++m)
; #pragma unroll
;                 for (int bj = 0; bj < 2; ++bj)
; #pragma unroll
;                     for (int n = 0; n < 2; ++n) bv[m][bj][n] = *(const f32x4*)(base + (size_t)(row0 + ai * 128 + m * 16) * 2048 + col0 + bj * 128 + n * 4);
; #pragma unroll
;             for (int m = m0; m < m0 + 2; ++m) { const size_t off = (size_t)(row0 + ai * 128 + m * 16) * 2048 + col0; float sq = 0.f;
; #pragma unroll
;                 for (int bj = 0; bj < 2; ++bj) { const f32x4 o0 = bv[m][bj][0] + scale * acc[ai][bj][m][0], o1 = bv[m][bj][1] + scale * acc[ai][bj][m][1];
;                     *(f32x4*)(out + off + bj * 128) = o0; *(f32x4*)(out + off + bj * 128 + 4) = o1;
;                     if (xb) { *(u32x4*)(xb + off + bj * 128) = __builtin_bit_cast(u32x4, pack8(o0, o1));
;                         sq += (o0[0] * o0[0] + o0[1] * o0[1] + o0[2] * o0[2] + o0[3] * o0[3]) + (o1[0] * o1[0] + o1[1] * o1[1] + o1[2] * o1[2] + o1[3] * o1[3]); } }
;                 if (ssout) { sq += __shfl_xor(sq, 16); sq += __shfl_xor(sq, 32);
;                     if (fq == 0) { if (red) red[(ai * 128 + wr * 64 + m * 16 + fr) * 4 + wc] = sq; else atomicAdd(ssout + (size_t)(row0 + ai * 128 + m * 16) * 8 + u.pn, sq); } } }
	s_waitcnt lgkmcnt(7)
	v_mfma_f32_16x16x32_bf16 v[60:63], v[128:131], v[154:157], v[60:63]
	v_mfma_f32_16x16x32_bf16 v[56:59], v[136:139], v[154:157], v[56:59]
	s_waitcnt lgkmcnt(5)
	v_mfma_f32_16x16x32_bf16 v[44:47], v[128:131], v[182:185], v[44:47]
	v_mfma_f32_16x16x32_bf16 v[40:43], v[136:139], v[182:185], v[40:43]
	s_waitcnt lgkmcnt(3)
	v_mfma_f32_16x16x32_bf16 v[28:31], v[128:131], v[190:193], v[28:31]
	v_mfma_f32_16x16x32_bf16 v[24:27], v[136:139], v[190:193], v[24:27]
	s_waitcnt lgkmcnt(1)
	v_mfma_f32_16x16x32_bf16 v[12:15], v[128:131], v[214:217], v[12:15]
	v_mfma_f32_16x16x32_bf16 v[8:11], v[136:139], v[214:217], v[8:11]
	v_mfma_f32_16x16x32_bf16 v[60:63], v[132:135], v[174:177], v[60:63]
	v_mfma_f32_16x16x32_bf16 v[56:59], v[140:143], v[174:177], v[56:59]
	v_mfma_f32_16x16x32_bf16 v[44:47], v[132:135], v[186:189], v[44:47]
	v_mfma_f32_16x16x32_bf16 v[40:43], v[140:143], v[186:189], v[40:43]
	v_mfma_f32_16x16x32_bf16 v[28:31], v[132:135], v[194:197], v[28:31]
	v_mfma_f32_16x16x32_bf16 v[24:27], v[140:143], v[194:197], v[24:27]
	s_waitcnt lgkmcnt(0)
	v_mfma_f32_16x16x32_bf16 v[12:15], v[132:135], v[218:221], v[12:15]
	v_mfma_f32_16x16x32_bf16 v[8:11], v[140:143], v[218:221], v[8:11]
	s_barrier
	s_add_u32 s28, s28, 0x100080
	s_addc_u32 s29, s29, 0
	s_add_i32 s30, s30, s36
	s_mov_b32 m0, s30
	s_nop 0
	global_load_lds_dwordx4 v160, s[28:29]
	s_add_i32 m0, s30, 0x2000
	s_nop 0
	global_load_lds_dwordx4 v148, s[28:29]
	s_waitcnt vmcnt(6)
	s_barrier
	v_mfma_f32_16x16x32_bf16 v[52:55], v[222:225], v[154:157], v[52:55]
	v_mfma_f32_16x16x32_bf16 v[48:51], v[230:233], v[154:157], v[48:51]
	v_mfma_f32_16x16x32_bf16 v[36:39], v[222:225], v[182:185], v[36:39]
	v_mfma_f32_16x16x32_bf16 v[32:35], v[230:233], v[182:185], v[32:35]
	v_mfma_f32_16x16x32_bf16 v[20:23], v[222:225], v[190:193], v[20:23]
	v_mfma_f32_16x16x32_bf16 v[16:19], v[230:233], v[190:193], v[16:19]
	v_mfma_f32_16x16x32_bf16 v[4:7], v[222:225], v[214:217], v[4:7]
	v_mfma_f32_16x16x32_bf16 v[0:3], v[230:233], v[214:217], v[0:3]
	v_mfma_f32_16x16x32_bf16 v[52:55], v[226:229], v[174:177], v[52:55]
	v_mfma_f32_16x16x32_bf16 v[48:51], v[234:237], v[174:177], v[48:51]
	v_mfma_f32_16x16x32_bf16 v[36:39], v[226:229], v[186:189], v[36:39]
	v_mfma_f32_16x16x32_bf16 v[32:35], v[234:237], v[186:189], v[32:35]
	v_mfma_f32_16x16x32_bf16 v[20:23], v[226:229], v[194:197], v[20:23]
	v_mfma_f32_16x16x32_bf16 v[16:19], v[234:237], v[194:197], v[16:19]
	v_mfma_f32_16x16x32_bf16 v[4:7], v[226:229], v[218:221], v[4:7]
	v_mfma_f32_16x16x32_bf16 v[0:3], v[234:237], v[218:221], v[0:3]
	s_add_i32 s48, s48, 2
	s_add_u32 s26, s26, 0x100
	s_addc_u32 s27, s27, 0
	s_add_u32 s46, s46, 0x100
	s_addc_u32 s47, s47, 0
	s_cmp_gt_u32 s48, 61
	s_barrier
	s_cbranch_scc0 .LBB0_404
	v_lshl_add_u32 v156, s24, 8, v167
	v_lshl_or_b32 v154, s14, 8, v179
	v_readlane_b32 s24, v254, 16
	v_ashrrev_i32_e32 v155, 31, v154
	v_readlane_b32 s25, v254, 17
	v_ashrrev_i32_e32 v157, 31, v156
	v_lshlrev_b64 v[128:129], 13, v[156:157]
	v_lshl_add_u64 v[158:159], v[154:155], 2, s[24:25]
	v_lshl_add_u64 v[214:215], v[158:159], 0, v[128:129]
	global_load_dwordx4 v[182:185], v[214:215], off offset:16
	global_load_dwordx4 v[186:189], v[214:215], off
	global_load_dwordx4 v[190:193], v[214:215], off offset:528
	global_load_dwordx4 v[194:197], v[214:215], off offset:512
	v_or_b32_e32 v174, 16, v156
	v_ashrrev_i32_e32 v175, 31, v174
	v_lshlrev_b64 v[128:129], 13, v[174:175]
	v_lshl_add_u64 v[176:177], v[158:159], 0, v[128:129]
	global_load_dwordx4 v[136:139], v[176:177], off offset:16
	global_load_dwordx4 v[140:143], v[176:177], off
	global_load_dwordx4 v[128:131], v[176:177], off offset:528
	global_load_dwordx4 v[132:135], v[176:177], off offset:512
	v_lshlrev_b64 v[216:217], 11, v[156:157]
	v_readlane_b32 s24, v250, 9
	v_lshl_add_u64 v[216:217], v[216:217], 0, v[154:155]
	v_readlane_b32 s25, v250, 10
	v_cmp_lt_i32_e32 vcc, v208, v206
	s_ashr_i32 s15, s14, 31
	s_waitcnt vmcnt(0)
	v_pk_add_f32 v[120:121], v[120:121], v[182:183]
	v_pk_add_f32 v[126:127], v[126:127], v[188:189]
	v_pk_add_f32 v[124:125], v[124:125], v[186:187]
	v_pk_add_f32 v[122:123], v[122:123], v[184:185]
	global_store_dwordx4 v[214:215], v[124:127], off
	global_store_dwordx4 v[214:215], v[120:123], off offset:16
	v_cvt_pk_bf16_f32 v184, v120, v121
	v_cvt_pk_bf16_f32 v182, v124, v125
	v_mul_f32_e32 v121, v121, v121
	v_cvt_pk_bf16_f32 v183, v126, v127
	v_cvt_pk_bf16_f32 v185, v122, v123
	v_lshl_add_u64 v[186:187], v[216:217], 1, s[24:25]
	v_fmac_f32_e32 v121, v120, v120
	v_pk_add_f32 v[118:119], v[118:119], v[196:197]
	v_pk_add_f32 v[116:117], v[116:117], v[194:195]
	v_pk_add_f32 v[112:113], v[112:113], v[190:191]
	global_store_dwordx4 v[186:187], v[182:185], off
	v_mul_f32_e32 v125, v125, v125
	v_fmac_f32_e32 v121, v122, v122
	v_pk_add_f32 v[114:115], v[114:115], v[192:193]
	global_store_dwordx4 v[214:215], v[116:119], off offset:512
	global_store_dwordx4 v[214:215], v[112:115], off offset:528
	v_cvt_pk_bf16_f32 v120, v116, v117
	v_cvt_pk_bf16_f32 v122, v112, v113
	v_mul_f32_e32 v117, v117, v117
	v_mul_f32_e32 v113, v113, v113
	v_fmac_f32_e32 v125, v124, v124
	v_fmac_f32_e32 v117, v116, v116
	v_fmac_f32_e32 v113, v112, v112
	v_fmac_f32_e32 v125, v126, v126
	v_fmac_f32_e32 v117, v118, v118
	v_fmac_f32_e32 v113, v114, v114
	v_fmac_f32_e32 v125, v127, v127
	v_fmac_f32_e32 v121, v123, v123
	v_fmac_f32_e32 v117, v119, v119
	v_fmac_f32_e32 v113, v115, v115
	v_add_f32_e32 v124, v125, v121
	v_add_f32_e32 v112, v117, v113
	v_cndmask_b32_e32 v113, v204, v208, vcc
	v_cvt_pk_bf16_f32 v121, v118, v119
	v_add_f32_e32 v112, v124, v112
	v_lshlrev_b32_e32 v118, 2, v113
	ds_bpermute_b32 v113, v118, v112
	v_cmp_lt_i32_e32 vcc, v207, v206
	v_cvt_pk_bf16_f32 v123, v114, v115
	global_store_dwordx4 v[186:187], v[120:123], off offset:256
	s_waitcnt lgkmcnt(0)
	v_add_f32_e32 v112, v112, v113
	v_cndmask_b32_e32 v113, v204, v207, vcc
	v_lshlrev_b32_e32 v119, 2, v113
	ds_bpermute_b32 v113, v119, v112
	s_and_saveexec_b64 s[24:25], s[6:7]
	s_cbranch_execz .LBB0_410
	s_waitcnt lgkmcnt(0)
	v_add_f32_e32 v112, v112, v113
	s_mov_b64 s[26:27], -1
	s_and_b64 vcc, exec, s[12:13]
	s_cbranch_vccz .LBB0_408
	v_readlane_b32 s26, v250, 59
	v_lshlrev_b64 v[114:115], 5, v[156:157]
	v_readlane_b32 s27, v250, 60
	s_nop 1
	v_lshl_add_u64 v[114:115], s[26:27], 0, v[114:115]
	v_lshl_add_u64 v[114:115], s[14:15], 2, v[114:115]
	global_atomic_add_f32 v[114:115], v112, off
	s_mov_b64 s[26:27], 0

; #define PG8_STAGE(bufoff, gbase, voff) do { _Pragma("unroll") for (int _i = 0; _i < 2; ++_i) \
;         __builtin_amdgcn_global_load_lds((const unsigned*)((const char*)(gbase) + (voff)[_i]), (LAS unsigned*)(lds + (bufoff) + ldsw + _i * 8192), 16, 0, 0); } while (0)
; #define PG8_LDA(dst, b, h) do { _Pragma("unroll") for (int m = 0; m < 4; ++m) _Pragma("unroll") for (int k = 0; k < 2; ++k) dst[m][k] = *(const LAS bf16x8*)(lds + PG8_SA(b, h) + aoff + m * 2048 + k * 1024); } while (0)
; #define PG8_LDB(dst, b, h) do { _Pragma("unroll") for (int n = 0; n < 2; ++n) _Pragma("unroll") for (int k = 0; k < 2; ++k) dst[n][k] = *(const LAS bf16x8*)(lds + PG8_SB(b, h) + boff + n * 2048 + k * 1024); } while (0)
; #define PG8_MMA(ai, bj, At, Bt) do { __builtin_amdgcn_s_setprio(1); _Pragma("unroll") for (int m = 0; m < 4; ++m) _Pragma("unroll") for (int n = 0; n < 2; ++n) _Pragma("unroll") for (int k = 0; k < 2; ++k) \
;         acc[ai][bj][m][n] = __builtin_amdgcn_mfma_f32_16x16x32_bf16(Bt[n][k], At[m][k], acc[ai][bj][m][n], 0, 0, 0); __builtin_amdgcn_s_setprio(0); } while (0)
; #define PG8_WAIT_L(n) asm volatile("s_waitcnt lgkmcnt(" #n ")" ::: "memory")
; #define PG8_BAR __builtin_amdgcn_s_barrier()
; #define PG8_SCHED __builtin_amdgcn_sched_barrier(0)
; template <class Epi>
; DEV void gemm_phase(LAS unsigned char* lds, const Gemm g, const StaticOrder& S, const Epi& E) {
;     ...
;             PG8_LDB(B0, 0, 0); PG8_SCHED; PG8_LDA(At, 0, 0); PG8_STAGE(PG8_SA(1, 1), a1 + hstep, voffA);
;             PG8_WAIT_L(8); PG8_BAR; PG8_WAIT_L(0); PG8_MMA(0, 0, At, B0); PG8_BAR; PG8_SCHED;
;             PG8_LDB(B1, 0, 1); PG8_STAGE(PG8_SB(0, 0), b2, voffB);
;             PG8_BAR; PG8_WAIT_L(0); PG8_MMA(0, 1, At, B1); PG8_BAR;
;             PG8_LDA(At, 0, 1); PG8_STAGE(PG8_SA(0, 0), a2, voffA);
;             PG8_BAR; PG8_WAIT_L(0); PG8_MMA(1, 0, At, B0); PG8_BAR; PG8_SCHED;
.LBB0_588:
	s_add_u32 s16, s14, 0xfff80080
	s_addc_u32 s17, s15, -1
	s_add_i32 s41, 0, 0x10000
	v_add_u32_e32 v154, s41, v167
	ds_read_b128 v[128:131], v154
	ds_read_b128 v[132:135], v154 offset:1024
	ds_read_b128 v[150:153], v154 offset:2048
	ds_read_b128 v[174:177], v154 offset:3072
	s_cmp_eq_u32 s40, 28
	s_cselect_b32 s19, s1, s17
	s_cselect_b32 s18, s9, s16
	s_cselect_b32 s17, s7, s37
	s_cselect_b32 s16, s35, s36
	s_add_i32 m0, s24, 0xc000
	ds_read_b128 v[182:185], v219
	ds_read_b128 v[190:193], v219 offset:1024
	ds_read_b128 v[194:197], v219 offset:2048
	ds_read_b128 v[220:223], v219 offset:3072
	ds_read_b128 v[224:227], v219 offset:4096
	ds_read_b128 v[228:231], v219 offset:5120
	ds_read_b128 v[232:235], v219 offset:6144
	ds_read_b128 v[236:239], v219 offset:7168
	global_load_lds_dwordx4 v146, s[14:15]
	s_add_i32 m0, s24, 0xe000
	s_nop 0
	global_load_lds_dwordx4 v148, s[14:15]
	s_waitcnt lgkmcnt(8)
	s_barrier
	s_waitcnt lgkmcnt(7)
	v_mfma_f32_16x16x32_bf16 v[124:127], v[128:131], v[182:185], v[124:127]
	v_mfma_f32_16x16x32_bf16 v[120:123], v[150:153], v[182:185], v[120:123]
	s_waitcnt lgkmcnt(5)
	v_mfma_f32_16x16x32_bf16 v[108:111], v[128:131], v[194:197], v[108:111]
	v_mfma_f32_16x16x32_bf16 v[104:107], v[150:153], v[194:197], v[104:107]
	s_waitcnt lgkmcnt(3)
	v_mfma_f32_16x16x32_bf16 v[92:95], v[128:131], v[224:227], v[92:95]
	v_mfma_f32_16x16x32_bf16 v[88:91], v[150:153], v[224:227], v[88:91]
	s_waitcnt lgkmcnt(1)
	v_mfma_f32_16x16x32_bf16 v[76:79], v[128:131], v[232:235], v[76:79]
	v_mfma_f32_16x16x32_bf16 v[72:75], v[150:153], v[232:235], v[72:75]
	v_mfma_f32_16x16x32_bf16 v[124:127], v[132:135], v[190:193], v[124:127]
	v_mfma_f32_16x16x32_bf16 v[120:123], v[174:177], v[190:193], v[120:123]
	v_mfma_f32_16x16x32_bf16 v[108:111], v[132:135], v[220:223], v[108:111]
	v_mfma_f32_16x16x32_bf16 v[104:107], v[174:177], v[220:223], v[104:107]
	v_mfma_f32_16x16x32_bf16 v[92:95], v[132:135], v[228:231], v[92:95]
	v_mfma_f32_16x16x32_bf16 v[88:91], v[174:177], v[228:231], v[88:91]
	s_waitcnt lgkmcnt(0)
	v_mfma_f32_16x16x32_bf16 v[76:79], v[132:135], v[236:239], v[76:79]
	v_mfma_f32_16x16x32_bf16 v[72:75], v[174:177], v[236:239], v[72:75]
	s_barrier
	s_add_i32 s44, 0, 0x14000
	v_add_u32_e32 v154, s44, v167
	s_add_i32 s41, s41, s22
	ds_read_b128 v[240:243], v154
	ds_read_b128 v[244:247], v154 offset:1024
	ds_read_b128 v[186:189], v154 offset:2048
	ds_read_b128 v[214:217], v154 offset:3072
	v_lshl_add_u64 v[154:155], s[16:17], 0, v[140:141]
	s_mov_b32 m0, s41
	v_lshl_add_u64 v[158:159], s[16:17], 0, v[136:137]
	global_load_lds_dwordx4 v140, s[16:17]
	s_add_i32 m0, s41, 0x2000
	s_nop 0
	global_load_lds_dwordx4 v136, s[16:17]
	s_barrier
	s_waitcnt lgkmcnt(3)
	v_mfma_f32_16x16x32_bf16 v[116:119], v[240:243], v[182:185], v[116:119]
	s_waitcnt lgkmcnt(1)
	v_mfma_f32_16x16x32_bf16 v[112:115], v[186:189], v[182:185], v[112:115]
	v_mfma_f32_16x16x32_bf16 v[100:103], v[240:243], v[194:197], v[100:103]
	v_mfma_f32_16x16x32_bf16 v[96:99], v[186:189], v[194:197], v[96:99]
	v_mfma_f32_16x16x32_bf16 v[84:87], v[240:243], v[224:227], v[84:87]
	v_mfma_f32_16x16x32_bf16 v[80:83], v[186:189], v[224:227], v[80:83]
	v_mfma_f32_16x16x32_bf16 v[68:71], v[240:243], v[232:235], v[68:71]
	v_mfma_f32_16x16x32_bf16 v[64:67], v[186:189], v[232:235], v[64:67]
	v_mfma_f32_16x16x32_bf16 v[116:119], v[244:247], v[190:193], v[116:119]
	s_waitcnt lgkmcnt(0)
	v_mfma_f32_16x16x32_bf16 v[112:115], v[214:217], v[190:193], v[112:115]
	v_mfma_f32_16x16x32_bf16 v[100:103], v[244:247], v[220:223], v[100:103]
	v_mfma_f32_16x16x32_bf16 v[96:99], v[214:217], v[220:223], v[96:99]
	v_mfma_f32_16x16x32_bf16 v[84:87], v[244:247], v[228:231], v[84:87]
	v_mfma_f32_16x16x32_bf16 v[80:83], v[214:217], v[228:231], v[80:83]
	v_mfma_f32_16x16x32_bf16 v[68:71], v[244:247], v[236:239], v[68:71]
	v_mfma_f32_16x16x32_bf16 v[64:67], v[214:217], v[236:239], v[64:67]
	s_mov_b32 m0, s24
	v_lshl_add_u64 v[178:179], s[18:19], 0, v[142:143]
	s_barrier
	ds_read_b128 v[182:185], v219 offset:16384
	ds_read_b128 v[190:193], v219 offset:17408
	ds_read_b128 v[194:197], v219 offset:18432
	ds_read_b128 v[220:223], v219 offset:19456
	ds_read_b128 v[224:227], v219 offset:20480
	ds_read_b128 v[228:231], v219 offset:21504
	ds_read_b128 v[232:235], v219 offset:22528
	ds_read_b128 v[236:239], v219 offset:23552
	global_load_lds_dwordx4 v142, s[18:19]
	v_lshl_add_u64 v[248:249], s[18:19], 0, v[138:139]
	s_mov_b32 m0, s25
	s_nop 0
	global_load_lds_dwordx4 v138, s[18:19]
	s_barrier
	s_waitcnt lgkmcnt(7)
	v_mfma_f32_16x16x32_bf16 v[60:63], v[128:131], v[182:185], v[60:63]
	v_mfma_f32_16x16x32_bf16 v[56:59], v[150:153], v[182:185], v[56:59]
	s_waitcnt lgkmcnt(5)
	v_mfma_f32_16x16x32_bf16 v[44:47], v[128:131], v[194:197], v[44:47]
	v_mfma_f32_16x16x32_bf16 v[40:43], v[150:153], v[194:197], v[40:43]
	s_waitcnt lgkmcnt(3)
	v_mfma_f32_16x16x32_bf16 v[28:31], v[128:131], v[224:227], v[28:31]
	v_mfma_f32_16x16x32_bf16 v[24:27], v[150:153], v[224:227], v[24:27]
	s_waitcnt lgkmcnt(1)
	v_mfma_f32_16x16x32_bf16 v[12:15], v[128:131], v[232:235], v[12:15]
	v_mfma_f32_16x16x32_bf16 v[8:11], v[150:153], v[232:235], v[8:11]
	v_mfma_f32_16x16x32_bf16 v[60:63], v[132:135], v[190:193], v[60:63]
	v_mfma_f32_16x16x32_bf16 v[56:59], v[174:177], v[190:193], v[56:59]
	v_mfma_f32_16x16x32_bf16 v[44:47], v[132:135], v[220:223], v[44:47]
	v_mfma_f32_16x16x32_bf16 v[40:43], v[174:177], v[220:223], v[40:43]
	v_mfma_f32_16x16x32_bf16 v[28:31], v[132:135], v[228:231], v[28:31]
	v_mfma_f32_16x16x32_bf16 v[24:27], v[174:177], v[228:231], v[24:27]
	s_waitcnt lgkmcnt(0)
	v_mfma_f32_16x16x32_bf16 v[12:15], v[132:135], v[236:239], v[12:15]
	v_mfma_f32_16x16x32_bf16 v[8:11], v[174:177], v[236:239], v[8:11]
	s_barrier
; #define PG8_STAGE(bufoff, gbase, voff) do { _Pragma("unroll") for (int _i = 0; _i < 2; ++_i) \
;         __builtin_amdgcn_global_load_lds((const unsigned*)((const char*)(gbase) + (voff)[_i]), (LAS unsigned*)(lds + (bufoff) + ldsw + _i * 8192), 16, 0, 0); } while (0)
; #define PG8_LDA(dst, b, h) do { _Pragma("unroll") for (int m = 0; m < 4; ++m) _Pragma("unroll") for (int k = 0; k < 2; ++k) dst[m][k] = *(const LAS bf16x8*)(lds + PG8_SA(b, h) + aoff + m * 2048 + k * 1024); } while (0)
; #define PG8_LDB(dst, b, h) do { _Pragma("unroll") for (int n = 0; n < 2; ++n) _Pragma("unroll") for (int k = 0; k < 2; ++k) dst[n][k] = *(const LAS bf16x8*)(lds + PG8_SB(b, h) + boff + n * 2048 + k * 1024); } while (0)
; #define PG8_MMA(ai, bj, At, Bt) do { __builtin_amdgcn_s_setprio(1); _Pragma("unroll") for (int m = 0; m < 4; ++m) _Pragma("unroll") for (int n = 0; n < 2; ++n) _Pragma("unroll") for (int k = 0; k < 2; ++k) \
;         acc[ai][bj][m][n] = __builtin_amdgcn_mfma_f32_16x16x32_bf16(Bt[n][k], At[m][k], acc[ai][bj][m][n], 0, 0, 0); __builtin_amdgcn_s_setprio(0); } while (0)
; #define PG8_WAIT_V(n) asm volatile("s_waitcnt vmcnt(" #n ")" ::: "memory")
; #define PG8_WAIT_L(n) asm volatile("s_waitcnt lgkmcnt(" #n ")" ::: "memory")
; #define PG8_BAR __builtin_amdgcn_s_barrier()
; #define PG8_SCHED __builtin_amdgcn_sched_barrier(0)
; template <class Epi>
; DEV void gemm_phase(LAS unsigned char* lds, const Gemm g, const StaticOrder& S, const Epi& E) {
;     ...
;             PG8_STAGE(PG8_SB(0, 1), b2 + hstep, voffB);
;             PG8_WAIT_V(6); PG8_BAR; PG8_MMA(1, 1, At, B1); PG8_BAR;
;             PG8_LDB(B0, 1, 0); PG8_SCHED; PG8_LDA(At, 1, 0); PG8_STAGE(PG8_SA(0, 1), a2 + hstep, voffA);
;             PG8_WAIT_L(8); PG8_BAR; PG8_WAIT_L(0); PG8_MMA(0, 0, At, B0); PG8_BAR; PG8_SCHED;
;             PG8_LDB(B1, 1, 1); PG8_STAGE(PG8_SB(1, 0), b3, voffB);
;             PG8_BAR; PG8_WAIT_L(0); PG8_MMA(0, 1, At, B1); PG8_BAR;
;             PG8_LDA(At, 1, 1); PG8_STAGE(PG8_SA(1, 0), a3, voffA);
	s_add_u32 s42, s16, 0x80000
	s_addc_u32 s43, s17, 0
	s_add_i32 s41, s44, s22
	s_mov_b32 m0, s41
	s_nop 0
	global_load_lds_dwordx4 v140, s[42:43]
	s_add_i32 m0, s41, 0x2000
	s_nop 0
	global_load_lds_dwordx4 v136, s[42:43]
	s_waitcnt vmcnt(6)
	s_barrier
	v_mfma_f32_16x16x32_bf16 v[52:55], v[240:243], v[182:185], v[52:55]
	v_mfma_f32_16x16x32_bf16 v[48:51], v[186:189], v[182:185], v[48:51]
	v_mfma_f32_16x16x32_bf16 v[36:39], v[240:243], v[194:197], v[36:39]
	v_mfma_f32_16x16x32_bf16 v[32:35], v[186:189], v[194:197], v[32:35]
	v_mfma_f32_16x16x32_bf16 v[20:23], v[240:243], v[224:227], v[20:23]
	v_mfma_f32_16x16x32_bf16 v[16:19], v[186:189], v[224:227], v[16:19]
	v_mfma_f32_16x16x32_bf16 v[4:7], v[240:243], v[232:235], v[4:7]
	v_mfma_f32_16x16x32_bf16 v[0:3], v[186:189], v[232:235], v[0:3]
	v_mfma_f32_16x16x32_bf16 v[52:55], v[244:247], v[190:193], v[52:55]
	v_mfma_f32_16x16x32_bf16 v[48:51], v[214:217], v[190:193], v[48:51]
	v_mfma_f32_16x16x32_bf16 v[36:39], v[244:247], v[220:223], v[36:39]
	v_mfma_f32_16x16x32_bf16 v[32:35], v[214:217], v[220:223], v[32:35]
	v_mfma_f32_16x16x32_bf16 v[20:23], v[244:247], v[228:231], v[20:23]
	v_mfma_f32_16x16x32_bf16 v[16:19], v[214:217], v[228:231], v[16:19]
	v_mfma_f32_16x16x32_bf16 v[4:7], v[244:247], v[236:239], v[4:7]
	v_mfma_f32_16x16x32_bf16 v[0:3], v[214:217], v[236:239], v[0:3]
	s_add_i32 s41, 0, 0x18000
	v_add_u32_e32 v156, s41, v167
	s_barrier
	ds_read_b128 v[128:131], v156
	ds_read_b128 v[132:135], v156 offset:1024
	ds_read_b128 v[150:153], v156 offset:2048
	ds_read_b128 v[174:177], v156 offset:3072
	s_add_u32 s18, s18, 0x80000
	s_addc_u32 s19, s19, 0
	s_mov_b32 m0, s26
	ds_read_b128 v[182:185], v219 offset:32768
	ds_read_b128 v[186:189], v219 offset:33792
	ds_read_b128 v[190:193], v219 offset:34816
	ds_read_b128 v[194:197], v219 offset:35840
	ds_read_b128 v[214:217], v219 offset:36864
	ds_read_b128 v[220:223], v219 offset:37888
	ds_read_b128 v[224:227], v219 offset:38912
	ds_read_b128 v[228:231], v219 offset:39936
	global_load_lds_dwordx4 v142, s[18:19]
	s_mov_b32 m0, s27
	s_nop 0
	global_load_lds_dwordx4 v138, s[18:19]
	s_waitcnt lgkmcnt(8)
	s_barrier
	s_waitcnt lgkmcnt(7)
	v_mfma_f32_16x16x32_bf16 v[124:127], v[128:131], v[182:185], v[124:127]
	v_mfma_f32_16x16x32_bf16 v[120:123], v[150:153], v[182:185], v[120:123]
	s_waitcnt lgkmcnt(5)
	v_mfma_f32_16x16x32_bf16 v[108:111], v[128:131], v[190:193], v[108:111]
	v_mfma_f32_16x16x32_bf16 v[104:107], v[150:153], v[190:193], v[104:107]
	s_waitcnt lgkmcnt(3)
	v_mfma_f32_16x16x32_bf16 v[92:95], v[128:131], v[214:217], v[92:95]
	v_mfma_f32_16x16x32_bf16 v[88:91], v[150:153], v[214:217], v[88:91]
	s_waitcnt lgkmcnt(1)
	v_mfma_f32_16x16x32_bf16 v[76:79], v[128:131], v[224:227], v[76:79]
	v_mfma_f32_16x16x32_bf16 v[72:75], v[150:153], v[224:227], v[72:75]
	v_mfma_f32_16x16x32_bf16 v[124:127], v[132:135], v[186:189], v[124:127]
	v_mfma_f32_16x16x32_bf16 v[120:123], v[174:177], v[186:189], v[120:123]
	v_mfma_f32_16x16x32_bf16 v[108:111], v[132:135], v[194:197], v[108:111]
	v_mfma_f32_16x16x32_bf16 v[104:107], v[174:177], v[194:197], v[104:107]
	v_mfma_f32_16x16x32_bf16 v[92:95], v[132:135], v[220:223], v[92:95]
	v_mfma_f32_16x16x32_bf16 v[88:91], v[174:177], v[220:223], v[88:91]
	s_waitcnt lgkmcnt(0)
	v_mfma_f32_16x16x32_bf16 v[76:79], v[132:135], v[228:231], v[76:79]
	v_mfma_f32_16x16x32_bf16 v[72:75], v[174:177], v[228:231], v[72:75]
	s_barrier
	s_add_i32 s18, 0, 0x1c000
	s_add_i32 s19, s41, s22
	v_add_u32_e32 v156, s18, v167
	v_lshl_add_u64 v[154:155], v[154:155], 0, s[2:3]
	s_mov_b32 m0, s19
	ds_read_b128 v[232:235], v156
	ds_read_b128 v[236:239], v156 offset:1024
	ds_read_b128 v[240:243], v156 offset:2048
	ds_read_b128 v[244:247], v156 offset:3072
	global_load_lds_dwordx4 v[154:155], off
	v_lshl_add_u64 v[154:155], v[158:159], 0, s[2:3]
	s_add_i32 m0, s19, 0x2000
	s_nop 0
	global_load_lds_dwordx4 v[154:155], off
	s_barrier
	s_waitcnt lgkmcnt(3)
	v_mfma_f32_16x16x32_bf16 v[116:119], v[232:235], v[182:185], v[116:119]
	s_waitcnt lgkmcnt(1)
	v_mfma_f32_16x16x32_bf16 v[112:115], v[240:243], v[182:185], v[112:115]
	v_mfma_f32_16x16x32_bf16 v[100:103], v[232:235], v[190:193], v[100:103]
	v_mfma_f32_16x16x32_bf16 v[96:99], v[240:243], v[190:193], v[96:99]
	v_mfma_f32_16x16x32_bf16 v[84:87], v[232:235], v[214:217], v[84:87]
	v_mfma_f32_16x16x32_bf16 v[80:83], v[240:243], v[214:217], v[80:83]
	v_mfma_f32_16x16x32_bf16 v[68:71], v[232:235], v[224:227], v[68:71]
	v_mfma_f32_16x16x32_bf16 v[64:67], v[240:243], v[224:227], v[64:67]
	v_mfma_f32_16x16x32_bf16 v[116:119], v[236:239], v[186:189], v[116:119]
	s_waitcnt lgkmcnt(0)
	v_mfma_f32_16x16x32_bf16 v[112:115], v[244:247], v[186:189], v[112:115]
	v_mfma_f32_16x16x32_bf16 v[100:103], v[236:239], v[194:197], v[100:103]
	v_mfma_f32_16x16x32_bf16 v[96:99], v[244:247], v[194:197], v[96:99]
	v_mfma_f32_16x16x32_bf16 v[84:87], v[236:239], v[220:223], v[84:87]
	v_mfma_f32_16x16x32_bf16 v[80:83], v[244:247], v[220:223], v[80:83]
	v_mfma_f32_16x16x32_bf16 v[68:71], v[236:239], v[228:231], v[68:71]
	v_mfma_f32_16x16x32_bf16 v[64:67], v[244:247], v[228:231], v[64:67]
	s_mov_b32 m0, s28
	v_lshl_add_u64 v[154:155], v[178:179], 0, s[2:3]
	s_barrier
	ds_read_b128 v[182:185], v219 offset:49152
	ds_read_b128 v[186:189], v219 offset:50176
	ds_read_b128 v[190:193], v219 offset:51200
	ds_read_b128 v[194:197], v219 offset:52224
	ds_read_b128 v[214:217], v219 offset:53248
	ds_read_b128 v[220:223], v219 offset:54272
	ds_read_b128 v[224:227], v219 offset:55296
	ds_read_b128 v[228:231], v219 offset:56320
	global_load_lds_dwordx4 v[154:155], off
	v_lshl_add_u64 v[154:155], v[248:249], 0, s[2:3]
	s_mov_b32 m0, s29
	s_nop 0
	global_load_lds_dwordx4 v[154:155], off
	s_barrier
; #define PG8_STAGE(bufoff, gbase, voff) do { _Pragma("unroll") for (int _i = 0; _i < 2; ++_i) \
;         __builtin_amdgcn_global_load_lds((const unsigned*)((const char*)(gbase) + (voff)[_i]), (LAS unsigned*)(lds + (bufoff) + ldsw + _i * 8192), 16, 0, 0); } while (0)
; #define PG8_MMA(ai, bj, At, Bt) do { __builtin_amdgcn_s_setprio(1); _Pragma("unroll") for (int m = 0; m < 4; ++m) _Pragma("unroll") for (int n = 0; n < 2; ++n) _Pragma("unroll") for (int k = 0; k < 2; ++k) \
;         acc[ai][bj][m][n] = __builtin_amdgcn_mfma_f32_16x16x32_bf16(Bt[n][k], At[m][k], acc[ai][bj][m][n], 0, 0, 0); __builtin_amdgcn_s_setprio(0); } while (0)
; #define PG8_WAIT_V(n) asm volatile("s_waitcnt vmcnt(" #n ")" ::: "memory")
; #define PG8_WAIT_L(n) asm volatile("s_waitcnt lgkmcnt(" #n ")" ::: "memory")
; #define PG8_BAR __builtin_amdgcn_s_barrier()
; #define PG8_SCHED __builtin_amdgcn_sched_barrier(0)
;     DEV void operator()(AccRef acc, const pg8::Unit& u, int wr, int wc, int fr, int fq) const { store_bf16_tile<0, false>(acc, O, ld, u.pm * 256 + wr * 64 + fr, u.pn * 256 + wc * 32 + 4 * fq, ss); }
; template <class Epi>
; DEV void gemm_phase(LAS unsigned char* lds, const Gemm g, const StaticOrder& S, const Epi& E) {
;     ...
;             PG8_BAR; PG8_WAIT_L(0); PG8_MMA(1, 0, At, B0); PG8_BAR; PG8_SCHED;
;             PG8_STAGE(PG8_SB(1, 1), b3 + hstep, voffB);
;             PG8_WAIT_V(6); PG8_BAR; PG8_MMA(1, 1, At, B1); PG8_BAR;
;     DEV void operator()(AccRef acc, const pg8::Unit& u, int wr, int wc, int fr, int fq) const {
;         const int ct = u.pn * 256, row0 = u.pm * 256 + wr * 64 + fr, cw = wc * 32 + 8 * fq;
;         if (ct < 4096) store_bf16_tile<1, true>(acc, UV, 4096, row0, ct + cw, ss);
;         else if (ct < 6144) store_bf16_tile<0, true>(acc, Z, 2048, row0, ct - 4096 + cw, ss);
;         else if (ct < 9216) store_bf16_tile<0, true>(acc, XBC, 3072, row0, ct - 6144 + cw, ss);
;         else if (wc == 0) {
; #pragma unroll
;             for (int ai = 0; ai < 2; ++ai)
; #pragma unroll
;                 for (int m = 0; m < 4; ++m) { const float rs = rowscale(ss, row0 + ai * 128 + m * 16);
; #pragma unroll
;                     for (int n = 0; n < 2; ++n) *(f32x4*)(DTR + (size_t)(row0 + ai * 128 + m * 16) * 32 + 8 * fq + 4 * n) = acc[ai][0][m][n] * rs; }
	s_waitcnt lgkmcnt(7)
	v_mfma_f32_16x16x32_bf16 v[60:63], v[128:131], v[182:185], v[60:63]
	v_mfma_f32_16x16x32_bf16 v[56:59], v[150:153], v[182:185], v[56:59]
	s_waitcnt lgkmcnt(5)
	v_mfma_f32_16x16x32_bf16 v[44:47], v[128:131], v[190:193], v[44:47]
	v_mfma_f32_16x16x32_bf16 v[40:43], v[150:153], v[190:193], v[40:43]
	s_waitcnt lgkmcnt(3)
	v_mfma_f32_16x16x32_bf16 v[28:31], v[128:131], v[214:217], v[28:31]
	v_mfma_f32_16x16x32_bf16 v[24:27], v[150:153], v[214:217], v[24:27]
	s_waitcnt lgkmcnt(1)
	v_mfma_f32_16x16x32_bf16 v[12:15], v[128:131], v[224:227], v[12:15]
	v_mfma_f32_16x16x32_bf16 v[8:11], v[150:153], v[224:227], v[8:11]
	v_mfma_f32_16x16x32_bf16 v[60:63], v[132:135], v[186:189], v[60:63]
	v_mfma_f32_16x16x32_bf16 v[56:59], v[174:177], v[186:189], v[56:59]
	v_mfma_f32_16x16x32_bf16 v[44:47], v[132:135], v[194:197], v[44:47]
	v_mfma_f32_16x16x32_bf16 v[40:43], v[174:177], v[194:197], v[40:43]
	v_mfma_f32_16x16x32_bf16 v[28:31], v[132:135], v[220:223], v[28:31]
	v_mfma_f32_16x16x32_bf16 v[24:27], v[174:177], v[220:223], v[24:27]
	s_waitcnt lgkmcnt(0)
	v_mfma_f32_16x16x32_bf16 v[12:15], v[132:135], v[228:231], v[12:15]
	v_mfma_f32_16x16x32_bf16 v[8:11], v[174:177], v[228:231], v[8:11]
	s_barrier
	s_add_u32 s16, s16, 0x80080
	s_addc_u32 s17, s17, 0
	s_add_i32 s18, s18, s22
	s_mov_b32 m0, s18
	s_nop 0
	global_load_lds_dwordx4 v140, s[16:17]
	s_add_i32 m0, s18, 0x2000
	s_nop 0
	global_load_lds_dwordx4 v136, s[16:17]
	s_waitcnt vmcnt(6)
	s_barrier
	v_mfma_f32_16x16x32_bf16 v[52:55], v[232:235], v[182:185], v[52:55]
	v_mfma_f32_16x16x32_bf16 v[48:51], v[240:243], v[182:185], v[48:51]
	v_mfma_f32_16x16x32_bf16 v[36:39], v[232:235], v[190:193], v[36:39]
	v_mfma_f32_16x16x32_bf16 v[32:35], v[240:243], v[190:193], v[32:35]
	v_mfma_f32_16x16x32_bf16 v[20:23], v[232:235], v[214:217], v[20:23]
	v_mfma_f32_16x16x32_bf16 v[16:19], v[240:243], v[214:217], v[16:19]
	v_mfma_f32_16x16x32_bf16 v[4:7], v[232:235], v[224:227], v[4:7]
	v_mfma_f32_16x16x32_bf16 v[0:3], v[240:243], v[224:227], v[0:3]
	v_mfma_f32_16x16x32_bf16 v[52:55], v[236:239], v[186:189], v[52:55]
	v_mfma_f32_16x16x32_bf16 v[48:51], v[244:247], v[186:189], v[48:51]
	v_mfma_f32_16x16x32_bf16 v[36:39], v[236:239], v[194:197], v[36:39]
	v_mfma_f32_16x16x32_bf16 v[32:35], v[244:247], v[194:197], v[32:35]
	v_mfma_f32_16x16x32_bf16 v[20:23], v[236:239], v[220:223], v[20:23]
	v_mfma_f32_16x16x32_bf16 v[16:19], v[244:247], v[220:223], v[16:19]
	v_mfma_f32_16x16x32_bf16 v[4:7], v[236:239], v[228:231], v[4:7]
	v_mfma_f32_16x16x32_bf16 v[0:3], v[244:247], v[228:231], v[0:3]
	s_add_i32 s40, s40, 2
	s_add_u32 s14, s14, 0x100
	s_addc_u32 s15, s15, 0
	s_add_u32 s36, s36, 0x100
	s_addc_u32 s37, s37, 0
	s_cmp_gt_u32 s40, 29
	s_barrier
	s_cbranch_scc0 .LBB0_588
	s_lshl_b32 s7, s34, 8
	v_lshl_add_u32 v150, s0, 8, v157
	s_cmp_gt_i32 s34, 15
	s_mov_b64 s[0:1], -1
	s_cbranch_scc0 .LBB0_601
	s_cmp_gt_u32 s34, 23
	s_cbranch_scc0 .LBB0_598
	s_cmp_gt_u32 s34, 35
	s_cbranch_scc0 .LBB0_595
	s_andn2_b64 vcc, exec, s[4:5]
	s_cbranch_vccnz .LBB0_594
	v_ashrrev_i32_e32 v151, 31, v150
	v_readlane_b32 s0, v251, 39
	v_lshlrev_b64 v[128:129], 5, v[150:151]
	v_readlane_b32 s1, v251, 40
	s_mov_b32 s9, 0x800000
	s_nop 0
	v_lshl_add_u64 v[132:133], s[0:1], 0, v[128:129]
	global_load_dwordx4 v[128:131], v[132:133], off offset:16
	s_nop 0
	global_load_dwordx4 v[132:135], v[132:133], off
	s_waitcnt vmcnt(0)
	v_mov_b32_e32 v152, v133
	v_mov_b32_e32 v153, v134
	v_mov_b32_e32 v133, v135
	v_pk_add_f32 v[132:133], v[152:153], v[132:133]
	v_mov_b32_e32 v134, v130
	v_mov_b32_e32 v135, v128
	v_mov_b32_e32 v128, v131
	v_pk_add_f32 v[128:129], v[134:135], v[128:129]
	v_add_f32_e32 v130, v132, v133
	v_add_f32_e32 v129, v130, v129
	v_add_f32_e32 v128, v128, v129
	v_fmamk_f32 v128, v128, 0x3a000000, v199
	v_cmp_gt_f32_e32 vcc, s9, v128
	v_mul_f32_e32 v129, 0x4b800000, v128
	v_lshlrev_b64 v[134:135], 7, v[150:151]
	v_cndmask_b32_e32 v128, v128, v129, vcc
	v_rsq_f32_e32 v128, v128
	v_lshl_add_u64 v[134:135], v[144:145], 0, v[134:135]
	v_or_b32_e32 v152, 16, v150
	v_ashrrev_i32_e32 v153, 31, v152
	v_mul_f32_e32 v129, 0x45800000, v128
	v_cndmask_b32_e32 v132, v128, v129, vcc
	v_pk_mul_f32 v[130:131], v[126:127], v[132:133] op_sel_hi:[1,0]
	v_pk_mul_f32 v[128:129], v[124:125], v[132:133] op_sel_hi:[1,0]
	global_store_dwordx4 v[134:135], v[128:131], off
	s_nop 1
	v_pk_mul_f32 v[130:131], v[122:123], v[132:133] op_sel_hi:[1,0]
	v_pk_mul_f32 v[128:129], v[120:121], v[132:133] op_sel_hi:[1,0]
	global_store_dwordx4 v[134:135], v[128:131], off offset:16
	s_nop 1
	v_lshlrev_b64 v[128:129], 5, v[152:153]
	v_lshl_add_u64 v[132:133], s[0:1], 0, v[128:129]
	global_load_dwordx4 v[128:131], v[132:133], off offset:16
	s_nop 0
	global_load_dwordx4 v[132:135], v[132:133], off
	s_waitcnt vmcnt(0)
	v_mov_b32_e32 v154, v133
	v_mov_b32_e32 v155, v134
	v_mov_b32_e32 v133, v135
	v_pk_add_f32 v[132:133], v[154:155], v[132:133]
	v_mov_b32_e32 v134, v130
	v_mov_b32_e32 v135, v128
	v_mov_b32_e32 v128, v131
	v_pk_add_f32 v[128:129], v[134:135], v[128:129]
	v_add_f32_e32 v130, v132, v133
	v_add_f32_e32 v129, v130, v129
	v_add_f32_e32 v128, v128, v129
	v_fmamk_f32 v128, v128, 0x3a000000, v199
	v_cmp_gt_f32_e32 vcc, s9, v128
	v_mul_f32_e32 v129, 0x4b800000, v128
	v_lshlrev_b64 v[134:135], 7, v[152:153]
	v_cndmask_b32_e32 v128, v128, v129, vcc
	v_rsq_f32_e32 v128, v128
	v_lshl_add_u64 v[134:135], v[144:145], 0, v[134:135]
	v_or_b32_e32 v152, 32, v150
	v_ashrrev_i32_e32 v153, 31, v152
	v_mul_f32_e32 v129, 0x45800000, v128
	v_cndmask_b32_e32 v132, v128, v129, vcc
	v_pk_mul_f32 v[130:131], v[110:111], v[132:133] op_sel_hi:[1,0]
	v_pk_mul_f32 v[128:129], v[108:109], v[132:133] op_sel_hi:[1,0]
	global_store_dwordx4 v[134:135], v[128:131], off
	s_nop 1
	v_pk_mul_f32 v[130:131], v[106:107], v[132:133] op_sel_hi:[1,0]
	v_pk_mul_f32 v[128:129], v[104:105], v[132:133] op_sel_hi:[1,0]
	global_store_dwordx4 v[134:135], v[128:131], off offset:16
	s_nop 1
	v_lshlrev_b64 v[128:129], 5, v[152:153]
	v_lshl_add_u64 v[132:133], s[0:1], 0, v[128:129]
	global_load_dwordx4 v[128:131], v[132:133], off offset:16
	s_nop 0
	global_load_dwordx4 v[132:135], v[132:133], off
	s_waitcnt vmcnt(0)
; DEV float rowscale(const float* ss, int row) { const f32x4 a = *(const f32x4*)(ss + (size_t)row * 8), b = *(const f32x4*)(ss + (size_t)row * 8 + 4);
;     return rsqrtf(((a[0] + a[1]) + (a[2] + a[3]) + (b[0] + b[1]) + (b[2] + b[3])) * (1.0f / 2048.0f) + EPS); }
;     DEV void operator()(AccRef acc, const pg8::Unit& u, int wr, int wc, int fr, int fq) const {
;     ...
;         else if (wc == 0) {
; #pragma unroll
;             for (int ai = 0; ai < 2; ++ai)
; #pragma unroll
;                 for (int m = 0; m < 4; ++m) { const float rs = rowscale(ss, row0 + ai * 128 + m * 16);
; #pragma unroll
;                     for (int n = 0; n < 2; ++n) *(f32x4*)(DTR + (size_t)(row0 + ai * 128 + m * 16) * 32 + 8 * fq + 4 * n) = acc[ai][0][m][n] * rs; }
	v_mov_b32_e32 v154, v133
	v_mov_b32_e32 v155, v134
	v_mov_b32_e32 v133, v135
	v_pk_add_f32 v[132:133], v[154:155], v[132:133]
	v_mov_b32_e32 v134, v130
	v_mov_b32_e32 v135, v128
	v_mov_b32_e32 v128, v131
	v_pk_add_f32 v[128:129], v[134:135], v[128:129]
	v_add_f32_e32 v130, v132, v133
	v_add_f32_e32 v129, v130, v129
	v_add_f32_e32 v128, v128, v129
	v_fmamk_f32 v128, v128, 0x3a000000, v199
	v_cmp_gt_f32_e32 vcc, s9, v128
	v_mul_f32_e32 v129, 0x4b800000, v128
	v_lshlrev_b64 v[134:135], 7, v[152:153]
	v_cndmask_b32_e32 v128, v128, v129, vcc
	v_rsq_f32_e32 v128, v128
	v_lshl_add_u64 v[134:135], v[144:145], 0, v[134:135]
	v_or_b32_e32 v152, 48, v150
	v_ashrrev_i32_e32 v153, 31, v152
	v_mul_f32_e32 v129, 0x45800000, v128
	v_cndmask_b32_e32 v132, v128, v129, vcc
	v_pk_mul_f32 v[130:131], v[94:95], v[132:133] op_sel_hi:[1,0]
	v_pk_mul_f32 v[128:129], v[92:93], v[132:133] op_sel_hi:[1,0]
	global_store_dwordx4 v[134:135], v[128:131], off
	s_nop 1
	v_pk_mul_f32 v[130:131], v[90:91], v[132:133] op_sel_hi:[1,0]
	v_pk_mul_f32 v[128:129], v[88:89], v[132:133] op_sel_hi:[1,0]
	global_store_dwordx4 v[134:135], v[128:131], off offset:16
	s_nop 1
	v_lshlrev_b64 v[128:129], 5, v[152:153]
	v_lshl_add_u64 v[132:133], s[0:1], 0, v[128:129]
	global_load_dwordx4 v[128:131], v[132:133], off offset:16
	s_nop 0
	global_load_dwordx4 v[132:135], v[132:133], off
	s_waitcnt vmcnt(0)
	v_mov_b32_e32 v154, v133
	v_mov_b32_e32 v155, v134
	v_mov_b32_e32 v133, v135
	v_pk_add_f32 v[132:133], v[154:155], v[132:133]
	v_mov_b32_e32 v134, v130
	v_mov_b32_e32 v135, v128
	v_mov_b32_e32 v128, v131
	v_pk_add_f32 v[128:129], v[134:135], v[128:129]
	v_add_f32_e32 v130, v132, v133
	v_add_f32_e32 v129, v130, v129
	v_add_f32_e32 v128, v128, v129
	v_fmamk_f32 v128, v128, 0x3a000000, v199
	v_cmp_gt_f32_e32 vcc, s9, v128
	v_mul_f32_e32 v129, 0x4b800000, v128
	v_lshlrev_b64 v[134:135], 7, v[152:153]
	v_cndmask_b32_e32 v128, v128, v129, vcc
	v_rsq_f32_e32 v128, v128
	v_lshl_add_u64 v[134:135], v[144:145], 0, v[134:135]
	v_add_u32_e32 v152, 0x80, v150
	v_ashrrev_i32_e32 v153, 31, v152
	v_mul_f32_e32 v129, 0x45800000, v128
	v_cndmask_b32_e32 v132, v128, v129, vcc
	v_pk_mul_f32 v[130:131], v[78:79], v[132:133] op_sel_hi:[1,0]
	v_pk_mul_f32 v[128:129], v[76:77], v[132:133] op_sel_hi:[1,0]
	global_store_dwordx4 v[134:135], v[128:131], off
	s_nop 1
	v_pk_mul_f32 v[130:131], v[74:75], v[132:133] op_sel_hi:[1,0]
	v_pk_mul_f32 v[128:129], v[72:73], v[132:133] op_sel_hi:[1,0]
	global_store_dwordx4 v[134:135], v[128:131], off offset:16
	s_nop 1
	v_lshlrev_b64 v[128:129], 5, v[152:153]
	v_lshl_add_u64 v[132:133], s[0:1], 0, v[128:129]
	global_load_dwordx4 v[128:131], v[132:133], off offset:16
	s_nop 0
	global_load_dwordx4 v[132:135], v[132:133], off
	s_waitcnt vmcnt(0)
	v_mov_b32_e32 v154, v133
	v_mov_b32_e32 v155, v134
	v_mov_b32_e32 v133, v135
	v_pk_add_f32 v[132:133], v[154:155], v[132:133]
	v_mov_b32_e32 v134, v130
	v_mov_b32_e32 v135, v128
	v_mov_b32_e32 v128, v131
	v_pk_add_f32 v[128:129], v[134:135], v[128:129]
	v_add_f32_e32 v130, v132, v133
	v_add_f32_e32 v129, v130, v129
	v_add_f32_e32 v128, v128, v129
	v_fmamk_f32 v128, v128, 0x3a000000, v199
	v_cmp_gt_f32_e32 vcc, s9, v128
	v_mul_f32_e32 v129, 0x4b800000, v128
	v_lshlrev_b64 v[134:135], 7, v[152:153]
	v_cndmask_b32_e32 v128, v128, v129, vcc
	v_rsq_f32_e32 v128, v128
	v_lshl_add_u64 v[134:135], v[144:145], 0, v[134:135]
	v_add_u32_e32 v152, 0x90, v150
	v_ashrrev_i32_e32 v153, 31, v152
	v_mul_f32_e32 v129, 0x45800000, v128
	v_cndmask_b32_e32 v132, v128, v129, vcc
	v_pk_mul_f32 v[130:131], v[62:63], v[132:133] op_sel_hi:[1,0]
	v_pk_mul_f32 v[128:129], v[60:61], v[132:133] op_sel_hi:[1,0]
	global_store_dwordx4 v[134:135], v[128:131], off
	s_nop 1
	v_pk_mul_f32 v[130:131], v[58:59], v[132:133] op_sel_hi:[1,0]
	v_pk_mul_f32 v[128:129], v[56:57], v[132:133] op_sel_hi:[1,0]
	global_store_dwordx4 v[134:135], v[128:131], off offset:16
	s_nop 1
	v_lshlrev_b64 v[128:129], 5, v[152:153]
	v_lshl_add_u64 v[132:133], s[0:1], 0, v[128:129]
	global_load_dwordx4 v[128:131], v[132:133], off offset:16
	s_nop 0
	global_load_dwordx4 v[132:135], v[132:133], off
	s_waitcnt vmcnt(0)
; DEV float rowscale(const float* ss, int row) { const f32x4 a = *(const f32x4*)(ss + (size_t)row * 8), b = *(const f32x4*)(ss + (size_t)row * 8 + 4);
;     return rsqrtf(((a[0] + a[1]) + (a[2] + a[3]) + (b[0] + b[1]) + (b[2] + b[3])) * (1.0f / 2048.0f) + EPS); }
;     DEV void operator()(AccRef acc, const pg8::Unit& u, int wr, int wc, int fr, int fq) const {
;     ...
;         else if (wc == 0) {
; #pragma unroll
;             for (int ai = 0; ai < 2; ++ai)
; #pragma unroll
;                 for (int m = 0; m < 4; ++m) { const float rs = rowscale(ss, row0 + ai * 128 + m * 16);
; #pragma unroll
;                     for (int n = 0; n < 2; ++n) *(f32x4*)(DTR + (size_t)(row0 + ai * 128 + m * 16) * 32 + 8 * fq + 4 * n) = acc[ai][0][m][n] * rs; }
	v_mov_b32_e32 v154, v133
	v_mov_b32_e32 v155, v134
	v_mov_b32_e32 v133, v135
	v_pk_add_f32 v[132:133], v[154:155], v[132:133]
	v_mov_b32_e32 v134, v130
	v_mov_b32_e32 v135, v128
	v_mov_b32_e32 v128, v131
	v_pk_add_f32 v[128:129], v[134:135], v[128:129]
	v_add_f32_e32 v130, v132, v133
	v_add_f32_e32 v129, v130, v129
	v_add_f32_e32 v128, v128, v129
	v_fmamk_f32 v128, v128, 0x3a000000, v199
	v_cmp_gt_f32_e32 vcc, s9, v128
	v_mul_f32_e32 v129, 0x4b800000, v128
	v_lshlrev_b64 v[134:135], 7, v[152:153]
	v_cndmask_b32_e32 v128, v128, v129, vcc
	v_rsq_f32_e32 v128, v128
	v_lshl_add_u64 v[134:135], v[144:145], 0, v[134:135]
	v_add_u32_e32 v152, 0xa0, v150
	v_ashrrev_i32_e32 v153, 31, v152
	v_mul_f32_e32 v129, 0x45800000, v128
	v_cndmask_b32_e32 v132, v128, v129, vcc
	v_pk_mul_f32 v[130:131], v[46:47], v[132:133] op_sel_hi:[1,0]
	v_pk_mul_f32 v[128:129], v[44:45], v[132:133] op_sel_hi:[1,0]
	global_store_dwordx4 v[134:135], v[128:131], off
	s_nop 1
	v_pk_mul_f32 v[130:131], v[42:43], v[132:133] op_sel_hi:[1,0]
	v_pk_mul_f32 v[128:129], v[40:41], v[132:133] op_sel_hi:[1,0]
	global_store_dwordx4 v[134:135], v[128:131], off offset:16
	s_nop 1
	v_lshlrev_b64 v[128:129], 5, v[152:153]
	v_lshl_add_u64 v[132:133], s[0:1], 0, v[128:129]
	global_load_dwordx4 v[128:131], v[132:133], off offset:16
	s_nop 0
	global_load_dwordx4 v[132:135], v[132:133], off
	s_waitcnt vmcnt(0)
	v_mov_b32_e32 v154, v133
	v_mov_b32_e32 v155, v134
	v_mov_b32_e32 v133, v135
	v_pk_add_f32 v[132:133], v[154:155], v[132:133]
	v_mov_b32_e32 v134, v130
	v_mov_b32_e32 v135, v128
	v_mov_b32_e32 v128, v131
	v_pk_add_f32 v[128:129], v[134:135], v[128:129]
	v_add_f32_e32 v130, v132, v133
	v_add_f32_e32 v129, v130, v129
	v_add_f32_e32 v128, v128, v129
	v_fmamk_f32 v128, v128, 0x3a000000, v199
	v_cmp_gt_f32_e32 vcc, s9, v128
	v_mul_f32_e32 v129, 0x4b800000, v128
	v_lshlrev_b64 v[134:135], 7, v[152:153]
	v_cndmask_b32_e32 v128, v128, v129, vcc
	v_rsq_f32_e32 v128, v128
	v_lshl_add_u64 v[134:135], v[144:145], 0, v[134:135]
	v_add_u32_e32 v152, 0xb0, v150
	v_ashrrev_i32_e32 v153, 31, v152
	v_mul_f32_e32 v129, 0x45800000, v128
	v_cndmask_b32_e32 v132, v128, v129, vcc
	v_pk_mul_f32 v[130:131], v[30:31], v[132:133] op_sel_hi:[1,0]
	v_pk_mul_f32 v[128:129], v[28:29], v[132:133] op_sel_hi:[1,0]
	global_store_dwordx4 v[134:135], v[128:131], off
	s_nop 1
	v_pk_mul_f32 v[130:131], v[26:27], v[132:133] op_sel_hi:[1,0]
	v_pk_mul_f32 v[128:129], v[24:25], v[132:133] op_sel_hi:[1,0]
	global_store_dwordx4 v[134:135], v[128:131], off offset:16
	s_nop 1
	v_lshlrev_b64 v[128:129], 5, v[152:153]
	v_lshl_add_u64 v[132:133], s[0:1], 0, v[128:129]
	global_load_dwordx4 v[128:131], v[132:133], off offset:16
	s_nop 0
	global_load_dwordx4 v[132:135], v[132:133], off
	s_waitcnt vmcnt(0)
	v_mov_b32_e32 v154, v133
	v_mov_b32_e32 v155, v134
	v_mov_b32_e32 v133, v135
	v_pk_add_f32 v[132:133], v[154:155], v[132:133]
	v_mov_b32_e32 v134, v130
	v_mov_b32_e32 v135, v128
	v_mov_b32_e32 v128, v131
	v_pk_add_f32 v[128:129], v[134:135], v[128:129]
	v_add_f32_e32 v130, v132, v133
	v_add_f32_e32 v129, v130, v129
	v_add_f32_e32 v128, v128, v129
	v_fmamk_f32 v128, v128, 0x3a000000, v199
	v_cmp_gt_f32_e32 vcc, s9, v128
	v_mul_f32_e32 v129, 0x4b800000, v128
	v_lshlrev_b64 v[134:135], 7, v[152:153]
	v_cndmask_b32_e32 v128, v128, v129, vcc
	v_rsq_f32_e32 v128, v128
	v_lshl_add_u64 v[134:135], v[144:145], 0, v[134:135]
	v_mul_f32_e32 v129, 0x45800000, v128
	v_cndmask_b32_e32 v132, v128, v129, vcc
	v_pk_mul_f32 v[130:131], v[14:15], v[132:133] op_sel_hi:[1,0]
	v_pk_mul_f32 v[128:129], v[12:13], v[132:133] op_sel_hi:[1,0]
	global_store_dwordx4 v[134:135], v[128:131], off
	s_nop 1
	v_pk_mul_f32 v[130:131], v[10:11], v[132:133] op_sel_hi:[1,0]
	v_pk_mul_f32 v[128:129], v[8:9], v[132:133] op_sel_hi:[1,0]
	global_store_dwordx4 v[134:135], v[128:131], off offset:16

; #define PG8_STAGE(bufoff, gbase, voff) do { _Pragma("unroll") for (int _i = 0; _i < 2; ++_i) \
;         __builtin_amdgcn_global_load_lds((const unsigned*)((const char*)(gbase) + (voff)[_i]), (LAS unsigned*)(lds + (bufoff) + ldsw + _i * 8192), 16, 0, 0); } while (0)
; #define PG8_LDA(dst, b, h) do { _Pragma("unroll") for (int m = 0; m < 4; ++m) _Pragma("unroll") for (int k = 0; k < 2; ++k) dst[m][k] = *(const LAS bf16x8*)(lds + PG8_SA(b, h) + aoff + m * 2048 + k * 1024); } while (0)
; #define PG8_LDB(dst, b, h) do { _Pragma("unroll") for (int n = 0; n < 2; ++n) _Pragma("unroll") for (int k = 0; k < 2; ++k) dst[n][k] = *(const LAS bf16x8*)(lds + PG8_SB(b, h) + boff + n * 2048 + k * 1024); } while (0)
; #define PG8_MMA(ai, bj, At, Bt) do { __builtin_amdgcn_s_setprio(1); _Pragma("unroll") for (int m = 0; m < 4; ++m) _Pragma("unroll") for (int n = 0; n < 2; ++n) _Pragma("unroll") for (int k = 0; k < 2; ++k) \
;         acc[ai][bj][m][n] = __builtin_amdgcn_mfma_f32_16x16x32_bf16(Bt[n][k], At[m][k], acc[ai][bj][m][n], 0, 0, 0); __builtin_amdgcn_s_setprio(0); } while (0)
; #define PG8_WAIT_L(n) asm volatile("s_waitcnt lgkmcnt(" #n ")" ::: "memory")
; #define PG8_BAR __builtin_amdgcn_s_barrier()
; #define PG8_SCHED __builtin_amdgcn_sched_barrier(0)
; template <class Epi>
; DEV void gemm_phase(LAS unsigned char* lds, const Gemm g, const StaticOrder& S, const Epi& E) {
;     ...
;             PG8_LDB(B0, 0, 0); PG8_SCHED; PG8_LDA(At, 0, 0); PG8_STAGE(PG8_SA(1, 1), a1 + hstep, voffA);
;             PG8_WAIT_L(8); PG8_BAR; PG8_WAIT_L(0); PG8_MMA(0, 0, At, B0); PG8_BAR; PG8_SCHED;
;             PG8_LDB(B1, 0, 1); PG8_STAGE(PG8_SB(0, 0), b2, voffB);
;             PG8_BAR; PG8_WAIT_L(0); PG8_MMA(0, 1, At, B1); PG8_BAR;
;             PG8_LDA(At, 0, 1); PG8_STAGE(PG8_SA(0, 0), a2, voffA);
;             PG8_BAR; PG8_WAIT_L(0); PG8_MMA(1, 0, At, B0); PG8_BAR; PG8_SCHED;
.LBB0_657:
	s_add_u32 s6, s28, 0x100
	s_addc_u32 s7, s29, 0
	s_add_i32 s55, 0, 0x10000
	v_add_u32_e32 v140, s55, v196
	ds_read_b128 v[128:131], v140
	ds_read_b128 v[132:135], v140 offset:1024
	ds_read_b128 v[136:139], v140 offset:2048
	ds_read_b128 v[140:143], v140 offset:3072
	s_cmpk_eq_i32 s54, 0x54
	s_cselect_b32 s35, s27, s7
	s_cselect_b32 s34, s26, s6
	s_cselect_b32 s31, s9, s53
	s_cselect_b32 s30, s8, s52
	s_add_i32 m0, s41, 0xc000
	ds_read_b128 v[144:147], v219
	ds_read_b128 v[148:151], v219 offset:1024
	ds_read_b128 v[152:155], v219 offset:2048
	ds_read_b128 v[156:159], v219 offset:3072
	ds_read_b128 v[184:187], v219 offset:4096
	ds_read_b128 v[188:191], v219 offset:5120
	ds_read_b128 v[192:195], v219 offset:6144
	ds_read_b128 v[220:223], v219 offset:7168
	global_load_lds_dwordx4 v180, s[28:29]
	s_add_i32 m0, s41, 0xe000
	s_nop 0
	global_load_lds_dwordx4 v182, s[28:29]
	s_waitcnt lgkmcnt(8)
	s_barrier
	s_waitcnt lgkmcnt(7)
	v_mfma_f32_16x16x32_bf16 v[124:127], v[128:131], v[144:147], v[124:127]
	v_mfma_f32_16x16x32_bf16 v[120:123], v[136:139], v[144:147], v[120:123]
	s_waitcnt lgkmcnt(5)
	v_mfma_f32_16x16x32_bf16 v[112:115], v[128:131], v[152:155], v[112:115]
	v_mfma_f32_16x16x32_bf16 v[104:107], v[136:139], v[152:155], v[104:107]
	s_waitcnt lgkmcnt(3)
	v_mfma_f32_16x16x32_bf16 v[92:95], v[128:131], v[184:187], v[92:95]
	v_mfma_f32_16x16x32_bf16 v[88:91], v[136:139], v[184:187], v[88:91]
	s_waitcnt lgkmcnt(1)
	v_mfma_f32_16x16x32_bf16 v[80:83], v[128:131], v[192:195], v[80:83]
	v_mfma_f32_16x16x32_bf16 v[72:75], v[136:139], v[192:195], v[72:75]
	v_mfma_f32_16x16x32_bf16 v[124:127], v[132:135], v[148:151], v[124:127]
	v_mfma_f32_16x16x32_bf16 v[120:123], v[140:143], v[148:151], v[120:123]
	v_mfma_f32_16x16x32_bf16 v[112:115], v[132:135], v[156:159], v[112:115]
	v_mfma_f32_16x16x32_bf16 v[104:107], v[140:143], v[156:159], v[104:107]
	v_mfma_f32_16x16x32_bf16 v[92:95], v[132:135], v[188:191], v[92:95]
	v_mfma_f32_16x16x32_bf16 v[88:91], v[140:143], v[188:191], v[88:91]
	s_waitcnt lgkmcnt(0)
	v_mfma_f32_16x16x32_bf16 v[80:83], v[132:135], v[220:223], v[80:83]
	v_mfma_f32_16x16x32_bf16 v[72:75], v[140:143], v[220:223], v[72:75]
	s_barrier
	s_add_i32 s56, 0, 0x14000
	v_add_u32_e32 v214, s56, v196
	s_add_i32 s28, s55, s40
	ds_read_b128 v[224:227], v214
	ds_read_b128 v[228:231], v214 offset:1024
	ds_read_b128 v[232:235], v214 offset:2048
	ds_read_b128 v[236:239], v214 offset:3072
	v_lshl_add_u64 v[214:215], s[30:31], 0, v[160:161]
	s_mov_b32 m0, s28
	v_lshl_add_u64 v[216:217], s[30:31], 0, v[178:179]
	global_load_lds_dwordx4 v160, s[30:31]
	s_add_i32 m0, s28, 0x2000
	s_nop 0
	global_load_lds_dwordx4 v178, s[30:31]
	s_barrier
	s_waitcnt lgkmcnt(3)
	v_mfma_f32_16x16x32_bf16 v[116:119], v[224:227], v[144:147], v[116:119]
	s_waitcnt lgkmcnt(1)
	v_mfma_f32_16x16x32_bf16 v[108:111], v[232:235], v[144:147], v[108:111]
	v_mfma_f32_16x16x32_bf16 v[100:103], v[224:227], v[152:155], v[100:103]
	v_mfma_f32_16x16x32_bf16 v[96:99], v[232:235], v[152:155], v[96:99]
	v_mfma_f32_16x16x32_bf16 v[84:87], v[224:227], v[184:187], v[84:87]
	v_mfma_f32_16x16x32_bf16 v[76:79], v[232:235], v[184:187], v[76:79]
	v_mfma_f32_16x16x32_bf16 v[68:71], v[224:227], v[192:195], v[68:71]
	v_mfma_f32_16x16x32_bf16 v[64:67], v[232:235], v[192:195], v[64:67]
	v_mfma_f32_16x16x32_bf16 v[116:119], v[228:231], v[148:151], v[116:119]
	s_waitcnt lgkmcnt(0)
	v_mfma_f32_16x16x32_bf16 v[108:111], v[236:239], v[148:151], v[108:111]
	v_mfma_f32_16x16x32_bf16 v[100:103], v[228:231], v[156:159], v[100:103]
	v_mfma_f32_16x16x32_bf16 v[96:99], v[236:239], v[156:159], v[96:99]
	v_mfma_f32_16x16x32_bf16 v[84:87], v[228:231], v[188:191], v[84:87]
	v_mfma_f32_16x16x32_bf16 v[76:79], v[236:239], v[188:191], v[76:79]
	v_mfma_f32_16x16x32_bf16 v[68:71], v[228:231], v[220:223], v[68:71]
	v_mfma_f32_16x16x32_bf16 v[64:67], v[236:239], v[220:223], v[64:67]
	s_mov_b32 m0, s41
	v_lshl_add_u64 v[240:241], s[34:35], 0, v[174:175]
	s_barrier
	ds_read_b128 v[144:147], v219 offset:16384
	ds_read_b128 v[148:151], v219 offset:17408
	ds_read_b128 v[152:155], v219 offset:18432
	ds_read_b128 v[156:159], v219 offset:19456
	ds_read_b128 v[184:187], v219 offset:20480
	ds_read_b128 v[188:191], v219 offset:21504
	ds_read_b128 v[192:195], v219 offset:22528
	ds_read_b128 v[220:223], v219 offset:23552
	global_load_lds_dwordx4 v174, s[34:35]
	v_lshl_add_u64 v[242:243], s[34:35], 0, v[176:177]
	s_mov_b32 m0, s42
	s_nop 0
	global_load_lds_dwordx4 v176, s[34:35]
	s_barrier
	s_waitcnt lgkmcnt(7)
	v_mfma_f32_16x16x32_bf16 v[60:63], v[128:131], v[144:147], v[60:63]
	v_mfma_f32_16x16x32_bf16 v[56:59], v[136:139], v[144:147], v[56:59]
	s_waitcnt lgkmcnt(5)
	v_mfma_f32_16x16x32_bf16 v[48:51], v[128:131], v[152:155], v[48:51]
	v_mfma_f32_16x16x32_bf16 v[40:43], v[136:139], v[152:155], v[40:43]
	s_waitcnt lgkmcnt(3)
	v_mfma_f32_16x16x32_bf16 v[28:31], v[128:131], v[184:187], v[28:31]
	v_mfma_f32_16x16x32_bf16 v[24:27], v[136:139], v[184:187], v[24:27]
	s_waitcnt lgkmcnt(1)
	v_mfma_f32_16x16x32_bf16 v[16:19], v[128:131], v[192:195], v[16:19]
	v_mfma_f32_16x16x32_bf16 v[8:11], v[136:139], v[192:195], v[8:11]
	v_mfma_f32_16x16x32_bf16 v[60:63], v[132:135], v[148:151], v[60:63]
	v_mfma_f32_16x16x32_bf16 v[56:59], v[140:143], v[148:151], v[56:59]
	v_mfma_f32_16x16x32_bf16 v[48:51], v[132:135], v[156:159], v[48:51]
	v_mfma_f32_16x16x32_bf16 v[40:43], v[140:143], v[156:159], v[40:43]
	v_mfma_f32_16x16x32_bf16 v[28:31], v[132:135], v[188:191], v[28:31]
	v_mfma_f32_16x16x32_bf16 v[24:27], v[140:143], v[188:191], v[24:27]
	s_waitcnt lgkmcnt(0)
	v_mfma_f32_16x16x32_bf16 v[16:19], v[132:135], v[220:223], v[16:19]
	v_mfma_f32_16x16x32_bf16 v[8:11], v[140:143], v[220:223], v[8:11]
	s_barrier
; #define PG8_STAGE(bufoff, gbase, voff) do { _Pragma("unroll") for (int _i = 0; _i < 2; ++_i) \
;         __builtin_amdgcn_global_load_lds((const unsigned*)((const char*)(gbase) + (voff)[_i]), (LAS unsigned*)(lds + (bufoff) + ldsw + _i * 8192), 16, 0, 0); } while (0)
; #define PG8_LDA(dst, b, h) do { _Pragma("unroll") for (int m = 0; m < 4; ++m) _Pragma("unroll") for (int k = 0; k < 2; ++k) dst[m][k] = *(const LAS bf16x8*)(lds + PG8_SA(b, h) + aoff + m * 2048 + k * 1024); } while (0)
; #define PG8_LDB(dst, b, h) do { _Pragma("unroll") for (int n = 0; n < 2; ++n) _Pragma("unroll") for (int k = 0; k < 2; ++k) dst[n][k] = *(const LAS bf16x8*)(lds + PG8_SB(b, h) + boff + n * 2048 + k * 1024); } while (0)
; #define PG8_MMA(ai, bj, At, Bt) do { __builtin_amdgcn_s_setprio(1); _Pragma("unroll") for (int m = 0; m < 4; ++m) _Pragma("unroll") for (int n = 0; n < 2; ++n) _Pragma("unroll") for (int k = 0; k < 2; ++k) \
;         acc[ai][bj][m][n] = __builtin_amdgcn_mfma_f32_16x16x32_bf16(Bt[n][k], At[m][k], acc[ai][bj][m][n], 0, 0, 0); __builtin_amdgcn_s_setprio(0); } while (0)
; #define PG8_WAIT_V(n) asm volatile("s_waitcnt vmcnt(" #n ")" ::: "memory")
; #define PG8_WAIT_L(n) asm volatile("s_waitcnt lgkmcnt(" #n ")" ::: "memory")
; #define PG8_BAR __builtin_amdgcn_s_barrier()
; #define PG8_SCHED __builtin_amdgcn_sched_barrier(0)
; template <class Epi>
; DEV void gemm_phase(LAS unsigned char* lds, const Gemm g, const StaticOrder& S, const Epi& E) {
;     ...
;             PG8_STAGE(PG8_SB(0, 1), b2 + hstep, voffB);
;             PG8_WAIT_V(6); PG8_BAR; PG8_MMA(1, 1, At, B1); PG8_BAR;
;             PG8_LDB(B0, 1, 0); PG8_SCHED; PG8_LDA(At, 1, 0); PG8_STAGE(PG8_SA(0, 1), a2 + hstep, voffA);
;             PG8_WAIT_L(8); PG8_BAR; PG8_WAIT_L(0); PG8_MMA(0, 0, At, B0); PG8_BAR; PG8_SCHED;
;             PG8_LDB(B1, 1, 1); PG8_STAGE(PG8_SB(1, 0), b3, voffB);
;             PG8_BAR; PG8_WAIT_L(0); PG8_MMA(0, 1, At, B1); PG8_BAR;
;             PG8_LDA(At, 1, 1); PG8_STAGE(PG8_SA(1, 0), a3, voffA);
	s_add_u32 s28, s30, 0x160000
	s_addc_u32 s29, s31, 0
	s_add_i32 s55, s56, s40
	s_mov_b32 m0, s55
	s_nop 0
	global_load_lds_dwordx4 v160, s[28:29]
	s_add_i32 m0, s55, 0x2000
	s_nop 0
	global_load_lds_dwordx4 v178, s[28:29]
	s_waitcnt vmcnt(6)
	s_barrier
	v_mfma_f32_16x16x32_bf16 v[52:55], v[224:227], v[144:147], v[52:55]
	v_mfma_f32_16x16x32_bf16 v[44:47], v[232:235], v[144:147], v[44:47]
	v_mfma_f32_16x16x32_bf16 v[36:39], v[224:227], v[152:155], v[36:39]
	v_mfma_f32_16x16x32_bf16 v[32:35], v[232:235], v[152:155], v[32:35]
	v_mfma_f32_16x16x32_bf16 v[20:23], v[224:227], v[184:187], v[20:23]
	v_mfma_f32_16x16x32_bf16 v[12:15], v[232:235], v[184:187], v[12:15]
	v_mfma_f32_16x16x32_bf16 v[4:7], v[224:227], v[192:195], v[4:7]
	v_mfma_f32_16x16x32_bf16 v[0:3], v[232:235], v[192:195], v[0:3]
	v_mfma_f32_16x16x32_bf16 v[52:55], v[228:231], v[148:151], v[52:55]
	v_mfma_f32_16x16x32_bf16 v[44:47], v[236:239], v[148:151], v[44:47]
	v_mfma_f32_16x16x32_bf16 v[36:39], v[228:231], v[156:159], v[36:39]
	v_mfma_f32_16x16x32_bf16 v[32:35], v[236:239], v[156:159], v[32:35]
	v_mfma_f32_16x16x32_bf16 v[20:23], v[228:231], v[188:191], v[20:23]
	v_mfma_f32_16x16x32_bf16 v[12:15], v[236:239], v[188:191], v[12:15]
	v_mfma_f32_16x16x32_bf16 v[4:7], v[228:231], v[220:223], v[4:7]
	v_mfma_f32_16x16x32_bf16 v[0:3], v[236:239], v[220:223], v[0:3]
	s_add_i32 s55, 0, 0x18000
	v_add_u32_e32 v140, s55, v196
	s_barrier
	ds_read_b128 v[128:131], v140
	ds_read_b128 v[132:135], v140 offset:1024
	ds_read_b128 v[136:139], v140 offset:2048
	ds_read_b128 v[140:143], v140 offset:3072
	s_add_u32 s28, s34, 0x160000
	s_addc_u32 s29, s35, 0
	s_mov_b32 m0, s43
	ds_read_b128 v[144:147], v219 offset:32768
	ds_read_b128 v[148:151], v219 offset:33792
	ds_read_b128 v[152:155], v219 offset:34816
	ds_read_b128 v[156:159], v219 offset:35840
	ds_read_b128 v[184:187], v219 offset:36864
	ds_read_b128 v[188:191], v219 offset:37888
	ds_read_b128 v[192:195], v219 offset:38912
	ds_read_b128 v[220:223], v219 offset:39936
	global_load_lds_dwordx4 v174, s[28:29]
	s_mov_b32 m0, s44
	s_nop 0
	global_load_lds_dwordx4 v176, s[28:29]
	s_waitcnt lgkmcnt(8)
	s_barrier
	s_waitcnt lgkmcnt(7)
	v_mfma_f32_16x16x32_bf16 v[124:127], v[128:131], v[144:147], v[124:127]
	v_mfma_f32_16x16x32_bf16 v[120:123], v[136:139], v[144:147], v[120:123]
	s_waitcnt lgkmcnt(5)
	v_mfma_f32_16x16x32_bf16 v[112:115], v[128:131], v[152:155], v[112:115]
	v_mfma_f32_16x16x32_bf16 v[104:107], v[136:139], v[152:155], v[104:107]
	s_waitcnt lgkmcnt(3)
	v_mfma_f32_16x16x32_bf16 v[92:95], v[128:131], v[184:187], v[92:95]
	v_mfma_f32_16x16x32_bf16 v[88:91], v[136:139], v[184:187], v[88:91]
	s_waitcnt lgkmcnt(1)
	v_mfma_f32_16x16x32_bf16 v[80:83], v[128:131], v[192:195], v[80:83]
	v_mfma_f32_16x16x32_bf16 v[72:75], v[136:139], v[192:195], v[72:75]
	v_mfma_f32_16x16x32_bf16 v[124:127], v[132:135], v[148:151], v[124:127]
	v_mfma_f32_16x16x32_bf16 v[120:123], v[140:143], v[148:151], v[120:123]
	v_mfma_f32_16x16x32_bf16 v[112:115], v[132:135], v[156:159], v[112:115]
	v_mfma_f32_16x16x32_bf16 v[104:107], v[140:143], v[156:159], v[104:107]
	v_mfma_f32_16x16x32_bf16 v[92:95], v[132:135], v[188:191], v[92:95]
	v_mfma_f32_16x16x32_bf16 v[88:91], v[140:143], v[188:191], v[88:91]
	s_waitcnt lgkmcnt(0)
	v_mfma_f32_16x16x32_bf16 v[80:83], v[132:135], v[220:223], v[80:83]
	v_mfma_f32_16x16x32_bf16 v[72:75], v[140:143], v[220:223], v[72:75]
	s_barrier
	s_add_i32 s34, 0, 0x1c000
	s_add_i32 s28, s55, s40
	v_add_u32_e32 v236, s34, v196
	v_lshl_add_u64 v[214:215], v[214:215], 0, s[2:3]
	s_mov_b32 m0, s28
	ds_read_b128 v[224:227], v236
	ds_read_b128 v[228:231], v236 offset:1024
	ds_read_b128 v[232:235], v236 offset:2048
	ds_read_b128 v[236:239], v236 offset:3072
	global_load_lds_dwordx4 v[214:215], off
	v_lshl_add_u64 v[214:215], v[216:217], 0, s[2:3]
	s_add_i32 m0, s28, 0x2000
	s_nop 0
	global_load_lds_dwordx4 v[214:215], off
	s_barrier
	s_waitcnt lgkmcnt(3)
	v_mfma_f32_16x16x32_bf16 v[116:119], v[224:227], v[144:147], v[116:119]
	s_waitcnt lgkmcnt(1)
	v_mfma_f32_16x16x32_bf16 v[108:111], v[232:235], v[144:147], v[108:111]
	v_mfma_f32_16x16x32_bf16 v[100:103], v[224:227], v[152:155], v[100:103]
	v_mfma_f32_16x16x32_bf16 v[96:99], v[232:235], v[152:155], v[96:99]
	v_mfma_f32_16x16x32_bf16 v[84:87], v[224:227], v[184:187], v[84:87]
	v_mfma_f32_16x16x32_bf16 v[76:79], v[232:235], v[184:187], v[76:79]
	v_mfma_f32_16x16x32_bf16 v[68:71], v[224:227], v[192:195], v[68:71]
	v_mfma_f32_16x16x32_bf16 v[64:67], v[232:235], v[192:195], v[64:67]
	v_mfma_f32_16x16x32_bf16 v[116:119], v[228:231], v[148:151], v[116:119]
	s_waitcnt lgkmcnt(0)
	v_mfma_f32_16x16x32_bf16 v[108:111], v[236:239], v[148:151], v[108:111]
	v_mfma_f32_16x16x32_bf16 v[100:103], v[228:231], v[156:159], v[100:103]
	v_mfma_f32_16x16x32_bf16 v[96:99], v[236:239], v[156:159], v[96:99]
	v_mfma_f32_16x16x32_bf16 v[84:87], v[228:231], v[188:191], v[84:87]
	v_mfma_f32_16x16x32_bf16 v[76:79], v[236:239], v[188:191], v[76:79]
	v_mfma_f32_16x16x32_bf16 v[68:71], v[228:231], v[220:223], v[68:71]
	v_mfma_f32_16x16x32_bf16 v[64:67], v[236:239], v[220:223], v[64:67]
	s_mov_b32 m0, s45
	v_lshl_add_u64 v[214:215], v[240:241], 0, s[2:3]
	s_barrier
	ds_read_b128 v[144:147], v219 offset:49152
	ds_read_b128 v[148:151], v219 offset:50176
	ds_read_b128 v[152:155], v219 offset:51200
	ds_read_b128 v[156:159], v219 offset:52224
	ds_read_b128 v[184:187], v219 offset:53248
	ds_read_b128 v[188:191], v219 offset:54272
	ds_read_b128 v[192:195], v219 offset:55296
	ds_read_b128 v[220:223], v219 offset:56320
	global_load_lds_dwordx4 v[214:215], off
	v_lshl_add_u64 v[214:215], v[242:243], 0, s[2:3]
	s_mov_b32 m0, s46
	s_nop 0
	global_load_lds_dwordx4 v[214:215], off
	s_barrier
; DEV bf16x8 pack8(f32x4 a, f32x4 b) { u32x4 w; w.x = cvt_pk_bf16(a[0], a[1]); w.y = cvt_pk_bf16(a[2], a[3]); w.z = cvt_pk_bf16(b[0], b[1]); w.w = cvt_pk_bf16(b[2], b[3]); return __builtin_bit_cast(bf16x8, w); }
; #define PG8_WAIT_V(n) asm volatile("s_waitcnt vmcnt(" #n ")" ::: "memory")
; #define PG8_WAIT_L(n) asm volatile("s_waitcnt lgkmcnt(" #n ")" ::: "memory")
; #define PG8_BAR __builtin_amdgcn_s_barrier()
; #define PG8_SCHED __builtin_amdgcn_sched_barrier(0)
; template <class Epi>
; DEV void gemm_phase(LAS unsigned char* lds, const Gemm g, const StaticOrder& S, const Epi& E) {
;     ...
;             PG8_BAR; PG8_WAIT_L(0); PG8_MMA(1, 0, At, B0); PG8_BAR; PG8_SCHED;
;             PG8_STAGE(PG8_SB(1, 1), b3 + hstep, voffB);
;             PG8_WAIT_V(6); PG8_BAR; PG8_MMA(1, 1, At, B1); PG8_BAR;
;     DEV void operator()(AccRef acc, const pg8::Unit& u, int wr, int wc, int fr, int fq) const {
;         const int row0 = u.pm * 256 + wr * 64 + fr, col0 = u.pn * 256 + wc * 32 + 8 * fq;
; #pragma unroll
;         for (int am = 0; am < 4; ++am) { const int ai = am >> 1, m0 = (am & 1) * 2;
;             f32x4 bv[4][2][2];
; #pragma unroll
;             for (int m = m0; m < m0 + 2; ++m)
; #pragma unroll
;                 for (int bj = 0; bj < 2; ++bj)
; #pragma unroll
;                     for (int n = 0; n < 2; ++n) bv[m][bj][n] = *(const f32x4*)(base + (size_t)(row0 + ai * 128 + m * 16) * 2048 + col0 + bj * 128 + n * 4);
; #pragma unroll
;             for (int m = m0; m < m0 + 2; ++m) { const size_t off = (size_t)(row0 + ai * 128 + m * 16) * 2048 + col0; float sq = 0.f;
; #pragma unroll
;                 for (int bj = 0; bj < 2; ++bj) { const f32x4 o0 = bv[m][bj][0] + scale * acc[ai][bj][m][0], o1 = bv[m][bj][1] + scale * acc[ai][bj][m][1];
;                     *(f32x4*)(out + off + bj * 128) = o0; *(f32x4*)(out + off + bj * 128 + 4) = o1;
;                     if (xb) { *(u32x4*)(xb + off + bj * 128) = __builtin_bit_cast(u32x4, pack8(o0, o1));
;                         sq += (o0[0] * o0[0] + o0[1] * o0[1] + o0[2] * o0[2] + o0[3] * o0[3]) + (o1[0] * o1[0] + o1[1] * o1[1] + o1[2] * o1[2] + o1[3] * o1[3]); } }
;                 if (ssout) { sq += __shfl_xor(sq, 16); sq += __shfl_xor(sq, 32);
;                     if (fq == 0) { if (red) red[(ai * 128 + wr * 64 + m * 16 + fr) * 4 + wc] = sq; else atomicAdd(ssout + (size_t)(row0 + ai * 128 + m * 16) * 8 + u.pn, sq); } } }
	s_waitcnt lgkmcnt(7)
	v_mfma_f32_16x16x32_bf16 v[60:63], v[128:131], v[144:147], v[60:63]
	v_mfma_f32_16x16x32_bf16 v[56:59], v[136:139], v[144:147], v[56:59]
	s_waitcnt lgkmcnt(5)
	v_mfma_f32_16x16x32_bf16 v[48:51], v[128:131], v[152:155], v[48:51]
	v_mfma_f32_16x16x32_bf16 v[40:43], v[136:139], v[152:155], v[40:43]
	s_waitcnt lgkmcnt(3)
	v_mfma_f32_16x16x32_bf16 v[28:31], v[128:131], v[184:187], v[28:31]
	v_mfma_f32_16x16x32_bf16 v[24:27], v[136:139], v[184:187], v[24:27]
	s_waitcnt lgkmcnt(1)
	v_mfma_f32_16x16x32_bf16 v[16:19], v[128:131], v[192:195], v[16:19]
	v_mfma_f32_16x16x32_bf16 v[8:11], v[136:139], v[192:195], v[8:11]
	v_mfma_f32_16x16x32_bf16 v[60:63], v[132:135], v[148:151], v[60:63]
	v_mfma_f32_16x16x32_bf16 v[56:59], v[140:143], v[148:151], v[56:59]
	v_mfma_f32_16x16x32_bf16 v[48:51], v[132:135], v[156:159], v[48:51]
	v_mfma_f32_16x16x32_bf16 v[40:43], v[140:143], v[156:159], v[40:43]
	v_mfma_f32_16x16x32_bf16 v[28:31], v[132:135], v[188:191], v[28:31]
	v_mfma_f32_16x16x32_bf16 v[24:27], v[140:143], v[188:191], v[24:27]
	s_waitcnt lgkmcnt(0)
	v_mfma_f32_16x16x32_bf16 v[16:19], v[132:135], v[220:223], v[16:19]
	v_mfma_f32_16x16x32_bf16 v[8:11], v[140:143], v[220:223], v[8:11]
	s_barrier
	s_add_u32 s28, s30, 0x160080
	s_addc_u32 s29, s31, 0
	s_add_i32 s30, s34, s40
	s_mov_b32 m0, s30
	s_nop 0
	global_load_lds_dwordx4 v160, s[28:29]
	s_add_i32 m0, s30, 0x2000
	s_nop 0
	global_load_lds_dwordx4 v178, s[28:29]
	s_waitcnt vmcnt(6)
	s_barrier
	v_mfma_f32_16x16x32_bf16 v[52:55], v[224:227], v[144:147], v[52:55]
	v_mfma_f32_16x16x32_bf16 v[44:47], v[232:235], v[144:147], v[44:47]
	v_mfma_f32_16x16x32_bf16 v[36:39], v[224:227], v[152:155], v[36:39]
	v_mfma_f32_16x16x32_bf16 v[32:35], v[232:235], v[152:155], v[32:35]
	v_mfma_f32_16x16x32_bf16 v[20:23], v[224:227], v[184:187], v[20:23]
	v_mfma_f32_16x16x32_bf16 v[12:15], v[232:235], v[184:187], v[12:15]
	v_mfma_f32_16x16x32_bf16 v[4:7], v[224:227], v[192:195], v[4:7]
	v_mfma_f32_16x16x32_bf16 v[0:3], v[232:235], v[192:195], v[0:3]
	v_mfma_f32_16x16x32_bf16 v[52:55], v[228:231], v[148:151], v[52:55]
	v_mfma_f32_16x16x32_bf16 v[44:47], v[236:239], v[148:151], v[44:47]
	v_mfma_f32_16x16x32_bf16 v[36:39], v[228:231], v[156:159], v[36:39]
	v_mfma_f32_16x16x32_bf16 v[32:35], v[236:239], v[156:159], v[32:35]
	v_mfma_f32_16x16x32_bf16 v[20:23], v[228:231], v[188:191], v[20:23]
	v_mfma_f32_16x16x32_bf16 v[12:15], v[236:239], v[188:191], v[12:15]
	v_mfma_f32_16x16x32_bf16 v[4:7], v[228:231], v[220:223], v[4:7]
	v_mfma_f32_16x16x32_bf16 v[0:3], v[236:239], v[220:223], v[0:3]
	s_add_i32 s54, s54, 2
	s_add_u32 s52, s52, 0x100
	s_addc_u32 s53, s53, 0
	s_cmpk_gt_u32 s54, 0x55
	s_mov_b64 s[28:29], s[6:7]
	s_barrier
	s_cbranch_scc0 .LBB0_657
	v_lshl_add_u32 v186, s23, 8, v167
	v_lshl_or_b32 v184, s22, 8, v197
	v_ashrrev_i32_e32 v185, 31, v184
	v_ashrrev_i32_e32 v187, 31, v186
	v_lshl_add_u64 v[188:189], v[184:185], 2, s[24:25]
	v_lshlrev_b64 v[128:129], 13, v[186:187]
	v_or_b32_e32 v190, 16, v186
	v_lshl_add_u64 v[128:129], v[188:189], 0, v[128:129]
	v_ashrrev_i32_e32 v191, 31, v190
	global_load_dwordx4 v[152:155], v[128:129], off offset:16
	global_load_dwordx4 v[156:159], v[128:129], off
	global_load_dwordx4 v[144:147], v[128:129], off offset:528
	global_load_dwordx4 v[148:151], v[128:129], off offset:512
	v_lshlrev_b64 v[128:129], 13, v[190:191]
	v_lshl_add_u64 v[132:133], v[188:189], 0, v[128:129]
	global_load_dwordx4 v[136:139], v[132:133], off offset:16
	global_load_dwordx4 v[140:143], v[132:133], off
	global_load_dwordx4 v[128:131], v[132:133], off offset:528
	s_nop 0
	global_load_dwordx4 v[132:135], v[132:133], off offset:512
	v_lshlrev_b64 v[192:193], 11, v[186:187]
	v_lshl_add_u64 v[194:195], v[192:193], 0, v[184:185]
	s_ashr_i32 s23, s22, 31
	v_lshl_add_u64 v[192:193], v[194:195], 2, s[68:69]
	s_mov_b64 s[28:29], -1
	s_andn2_b64 vcc, exec, s[18:19]
	s_waitcnt vmcnt(0)
	v_pk_fma_f32 v[152:153], v[120:121], 0.5, v[152:153] op_sel_hi:[1,0,1]
	v_cndmask_b32_e64 v120, 0, 1, s[18:19]
	v_pk_fma_f32 v[158:159], v[126:127], 0.5, v[158:159] op_sel_hi:[1,0,1]
	v_pk_fma_f32 v[156:157], v[124:125], 0.5, v[156:157] op_sel_hi:[1,0,1]
	v_pk_fma_f32 v[154:155], v[122:123], 0.5, v[154:155] op_sel_hi:[1,0,1]
	v_cmp_ne_u32_e64 s[6:7], 1, v120
	v_pk_fma_f32 v[120:121], v[116:117], 0.5, v[148:149] op_sel_hi:[1,0,1]
	v_pk_fma_f32 v[124:125], v[108:109], 0.5, v[144:145] op_sel_hi:[1,0,1]
	global_store_dwordx4 v[192:193], v[156:159], off
	global_store_dwordx4 v[192:193], v[152:155], off offset:16
	s_cbranch_vccnz .LBB0_665
	v_mul_f32_e32 v108, v157, v157
	v_mul_f32_e32 v109, v153, v153
	v_fmac_f32_e32 v108, v156, v156
	v_fmac_f32_e32 v109, v152, v152
	v_fmac_f32_e32 v108, v158, v158
	v_fmac_f32_e32 v109, v154, v154
	v_fmac_f32_e32 v108, v159, v159
	v_fmac_f32_e32 v109, v155, v155
	v_add_f32_e32 v108, v108, v109
	v_mul_f32_e32 v109, v121, v121
	v_mul_f32_e32 v144, v125, v125
	v_pk_fma_f32 v[122:123], v[118:119], 0.5, v[150:151] op_sel_hi:[1,0,1]
	v_pk_fma_f32 v[126:127], v[110:111], 0.5, v[146:147] op_sel_hi:[1,0,1]
	v_fmac_f32_e32 v109, v120, v120
	v_fmac_f32_e32 v144, v124, v124
	v_fmac_f32_e32 v109, v122, v122
	v_fmac_f32_e32 v144, v126, v126
	v_fmac_f32_e32 v109, v123, v123
	v_fmac_f32_e32 v144, v127, v127
	v_add_f32_e32 v109, v109, v144
	v_cmp_lt_i32_e32 vcc, v208, v206
	v_add_f32_e32 v108, v108, v109
	v_readlane_b32 s28, v250, 9
	v_cndmask_b32_e32 v109, v204, v208, vcc
	v_lshlrev_b32_e32 v109, 2, v109
	ds_bpermute_b32 v109, v109, v108
	v_cmp_lt_i32_e32 vcc, v207, v206
	v_readlane_b32 s29, v250, 10
	v_cvt_pk_bf16_f32 v220, v156, v157
	v_cvt_pk_bf16_f32 v221, v158, v159
	s_waitcnt lgkmcnt(0)
	v_add_f32_e32 v108, v108, v109
	v_cndmask_b32_e32 v109, v204, v207, vcc
	v_lshlrev_b32_e32 v109, 2, v109
	ds_bpermute_b32 v109, v109, v108
	v_cvt_pk_bf16_f32 v222, v152, v153
	v_cvt_pk_bf16_f32 v223, v154, v155
	v_lshl_add_u64 v[116:117], v[194:195], 1, s[28:29]
	v_cvt_pk_bf16_f32 v152, v120, v121
	v_cvt_pk_bf16_f32 v153, v122, v123
	v_cvt_pk_bf16_f32 v154, v124, v125
	v_cvt_pk_bf16_f32 v155, v126, v127
	global_store_dwordx4 v[116:117], v[220:223], off
	global_store_dwordx4 v[192:193], v[120:123], off offset:512
	global_store_dwordx4 v[192:193], v[124:127], off offset:528
	global_store_dwordx4 v[116:117], v[152:155], off offset:256
	s_and_saveexec_b64 s[28:29], s[10:11]
	s_cbranch_execz .LBB0_664
	s_waitcnt lgkmcnt(0)
	v_add_f32_e32 v108, v108, v109
	s_andn2_b64 vcc, exec, s[20:21]
	s_mov_b64 s[30:31], -1
	s_cbranch_vccnz .LBB0_662
	s_mov_b64 s[30:31], 0
	ds_write_b32 v218, v108

; #define PG8_STAGE(bufoff, gbase, voff) do { _Pragma("unroll") for (int _i = 0; _i < 2; ++_i) \
;         __builtin_amdgcn_global_load_lds((const unsigned*)((const char*)(gbase) + (voff)[_i]), (LAS unsigned*)(lds + (bufoff) + ldsw + _i * 8192), 16, 0, 0); } while (0)
; #define PG8_LDA(dst, b, h) do { _Pragma("unroll") for (int m = 0; m < 4; ++m) _Pragma("unroll") for (int k = 0; k < 2; ++k) dst[m][k] = *(const LAS bf16x8*)(lds + PG8_SA(b, h) + aoff + m * 2048 + k * 1024); } while (0)
; #define PG8_LDB(dst, b, h) do { _Pragma("unroll") for (int n = 0; n < 2; ++n) _Pragma("unroll") for (int k = 0; k < 2; ++k) dst[n][k] = *(const LAS bf16x8*)(lds + PG8_SB(b, h) + boff + n * 2048 + k * 1024); } while (0)
; #define PG8_MMA(ai, bj, At, Bt) do { __builtin_amdgcn_s_setprio(1); _Pragma("unroll") for (int m = 0; m < 4; ++m) _Pragma("unroll") for (int n = 0; n < 2; ++n) _Pragma("unroll") for (int k = 0; k < 2; ++k) \
;         acc[ai][bj][m][n] = __builtin_amdgcn_mfma_f32_16x16x32_bf16(Bt[n][k], At[m][k], acc[ai][bj][m][n], 0, 0, 0); __builtin_amdgcn_s_setprio(0); } while (0)
; #define PG8_WAIT_L(n) asm volatile("s_waitcnt lgkmcnt(" #n ")" ::: "memory")
; #define PG8_BAR __builtin_amdgcn_s_barrier()
; #define PG8_SCHED __builtin_amdgcn_sched_barrier(0)
; template <class Epi>
; DEV void gemm_phase(LAS unsigned char* lds, const Gemm g, const StaticOrder& S, const Epi& E) {
;     ...
;             PG8_LDB(B0, 0, 0); PG8_SCHED; PG8_LDA(At, 0, 0); PG8_STAGE(PG8_SA(1, 1), a1 + hstep, voffA);
;             PG8_WAIT_L(8); PG8_BAR; PG8_WAIT_L(0); PG8_MMA(0, 0, At, B0); PG8_BAR; PG8_SCHED;
;             PG8_LDB(B1, 0, 1); PG8_STAGE(PG8_SB(0, 0), b2, voffB);
;             PG8_BAR; PG8_WAIT_L(0); PG8_MMA(0, 1, At, B1); PG8_BAR;
;             PG8_LDA(At, 0, 1); PG8_STAGE(PG8_SA(0, 0), a2, voffA);
;             PG8_BAR; PG8_WAIT_L(0); PG8_MMA(1, 0, At, B0); PG8_BAR; PG8_SCHED;
.LBB0_755:
	s_add_u32 s22, s20, 0xfff80080
	s_addc_u32 s23, s21, -1
	s_add_i32 s47, 0, 0x10000
	v_add_u32_e32 v146, s47, v155
	ds_read_b128 v[128:131], v146
	ds_read_b128 v[132:135], v146 offset:1024
	ds_read_b128 v[150:153], v146 offset:2048
	ds_read_b128 v[174:177], v146 offset:3072
	s_cmp_eq_u32 s46, 28
	s_cselect_b32 s25, s5, s23
	s_cselect_b32 s24, s15, s22
	s_cselect_b32 s23, s11, s45
	s_cselect_b32 s22, s43, s44
	s_add_i32 m0, s34, 0xc000
	ds_read_b128 v[178:181], v167
	ds_read_b128 v[182:185], v167 offset:1024
	ds_read_b128 v[186:189], v167 offset:2048
	ds_read_b128 v[190:193], v167 offset:3072
	ds_read_b128 v[194:197], v167 offset:4096
	ds_read_b128 v[218:221], v167 offset:5120
	ds_read_b128 v[222:225], v167 offset:6144
	ds_read_b128 v[226:229], v167 offset:7168
	global_load_lds_dwordx4 v142, s[20:21]
	s_add_i32 m0, s34, 0xe000
	s_nop 0
	global_load_lds_dwordx4 v144, s[20:21]
	s_waitcnt lgkmcnt(8)
	s_barrier
	s_waitcnt lgkmcnt(7)
	v_mfma_f32_16x16x32_bf16 v[124:127], v[128:131], v[178:181], v[124:127]
	v_mfma_f32_16x16x32_bf16 v[116:119], v[150:153], v[178:181], v[116:119]
	s_waitcnt lgkmcnt(5)
	v_mfma_f32_16x16x32_bf16 v[108:111], v[128:131], v[186:189], v[108:111]
	v_mfma_f32_16x16x32_bf16 v[100:103], v[150:153], v[186:189], v[100:103]
	s_waitcnt lgkmcnt(3)
	v_mfma_f32_16x16x32_bf16 v[92:95], v[128:131], v[194:197], v[92:95]
	v_mfma_f32_16x16x32_bf16 v[84:87], v[150:153], v[194:197], v[84:87]
	s_waitcnt lgkmcnt(1)
	v_mfma_f32_16x16x32_bf16 v[76:79], v[128:131], v[222:225], v[76:79]
	v_mfma_f32_16x16x32_bf16 v[68:71], v[150:153], v[222:225], v[68:71]
	v_mfma_f32_16x16x32_bf16 v[124:127], v[132:135], v[182:185], v[124:127]
	v_mfma_f32_16x16x32_bf16 v[116:119], v[174:177], v[182:185], v[116:119]
	v_mfma_f32_16x16x32_bf16 v[108:111], v[132:135], v[190:193], v[108:111]
	v_mfma_f32_16x16x32_bf16 v[100:103], v[174:177], v[190:193], v[100:103]
	v_mfma_f32_16x16x32_bf16 v[92:95], v[132:135], v[218:221], v[92:95]
	v_mfma_f32_16x16x32_bf16 v[84:87], v[174:177], v[218:221], v[84:87]
	s_waitcnt lgkmcnt(0)
	v_mfma_f32_16x16x32_bf16 v[76:79], v[132:135], v[226:229], v[76:79]
	v_mfma_f32_16x16x32_bf16 v[68:71], v[174:177], v[226:229], v[68:71]
	s_barrier
	s_add_i32 s50, 0, 0x14000
	v_add_u32_e32 v146, s50, v155
	s_add_i32 s47, s47, s30
	ds_read_b128 v[230:233], v146
	ds_read_b128 v[234:237], v146 offset:1024
	ds_read_b128 v[238:241], v146 offset:2048
	ds_read_b128 v[242:245], v146 offset:3072
	v_lshl_add_u64 v[146:147], s[22:23], 0, v[160:161]
	s_mov_b32 m0, s47
	v_lshl_add_u64 v[158:159], s[22:23], 0, v[136:137]
	global_load_lds_dwordx4 v160, s[22:23]
	s_add_i32 m0, s47, 0x2000
	s_nop 0
	global_load_lds_dwordx4 v136, s[22:23]
	s_barrier
	s_waitcnt lgkmcnt(3)
	v_mfma_f32_16x16x32_bf16 v[120:123], v[230:233], v[178:181], v[120:123]
	s_waitcnt lgkmcnt(1)
	v_mfma_f32_16x16x32_bf16 v[112:115], v[238:241], v[178:181], v[112:115]
	v_mfma_f32_16x16x32_bf16 v[104:107], v[230:233], v[186:189], v[104:107]
	v_mfma_f32_16x16x32_bf16 v[96:99], v[238:241], v[186:189], v[96:99]
	v_mfma_f32_16x16x32_bf16 v[88:91], v[230:233], v[194:197], v[88:91]
	v_mfma_f32_16x16x32_bf16 v[80:83], v[238:241], v[194:197], v[80:83]
	v_mfma_f32_16x16x32_bf16 v[72:75], v[230:233], v[222:225], v[72:75]
	v_mfma_f32_16x16x32_bf16 v[64:67], v[238:241], v[222:225], v[64:67]
	v_mfma_f32_16x16x32_bf16 v[120:123], v[234:237], v[182:185], v[120:123]
	s_waitcnt lgkmcnt(0)
	v_mfma_f32_16x16x32_bf16 v[112:115], v[242:245], v[182:185], v[112:115]
	v_mfma_f32_16x16x32_bf16 v[104:107], v[234:237], v[190:193], v[104:107]
	v_mfma_f32_16x16x32_bf16 v[96:99], v[242:245], v[190:193], v[96:99]
	v_mfma_f32_16x16x32_bf16 v[88:91], v[234:237], v[218:221], v[88:91]
	v_mfma_f32_16x16x32_bf16 v[80:83], v[242:245], v[218:221], v[80:83]
	v_mfma_f32_16x16x32_bf16 v[72:75], v[234:237], v[226:229], v[72:75]
	v_mfma_f32_16x16x32_bf16 v[64:67], v[242:245], v[226:229], v[64:67]
	s_mov_b32 m0, s34
	v_lshl_add_u64 v[214:215], s[24:25], 0, v[140:141]
	s_barrier
	ds_read_b128 v[178:181], v167 offset:16384
	ds_read_b128 v[182:185], v167 offset:17408
	ds_read_b128 v[186:189], v167 offset:18432
	ds_read_b128 v[190:193], v167 offset:19456
	ds_read_b128 v[194:197], v167 offset:20480
	ds_read_b128 v[218:221], v167 offset:21504
	ds_read_b128 v[222:225], v167 offset:22528
	ds_read_b128 v[226:229], v167 offset:23552
	global_load_lds_dwordx4 v140, s[24:25]
	v_lshl_add_u64 v[216:217], s[24:25], 0, v[138:139]
	s_mov_b32 m0, s35
	s_nop 0
	global_load_lds_dwordx4 v138, s[24:25]
	s_barrier
	s_waitcnt lgkmcnt(7)
	v_mfma_f32_16x16x32_bf16 v[60:63], v[128:131], v[178:181], v[60:63]
	v_mfma_f32_16x16x32_bf16 v[52:55], v[150:153], v[178:181], v[52:55]
	s_waitcnt lgkmcnt(5)
	v_mfma_f32_16x16x32_bf16 v[44:47], v[128:131], v[186:189], v[44:47]
	v_mfma_f32_16x16x32_bf16 v[36:39], v[150:153], v[186:189], v[36:39]
	s_waitcnt lgkmcnt(3)
	v_mfma_f32_16x16x32_bf16 v[28:31], v[128:131], v[194:197], v[28:31]
	v_mfma_f32_16x16x32_bf16 v[20:23], v[150:153], v[194:197], v[20:23]
	s_waitcnt lgkmcnt(1)
	v_mfma_f32_16x16x32_bf16 v[12:15], v[128:131], v[222:225], v[12:15]
	v_mfma_f32_16x16x32_bf16 v[4:7], v[150:153], v[222:225], v[4:7]
	v_mfma_f32_16x16x32_bf16 v[60:63], v[132:135], v[182:185], v[60:63]
	v_mfma_f32_16x16x32_bf16 v[52:55], v[174:177], v[182:185], v[52:55]
	v_mfma_f32_16x16x32_bf16 v[44:47], v[132:135], v[190:193], v[44:47]
	v_mfma_f32_16x16x32_bf16 v[36:39], v[174:177], v[190:193], v[36:39]
	v_mfma_f32_16x16x32_bf16 v[28:31], v[132:135], v[218:221], v[28:31]
	v_mfma_f32_16x16x32_bf16 v[20:23], v[174:177], v[218:221], v[20:23]
	s_waitcnt lgkmcnt(0)
	v_mfma_f32_16x16x32_bf16 v[12:15], v[132:135], v[226:229], v[12:15]
	v_mfma_f32_16x16x32_bf16 v[4:7], v[174:177], v[226:229], v[4:7]
	s_barrier
; #define PG8_STAGE(bufoff, gbase, voff) do { _Pragma("unroll") for (int _i = 0; _i < 2; ++_i) \
;         __builtin_amdgcn_global_load_lds((const unsigned*)((const char*)(gbase) + (voff)[_i]), (LAS unsigned*)(lds + (bufoff) + ldsw + _i * 8192), 16, 0, 0); } while (0)
; #define PG8_LDA(dst, b, h) do { _Pragma("unroll") for (int m = 0; m < 4; ++m) _Pragma("unroll") for (int k = 0; k < 2; ++k) dst[m][k] = *(const LAS bf16x8*)(lds + PG8_SA(b, h) + aoff + m * 2048 + k * 1024); } while (0)
; #define PG8_LDB(dst, b, h) do { _Pragma("unroll") for (int n = 0; n < 2; ++n) _Pragma("unroll") for (int k = 0; k < 2; ++k) dst[n][k] = *(const LAS bf16x8*)(lds + PG8_SB(b, h) + boff + n * 2048 + k * 1024); } while (0)
; #define PG8_MMA(ai, bj, At, Bt) do { __builtin_amdgcn_s_setprio(1); _Pragma("unroll") for (int m = 0; m < 4; ++m) _Pragma("unroll") for (int n = 0; n < 2; ++n) _Pragma("unroll") for (int k = 0; k < 2; ++k) \
;         acc[ai][bj][m][n] = __builtin_amdgcn_mfma_f32_16x16x32_bf16(Bt[n][k], At[m][k], acc[ai][bj][m][n], 0, 0, 0); __builtin_amdgcn_s_setprio(0); } while (0)
; #define PG8_WAIT_V(n) asm volatile("s_waitcnt vmcnt(" #n ")" ::: "memory")
; #define PG8_WAIT_L(n) asm volatile("s_waitcnt lgkmcnt(" #n ")" ::: "memory")
; #define PG8_BAR __builtin_amdgcn_s_barrier()
; #define PG8_SCHED __builtin_amdgcn_sched_barrier(0)
; template <class Epi>
; DEV void gemm_phase(LAS unsigned char* lds, const Gemm g, const StaticOrder& S, const Epi& E) {
;     ...
;             PG8_STAGE(PG8_SB(0, 1), b2 + hstep, voffB);
;             PG8_WAIT_V(6); PG8_BAR; PG8_MMA(1, 1, At, B1); PG8_BAR;
;             PG8_LDB(B0, 1, 0); PG8_SCHED; PG8_LDA(At, 1, 0); PG8_STAGE(PG8_SA(0, 1), a2 + hstep, voffA);
;             PG8_WAIT_L(8); PG8_BAR; PG8_WAIT_L(0); PG8_MMA(0, 0, At, B0); PG8_BAR; PG8_SCHED;
;             PG8_LDB(B1, 1, 1); PG8_STAGE(PG8_SB(1, 0), b3, voffB);
;             PG8_BAR; PG8_WAIT_L(0); PG8_MMA(0, 1, At, B1); PG8_BAR;
;             PG8_LDA(At, 1, 1); PG8_STAGE(PG8_SA(1, 0), a3, voffA);
	s_add_u32 s48, s22, 0x80000
	s_addc_u32 s49, s23, 0
	s_add_i32 s47, s50, s30
	s_mov_b32 m0, s47
	s_nop 0
	global_load_lds_dwordx4 v160, s[48:49]
	s_add_i32 m0, s47, 0x2000
	s_nop 0
	global_load_lds_dwordx4 v136, s[48:49]
	s_waitcnt vmcnt(6)
	s_barrier
	v_mfma_f32_16x16x32_bf16 v[56:59], v[230:233], v[178:181], v[56:59]
	v_mfma_f32_16x16x32_bf16 v[48:51], v[238:241], v[178:181], v[48:51]
	v_mfma_f32_16x16x32_bf16 v[40:43], v[230:233], v[186:189], v[40:43]
	v_mfma_f32_16x16x32_bf16 v[32:35], v[238:241], v[186:189], v[32:35]
	v_mfma_f32_16x16x32_bf16 v[24:27], v[230:233], v[194:197], v[24:27]
	v_mfma_f32_16x16x32_bf16 v[16:19], v[238:241], v[194:197], v[16:19]
	v_mfma_f32_16x16x32_bf16 v[8:11], v[230:233], v[222:225], v[8:11]
	v_mfma_f32_16x16x32_bf16 v[0:3], v[238:241], v[222:225], v[0:3]
	v_mfma_f32_16x16x32_bf16 v[56:59], v[234:237], v[182:185], v[56:59]
	v_mfma_f32_16x16x32_bf16 v[48:51], v[242:245], v[182:185], v[48:51]
	v_mfma_f32_16x16x32_bf16 v[40:43], v[234:237], v[190:193], v[40:43]
	v_mfma_f32_16x16x32_bf16 v[32:35], v[242:245], v[190:193], v[32:35]
	v_mfma_f32_16x16x32_bf16 v[24:27], v[234:237], v[218:221], v[24:27]
	v_mfma_f32_16x16x32_bf16 v[16:19], v[242:245], v[218:221], v[16:19]
	v_mfma_f32_16x16x32_bf16 v[8:11], v[234:237], v[226:229], v[8:11]
	v_mfma_f32_16x16x32_bf16 v[0:3], v[242:245], v[226:229], v[0:3]
	s_add_i32 s47, 0, 0x18000
	v_add_u32_e32 v148, s47, v155
	s_barrier
	ds_read_b128 v[128:131], v148
	ds_read_b128 v[132:135], v148 offset:1024
	ds_read_b128 v[150:153], v148 offset:2048
	ds_read_b128 v[174:177], v148 offset:3072
	s_add_u32 s24, s24, 0x80000
	s_addc_u32 s25, s25, 0
	s_mov_b32 m0, s36
	ds_read_b128 v[178:181], v167 offset:32768
	ds_read_b128 v[182:185], v167 offset:33792
	ds_read_b128 v[186:189], v167 offset:34816
	ds_read_b128 v[190:193], v167 offset:35840
	ds_read_b128 v[194:197], v167 offset:36864
	ds_read_b128 v[218:221], v167 offset:37888
	ds_read_b128 v[222:225], v167 offset:38912
	ds_read_b128 v[226:229], v167 offset:39936
	global_load_lds_dwordx4 v140, s[24:25]
	s_mov_b32 m0, s37
	s_nop 0
	global_load_lds_dwordx4 v138, s[24:25]
	s_waitcnt lgkmcnt(8)
	s_barrier
	s_waitcnt lgkmcnt(7)
	v_mfma_f32_16x16x32_bf16 v[124:127], v[128:131], v[178:181], v[124:127]
	v_mfma_f32_16x16x32_bf16 v[116:119], v[150:153], v[178:181], v[116:119]
	s_waitcnt lgkmcnt(5)
	v_mfma_f32_16x16x32_bf16 v[108:111], v[128:131], v[186:189], v[108:111]
	v_mfma_f32_16x16x32_bf16 v[100:103], v[150:153], v[186:189], v[100:103]
	s_waitcnt lgkmcnt(3)
	v_mfma_f32_16x16x32_bf16 v[92:95], v[128:131], v[194:197], v[92:95]
	v_mfma_f32_16x16x32_bf16 v[84:87], v[150:153], v[194:197], v[84:87]
	s_waitcnt lgkmcnt(1)
	v_mfma_f32_16x16x32_bf16 v[76:79], v[128:131], v[222:225], v[76:79]
	v_mfma_f32_16x16x32_bf16 v[68:71], v[150:153], v[222:225], v[68:71]
	v_mfma_f32_16x16x32_bf16 v[124:127], v[132:135], v[182:185], v[124:127]
	v_mfma_f32_16x16x32_bf16 v[116:119], v[174:177], v[182:185], v[116:119]
	v_mfma_f32_16x16x32_bf16 v[108:111], v[132:135], v[190:193], v[108:111]
	v_mfma_f32_16x16x32_bf16 v[100:103], v[174:177], v[190:193], v[100:103]
	v_mfma_f32_16x16x32_bf16 v[92:95], v[132:135], v[218:221], v[92:95]
	v_mfma_f32_16x16x32_bf16 v[84:87], v[174:177], v[218:221], v[84:87]
	s_waitcnt lgkmcnt(0)
	v_mfma_f32_16x16x32_bf16 v[76:79], v[132:135], v[226:229], v[76:79]
	v_mfma_f32_16x16x32_bf16 v[68:71], v[174:177], v[226:229], v[68:71]
	s_barrier
	s_add_i32 s24, 0, 0x1c000
	s_add_i32 s25, s47, s30
	v_add_u32_e32 v148, s24, v155
	v_lshl_add_u64 v[146:147], v[146:147], 0, s[2:3]
	s_mov_b32 m0, s25
	ds_read_b128 v[230:233], v148
	ds_read_b128 v[234:237], v148 offset:1024
	ds_read_b128 v[238:241], v148 offset:2048
	ds_read_b128 v[242:245], v148 offset:3072
	global_load_lds_dwordx4 v[146:147], off
	v_lshl_add_u64 v[146:147], v[158:159], 0, s[2:3]
	s_add_i32 m0, s25, 0x2000
	s_nop 0
	global_load_lds_dwordx4 v[146:147], off
	s_barrier
	s_waitcnt lgkmcnt(3)
	v_mfma_f32_16x16x32_bf16 v[120:123], v[230:233], v[178:181], v[120:123]
	s_waitcnt lgkmcnt(1)
	v_mfma_f32_16x16x32_bf16 v[112:115], v[238:241], v[178:181], v[112:115]
	v_mfma_f32_16x16x32_bf16 v[104:107], v[230:233], v[186:189], v[104:107]
	v_mfma_f32_16x16x32_bf16 v[96:99], v[238:241], v[186:189], v[96:99]
	v_mfma_f32_16x16x32_bf16 v[88:91], v[230:233], v[194:197], v[88:91]
	v_mfma_f32_16x16x32_bf16 v[80:83], v[238:241], v[194:197], v[80:83]
	v_mfma_f32_16x16x32_bf16 v[72:75], v[230:233], v[222:225], v[72:75]
	v_mfma_f32_16x16x32_bf16 v[64:67], v[238:241], v[222:225], v[64:67]
	v_mfma_f32_16x16x32_bf16 v[120:123], v[234:237], v[182:185], v[120:123]
	s_waitcnt lgkmcnt(0)
	v_mfma_f32_16x16x32_bf16 v[112:115], v[242:245], v[182:185], v[112:115]
	v_mfma_f32_16x16x32_bf16 v[104:107], v[234:237], v[190:193], v[104:107]
	v_mfma_f32_16x16x32_bf16 v[96:99], v[242:245], v[190:193], v[96:99]
	v_mfma_f32_16x16x32_bf16 v[88:91], v[234:237], v[218:221], v[88:91]
	v_mfma_f32_16x16x32_bf16 v[80:83], v[242:245], v[218:221], v[80:83]
	v_mfma_f32_16x16x32_bf16 v[72:75], v[234:237], v[226:229], v[72:75]
	v_mfma_f32_16x16x32_bf16 v[64:67], v[242:245], v[226:229], v[64:67]
	s_mov_b32 m0, s38
	v_lshl_add_u64 v[146:147], v[214:215], 0, s[2:3]
	s_barrier
	ds_read_b128 v[178:181], v167 offset:49152
	ds_read_b128 v[182:185], v167 offset:50176
	ds_read_b128 v[186:189], v167 offset:51200
	ds_read_b128 v[190:193], v167 offset:52224
	ds_read_b128 v[194:197], v167 offset:53248
	ds_read_b128 v[218:221], v167 offset:54272
	ds_read_b128 v[222:225], v167 offset:55296
	ds_read_b128 v[226:229], v167 offset:56320
	global_load_lds_dwordx4 v[146:147], off
	v_lshl_add_u64 v[146:147], v[216:217], 0, s[2:3]
	s_mov_b32 m0, s39
	s_nop 0
	global_load_lds_dwordx4 v[146:147], off
	s_barrier
; #define PG8_STAGE(bufoff, gbase, voff) do { _Pragma("unroll") for (int _i = 0; _i < 2; ++_i) \
;         __builtin_amdgcn_global_load_lds((const unsigned*)((const char*)(gbase) + (voff)[_i]), (LAS unsigned*)(lds + (bufoff) + ldsw + _i * 8192), 16, 0, 0); } while (0)
; #define PG8_MMA(ai, bj, At, Bt) do { __builtin_amdgcn_s_setprio(1); _Pragma("unroll") for (int m = 0; m < 4; ++m) _Pragma("unroll") for (int n = 0; n < 2; ++n) _Pragma("unroll") for (int k = 0; k < 2; ++k) \
;         acc[ai][bj][m][n] = __builtin_amdgcn_mfma_f32_16x16x32_bf16(Bt[n][k], At[m][k], acc[ai][bj][m][n], 0, 0, 0); __builtin_amdgcn_s_setprio(0); } while (0)
; #define PG8_WAIT_V(n) asm volatile("s_waitcnt vmcnt(" #n ")" ::: "memory")
; #define PG8_WAIT_L(n) asm volatile("s_waitcnt lgkmcnt(" #n ")" ::: "memory")
; #define PG8_BAR __builtin_amdgcn_s_barrier()
; #define PG8_SCHED __builtin_amdgcn_sched_barrier(0)
; template <class Epi>
; DEV void gemm_phase(LAS unsigned char* lds, const Gemm g, const StaticOrder& S, const Epi& E) {
;     ...
;             PG8_BAR; PG8_WAIT_L(0); PG8_MMA(1, 0, At, B0); PG8_BAR; PG8_SCHED;
;             PG8_STAGE(PG8_SB(1, 1), b3 + hstep, voffB);
;             PG8_WAIT_V(6); PG8_BAR; PG8_MMA(1, 1, At, B1); PG8_BAR;
;     DEV void operator()(AccRef acc, const pg8::Unit& u, int wr, int wc, int fr, int fq) const {
;         const int row0 = u.pm * 256 + wr * 64 + fr, col0 = u.pn * 128 + wc * 32 + 8 * fq;
;         float rsv[2][4];
; #pragma unroll
;         for (int ai = 0; ai < 2; ++ai)
; #pragma unroll
;             for (int m = 0; m < 4; ++m) rsv[ai][m] = rowscale(ss, row0 + ai * 128 + m * 16);
; #pragma unroll
;         for (int ai = 0; ai < 2; ++ai)
; #pragma unroll
;             for (int m = 0; m < 4; ++m) { u16* rowp = O + (size_t)(row0 + ai * 128 + m * 16) * 5632 + col0; const float rs = rsv[ai][m]; f32x4 r[2];
; #pragma unroll
;                 for (int n = 0; n < 2; ++n) { const f32x4 g = acc[ai][0][m][n] * rs, uu = acc[ai][1][m][n] * rs;
	s_waitcnt lgkmcnt(7)
	v_mfma_f32_16x16x32_bf16 v[60:63], v[128:131], v[178:181], v[60:63]
	v_mfma_f32_16x16x32_bf16 v[52:55], v[150:153], v[178:181], v[52:55]
	s_waitcnt lgkmcnt(5)
	v_mfma_f32_16x16x32_bf16 v[44:47], v[128:131], v[186:189], v[44:47]
	v_mfma_f32_16x16x32_bf16 v[36:39], v[150:153], v[186:189], v[36:39]
	s_waitcnt lgkmcnt(3)
	v_mfma_f32_16x16x32_bf16 v[28:31], v[128:131], v[194:197], v[28:31]
	v_mfma_f32_16x16x32_bf16 v[20:23], v[150:153], v[194:197], v[20:23]
	s_waitcnt lgkmcnt(1)
	v_mfma_f32_16x16x32_bf16 v[12:15], v[128:131], v[222:225], v[12:15]
	v_mfma_f32_16x16x32_bf16 v[4:7], v[150:153], v[222:225], v[4:7]
	v_mfma_f32_16x16x32_bf16 v[60:63], v[132:135], v[182:185], v[60:63]
	v_mfma_f32_16x16x32_bf16 v[52:55], v[174:177], v[182:185], v[52:55]
	v_mfma_f32_16x16x32_bf16 v[44:47], v[132:135], v[190:193], v[44:47]
	v_mfma_f32_16x16x32_bf16 v[36:39], v[174:177], v[190:193], v[36:39]
	v_mfma_f32_16x16x32_bf16 v[28:31], v[132:135], v[218:221], v[28:31]
	v_mfma_f32_16x16x32_bf16 v[20:23], v[174:177], v[218:221], v[20:23]
	s_waitcnt lgkmcnt(0)
	v_mfma_f32_16x16x32_bf16 v[12:15], v[132:135], v[226:229], v[12:15]
	v_mfma_f32_16x16x32_bf16 v[4:7], v[174:177], v[226:229], v[4:7]
	s_barrier
	s_add_u32 s22, s22, 0x80080
	s_addc_u32 s23, s23, 0
	s_add_i32 s24, s24, s30
	s_mov_b32 m0, s24
	s_nop 0
	global_load_lds_dwordx4 v160, s[22:23]
	s_add_i32 m0, s24, 0x2000
	s_nop 0
	global_load_lds_dwordx4 v136, s[22:23]
	s_waitcnt vmcnt(6)
	s_barrier
	v_mfma_f32_16x16x32_bf16 v[56:59], v[230:233], v[178:181], v[56:59]
	v_mfma_f32_16x16x32_bf16 v[48:51], v[238:241], v[178:181], v[48:51]
	v_mfma_f32_16x16x32_bf16 v[40:43], v[230:233], v[186:189], v[40:43]
	v_mfma_f32_16x16x32_bf16 v[32:35], v[238:241], v[186:189], v[32:35]
	v_mfma_f32_16x16x32_bf16 v[24:27], v[230:233], v[194:197], v[24:27]
	v_mfma_f32_16x16x32_bf16 v[16:19], v[238:241], v[194:197], v[16:19]
	v_mfma_f32_16x16x32_bf16 v[8:11], v[230:233], v[222:225], v[8:11]
	v_mfma_f32_16x16x32_bf16 v[0:3], v[238:241], v[222:225], v[0:3]
	v_mfma_f32_16x16x32_bf16 v[56:59], v[234:237], v[182:185], v[56:59]
	v_mfma_f32_16x16x32_bf16 v[48:51], v[242:245], v[182:185], v[48:51]
	v_mfma_f32_16x16x32_bf16 v[40:43], v[234:237], v[190:193], v[40:43]
	v_mfma_f32_16x16x32_bf16 v[32:35], v[242:245], v[190:193], v[32:35]
	v_mfma_f32_16x16x32_bf16 v[24:27], v[234:237], v[218:221], v[24:27]
	v_mfma_f32_16x16x32_bf16 v[16:19], v[242:245], v[218:221], v[16:19]
	v_mfma_f32_16x16x32_bf16 v[8:11], v[234:237], v[226:229], v[8:11]
	v_mfma_f32_16x16x32_bf16 v[0:3], v[242:245], v[226:229], v[0:3]
	s_add_i32 s46, s46, 2
	s_add_u32 s20, s20, 0x100
	s_addc_u32 s21, s21, 0
	s_add_u32 s44, s44, 0x100
	s_addc_u32 s45, s45, 0
	s_cmp_gt_u32 s46, 29
	s_barrier
	s_cbranch_scc0 .LBB0_755
	v_lshl_add_u32 v186, s4, 8, v149
	v_ashrrev_i32_e32 v187, 31, v186
	v_lshlrev_b64 v[146:147], 5, v[186:187]
	v_lshl_add_u64 v[146:147], s[8:9], 0, v[146:147]
	v_add_co_u32_e32 v158, vcc, 0x1000, v146
	global_load_dwordx4 v[218:221], v[146:147], off
	global_load_dwordx4 v[222:225], v[146:147], off offset:16
	v_addc_co_u32_e32 v159, vcc, 0, v147, vcc
	global_load_dwordx4 v[174:177], v[146:147], off offset:512
	global_load_dwordx4 v[230:233], v[146:147], off offset:528
	global_load_dwordx4 v[234:237], v[146:147], off offset:1024
	global_load_dwordx4 v[238:241], v[146:147], off offset:1040
	global_load_dwordx4 v[242:245], v[146:147], off offset:1536
	global_load_dwordx4 v[246:249], v[146:147], off offset:1552
	global_load_dwordx4 v[190:193], v[158:159], off
	global_load_dwordx4 v[194:197], v[158:159], off offset:16
	global_load_dwordx4 v[214:217], v[158:159], off offset:512
	global_load_dwordx4 v[132:135], v[158:159], off offset:528
	global_load_dwordx4 v[150:153], v[158:159], off offset:1024
	global_load_dwordx4 v[128:131], v[158:159], off offset:1040
	global_load_dwordx4 v[226:229], v[158:159], off offset:1536
	global_load_dwordx4 v[180:183], v[158:159], off offset:1552
	s_mov_b32 s12, 0x3a000000
	s_mov_b64 s[22:23], s[18:19]
	s_mov_b64 s[20:21], s[16:17]
	s_movk_i32 s11, 0x2c00
	v_readlane_b32 s4, v250, 11
	v_readlane_b32 s5, v250, 12
	s_waitcnt vmcnt(14)
	v_add_f32_e32 v218, v218, v219
	v_add_f32_e32 v220, v220, v221
	v_add_f32_e32 v222, v222, v223
	v_add_f32_e32 v224, v224, v225
	v_add_f32_e32 v218, v218, v220
	v_add_f32_e32 v218, v218, v222
	v_add_f32_e32 v218, v218, v224
	v_fmamk_f32 v218, v218, 0x3a000000, v199
	v_rsq_f32_e32 v184, v218
	s_waitcnt vmcnt(12)
	v_add_f32_e32 v174, v174, v175
	v_add_f32_e32 v176, v176, v177
	v_add_f32_e32 v230, v230, v231
	v_add_f32_e32 v232, v232, v233
	v_add_f32_e32 v174, v174, v176
	v_add_f32_e32 v174, v174, v230
	v_add_f32_e32 v174, v174, v232
	v_fmamk_f32 v174, v174, 0x3a000000, v199
	v_rsq_f32_e32 v176, v174
	v_pk_mul_f32 v[124:125], v[124:125], v[184:185] op_sel_hi:[1,0]
	v_pk_mul_f32 v[120:121], v[120:121], v[184:185] op_sel_hi:[1,0]
	v_pk_mul_f32 v[122:123], v[122:123], v[184:185] op_sel_hi:[1,0]
	v_pk_mul_f32 v[116:117], v[116:117], v[184:185] op_sel_hi:[1,0]
	v_pk_mul_f32 v[112:113], v[112:113], v[184:185] op_sel_hi:[1,0]
	v_pk_mul_f32 v[114:115], v[114:115], v[184:185] op_sel_hi:[1,0]
	s_waitcnt vmcnt(10)
	v_add_f32_e32 v234, v234, v235
	v_add_f32_e32 v236, v236, v237
	v_add_f32_e32 v238, v238, v239
	v_add_f32_e32 v240, v240, v241
	v_add_f32_e32 v234, v234, v236
	v_add_f32_e32 v234, v234, v238
	v_add_f32_e32 v234, v234, v240
	v_fmamk_f32 v234, v234, 0x3a000000, v199
	v_rsq_f32_e32 v178, v234
	v_pk_mul_f32 v[108:109], v[108:109], v[176:177] op_sel_hi:[1,0]
	v_pk_mul_f32 v[104:105], v[104:105], v[176:177] op_sel_hi:[1,0]
	v_pk_mul_f32 v[106:107], v[106:107], v[176:177] op_sel_hi:[1,0]
	v_pk_mul_f32 v[100:101], v[100:101], v[176:177] op_sel_hi:[1,0]
	v_pk_mul_f32 v[96:97], v[96:97], v[176:177] op_sel_hi:[1,0]
	v_pk_mul_f32 v[98:99], v[98:99], v[176:177] op_sel_hi:[1,0]
	s_waitcnt vmcnt(8)
; DEV float siluf(float x) { return x * __builtin_amdgcn_rcpf(1.0f + __builtin_amdgcn_exp2f(x * -1.4426950408889634f)); }
;     DEV void operator()(AccRef acc, const pg8::Unit& u, int wr, int wc, int fr, int fq) const {
;     ...
;             for (int m = 0; m < 4; ++m) rsv[ai][m] = rowscale(ss, row0 + ai * 128 + m * 16);
; #pragma unroll
;         for (int ai = 0; ai < 2; ++ai)
; #pragma unroll
;             for (int m = 0; m < 4; ++m) { u16* rowp = O + (size_t)(row0 + ai * 128 + m * 16) * 5632 + col0; const float rs = rsv[ai][m]; f32x4 r[2];
; #pragma unroll
;                 for (int n = 0; n < 2; ++n) { const f32x4 g = acc[ai][0][m][n] * rs, uu = acc[ai][1][m][n] * rs;
; #pragma unroll
;                     for (int e = 0; e < 4; ++e) r[n][e] = siluf(g[e]) * uu[e]; }
	v_add_f32_e32 v242, v242, v243
	v_add_f32_e32 v244, v244, v245
	v_add_f32_e32 v246, v246, v247
	v_add_f32_e32 v248, v248, v249
	v_add_f32_e32 v242, v242, v244
	v_add_f32_e32 v242, v242, v246
	v_add_f32_e32 v242, v242, v248
	v_fmamk_f32 v242, v242, 0x3a000000, v199
	v_rsq_f32_e32 v154, v242
	v_pk_mul_f32 v[92:93], v[92:93], v[178:179] op_sel_hi:[1,0]
	v_pk_mul_f32 v[88:89], v[88:89], v[178:179] op_sel_hi:[1,0]
	v_pk_mul_f32 v[90:91], v[90:91], v[178:179] op_sel_hi:[1,0]
	v_pk_mul_f32 v[84:85], v[84:85], v[178:179] op_sel_hi:[1,0]
	v_pk_mul_f32 v[80:81], v[80:81], v[178:179] op_sel_hi:[1,0]
	v_pk_mul_f32 v[82:83], v[82:83], v[178:179] op_sel_hi:[1,0]
	s_waitcnt vmcnt(6)
	v_add_f32_e32 v190, v190, v191
	v_add_f32_e32 v192, v192, v193
	v_add_f32_e32 v194, v194, v195
	v_add_f32_e32 v196, v196, v197
	v_add_f32_e32 v190, v190, v192
	v_add_f32_e32 v190, v190, v194
	v_add_f32_e32 v190, v190, v196
	v_fmamk_f32 v190, v190, 0x3a000000, v199
	v_rsq_f32_e32 v156, v190
	v_pk_mul_f32 v[76:77], v[76:77], v[154:155] op_sel_hi:[1,0]
	v_pk_mul_f32 v[72:73], v[72:73], v[154:155] op_sel_hi:[1,0]
	v_pk_mul_f32 v[74:75], v[74:75], v[154:155] op_sel_hi:[1,0]
	v_pk_mul_f32 v[68:69], v[68:69], v[154:155] op_sel_hi:[1,0]
	v_pk_mul_f32 v[64:65], v[64:65], v[154:155] op_sel_hi:[1,0]
	v_pk_mul_f32 v[66:67], v[66:67], v[154:155] op_sel_hi:[1,0]
	s_waitcnt vmcnt(4)
	v_add_f32_e32 v214, v214, v215
	v_add_f32_e32 v216, v216, v217
	v_add_f32_e32 v132, v132, v133
	v_add_f32_e32 v134, v134, v135
	v_add_f32_e32 v214, v214, v216
	v_add_f32_e32 v214, v214, v132
	v_add_f32_e32 v214, v214, v134
	v_fmamk_f32 v214, v214, 0x3a000000, v199
	v_rsq_f32_e32 v148, v214
	v_pk_mul_f32 v[60:61], v[60:61], v[156:157] op_sel_hi:[1,0]
	v_pk_mul_f32 v[56:57], v[56:57], v[156:157] op_sel_hi:[1,0]
	v_pk_mul_f32 v[58:59], v[58:59], v[156:157] op_sel_hi:[1,0]
	v_pk_mul_f32 v[52:53], v[52:53], v[156:157] op_sel_hi:[1,0]
	v_pk_mul_f32 v[48:49], v[48:49], v[156:157] op_sel_hi:[1,0]
	v_pk_mul_f32 v[50:51], v[50:51], v[156:157] op_sel_hi:[1,0]
	s_waitcnt vmcnt(2)
	v_add_f32_e32 v150, v150, v151
	v_add_f32_e32 v152, v152, v153
	v_add_f32_e32 v128, v128, v129
	v_add_f32_e32 v130, v130, v131
	v_add_f32_e32 v150, v150, v152
	v_add_f32_e32 v150, v150, v128
	v_add_f32_e32 v150, v150, v130
	v_fmamk_f32 v150, v150, 0x3a000000, v199
	v_rsq_f32_e32 v130, v150
	v_pk_mul_f32 v[44:45], v[44:45], v[148:149] op_sel_hi:[1,0]
	v_pk_mul_f32 v[40:41], v[40:41], v[148:149] op_sel_hi:[1,0]
	v_pk_mul_f32 v[42:43], v[42:43], v[148:149] op_sel_hi:[1,0]
	v_pk_mul_f32 v[36:37], v[36:37], v[148:149] op_sel_hi:[1,0]
	v_pk_mul_f32 v[32:33], v[32:33], v[148:149] op_sel_hi:[1,0]
	v_pk_mul_f32 v[34:35], v[34:35], v[148:149] op_sel_hi:[1,0]
	s_waitcnt vmcnt(0)
	v_add_f32_e32 v226, v226, v227
	v_add_f32_e32 v228, v228, v229
	v_add_f32_e32 v180, v180, v181
	v_add_f32_e32 v182, v182, v183
	v_add_f32_e32 v226, v226, v228
	v_add_f32_e32 v226, v226, v180
	v_add_f32_e32 v226, v226, v182
	v_fmamk_f32 v226, v226, 0x3a000000, v199
	v_rsq_f32_e32 v128, v226
	v_pk_mul_f32 v[28:29], v[28:29], v[130:131] op_sel_hi:[1,0]
	v_or_b32_e32 v182, 16, v186
	v_ashrrev_i32_e32 v183, 31, v182
	v_or_b32_e32 v180, 32, v186
	v_ashrrev_i32_e32 v181, 31, v180
	v_or_b32_e32 v174, 48, v186
	v_ashrrev_i32_e32 v175, 31, v174
	v_add_u32_e32 v158, 0x80, v186
	v_ashrrev_i32_e32 v159, 31, v158
	v_add_u32_e32 v152, 0x90, v186
	v_ashrrev_i32_e32 v153, 31, v152
	v_add_u32_e32 v150, 0xa0, v186
	v_ashrrev_i32_e32 v151, 31, v150
	v_add_u32_e32 v146, 0xb0, v186
	v_ashrrev_i32_e32 v147, 31, v146
	v_lshl_or_b32 v134, s42, 7, v157
	v_ashrrev_i32_e32 v135, 31, v134
	s_mov_b32 s42, s10
	v_mul_f32_e32 v129, 0xbfb8aa3b, v124
	v_exp_f32_e32 v129, v129
	v_mov_b64_e32 v[132:133], s[4:5]
	v_mad_i64_i32 v[186:187], s[4:5], v186, s11, v[132:133]
	v_add_f32_e32 v129, 1.0, v129
	v_rcp_f32_e32 v188, v129
	v_mul_f32_e32 v129, 0xbfb8aa3b, v125
	v_exp_f32_e32 v129, v129
	v_pk_mul_f32 v[24:25], v[24:25], v[130:131] op_sel_hi:[1,0]
	v_pk_mul_f32 v[26:27], v[26:27], v[130:131] op_sel_hi:[1,0]
	v_pk_mul_f32 v[20:21], v[20:21], v[130:131] op_sel_hi:[1,0]
	v_add_f32_e32 v129, 1.0, v129
	v_rcp_f32_e32 v189, v129
	v_pk_mul_f32 v[16:17], v[16:17], v[130:131] op_sel_hi:[1,0]
	v_pk_mul_f32 v[18:19], v[18:19], v[130:131] op_sel_hi:[1,0]
	v_pk_mul_f32 v[12:13], v[12:13], v[128:129] op_sel_hi:[1,0]
	v_pk_mul_f32 v[124:125], v[124:125], v[188:189]
	v_pk_mul_f32 v[8:9], v[8:9], v[128:129] op_sel_hi:[1,0]
	v_pk_mul_f32 v[120:121], v[120:121], v[124:125]
	v_pk_mul_f32 v[124:125], v[126:127], v[184:185] op_sel_hi:[1,0]
	v_pk_mul_f32 v[10:11], v[10:11], v[128:129] op_sel_hi:[1,0]
	v_mul_f32_e32 v126, 0xbfb8aa3b, v124
	v_mul_f32_e32 v127, 0xbfb8aa3b, v125
	v_exp_f32_e32 v126, v126
	v_exp_f32_e32 v127, v127
	v_pk_mul_f32 v[4:5], v[4:5], v[128:129] op_sel_hi:[1,0]
	v_pk_mul_f32 v[0:1], v[0:1], v[128:129] op_sel_hi:[1,0]
	v_add_f32_e32 v126, 1.0, v126
	v_add_f32_e32 v127, 1.0, v127
	v_rcp_f32_e32 v126, v126
	v_rcp_f32_e32 v127, v127
	v_pk_mul_f32 v[2:3], v[2:3], v[128:129] op_sel_hi:[1,0]
	s_and_b64 vcc, exec, s[0:1]
	v_pk_mul_f32 v[124:125], v[124:125], v[126:127]
	s_nop 0
	v_pk_mul_f32 v[122:123], v[122:123], v[124:125]
	v_mul_f32_e32 v124, 0xbfb8aa3b, v116
	v_mul_f32_e32 v125, 0xbfb8aa3b, v117
	v_exp_f32_e32 v124, v124
	v_exp_f32_e32 v125, v125
	v_add_f32_e32 v124, 1.0, v124
	v_add_f32_e32 v125, 1.0, v125
	v_rcp_f32_e32 v124, v124
	v_rcp_f32_e32 v125, v125
	s_nop 0
	v_pk_mul_f32 v[116:117], v[116:117], v[124:125]
	s_nop 0
	v_pk_mul_f32 v[116:117], v[112:113], v[116:117]
	v_pk_mul_f32 v[112:113], v[118:119], v[184:185] op_sel_hi:[1,0]
	v_cvt_pk_bf16_f32 v116, v116, v117
	v_mul_f32_e32 v118, 0xbfb8aa3b, v112
; DEV float siluf(float x) { return x * __builtin_amdgcn_rcpf(1.0f + __builtin_amdgcn_exp2f(x * -1.4426950408889634f)); }
; DEV bf16x8 pack8(f32x4 a, f32x4 b) { u32x4 w; w.x = cvt_pk_bf16(a[0], a[1]); w.y = cvt_pk_bf16(a[2], a[3]); w.z = cvt_pk_bf16(b[0], b[1]); w.w = cvt_pk_bf16(b[2], b[3]); return __builtin_bit_cast(bf16x8, w); }
;     DEV void operator()(AccRef acc, const pg8::Unit& u, int wr, int wc, int fr, int fq) const {
;     ...
;             for (int m = 0; m < 4; ++m) { u16* rowp = O + (size_t)(row0 + ai * 128 + m * 16) * 5632 + col0; const float rs = rsv[ai][m]; f32x4 r[2];
; #pragma unroll
;                 for (int n = 0; n < 2; ++n) { const f32x4 g = acc[ai][0][m][n] * rs, uu = acc[ai][1][m][n] * rs;
; #pragma unroll
;                     for (int e = 0; e < 4; ++e) r[n][e] = siluf(g[e]) * uu[e]; }
;                 *(u32x4*)rowp = __builtin_bit_cast(u32x4, pack8(r[0], r[1])); }
	v_mul_f32_e32 v119, 0xbfb8aa3b, v113
	v_exp_f32_e32 v118, v118
	v_exp_f32_e32 v119, v119
	v_add_f32_e32 v118, 1.0, v118
	v_add_f32_e32 v119, 1.0, v119
	v_rcp_f32_e32 v118, v118
	v_rcp_f32_e32 v119, v119
	s_nop 0
	v_pk_mul_f32 v[112:113], v[112:113], v[118:119]
	s_nop 0
	v_pk_mul_f32 v[118:119], v[114:115], v[112:113]
	v_lshlrev_b64 v[112:113], 1, v[134:135]
	v_lshl_add_u64 v[124:125], v[186:187], 0, v[112:113]
	v_cvt_pk_bf16_f32 v114, v120, v121
	v_cvt_pk_bf16_f32 v115, v122, v123
	v_cvt_pk_bf16_f32 v117, v118, v119
	global_store_dwordx4 v[124:125], v[114:117], off
	s_nop 1
	v_mul_f32_e32 v116, 0xbfb8aa3b, v108
	v_mul_f32_e32 v117, 0xbfb8aa3b, v109
	v_exp_f32_e32 v116, v116
	v_exp_f32_e32 v117, v117
	v_mad_i64_i32 v[114:115], s[4:5], v182, s11, v[132:133]
	v_add_f32_e32 v116, 1.0, v116
	v_add_f32_e32 v117, 1.0, v117
	v_rcp_f32_e32 v116, v116
	v_rcp_f32_e32 v117, v117
	s_nop 0
	v_pk_mul_f32 v[108:109], v[108:109], v[116:117]
	s_nop 0
	v_pk_mul_f32 v[104:105], v[104:105], v[108:109]
	v_pk_mul_f32 v[108:109], v[110:111], v[176:177] op_sel_hi:[1,0]
	s_nop 0
	v_mul_f32_e32 v110, 0xbfb8aa3b, v108
	v_mul_f32_e32 v111, 0xbfb8aa3b, v109
	v_exp_f32_e32 v110, v110
	v_exp_f32_e32 v111, v111
	v_add_f32_e32 v110, 1.0, v110
	v_add_f32_e32 v111, 1.0, v111
	v_rcp_f32_e32 v110, v110
	v_rcp_f32_e32 v111, v111
	s_nop 0
	v_pk_mul_f32 v[108:109], v[108:109], v[110:111]
	s_nop 0
	v_pk_mul_f32 v[106:107], v[106:107], v[108:109]
	v_mul_f32_e32 v108, 0xbfb8aa3b, v100
	v_mul_f32_e32 v109, 0xbfb8aa3b, v101
	v_exp_f32_e32 v108, v108
	v_exp_f32_e32 v109, v109
	v_add_f32_e32 v108, 1.0, v108
	v_add_f32_e32 v109, 1.0, v109
	v_rcp_f32_e32 v108, v108
	v_rcp_f32_e32 v109, v109
	s_nop 0
	v_pk_mul_f32 v[100:101], v[100:101], v[108:109]
	s_nop 0
	v_pk_mul_f32 v[100:101], v[96:97], v[100:101]
	v_pk_mul_f32 v[96:97], v[102:103], v[176:177] op_sel_hi:[1,0]
	v_lshl_add_u64 v[108:109], v[114:115], 0, v[112:113]
	v_mul_f32_e32 v102, 0xbfb8aa3b, v96
	v_mul_f32_e32 v103, 0xbfb8aa3b, v97
	v_exp_f32_e32 v102, v102
	v_exp_f32_e32 v103, v103
	v_add_f32_e32 v102, 1.0, v102
	v_add_f32_e32 v103, 1.0, v103
	v_rcp_f32_e32 v102, v102
	v_rcp_f32_e32 v103, v103
	s_nop 0
	v_pk_mul_f32 v[96:97], v[96:97], v[102:103]
	s_nop 0
	v_pk_mul_f32 v[102:103], v[98:99], v[96:97]
	v_cvt_pk_bf16_f32 v96, v104, v105
	v_cvt_pk_bf16_f32 v97, v106, v107
	v_cvt_pk_bf16_f32 v98, v100, v101
	v_cvt_pk_bf16_f32 v99, v102, v103
	global_store_dwordx4 v[108:109], v[96:99], off
	s_nop 1
	v_mul_f32_e32 v98, 0xbfb8aa3b, v92
	v_mul_f32_e32 v99, 0xbfb8aa3b, v93
	v_exp_f32_e32 v98, v98
	v_exp_f32_e32 v99, v99
	v_mad_i64_i32 v[96:97], s[4:5], v180, s11, v[132:133]
	v_add_f32_e32 v98, 1.0, v98
	v_add_f32_e32 v99, 1.0, v99
	v_rcp_f32_e32 v98, v98
	v_rcp_f32_e32 v99, v99
	s_nop 0
	v_pk_mul_f32 v[92:93], v[92:93], v[98:99]
	s_nop 0
	v_pk_mul_f32 v[88:89], v[88:89], v[92:93]
	v_pk_mul_f32 v[92:93], v[94:95], v[178:179] op_sel_hi:[1,0]
	s_nop 0
	v_mul_f32_e32 v94, 0xbfb8aa3b, v92
	v_mul_f32_e32 v95, 0xbfb8aa3b, v93
	v_exp_f32_e32 v94, v94
	v_exp_f32_e32 v95, v95
	v_add_f32_e32 v94, 1.0, v94
	v_add_f32_e32 v95, 1.0, v95
	v_rcp_f32_e32 v94, v94
	v_rcp_f32_e32 v95, v95
	s_nop 0
	v_pk_mul_f32 v[92:93], v[92:93], v[94:95]
	s_nop 0
	v_pk_mul_f32 v[90:91], v[90:91], v[92:93]
	v_mul_f32_e32 v92, 0xbfb8aa3b, v84
	v_mul_f32_e32 v93, 0xbfb8aa3b, v85
	v_exp_f32_e32 v92, v92
	v_exp_f32_e32 v93, v93
	v_add_f32_e32 v92, 1.0, v92
	v_add_f32_e32 v93, 1.0, v93
	v_rcp_f32_e32 v92, v92
	v_rcp_f32_e32 v93, v93
	s_nop 0
	v_pk_mul_f32 v[84:85], v[84:85], v[92:93]
	s_nop 0
	v_pk_mul_f32 v[84:85], v[80:81], v[84:85]
	v_pk_mul_f32 v[80:81], v[86:87], v[178:179] op_sel_hi:[1,0]
	v_lshl_add_u64 v[92:93], v[96:97], 0, v[112:113]
	v_mul_f32_e32 v86, 0xbfb8aa3b, v80
	v_mul_f32_e32 v87, 0xbfb8aa3b, v81
	v_exp_f32_e32 v86, v86
	v_exp_f32_e32 v87, v87
	v_add_f32_e32 v86, 1.0, v86
	v_add_f32_e32 v87, 1.0, v87
	v_rcp_f32_e32 v86, v86
	v_rcp_f32_e32 v87, v87
	s_nop 0
	v_pk_mul_f32 v[80:81], v[80:81], v[86:87]
	s_nop 0
	v_pk_mul_f32 v[86:87], v[82:83], v[80:81]
	v_cvt_pk_bf16_f32 v80, v88, v89
	v_cvt_pk_bf16_f32 v81, v90, v91
	v_cvt_pk_bf16_f32 v82, v84, v85
	v_cvt_pk_bf16_f32 v83, v86, v87
	global_store_dwordx4 v[92:93], v[80:83], off
	s_nop 1
	v_mul_f32_e32 v82, 0xbfb8aa3b, v76
	v_mul_f32_e32 v83, 0xbfb8aa3b, v77
	v_exp_f32_e32 v82, v82
	v_exp_f32_e32 v83, v83
	v_mad_i64_i32 v[80:81], s[4:5], v174, s11, v[132:133]
	v_add_f32_e32 v82, 1.0, v82
	v_add_f32_e32 v83, 1.0, v83
	v_rcp_f32_e32 v82, v82
	v_rcp_f32_e32 v83, v83
	s_nop 0
	v_pk_mul_f32 v[76:77], v[76:77], v[82:83]
	s_nop 0
	v_pk_mul_f32 v[72:73], v[72:73], v[76:77]
	v_pk_mul_f32 v[76:77], v[78:79], v[154:155] op_sel_hi:[1,0]
	s_nop 0
	v_mul_f32_e32 v78, 0xbfb8aa3b, v76
	v_mul_f32_e32 v79, 0xbfb8aa3b, v77
	v_exp_f32_e32 v78, v78
	v_exp_f32_e32 v79, v79
	v_add_f32_e32 v78, 1.0, v78
	v_add_f32_e32 v79, 1.0, v79
	v_rcp_f32_e32 v78, v78
	v_rcp_f32_e32 v79, v79
	s_nop 0
	v_pk_mul_f32 v[76:77], v[76:77], v[78:79]
	s_nop 0
	v_pk_mul_f32 v[74:75], v[74:75], v[76:77]
	v_mul_f32_e32 v76, 0xbfb8aa3b, v68
	v_mul_f32_e32 v77, 0xbfb8aa3b, v69
	v_exp_f32_e32 v76, v76
	v_exp_f32_e32 v77, v77
	v_add_f32_e32 v76, 1.0, v76
	v_add_f32_e32 v77, 1.0, v77
	v_rcp_f32_e32 v76, v76
	v_rcp_f32_e32 v77, v77
	s_nop 0
	v_pk_mul_f32 v[68:69], v[68:69], v[76:77]
	s_nop 0
	v_pk_mul_f32 v[68:69], v[64:65], v[68:69]
	v_pk_mul_f32 v[64:65], v[70:71], v[154:155] op_sel_hi:[1,0]
	v_lshl_add_u64 v[76:77], v[80:81], 0, v[112:113]
	v_mul_f32_e32 v70, 0xbfb8aa3b, v64
	v_mul_f32_e32 v71, 0xbfb8aa3b, v65
	v_exp_f32_e32 v70, v70
	v_exp_f32_e32 v71, v71
	v_add_f32_e32 v70, 1.0, v70
	v_add_f32_e32 v71, 1.0, v71
	v_rcp_f32_e32 v70, v70
	v_rcp_f32_e32 v71, v71
; DEV float siluf(float x) { return x * __builtin_amdgcn_rcpf(1.0f + __builtin_amdgcn_exp2f(x * -1.4426950408889634f)); }
; DEV bf16x8 pack8(f32x4 a, f32x4 b) { u32x4 w; w.x = cvt_pk_bf16(a[0], a[1]); w.y = cvt_pk_bf16(a[2], a[3]); w.z = cvt_pk_bf16(b[0], b[1]); w.w = cvt_pk_bf16(b[2], b[3]); return __builtin_bit_cast(bf16x8, w); }
;     DEV void operator()(AccRef acc, const pg8::Unit& u, int wr, int wc, int fr, int fq) const {
;     ...
;             for (int m = 0; m < 4; ++m) { u16* rowp = O + (size_t)(row0 + ai * 128 + m * 16) * 5632 + col0; const float rs = rsv[ai][m]; f32x4 r[2];
; #pragma unroll
;                 for (int n = 0; n < 2; ++n) { const f32x4 g = acc[ai][0][m][n] * rs, uu = acc[ai][1][m][n] * rs;
; #pragma unroll
;                     for (int e = 0; e < 4; ++e) r[n][e] = siluf(g[e]) * uu[e]; }
;                 *(u32x4*)rowp = __builtin_bit_cast(u32x4, pack8(r[0], r[1])); }
	s_nop 0
	v_pk_mul_f32 v[64:65], v[64:65], v[70:71]
	s_nop 0
	v_pk_mul_f32 v[70:71], v[66:67], v[64:65]
	v_cvt_pk_bf16_f32 v64, v72, v73
	v_cvt_pk_bf16_f32 v65, v74, v75
	v_cvt_pk_bf16_f32 v66, v68, v69
	v_cvt_pk_bf16_f32 v67, v70, v71
	global_store_dwordx4 v[76:77], v[64:67], off
	s_nop 1
	v_mul_f32_e32 v66, 0xbfb8aa3b, v60
	v_mul_f32_e32 v67, 0xbfb8aa3b, v61
	v_exp_f32_e32 v66, v66
	v_exp_f32_e32 v67, v67
	v_mad_i64_i32 v[64:65], s[4:5], v158, s11, v[132:133]
	v_add_f32_e32 v66, 1.0, v66
	v_add_f32_e32 v67, 1.0, v67
	v_rcp_f32_e32 v66, v66
	v_rcp_f32_e32 v67, v67
	s_nop 0
	v_pk_mul_f32 v[60:61], v[60:61], v[66:67]
	s_nop 0
	v_pk_mul_f32 v[56:57], v[56:57], v[60:61]
	v_pk_mul_f32 v[60:61], v[62:63], v[156:157] op_sel_hi:[1,0]
	s_nop 0
	v_mul_f32_e32 v62, 0xbfb8aa3b, v60
	v_mul_f32_e32 v63, 0xbfb8aa3b, v61
	v_exp_f32_e32 v62, v62
	v_exp_f32_e32 v63, v63
	v_add_f32_e32 v62, 1.0, v62
	v_add_f32_e32 v63, 1.0, v63
	v_rcp_f32_e32 v62, v62
	v_rcp_f32_e32 v63, v63
	s_nop 0
	v_pk_mul_f32 v[60:61], v[60:61], v[62:63]
	s_nop 0
	v_pk_mul_f32 v[58:59], v[58:59], v[60:61]
	v_mul_f32_e32 v60, 0xbfb8aa3b, v52
	v_mul_f32_e32 v61, 0xbfb8aa3b, v53
	v_exp_f32_e32 v60, v60
	v_exp_f32_e32 v61, v61
	v_add_f32_e32 v60, 1.0, v60
	v_add_f32_e32 v61, 1.0, v61
	v_rcp_f32_e32 v60, v60
	v_rcp_f32_e32 v61, v61
	s_nop 0
	v_pk_mul_f32 v[52:53], v[52:53], v[60:61]
	s_nop 0
	v_pk_mul_f32 v[52:53], v[48:49], v[52:53]
	v_pk_mul_f32 v[48:49], v[54:55], v[156:157] op_sel_hi:[1,0]
	v_lshl_add_u64 v[60:61], v[64:65], 0, v[112:113]
	v_mul_f32_e32 v54, 0xbfb8aa3b, v48
	v_mul_f32_e32 v55, 0xbfb8aa3b, v49
	v_exp_f32_e32 v54, v54
	v_exp_f32_e32 v55, v55
	v_add_f32_e32 v54, 1.0, v54
	v_add_f32_e32 v55, 1.0, v55
	v_rcp_f32_e32 v54, v54
	v_rcp_f32_e32 v55, v55
	s_nop 0
	v_pk_mul_f32 v[48:49], v[48:49], v[54:55]
	s_nop 0
	v_pk_mul_f32 v[54:55], v[50:51], v[48:49]
	v_cvt_pk_bf16_f32 v48, v56, v57
	v_cvt_pk_bf16_f32 v49, v58, v59
	v_cvt_pk_bf16_f32 v50, v52, v53
	v_cvt_pk_bf16_f32 v51, v54, v55
	global_store_dwordx4 v[60:61], v[48:51], off
	s_nop 1
	v_mul_f32_e32 v50, 0xbfb8aa3b, v44
	v_mul_f32_e32 v51, 0xbfb8aa3b, v45
	v_exp_f32_e32 v50, v50
	v_exp_f32_e32 v51, v51
	v_mad_i64_i32 v[48:49], s[4:5], v152, s11, v[132:133]
	v_add_f32_e32 v50, 1.0, v50
	v_add_f32_e32 v51, 1.0, v51
	v_rcp_f32_e32 v50, v50
	v_rcp_f32_e32 v51, v51
	s_nop 0
	v_pk_mul_f32 v[44:45], v[44:45], v[50:51]
	s_nop 0
	v_pk_mul_f32 v[40:41], v[40:41], v[44:45]
	v_pk_mul_f32 v[44:45], v[46:47], v[148:149] op_sel_hi:[1,0]
	s_nop 0
	v_mul_f32_e32 v46, 0xbfb8aa3b, v44
	v_mul_f32_e32 v47, 0xbfb8aa3b, v45
	v_exp_f32_e32 v46, v46
	v_exp_f32_e32 v47, v47
	v_add_f32_e32 v46, 1.0, v46
	v_add_f32_e32 v47, 1.0, v47
	v_rcp_f32_e32 v46, v46
	v_rcp_f32_e32 v47, v47
	s_nop 0
	v_pk_mul_f32 v[44:45], v[44:45], v[46:47]
	s_nop 0
	v_pk_mul_f32 v[42:43], v[42:43], v[44:45]
	v_mul_f32_e32 v44, 0xbfb8aa3b, v36
	v_mul_f32_e32 v45, 0xbfb8aa3b, v37
	v_exp_f32_e32 v44, v44
	v_exp_f32_e32 v45, v45
	v_add_f32_e32 v44, 1.0, v44
	v_add_f32_e32 v45, 1.0, v45
	v_rcp_f32_e32 v44, v44
	v_rcp_f32_e32 v45, v45
	s_nop 0
	v_pk_mul_f32 v[36:37], v[36:37], v[44:45]
	s_nop 0
	v_pk_mul_f32 v[36:37], v[32:33], v[36:37]
	v_pk_mul_f32 v[32:33], v[38:39], v[148:149] op_sel_hi:[1,0]
	v_lshl_add_u64 v[44:45], v[48:49], 0, v[112:113]
	v_mul_f32_e32 v38, 0xbfb8aa3b, v32
	v_mul_f32_e32 v39, 0xbfb8aa3b, v33
	v_exp_f32_e32 v38, v38
	v_exp_f32_e32 v39, v39
	v_add_f32_e32 v38, 1.0, v38
	v_add_f32_e32 v39, 1.0, v39
	v_rcp_f32_e32 v38, v38
	v_rcp_f32_e32 v39, v39
	s_nop 0
	v_pk_mul_f32 v[32:33], v[32:33], v[38:39]
	s_nop 0
	v_pk_mul_f32 v[38:39], v[34:35], v[32:33]
	v_cvt_pk_bf16_f32 v32, v40, v41
	v_cvt_pk_bf16_f32 v33, v42, v43
; DEV float siluf(float x) { return x * __builtin_amdgcn_rcpf(1.0f + __builtin_amdgcn_exp2f(x * -1.4426950408889634f)); }
; DEV bf16x8 pack8(f32x4 a, f32x4 b) { u32x4 w; w.x = cvt_pk_bf16(a[0], a[1]); w.y = cvt_pk_bf16(a[2], a[3]); w.z = cvt_pk_bf16(b[0], b[1]); w.w = cvt_pk_bf16(b[2], b[3]); return __builtin_bit_cast(bf16x8, w); }
; #define PG8_WAIT_V(n) asm volatile("s_waitcnt vmcnt(" #n ")" ::: "memory")
; #define PG8_BAR __builtin_amdgcn_s_barrier()
; template <class Epi>
; DEV void gemm_phase(LAS unsigned char* lds, const Gemm g, const StaticOrder& S, const Epi& E) {
;     ...
;         E(acc, cur, wr, wc, fr, fq);
;         if (!has_next) break;
; #pragma unroll
;         for (int a = 0; a < 2; ++a)
; #pragma unroll
;             for (int b = 0; b < 2; ++b)
; #pragma unroll
;                 for (int m = 0; m < 4; ++m)
; #pragma unroll
;                     for (int n = 0; n < 2; ++n) acc[a][b][m][n] = (f32x4){0.f, 0.f, 0.f, 0.f};
;         cur = nxt; cA = nA; cB = nB; ++ui;
;     }
;     PG8_WAIT_V(0);
;     if (wr == 0) PG8_BAR;
;     DEV void operator()(AccRef acc, const pg8::Unit& u, int wr, int wc, int fr, int fq) const {
;     ...
;             for (int m = 0; m < 4; ++m) { u16* rowp = O + (size_t)(row0 + ai * 128 + m * 16) * 5632 + col0; const float rs = rsv[ai][m]; f32x4 r[2];
; #pragma unroll
;                 for (int n = 0; n < 2; ++n) { const f32x4 g = acc[ai][0][m][n] * rs, uu = acc[ai][1][m][n] * rs;
; #pragma unroll
;                     for (int e = 0; e < 4; ++e) r[n][e] = siluf(g[e]) * uu[e]; }
;                 *(u32x4*)rowp = __builtin_bit_cast(u32x4, pack8(r[0], r[1])); }
	v_cvt_pk_bf16_f32 v34, v36, v37
	v_cvt_pk_bf16_f32 v35, v38, v39
	global_store_dwordx4 v[44:45], v[32:35], off
	s_nop 1
	v_mul_f32_e32 v34, 0xbfb8aa3b, v28
	v_mul_f32_e32 v35, 0xbfb8aa3b, v29
	v_exp_f32_e32 v34, v34
	v_exp_f32_e32 v35, v35
	v_mad_i64_i32 v[32:33], s[4:5], v150, s11, v[132:133]
	v_add_f32_e32 v34, 1.0, v34
	v_add_f32_e32 v35, 1.0, v35
	v_rcp_f32_e32 v34, v34
	v_rcp_f32_e32 v35, v35
	s_nop 0
	v_pk_mul_f32 v[28:29], v[28:29], v[34:35]
	s_nop 0
	v_pk_mul_f32 v[24:25], v[24:25], v[28:29]
	v_pk_mul_f32 v[28:29], v[30:31], v[130:131] op_sel_hi:[1,0]
	s_nop 0
	v_mul_f32_e32 v30, 0xbfb8aa3b, v28
	v_mul_f32_e32 v31, 0xbfb8aa3b, v29
	v_exp_f32_e32 v30, v30
	v_exp_f32_e32 v31, v31
	v_add_f32_e32 v30, 1.0, v30
	v_add_f32_e32 v31, 1.0, v31
	v_rcp_f32_e32 v30, v30
	v_rcp_f32_e32 v31, v31
	s_nop 0
	v_pk_mul_f32 v[28:29], v[28:29], v[30:31]
	s_nop 0
	v_pk_mul_f32 v[26:27], v[26:27], v[28:29]
	v_mul_f32_e32 v28, 0xbfb8aa3b, v20
	v_mul_f32_e32 v29, 0xbfb8aa3b, v21
	v_exp_f32_e32 v28, v28
	v_exp_f32_e32 v29, v29
	v_add_f32_e32 v28, 1.0, v28
	v_add_f32_e32 v29, 1.0, v29
	v_rcp_f32_e32 v28, v28
	v_rcp_f32_e32 v29, v29
	s_nop 0
	v_pk_mul_f32 v[20:21], v[20:21], v[28:29]
	s_nop 0
	v_pk_mul_f32 v[20:21], v[16:17], v[20:21]
	v_pk_mul_f32 v[16:17], v[22:23], v[130:131] op_sel_hi:[1,0]
	v_lshl_add_u64 v[28:29], v[32:33], 0, v[112:113]
	v_mul_f32_e32 v22, 0xbfb8aa3b, v16
	v_mul_f32_e32 v23, 0xbfb8aa3b, v17
	v_exp_f32_e32 v22, v22
	v_exp_f32_e32 v23, v23
	v_add_f32_e32 v22, 1.0, v22
	v_add_f32_e32 v23, 1.0, v23
	v_rcp_f32_e32 v22, v22
	v_rcp_f32_e32 v23, v23
	s_nop 0
	v_pk_mul_f32 v[16:17], v[16:17], v[22:23]
	s_nop 0
	v_pk_mul_f32 v[22:23], v[18:19], v[16:17]
	v_cvt_pk_bf16_f32 v16, v24, v25
	v_cvt_pk_bf16_f32 v17, v26, v27
	v_cvt_pk_bf16_f32 v18, v20, v21
	v_cvt_pk_bf16_f32 v19, v22, v23
	global_store_dwordx4 v[28:29], v[16:19], off
	s_nop 1
	v_mul_f32_e32 v18, 0xbfb8aa3b, v12
	v_mul_f32_e32 v19, 0xbfb8aa3b, v13
	v_exp_f32_e32 v18, v18
	v_exp_f32_e32 v19, v19
	v_mad_i64_i32 v[16:17], s[4:5], v146, s11, v[132:133]
	v_add_f32_e32 v18, 1.0, v18
	v_add_f32_e32 v19, 1.0, v19
	v_rcp_f32_e32 v18, v18
	v_rcp_f32_e32 v19, v19
	s_mov_b32 s4, s14
	v_pk_mul_f32 v[12:13], v[12:13], v[18:19]
	s_nop 0
	v_pk_mul_f32 v[8:9], v[8:9], v[12:13]
	v_pk_mul_f32 v[12:13], v[14:15], v[128:129] op_sel_hi:[1,0]
	s_nop 0
	v_mul_f32_e32 v14, 0xbfb8aa3b, v12
	v_mul_f32_e32 v15, 0xbfb8aa3b, v13
	v_exp_f32_e32 v14, v14
	v_exp_f32_e32 v15, v15
	v_add_f32_e32 v14, 1.0, v14
	v_add_f32_e32 v15, 1.0, v15
	v_rcp_f32_e32 v14, v14
	v_rcp_f32_e32 v15, v15
	s_nop 0
	v_pk_mul_f32 v[12:13], v[12:13], v[14:15]
	s_nop 0
	v_pk_mul_f32 v[10:11], v[10:11], v[12:13]
	v_mul_f32_e32 v12, 0xbfb8aa3b, v4
	v_mul_f32_e32 v13, 0xbfb8aa3b, v5
	v_exp_f32_e32 v12, v12
	v_exp_f32_e32 v13, v13
	v_add_f32_e32 v12, 1.0, v12
	v_add_f32_e32 v13, 1.0, v13
	v_rcp_f32_e32 v12, v12
	v_rcp_f32_e32 v13, v13
	s_nop 0
	v_pk_mul_f32 v[4:5], v[4:5], v[12:13]
	s_nop 0
	v_pk_mul_f32 v[4:5], v[0:1], v[4:5]
	v_pk_mul_f32 v[0:1], v[6:7], v[128:129] op_sel_hi:[1,0]
	v_lshl_add_u64 v[12:13], v[16:17], 0, v[112:113]
	v_mul_f32_e32 v6, 0xbfb8aa3b, v0
	v_mul_f32_e32 v7, 0xbfb8aa3b, v1
	v_exp_f32_e32 v6, v6
	v_exp_f32_e32 v7, v7
	v_add_f32_e32 v6, 1.0, v6
	v_add_f32_e32 v7, 1.0, v7
	v_rcp_f32_e32 v6, v6
	v_rcp_f32_e32 v7, v7
	s_nop 0
	v_pk_mul_f32 v[0:1], v[0:1], v[6:7]
	s_nop 0
	v_pk_mul_f32 v[6:7], v[2:3], v[0:1]
	v_cvt_pk_bf16_f32 v0, v8, v9
	v_cvt_pk_bf16_f32 v1, v10, v11
	v_cvt_pk_bf16_f32 v2, v4, v5
	v_cvt_pk_bf16_f32 v3, v6, v7
	global_store_dwordx4 v[12:13], v[0:3], off
	s_cbranch_vccz .LBB0_752
	s_waitcnt vmcnt(0)
	s_cmpk_gt_u32 s27, 0xff
	s_cbranch_scc1 .LBB0_759
	s_barrier
